# u-phase: one-instruction row addresses and select-free first reduction level, act / v-phase code kept at the same placement
# speedup vs baseline: 1.0115x; 1.0115x over previous
; #define LAS __attribute__((address_space(3)))
; #define MFMA32(a, b, c) __builtin_amdgcn_mfma_f32_32x32x16_bf16((a), (b), (c), 0, 0, 0)
; #define CE_(a, b) ce_desc(v[a], v[b])
; __device__ __forceinline__ void sort16_desc(int (&v)[16]) {
;     ...
;     CE_(0,13); CE_(1,12); CE_(2,15); CE_(3,14); CE_(4,8); CE_(5,6); CE_(7,11); CE_(9,10);
;     CE_(0,5); CE_(1,7); CE_(2,9); CE_(3,4); CE_(6,13); CE_(8,14); CE_(10,15); CE_(11,12);
;     CE_(0,1); CE_(2,3); CE_(4,5); CE_(6,8); CE_(7,9); CE_(10,11); CE_(12,13); CE_(14,15);
;     CE_(0,2); CE_(1,3); CE_(4,10); CE_(5,11); CE_(6,7); CE_(8,9); CE_(12,14); CE_(13,15);
;     CE_(1,2); CE_(3,12); CE_(4,6); CE_(5,7); CE_(8,10); CE_(9,11); CE_(13,14);
;     CE_(1,4); CE_(2,6); CE_(5,8); CE_(7,10); CE_(9,13); CE_(11,14);
;     CE_(2,4); CE_(3,6); CE_(9,12); CE_(11,13);
;     CE_(3,5); CE_(6,8); CE_(7,9); CE_(10,12);
;     CE_(3,4); CE_(5,6); CE_(7,8); CE_(9,10); CE_(11,12);
;     CE_(6,7); CE_(8,9);
;     ...
; }
; __device__ __forceinline__ void route_task(int task, int tl0, const bf16* QP  , const LAS bf16* KHL, LAS unsigned short* EL, LAS float* GL, int lane) {
;     const int r = lane & 31, hi = lane >> 5, t = 4 * task + (r >> 3), head = r & 7;
;     int top[2][16]; bf16x8 qa[2][4];
;     { unsigned qo = (unsigned)t * (unsigned)D + (unsigned)(head * 128 + 8 * hi); asm volatile("" : "+v"(qo)); const bf16* qp = QP + qo;
; #pragma unroll
;       for (int hf = 0; hf < 2; ++hf)
; #pragma unroll
;         for (int ks = 0; ks < 4; ++ks) qa[hf][ks] = ldg8(qp + 64 * hf + 16 * ks); }
; #pragma unroll
;     for (int half = 0; half < 2; ++half) {
;         int cur[16];
; #pragma unroll
;         for (int kt = 0; kt < 4; ++kt) {
;             f32x16 X;
; #pragma unroll
;             for (int i = 0; i < 16; ++i) X[i] = 8.f;
;             const LAS bf16* khp = KHL + (half * 128 + 32 * kt + r) * 72 + 8 * hi;
; #pragma unroll
;             for (int ks = 0; ks < 4; ++ks) {
;                 const bf16x8 kh = lds8(khp + 16 * ks);
;                 X = MFMA32(kh, qa[half][ks], X);
;             }
;             int grp[16];
; #pragma unroll
;             for (int i = 0; i < 16; ++i) grp[i] = (int)((__float_as_uint(X[i]) | 127u) - (unsigned)(32 * kt + (i & 3) + 8 * (i >> 2)));
;             sort16_desc(grp);
.LBB0_666:
	s_or_b64 exec, exec, s[10:11]
	s_lshl_b32 s10, s2, 4
	s_add_i32 s10, s10, s95
	s_lshl_b32 s10, s10, 12
	v_or_b32_e32 v82, s10, v88
	s_waitcnt lgkmcnt(0)
	s_barrier
	s_add_i32 s11, 0, 0x12000
	v_lshl_add_u64 v[70:71], v[82:83], 1, s[80:81]
	global_load_dwordx4 v[62:65], v[70:71], off
	global_load_dwordx4 v[54:57], v[70:71], off offset:32
	global_load_dwordx4 v[58:61], v[70:71], off offset:64
	global_load_dwordx4 v[50:53], v[70:71], off offset:96
	ds_read_b128 v[34:37], v94
	ds_read_b128 v[38:41], v94 offset:32
	s_add_i32 s10, s10, 0x8000
	s_mov_b32 s41, 0
	s_waitcnt vmcnt(3) lgkmcnt(1)
	v_mfma_f32_32x32x16_bf16 v[18:33], v[34:37], v[62:65], v[2:17]
	ds_read_b128 v[34:37], v94 offset:64
	ds_read_b128 v[66:69], v94 offset:96
	s_waitcnt vmcnt(2) lgkmcnt(2)
	v_mfma_f32_32x32x16_bf16 v[18:33], v[38:41], v[54:57], v[18:33]
	v_and_b32_e32 v38, 64, v112
	v_add_u32_e32 v122, 64, v38
	v_cmp_lt_i32_e32 vcc, v113, v122
	s_waitcnt vmcnt(1) lgkmcnt(1)
	v_mfma_f32_32x32x16_bf16 v[18:33], v[34:37], v[58:61], v[18:33]
	v_cndmask_b32_e32 v34, v112, v113, vcc
	v_lshlrev_b32_e32 v123, 2, v34
	global_load_dwordx4 v[46:49], v[70:71], off offset:128
	global_load_dwordx4 v[42:45], v[70:71], off offset:160
	global_load_dwordx4 v[38:41], v[70:71], off offset:192
	global_load_dwordx4 v[34:37], v[70:71], off offset:224
	s_waitcnt vmcnt(4) lgkmcnt(0)
	v_mfma_f32_32x32x16_bf16 v[18:33], v[66:69], v[50:53], v[18:33]
	s_nop 11
	s_movk_i32 s42, 0x7f
	s_movk_i32 s43, 0xff80
	v_bitop3_b32 v21, v21, s42, 3 bitop3:0x56
	v_bitop3_b32 v32, v32, s42, 26 bitop3:0x56
	v_bitop3_b32 v22, v22, s42, 8 bitop3:0x56
	v_bitop3_b32 v26, v26, s42, 16 bitop3:0x56
	v_bitop3_b32 v31, v31, s42, 25 bitop3:0x56
	v_bitop3_b32 v23, v23, s42, 9 bitop3:0x56
	v_bitop3_b32 v24, v24, s42, 10 bitop3:0x56
	v_bitop3_b32 v27, v27, s42, 17 bitop3:0x56
	v_bitop3_b32 v28, v28, s42, 18 bitop3:0x56
	v_bitop3_b32 v20, v20, s42, 2 bitop3:0x56
	v_bitop3_b32 v33, v33, s42, 27 bitop3:0x56
	v_bitop3_b32 v25, v25, s42, 11 bitop3:0x56
	v_bitop3_b32 v29, v29, s42, 19 bitop3:0x56
	v_bitop3_b32 v19, v19, s42, 1 bitop3:0x56
	v_bitop3_b32 v30, v30, s42, 24 bitop3:0x56
	v_or_b32_e32 v18, 0x7f, v18
	v_max_i32_e32 v66, v21, v32
	v_max_i32_e32 v67, v22, v26
	v_max_i32_e32 v68, v18, v31
	v_max_i32_e32 v69, v23, v24
	v_min_i32_e32 v70, v27, v28
	v_min_i32_e32 v71, v20, v33
	v_min_i32_e32 v72, v25, v29
	v_min_i32_e32 v73, v19, v30
	v_min_i32_e32 v23, v23, v24
	v_min_i32_e32 v18, v18, v31
	v_min_i32_e32 v22, v22, v26
	v_min_i32_e32 v21, v21, v32
	v_max_i32_e32 v19, v19, v30
	v_max_i32_e32 v24, v25, v29
	v_max_i32_e32 v20, v20, v33
	v_max_i32_e32 v25, v27, v28
	v_min_i32_e32 v26, v66, v67
	v_min_i32_e32 v27, v68, v69
	v_max_i32_e32 v28, v70, v71
	v_max_i32_e32 v29, v72, v73
	v_max_i32_e32 v30, v23, v18
	v_max_i32_e32 v31, v22, v21
	v_min_i32_e32 v32, v19, v24
	v_min_i32_e32 v33, v20, v25
	v_min_i32_e32 v18, v23, v18
	v_min_i32_e32 v21, v22, v21
	v_min_i32_e32 v22, v70, v71
	v_max_i32_e32 v23, v68, v69
	v_max_i32_e32 v19, v19, v24
	v_max_i32_e32 v20, v20, v25
	v_max_i32_e32 v24, v66, v67
	v_min_i32_e32 v25, v26, v27
	v_max_i32_e32 v67, v30, v31
	v_min_i32_e32 v30, v30, v31
	v_min_i32_e32 v31, v32, v33
	v_max_i32_e32 v26, v26, v27
	v_max_i32_e32 v27, v28, v29
	v_min_i32_e32 v66, v28, v29
	v_max_i32_e32 v68, v32, v33
	v_min_i32_e32 v75, v21, v22
	v_max_i32_e32 v21, v21, v22
	v_min_i32_e32 v22, v23, v19
	v_min_i32_e32 v28, v20, v24
	v_max_i32_e32 v33, v30, v31
	v_min_i32_e32 v69, v26, v27
	v_max_i32_e32 v29, v25, v66
	v_min_i32_e32 v32, v67, v68
	v_min_i32_e32 v77, v25, v66
	v_min_i32_e32 v25, v22, v28
	v_max_i32_e32 v80, v22, v28
	v_min_i32_e32 v22, v33, v69
	v_max_i32_e32 v125, v20, v24
	v_max_i32_e32 v129, v67, v68
	v_max_i32_e32 v24, v33, v69
	ds_read_b128 v[66:69], v95
	v_min_i32_e32 v72, v72, v73
	v_min_i32_e32 v74, v72, v18
	v_max_i32_e32 v18, v72, v18
	v_max_i32_e32 v124, v23, v19
	v_min_i32_e32 v76, v30, v31
	v_max_i32_e32 v78, v74, v75
	v_min_i32_e32 v79, v18, v21
	v_min_i32_e32 v126, v124, v125
	v_max_i32_e32 v128, v26, v27
	v_max_i32_e32 v18, v18, v21
	v_max_i32_e32 v81, v76, v77
	v_max_i32_e32 v82, v78, v79
	v_min_i32_e32 v127, v80, v126
	v_min_i32_e32 v130, v128, v129
	v_min_i32_e32 v21, v29, v32
	v_min_i32_e32 v28, v25, v18
	v_max_i32_e32 v18, v25, v18
	v_max_i32_e32 v30, v81, v82
	v_min_i32_e32 v19, v127, v130
	v_max_i32_e32 v23, v29, v32
	v_max_i32_e32 v25, v21, v22
	v_max_i32_e32 v31, v30, v28
	v_min_i32_e32 v20, v18, v19
	v_min_i32_e32 v26, v23, v24
	v_max_i32_e32 v70, v25, v31
	v_min_i32_e32 v27, v20, v26
	v_min_i32_e32 v131, v70, v27
	v_max_i32_e32 v143, v70, v27
	ds_read_b128 v[70:73], v95 offset:32
	v_min_i32_e32 v132, v25, v31
	v_min_i32_e32 v133, v21, v22
	v_min_i32_e32 v134, v30, v28
	v_max_i32_e32 v138, v18, v19
	v_max_i32_e32 v139, v23, v24
	v_max_i32_e32 v141, v20, v26
	s_waitcnt lgkmcnt(1)
	v_mfma_f32_32x32x16_bf16 v[18:33], v[66:69], v[62:65], v[2:17]
	ds_read_b128 v[66:69], v95 offset:64
	v_max_i32_e32 v135, v133, v134
	v_max_i32_e32 v136, v132, v135
	v_min_i32_e32 v76, v76, v77
	v_min_i32_e32 v77, v78, v79
	v_min_i32_e32 v132, v132, v135
	v_max_i32_e32 v127, v127, v130
	s_waitcnt lgkmcnt(1)
	v_mfma_f32_32x32x16_bf16 v[18:33], v[70:73], v[54:57], v[18:33]
	ds_read_b128 v[70:73], v95 offset:96
	v_max_i32_e32 v80, v80, v126
	v_min_i32_e32 v74, v74, v75
	v_min_i32_e32 v140, v138, v139
	v_max_i32_e32 v78, v76, v77
	v_min_i32_e32 v79, v81, v82
	v_min_i32_e32 v82, v133, v134
	s_waitcnt lgkmcnt(1)
	v_mfma_f32_32x32x16_bf16 v[18:33], v[66:69], v[58:61], v[18:33]
	v_max_i32_e32 v66, v128, v129
	v_max_i32_e32 v134, v138, v139
	v_min_i32_e32 v76, v76, v77
	v_max_i32_e32 v81, v78, v79
	v_min_i32_e32 v78, v78, v79
	v_min_i32_e32 v67, v80, v66
	v_min_i32_e32 v142, v140, v141
	s_waitcnt lgkmcnt(0)
; #define LAS __attribute__((address_space(3)))
; #define MFMA32(a, b, c) __builtin_amdgcn_mfma_f32_32x32x16_bf16((a), (b), (c), 0, 0, 0)
; #define CE_(a, b) ce_desc(v[a], v[b])
; __device__ __forceinline__ void sort16_desc(int (&v)[16]) {
;     ...
;     CE_(0,13); CE_(1,12); CE_(2,15); CE_(3,14); CE_(4,8); CE_(5,6); CE_(7,11); CE_(9,10);
;     CE_(0,5); CE_(1,7); CE_(2,9); CE_(3,4); CE_(6,13); CE_(8,14); CE_(10,15); CE_(11,12);
;     CE_(0,1); CE_(2,3); CE_(4,5); CE_(6,8); CE_(7,9); CE_(10,11); CE_(12,13); CE_(14,15);
;     CE_(0,2); CE_(1,3); CE_(4,10); CE_(5,11); CE_(6,7); CE_(8,9); CE_(12,14); CE_(13,15);
;     CE_(1,2); CE_(3,12); CE_(4,6); CE_(5,7); CE_(8,10); CE_(9,11); CE_(13,14);
;     CE_(1,4); CE_(2,6); CE_(5,8); CE_(7,10); CE_(9,13); CE_(11,14);
;     CE_(2,4); CE_(3,6); CE_(9,12); CE_(11,13);
;     CE_(3,5); CE_(6,8); CE_(7,9); CE_(10,12);
;     CE_(3,4); CE_(5,6); CE_(7,8); CE_(9,10); CE_(11,12);
;     CE_(6,7); CE_(8,9);
;     ...
; }
; __device__ __forceinline__ void merge16_desc(int (&a)[16], const int (&b)[16]) {
; #pragma unroll
;     for (int i = 0; i < 16; ++i) a[i] = a[i] > b[15 - i] ? a[i] : b[15 - i];
; #pragma unroll
;     for (int j = 8; j > 0; j >>= 1)
; #pragma unroll
;         for (int i = 0; i < 16; ++i) { const int l = i ^ j; if (l > i) ce_desc(a[i], a[l]); }
; }
; __device__ __forceinline__ void route_task(int task, int tl0, const bf16* QP  , const LAS bf16* KHL, LAS unsigned short* EL, LAS float* GL, int lane) {
;     ...
;         for (int kt = 0; kt < 4; ++kt) {
;             f32x16 X;
; #pragma unroll
;             for (int i = 0; i < 16; ++i) X[i] = 8.f;
;             const LAS bf16* khp = KHL + (half * 128 + 32 * kt + r) * 72 + 8 * hi;
; #pragma unroll
;             for (int ks = 0; ks < 4; ++ks) {
;                 const bf16x8 kh = lds8(khp + 16 * ks);
;                 X = MFMA32(kh, qa[half][ks], X);
;             }
;             int grp[16];
; #pragma unroll
;             for (int i = 0; i < 16; ++i) grp[i] = (int)((__float_as_uint(X[i]) | 127u) - (unsigned)(32 * kt + (i & 3) + 8 * (i >> 2)));
;             sort16_desc(grp);
;             if (kt == 0) {
; #pragma unroll
;                 for (int i = 0; i < 16; ++i) cur[i] = grp[i];
;             } else merge16_desc(cur, grp);
	v_mfma_f32_32x32x16_bf16 v[18:33], v[70:73], v[50:53], v[18:33]
	v_min_i32_e32 v68, v127, v67
	v_min_i32_e32 v137, v131, v136
	v_min_i32_e32 v144, v142, v143
	v_min_i32_e32 v133, v81, v82
	v_min_i32_e32 v69, v134, v68
	s_nop 6
	v_bitop3_b32 v21, v21, s42, 35 bitop3:0x56
	v_bitop3_b32 v32, v32, s42, 58 bitop3:0x56
	v_bitop3_b32 v22, v22, s42, 40 bitop3:0x56
	v_bitop3_b32 v26, v26, s42, 48 bitop3:0x56
	v_bitop3_b32 v18, v18, s42, 32 bitop3:0x56
	v_bitop3_b32 v31, v31, s42, 57 bitop3:0x56
	v_bitop3_b32 v23, v23, s42, 41 bitop3:0x56
	v_bitop3_b32 v24, v24, s42, 42 bitop3:0x56
	v_bitop3_b32 v27, v27, s42, 49 bitop3:0x56
	v_bitop3_b32 v28, v28, s42, 50 bitop3:0x56
	v_bitop3_b32 v20, v20, s42, 34 bitop3:0x56
	v_bitop3_b32 v33, v33, s42, 59 bitop3:0x56
	v_bitop3_b32 v25, v25, s42, 43 bitop3:0x56
	v_bitop3_b32 v29, v29, s42, 51 bitop3:0x56
	v_bitop3_b32 v19, v19, s42, 33 bitop3:0x56
	v_bitop3_b32 v30, v30, s42, 56 bitop3:0x56
	v_max_i32_e32 v70, v21, v32
	v_max_i32_e32 v71, v22, v26
	v_max_i32_e32 v73, v18, v31
	v_max_i32_e32 v75, v23, v24
	v_min_i32_e32 v126, v27, v28
	v_min_i32_e32 v128, v20, v33
	v_min_i32_e32 v130, v25, v29
	v_min_i32_e32 v135, v19, v30
	v_min_i32_e32 v23, v23, v24
	v_min_i32_e32 v18, v18, v31
	v_min_i32_e32 v22, v22, v26
	v_min_i32_e32 v21, v21, v32
	v_max_i32_e32 v19, v19, v30
	v_max_i32_e32 v25, v25, v29
	v_max_i32_e32 v20, v20, v33
	v_max_i32_e32 v27, v27, v28
	v_min_i32_e32 v72, v70, v71
	v_min_i32_e32 v77, v73, v75
	v_max_i32_e32 v129, v126, v128
	v_max_i32_e32 v138, v130, v135
	v_max_i32_e32 v24, v23, v18
	v_max_i32_e32 v26, v22, v21
	v_min_i32_e32 v29, v19, v25
	v_min_i32_e32 v28, v20, v27
	v_min_i32_e32 v130, v130, v135
	v_min_i32_e32 v18, v23, v18
	v_min_i32_e32 v21, v22, v21
	v_min_i32_e32 v22, v126, v128
	v_max_i32_e32 v73, v73, v75
	v_max_i32_e32 v19, v19, v25
	v_max_i32_e32 v20, v20, v27
	v_max_i32_e32 v27, v70, v71
	v_min_i32_e32 v79, v72, v77
	v_min_i32_e32 v139, v129, v138
	v_max_i32_e32 v31, v24, v26
	v_max_i32_e32 v30, v29, v28
	v_min_i32_e32 v24, v24, v26
	v_min_i32_e32 v26, v29, v28
	v_max_i32_e32 v29, v72, v77
	v_max_i32_e32 v72, v129, v138
	v_min_i32_e32 v23, v130, v18
	v_min_i32_e32 v126, v21, v22
	v_max_i32_e32 v18, v130, v18
	v_max_i32_e32 v21, v21, v22
	v_min_i32_e32 v25, v73, v19
	v_min_i32_e32 v70, v20, v27
	v_max_i32_e32 v19, v73, v19
	v_max_i32_e32 v20, v20, v27
	v_min_i32_e32 v32, v31, v30
	v_max_i32_e32 v28, v24, v26
	v_min_i32_e32 v77, v29, v72
	v_min_i32_e32 v24, v24, v26
	v_min_i32_e32 v26, v79, v139
	v_max_i32_e32 v128, v23, v126
	v_min_i32_e32 v22, v18, v21
	v_min_i32_e32 v71, v25, v70
	v_max_i32_e32 v25, v25, v70
	v_min_i32_e32 v27, v19, v20
	v_max_i32_e32 v29, v29, v72
	v_max_i32_e32 v30, v31, v30
	v_max_i32_e32 v145, v79, v139
	v_max_i32_e32 v79, v24, v26
	v_max_i32_e32 v130, v128, v22
	v_max_i32_e32 v18, v18, v21
	v_min_i32_e32 v70, v25, v27
	v_min_i32_e32 v31, v29, v30
	v_min_i32_e32 v33, v145, v32
	v_min_i32_e32 v129, v28, v77
	v_max_i32_e32 v135, v79, v130
	v_min_i32_e32 v21, v71, v18
	v_max_i32_e32 v18, v71, v18
	v_min_i32_e32 v71, v70, v31
	v_max_i32_e32 v32, v145, v32
	v_max_i32_e32 v28, v28, v77
	v_max_i32_e32 v138, v33, v129
	v_max_i32_e32 v75, v135, v21
	v_min_i32_e32 v72, v18, v71
	v_min_i32_e32 v73, v32, v28
	v_min_i32_e32 v33, v33, v129
	v_min_i32_e32 v21, v135, v21
	v_max_i32_e32 v18, v18, v71
	v_max_i32_e32 v28, v32, v28
	v_min_i32_e32 v24, v24, v26
	v_min_i32_e32 v22, v128, v22
	v_max_i32_e32 v25, v25, v27
	v_max_i32_e32 v27, v29, v30
	v_max_i32_e32 v139, v138, v75
	v_min_i32_e32 v77, v72, v73
	v_min_i32_e32 v75, v138, v75
	v_max_i32_e32 v129, v33, v21
	v_min_i32_e32 v32, v18, v28
	v_max_i32_e32 v71, v72, v73
	v_max_i32_e32 v26, v24, v22
	v_min_i32_e32 v79, v79, v130
	v_max_i32_e32 v18, v18, v28
	v_max_i32_e32 v28, v70, v31
	v_min_i32_e32 v29, v25, v27
	v_min_i32_e32 v145, v139, v77
	v_max_i32_e32 v135, v75, v129
	v_min_i32_e32 v72, v32, v71
	v_max_i32_e32 v73, v139, v77
	v_max_i32_e32 v128, v26, v79
	v_min_i32_e32 v21, v33, v21
	v_min_i32_e32 v30, v28, v29
	v_min_i32_e32 v138, v145, v135
	v_min_i32_e32 v77, v72, v73
	v_min_i32_e32 v33, v128, v21
	v_min_i32_e32 v75, v75, v129
	v_min_i32_e32 v31, v18, v30
	v_min_i32_e32 v26, v26, v79
	v_min_i32_e32 v22, v24, v22
	v_min_i32_e32 v23, v23, v126
	v_max3_i32 v23, v124, v125, v23
	v_max3_i32 v22, v80, v66, v22
	v_max3_i32 v24, v127, v67, v26
	v_max3_i32 v26, v134, v68, v33
	v_max3_i32 v21, v69, v128, v21
	v_max3_i32 v33, v140, v141, v75
	v_max3_i32 v66, v142, v143, v138
	v_max3_i32 v67, v144, v145, v135
	v_max3_i32 v68, v131, v136, v77
	v_max3_i32 v69, v137, v72, v73
	v_max3_i32 v32, v132, v32, v71
	v_max3_i32 v31, v81, v82, v31
	v_max3_i32 v18, v133, v18, v30
	v_max3_i32 v28, v78, v28, v29
	v_max3_i32 v25, v76, v25, v27
	v_max3_i32 v19, v74, v19, v20
	v_max_i32_e32 v20, v23, v68
	v_min_i32_e32 v23, v23, v68
	v_max_i32_e32 v27, v22, v69
	v_min_i32_e32 v22, v22, v69
	v_max_i32_e32 v29, v24, v32
	v_min_i32_e32 v24, v24, v32
	v_max_i32_e32 v30, v26, v31
	v_min_i32_e32 v26, v26, v31
	v_max_i32_e32 v31, v21, v18
	v_min_i32_e32 v18, v21, v18
	v_max_i32_e32 v21, v33, v28
	v_min_i32_e32 v28, v33, v28
	v_max_i32_e32 v32, v66, v25
	v_min_i32_e32 v25, v66, v25
	v_max_i32_e32 v33, v67, v19
	v_min_i32_e32 v19, v67, v19
	ds_read_b128 v[66:69], v94 offset:9216
	v_max_i32_e32 v70, v20, v31
	v_min_i32_e32 v74, v20, v31
	v_max_i32_e32 v20, v27, v21
	v_min_i32_e32 v75, v27, v21
	v_max_i32_e32 v21, v29, v32
	v_max_i32_e32 v27, v30, v33
	v_max_i32_e32 v127, v70, v21
	v_min_i32_e32 v128, v70, v21
	ds_read_b128 v[70:73], v94 offset:9248
	v_min_i32_e32 v76, v29, v32
	v_min_i32_e32 v77, v30, v33
	v_max_i32_e32 v78, v23, v18
	v_min_i32_e32 v79, v23, v18
	v_max_i32_e32 v80, v22, v28
	v_min_i32_e32 v81, v22, v28
	v_max_i32_e32 v82, v24, v25
	v_min_i32_e32 v124, v24, v25
	v_max_i32_e32 v125, v26, v19
	v_min_i32_e32 v126, v26, v19
	v_max_i32_e32 v129, v20, v27
	v_min_i32_e32 v130, v20, v27
	s_waitcnt lgkmcnt(1)
; #define LAS __attribute__((address_space(3)))
; #define MFMA32(a, b, c) __builtin_amdgcn_mfma_f32_32x32x16_bf16((a), (b), (c), 0, 0, 0)
; #define CE_(a, b) ce_desc(v[a], v[b])
; __device__ __forceinline__ void sort16_desc(int (&v)[16]) {
;     ...
;     CE_(0,13); CE_(1,12); CE_(2,15); CE_(3,14); CE_(4,8); CE_(5,6); CE_(7,11); CE_(9,10);
;     CE_(0,5); CE_(1,7); CE_(2,9); CE_(3,4); CE_(6,13); CE_(8,14); CE_(10,15); CE_(11,12);
;     CE_(0,1); CE_(2,3); CE_(4,5); CE_(6,8); CE_(7,9); CE_(10,11); CE_(12,13); CE_(14,15);
;     CE_(0,2); CE_(1,3); CE_(4,10); CE_(5,11); CE_(6,7); CE_(8,9); CE_(12,14); CE_(13,15);
;     CE_(1,2); CE_(3,12); CE_(4,6); CE_(5,7); CE_(8,10); CE_(9,11); CE_(13,14);
;     CE_(1,4); CE_(2,6); CE_(5,8); CE_(7,10); CE_(9,13); CE_(11,14);
;     CE_(2,4); CE_(3,6); CE_(9,12); CE_(11,13);
;     CE_(3,5); CE_(6,8); CE_(7,9); CE_(10,12);
;     CE_(3,4); CE_(5,6); CE_(7,8); CE_(9,10); CE_(11,12);
;     CE_(6,7); CE_(8,9);
;     ...
; }
; __device__ __forceinline__ void merge16_desc(int (&a)[16], const int (&b)[16]) {
; #pragma unroll
;     for (int i = 0; i < 16; ++i) a[i] = a[i] > b[15 - i] ? a[i] : b[15 - i];
; #pragma unroll
;     for (int j = 8; j > 0; j >>= 1)
; #pragma unroll
;         for (int i = 0; i < 16; ++i) { const int l = i ^ j; if (l > i) ce_desc(a[i], a[l]); }
; }
; __device__ __forceinline__ void route_task(int task, int tl0, const bf16* QP  , const LAS bf16* KHL, LAS unsigned short* EL, LAS float* GL, int lane) {
;     ...
;         for (int kt = 0; kt < 4; ++kt) {
;             f32x16 X;
; #pragma unroll
;             for (int i = 0; i < 16; ++i) X[i] = 8.f;
;             const LAS bf16* khp = KHL + (half * 128 + 32 * kt + r) * 72 + 8 * hi;
; #pragma unroll
;             for (int ks = 0; ks < 4; ++ks) {
;                 const bf16x8 kh = lds8(khp + 16 * ks);
;                 X = MFMA32(kh, qa[half][ks], X);
;             }
;             int grp[16];
; #pragma unroll
;             for (int i = 0; i < 16; ++i) grp[i] = (int)((__float_as_uint(X[i]) | 127u) - (unsigned)(32 * kt + (i & 3) + 8 * (i >> 2)));
;             sort16_desc(grp);
;             if (kt == 0) {
; #pragma unroll
;                 for (int i = 0; i < 16; ++i) cur[i] = grp[i];
;             } else merge16_desc(cur, grp);
	v_mfma_f32_32x32x16_bf16 v[18:33], v[66:69], v[62:65], v[2:17]
	ds_read_b128 v[66:69], v94 offset:9280
	v_max_i32_e32 v131, v74, v76
	v_min_i32_e32 v74, v74, v76
	v_max_i32_e32 v76, v75, v77
	v_min_i32_e32 v75, v75, v77
	v_max_i32_e32 v77, v78, v82
	v_min_i32_e32 v78, v78, v82
	s_waitcnt lgkmcnt(1)
	v_mfma_f32_32x32x16_bf16 v[18:33], v[70:73], v[54:57], v[18:33]
	ds_read_b128 v[70:73], v94 offset:9312
	v_max_i32_e32 v82, v80, v125
	v_min_i32_e32 v80, v80, v125
	v_max_i32_e32 v125, v79, v124
	v_min_i32_e32 v79, v79, v124
	v_max_i32_e32 v124, v81, v126
	v_min_i32_e32 v81, v81, v126
	s_waitcnt lgkmcnt(1)
	v_mfma_f32_32x32x16_bf16 v[18:33], v[66:69], v[58:61], v[18:33]
	v_min_i32_e32 v126, v127, v129
	v_min_i32_e32 v66, v128, v130
	v_min_i32_e32 v67, v131, v76
	v_min_i32_e32 v69, v77, v82
	v_min_i32_e32 v132, v78, v80
	v_min_i32_e32 v133, v125, v124
	v_min_i32_e32 v68, v74, v75
	s_waitcnt lgkmcnt(0)
	v_mfma_f32_32x32x16_bf16 v[18:33], v[70:73], v[50:53], v[18:33]
	v_min_i32_e32 v134, v79, v81
	s_nop 10
	v_and_or_b32 v21, v21, s43, 60
	v_and_or_b32 v32, v32, s43, 37
	v_and_or_b32 v22, v22, s43, 55
	v_and_or_b32 v26, v26, s43, 47
	v_bitop3_b32 v18, v18, s42, 64 bitop3:0x56
	v_and_or_b32 v31, v31, s43, 38
	v_and_or_b32 v23, v23, s43, 54
	v_and_or_b32 v24, v24, s43, 53
	v_and_or_b32 v27, v27, s43, 46
	v_and_or_b32 v28, v28, s43, 45
	v_and_or_b32 v20, v20, s43, 61
	v_and_or_b32 v33, v33, s43, 36
	v_and_or_b32 v25, v25, s43, 52
	v_and_or_b32 v29, v29, s43, 44
	v_and_or_b32 v19, v19, s43, 62
	v_and_or_b32 v30, v30, s43, 39
	v_max_i32_e32 v70, v21, v32
	v_max_i32_e32 v71, v22, v26
	v_max_i32_e32 v73, v18, v31
	v_max_i32_e32 v135, v23, v24
	v_min_i32_e32 v138, v27, v28
	v_min_i32_e32 v139, v20, v33
	v_min_i32_e32 v141, v25, v29
	v_min_i32_e32 v142, v19, v30
	v_min_i32_e32 v23, v23, v24
	v_min_i32_e32 v18, v18, v31
	v_min_i32_e32 v22, v22, v26
	v_min_i32_e32 v21, v21, v32
	v_max_i32_e32 v19, v19, v30
	v_max_i32_e32 v25, v25, v29
	v_max_i32_e32 v20, v20, v33
	v_max_i32_e32 v27, v27, v28
	v_min_i32_e32 v72, v70, v71
	v_min_i32_e32 v136, v73, v135
	v_max_i32_e32 v140, v138, v139
	v_max_i32_e32 v143, v141, v142
	v_max_i32_e32 v24, v23, v18
	v_max_i32_e32 v26, v22, v21
	v_min_i32_e32 v29, v19, v25
	v_min_i32_e32 v28, v20, v27
	v_min_i32_e32 v141, v141, v142
	v_min_i32_e32 v18, v23, v18
	v_min_i32_e32 v21, v22, v21
	v_min_i32_e32 v22, v138, v139
	v_max_i32_e32 v73, v73, v135
	v_max_i32_e32 v19, v19, v25
	v_max_i32_e32 v20, v20, v27
	v_max_i32_e32 v27, v70, v71
	v_min_i32_e32 v137, v72, v136
	v_min_i32_e32 v144, v140, v143
	v_max_i32_e32 v31, v24, v26
	v_max_i32_e32 v30, v29, v28
	v_min_i32_e32 v24, v24, v26
	v_min_i32_e32 v26, v29, v28
	v_max_i32_e32 v29, v72, v136
	v_max_i32_e32 v72, v140, v143
	v_min_i32_e32 v23, v141, v18
	v_min_i32_e32 v138, v21, v22
	v_max_i32_e32 v18, v141, v18
	v_max_i32_e32 v21, v21, v22
	v_min_i32_e32 v25, v73, v19
	v_min_i32_e32 v70, v20, v27
	v_max_i32_e32 v19, v73, v19
	v_max_i32_e32 v20, v20, v27
	v_min_i32_e32 v32, v31, v30
	v_max_i32_e32 v28, v24, v26
	v_min_i32_e32 v136, v29, v72
	v_min_i32_e32 v24, v24, v26
	v_min_i32_e32 v26, v137, v144
	v_max_i32_e32 v139, v23, v138
	v_min_i32_e32 v22, v18, v21
	v_min_i32_e32 v71, v25, v70
	v_max_i32_e32 v25, v25, v70
	v_min_i32_e32 v27, v19, v20
	v_max_i32_e32 v29, v29, v72
	v_max_i32_e32 v30, v31, v30
	v_max_i32_e32 v145, v137, v144
	v_max_i32_e32 v137, v24, v26
	v_max_i32_e32 v141, v139, v22
	v_max_i32_e32 v18, v18, v21
	v_min_i32_e32 v70, v25, v27
	v_min_i32_e32 v31, v29, v30
	v_min_i32_e32 v33, v145, v32
	v_min_i32_e32 v140, v28, v136
	v_max_i32_e32 v142, v137, v141
	v_min_i32_e32 v21, v71, v18
	v_max_i32_e32 v18, v71, v18
	v_min_i32_e32 v71, v70, v31
	v_max_i32_e32 v32, v145, v32
	v_max_i32_e32 v28, v28, v136
	v_max_i32_e32 v143, v33, v140
	v_max_i32_e32 v135, v142, v21
	v_min_i32_e32 v72, v18, v71
	v_min_i32_e32 v73, v32, v28
	v_min_i32_e32 v33, v33, v140
	v_min_i32_e32 v21, v142, v21
	v_max_i32_e32 v18, v18, v71
	v_max_i32_e32 v28, v32, v28
	v_min_i32_e32 v24, v24, v26
	v_min_i32_e32 v22, v139, v22
	v_max_i32_e32 v25, v25, v27
	v_max_i32_e32 v27, v29, v30
	v_max_i32_e32 v144, v143, v135
	v_min_i32_e32 v136, v72, v73
	v_min_i32_e32 v135, v143, v135
	v_max_i32_e32 v140, v33, v21
	v_min_i32_e32 v32, v18, v28
	v_max_i32_e32 v71, v72, v73
	v_max_i32_e32 v26, v24, v22
	v_min_i32_e32 v137, v137, v141
	v_max_i32_e32 v18, v18, v28
	v_max_i32_e32 v28, v70, v31
	v_min_i32_e32 v29, v25, v27
	v_min_i32_e32 v145, v144, v136
	v_max_i32_e32 v142, v135, v140
	v_min_i32_e32 v72, v32, v71
	v_max_i32_e32 v73, v144, v136
	v_max_i32_e32 v139, v26, v137
	v_min_i32_e32 v21, v33, v21
	v_min_i32_e32 v30, v28, v29
	v_min_i32_e32 v143, v145, v142
	v_min_i32_e32 v136, v72, v73
	v_min_i32_e32 v33, v139, v21
	v_max_i32_e32 v21, v139, v21
	v_min_i32_e32 v135, v135, v140
	v_max_i32_e32 v32, v32, v71
	v_min_i32_e32 v31, v18, v30
	v_max_i32_e32 v18, v18, v30
	v_min_i32_e32 v26, v26, v137
	v_min_i32_e32 v22, v24, v22
	v_max_i32_e32 v24, v25, v27
	v_min_i32_e32 v23, v23, v138
	v_max3_i32 v23, v127, v129, v23
	v_max_i32_e32 v22, v126, v22
	v_max3_i32 v25, v128, v130, v26
	v_max_i32_e32 v26, v66, v33
	v_max3_i32 v21, v131, v76, v21
	v_max_i32_e32 v27, v67, v135
	v_max3_i32 v30, v74, v75, v143
	v_max3_i32 v66, v77, v82, v136
	v_max3_i32 v67, v69, v72, v73
	v_max3_i32 v32, v78, v80, v32
	v_max_i32_e32 v31, v132, v31
	v_max3_i32 v18, v125, v124, v18
	v_max3_i32 v28, v133, v28, v29
	v_max3_i32 v24, v79, v81, v24
	v_max3_i32 v33, v68, v145, v142
	v_max3_i32 v19, v134, v19, v20
	v_max_i32_e32 v20, v23, v66
	v_min_i32_e32 v23, v23, v66
	v_max_i32_e32 v29, v22, v67
	v_max_i32_e32 v66, v25, v32
	v_min_i32_e32 v25, v25, v32
	v_max_i32_e32 v32, v26, v31
	v_min_i32_e32 v26, v26, v31
	v_max_i32_e32 v31, v21, v18
	v_min_i32_e32 v18, v21, v18
	v_max_i32_e32 v21, v27, v28
	v_min_i32_e32 v27, v27, v28
	v_max_i32_e32 v28, v30, v24
	v_min_i32_e32 v22, v22, v67
	v_min_i32_e32 v24, v30, v24
	v_max_i32_e32 v30, v33, v19
	v_min_i32_e32 v19, v33, v19
	v_max_i32_e32 v33, v20, v31
	v_min_i32_e32 v74, v20, v31
	v_max_i32_e32 v20, v29, v21
	v_min_i32_e32 v75, v29, v21
	v_max_i32_e32 v21, v66, v28
	v_min_i32_e32 v76, v66, v28
	ds_read_b128 v[66:69], v96
	ds_read_b128 v[70:73], v96 offset:32
	v_max_i32_e32 v28, v32, v30
	v_min_i32_e32 v77, v32, v30
	v_max_i32_e32 v78, v23, v18
	v_min_i32_e32 v79, v23, v18
	v_max_i32_e32 v80, v22, v27
	v_min_i32_e32 v81, v22, v27
	v_max_i32_e32 v82, v25, v24
	v_min_i32_e32 v124, v25, v24
	v_max_i32_e32 v125, v26, v19
	v_min_i32_e32 v126, v26, v19
	v_max_i32_e32 v127, v33, v21
	v_min_i32_e32 v128, v33, v21
	v_max_i32_e32 v129, v20, v28
	v_min_i32_e32 v130, v20, v28
	s_waitcnt lgkmcnt(1)
; #define LAS __attribute__((address_space(3)))
; #define MFMA32(a, b, c) __builtin_amdgcn_mfma_f32_32x32x16_bf16((a), (b), (c), 0, 0, 0)
; #define CE_(a, b) ce_desc(v[a], v[b])
; __device__ __forceinline__ void sort16_desc(int (&v)[16]) {
;     ...
;     CE_(0,13); CE_(1,12); CE_(2,15); CE_(3,14); CE_(4,8); CE_(5,6); CE_(7,11); CE_(9,10);
;     CE_(0,5); CE_(1,7); CE_(2,9); CE_(3,4); CE_(6,13); CE_(8,14); CE_(10,15); CE_(11,12);
;     CE_(0,1); CE_(2,3); CE_(4,5); CE_(6,8); CE_(7,9); CE_(10,11); CE_(12,13); CE_(14,15);
;     CE_(0,2); CE_(1,3); CE_(4,10); CE_(5,11); CE_(6,7); CE_(8,9); CE_(12,14); CE_(13,15);
;     CE_(1,2); CE_(3,12); CE_(4,6); CE_(5,7); CE_(8,10); CE_(9,11); CE_(13,14);
;     CE_(1,4); CE_(2,6); CE_(5,8); CE_(7,10); CE_(9,13); CE_(11,14);
;     CE_(2,4); CE_(3,6); CE_(9,12); CE_(11,13);
;     CE_(3,5); CE_(6,8); CE_(7,9); CE_(10,12);
;     CE_(3,4); CE_(5,6); CE_(7,8); CE_(9,10); CE_(11,12);
;     CE_(6,7); CE_(8,9);
;     ...
; }
; __device__ __forceinline__ void merge16_desc(int (&a)[16], const int (&b)[16]) {
; #pragma unroll
;     for (int i = 0; i < 16; ++i) a[i] = a[i] > b[15 - i] ? a[i] : b[15 - i];
; #pragma unroll
;     for (int j = 8; j > 0; j >>= 1)
; #pragma unroll
;         for (int i = 0; i < 16; ++i) { const int l = i ^ j; if (l > i) ce_desc(a[i], a[l]); }
; }
; __device__ __forceinline__ void route_task(int task, int tl0, const bf16* QP  , const LAS bf16* KHL, LAS unsigned short* EL, LAS float* GL, int lane) {
;     ...
;         for (int kt = 0; kt < 4; ++kt) {
;             f32x16 X;
; #pragma unroll
;             for (int i = 0; i < 16; ++i) X[i] = 8.f;
;             const LAS bf16* khp = KHL + (half * 128 + 32 * kt + r) * 72 + 8 * hi;
; #pragma unroll
;             for (int ks = 0; ks < 4; ++ks) {
;                 const bf16x8 kh = lds8(khp + 16 * ks);
;                 X = MFMA32(kh, qa[half][ks], X);
;             }
;             int grp[16];
; #pragma unroll
;             for (int i = 0; i < 16; ++i) grp[i] = (int)((__float_as_uint(X[i]) | 127u) - (unsigned)(32 * kt + (i & 3) + 8 * (i >> 2)));
;             sort16_desc(grp);
;             if (kt == 0) {
; #pragma unroll
;                 for (int i = 0; i < 16; ++i) cur[i] = grp[i];
;             } else merge16_desc(cur, grp);
	v_mfma_f32_32x32x16_bf16 v[18:33], v[66:69], v[62:65], v[2:17]
	ds_read_b128 v[62:65], v96 offset:64
	v_max_i32_e32 v67, v75, v77
	v_min_i32_e32 v68, v75, v77
	v_max_i32_e32 v75, v80, v125
	v_max_i32_e32 v131, v74, v76
	v_min_i32_e32 v66, v74, v76
	v_max_i32_e32 v69, v78, v82
	s_waitcnt lgkmcnt(1)
	v_mfma_f32_32x32x16_bf16 v[18:33], v[70:73], v[54:57], v[18:33]
	ds_read_b128 v[54:57], v96 offset:96
	v_min_i32_e32 v70, v80, v125
	v_max_i32_e32 v71, v79, v124
	v_min_i32_e32 v72, v79, v124
	v_min_i32_e32 v74, v78, v82
	v_max_i32_e32 v73, v81, v126
	v_min_i32_e32 v76, v81, v126
	s_waitcnt lgkmcnt(1)
	v_mfma_f32_32x32x16_bf16 v[18:33], v[62:65], v[58:61], v[18:33]
	v_min_i32_e32 v77, v127, v129
	v_min_i32_e32 v58, v128, v130
	v_min_i32_e32 v59, v131, v67
	v_min_i32_e32 v60, v66, v68
	v_min_i32_e32 v61, v69, v75
	v_min_i32_e32 v62, v74, v70
	v_min_i32_e32 v63, v71, v73
	s_waitcnt lgkmcnt(0)
	v_mfma_f32_32x32x16_bf16 v[18:33], v[54:57], v[50:53], v[18:33]
	v_min_i32_e32 v64, v72, v76
	s_nop 10
	v_and_or_b32 v25, v25, s43, 20
	v_and_or_b32 v29, v29, s43, 12
	v_and_or_b32 v19, v19, s43, 30
	v_and_or_b32 v30, v30, s43, 7
	v_and_or_b32 v23, v23, s43, 22
	v_and_or_b32 v24, v24, s43, 21
	v_and_or_b32 v18, v18, s43, 31
	v_and_or_b32 v31, v31, s43, 6
	v_and_or_b32 v22, v22, s43, 23
	v_and_or_b32 v26, v26, s43, 15
	v_and_or_b32 v21, v21, s43, 28
	v_and_or_b32 v32, v32, s43, 5
	v_and_or_b32 v27, v27, s43, 14
	v_and_or_b32 v28, v28, s43, 13
	v_and_or_b32 v20, v20, s43, 29
	v_and_or_b32 v33, v33, s43, 4
	v_min_i32_e32 v50, v25, v29
	v_min_i32_e32 v51, v19, v30
	v_min_i32_e32 v53, v23, v24
	v_min_i32_e32 v54, v18, v31
	v_min_i32_e32 v57, v22, v26
	v_min_i32_e32 v65, v21, v32
	v_min_i32_e32 v79, v27, v28
	v_min_i32_e32 v80, v20, v33
	v_max_i32_e32 v18, v18, v31
	v_max_i32_e32 v23, v23, v24
	v_max_i32_e32 v19, v19, v30
	v_max_i32_e32 v25, v25, v29
	v_max_i32_e32 v20, v20, v33
	v_max_i32_e32 v27, v27, v28
	v_max_i32_e32 v21, v21, v32
	v_max_i32_e32 v22, v22, v26
	v_max_i32_e32 v24, v18, v23
	v_max_i32_e32 v29, v19, v25
	v_max_i32_e32 v28, v20, v27
	v_max_i32_e32 v26, v21, v22
	v_min_i32_e32 v30, v24, v29
	v_min_i32_e32 v31, v28, v26
	v_min_i32_e32 v55, v53, v54
	v_min_i32_e32 v32, v30, v31
	v_max_i32_e32 v30, v30, v31
	v_min_i32_e32 v21, v21, v22
	v_min_i32_e32 v18, v18, v23
	v_max_i32_e32 v23, v79, v80
	v_max_i32_e32 v31, v50, v51
	v_max_i32_e32 v53, v53, v54
	v_max_i32_e32 v54, v57, v65
	v_min_i32_e32 v19, v19, v25
	v_min_i32_e32 v20, v20, v27
	v_min_i32_e32 v52, v50, v51
	v_min_i32_e32 v78, v57, v65
	v_min_i32_e32 v81, v79, v80
	v_max_i32_e32 v22, v21, v18
	v_max_i32_e32 v57, v53, v54
	v_max_i32_e32 v25, v19, v20
	v_min_i32_e32 v18, v21, v18
	v_min_i32_e32 v21, v23, v31
	v_min_i32_e32 v56, v52, v55
	v_min_i32_e32 v82, v78, v81
	v_max_i32_e32 v33, v52, v55
	v_max_i32_e32 v52, v78, v81
	v_max_i32_e32 v24, v24, v29
	v_max_i32_e32 v26, v28, v26
	v_max_i32_e32 v50, v23, v31
	v_max_i32_e32 v27, v57, v25
	v_max_i32_e32 v23, v18, v21
	v_min_i32_e32 v25, v57, v25
	v_min_i32_e32 v53, v53, v54
	v_min_i32_e32 v19, v19, v20
	v_max_i32_e32 v55, v33, v52
	v_min_i32_e32 v28, v24, v26
	v_max_i32_e32 v51, v22, v50
	v_max_i32_e32 v31, v23, v25
	v_max_i32_e32 v20, v53, v19
	v_min_i32_e32 v23, v23, v25
	v_min_i32_e32 v19, v53, v19
	v_min_i32_e32 v18, v18, v21
	v_max_i32_e32 v25, v56, v82
	v_min_i32_e32 v33, v33, v52
	v_min_i32_e32 v29, v30, v28
	v_min_i32_e32 v65, v51, v27
	v_min_i32_e32 v22, v22, v50
	v_max_i32_e32 v21, v19, v18
	v_max_i32_e32 v52, v25, v33
	v_max_i32_e32 v78, v32, v55
	v_min_i32_e32 v79, v29, v65
	v_max_i32_e32 v50, v20, v22
	v_min_i32_e32 v20, v20, v22
	v_max_i32_e32 v53, v21, v52
	v_min_i32_e32 v32, v32, v55
	v_max_i32_e32 v80, v78, v79
	v_max_i32_e32 v54, v31, v50
	v_min_i32_e32 v78, v78, v79
	v_min_i32_e32 v31, v31, v50
	v_max_i32_e32 v22, v23, v20
	v_max_i32_e32 v55, v53, v32
	v_min_i32_e32 v18, v19, v18
	v_min_i32_e32 v19, v25, v33
	v_min_i32_e32 v20, v23, v20
	v_min_i32_e32 v23, v53, v32
	v_max_i32_e32 v28, v30, v28
	v_max_i32_e32 v27, v51, v27
	v_min_i32_e32 v124, v56, v82
	v_min_i32_e32 v57, v80, v54
	v_max_i32_e32 v50, v78, v31
	v_max_i32_e32 v56, v22, v55
	v_min_i32_e32 v31, v78, v31
	v_max_i32_e32 v25, v18, v19
	v_min_i32_e32 v21, v21, v52
	v_min_i32_e32 v32, v20, v23
	v_max_i32_e32 v29, v29, v65
	v_min_i32_e32 v30, v28, v27
	v_min_i32_e32 v22, v22, v55
	v_max_i32_e32 v20, v20, v23
	v_min_i32_e32 v79, v57, v50
	v_max_i32_e32 v78, v56, v31
	v_max_i32_e32 v33, v25, v21
	v_max_i32_e32 v53, v80, v54
	v_min_i32_e32 v51, v29, v30
	v_min_i32_e32 v31, v56, v31
	v_max_i32_e32 v23, v22, v20
	v_min_i32_e32 v81, v79, v78
	v_max_i32_e32 v52, v33, v32
	v_max_i32_e32 v54, v53, v51
	v_min_i32_e32 v21, v25, v21
	v_max_i32_e32 v25, v57, v50
	v_min_i32_e32 v55, v31, v23
	v_max_i32_e32 v27, v28, v27
	v_min_i32_e32 v18, v18, v19
	v_min_i32_e32 v20, v22, v20
	v_min_i32_e32 v32, v33, v32
	v_min_i32_e32 v33, v53, v51
	v_max3_i32 v124, v127, v129, v124
	v_max3_i32 v69, v69, v75, v81
	v_max3_i32 v52, v131, v67, v52
	v_max3_i32 v54, v71, v73, v54
	v_max3_i32 v21, v128, v130, v21
	v_max3_i32 v25, v74, v70, v25
	v_max3_i32 v55, v66, v68, v55
	v_max3_i32 v27, v72, v76, v27
	v_max_i32_e32 v18, v77, v18
	v_max3_i32 v19, v61, v79, v78
	v_max_i32_e32 v20, v59, v20
	v_max3_i32 v22, v63, v29, v30
	v_max_i32_e32 v32, v58, v32
	v_max_i32_e32 v33, v62, v33
	v_max3_i32 v23, v60, v31, v23
	v_max3_i32 v24, v64, v24, v26
	v_min_i32_e32 v65, v52, v54
	v_min_i32_e32 v50, v21, v25
	v_min_i32_e32 v61, v18, v19
	v_min_i32_e32 v29, v20, v22
	v_min_i32_e32 v26, v23, v24
	v_max_i32_e32 v59, v124, v69
	v_max_i32_e32 v52, v52, v54
	v_max_i32_e32 v21, v21, v25
	v_max_i32_e32 v25, v55, v27
; __device__ __forceinline__ void merge16_desc(int (&a)[16], const int (&b)[16]) {
; #pragma unroll
;     for (int i = 0; i < 16; ++i) a[i] = a[i] > b[15 - i] ? a[i] : b[15 - i];
; #pragma unroll
;     for (int j = 8; j > 0; j >>= 1)
; #pragma unroll
;         for (int i = 0; i < 16; ++i) { const int l = i ^ j; if (l > i) ce_desc(a[i], a[l]); }
; }
; __device__ __forceinline__ void route_task(int task, int tl0, const bf16* QP  , const LAS bf16* KHL, LAS unsigned short* EL, LAS float* GL, int lane) {
;     ...
;             } else merge16_desc(cur, grp);
;         }
;         { const unsigned h4 = 4u * (unsigned)hi;
; #pragma unroll
;           for (int i = 0; i < 16; ++i) cur[i] -= (int)h4; }
;         int oth[16];
; #pragma unroll
;         for (int i = 0; i < 16; ++i) oth[i] = __shfl_xor(cur[i], 32);
;         merge16_desc(cur, oth);
; #pragma unroll
;         for (int i = 0; i < 16; ++i) top[half][i] = cur[i];
;     }
	v_max_i32_e32 v18, v18, v19
	v_max_i32_e32 v19, v20, v22
	v_max_i32_e32 v22, v32, v33
	v_max_i32_e32 v23, v23, v24
	v_min_i32_e32 v28, v55, v27
	v_max_i32_e32 v54, v59, v52
	v_max_i32_e32 v27, v21, v25
	v_max_i32_e32 v20, v18, v19
	v_max_i32_e32 v24, v22, v23
	v_min_i32_e32 v51, v32, v33
	v_max_i32_e32 v55, v54, v27
	v_max_i32_e32 v32, v20, v24
	v_min_i32_e32 v27, v54, v27
	v_min_i32_e32 v20, v20, v24
	v_max_i32_e32 v24, v27, v20
	v_min_i32_e32 v20, v27, v20
	v_min_i32_e32 v27, v59, v52
	v_min_i32_e32 v21, v21, v25
	v_min_i32_e32 v18, v18, v19
	v_min_i32_e32 v19, v22, v23
	v_min_i32_e32 v75, v124, v69
	v_max_i32_e32 v25, v27, v21
	v_max_i32_e32 v22, v18, v19
	v_min_i32_e32 v21, v27, v21
	v_min_i32_e32 v18, v18, v19
	v_min_i32_e32 v56, v50, v28
	v_min_i32_e32 v31, v51, v26
	v_max_i32_e32 v23, v25, v22
	v_min_i32_e32 v22, v25, v22
	v_max_i32_e32 v19, v21, v18
	v_min_i32_e32 v18, v21, v18
	v_max_i32_e32 v21, v75, v65
	v_max_i32_e32 v25, v50, v28
	v_max_i32_e32 v28, v61, v29
	v_max_i32_e32 v26, v51, v26
	v_min_i32_e32 v67, v75, v65
	v_min_i32_e32 v30, v61, v29
	v_max_i32_e32 v27, v21, v25
	v_min_i32_e32 v21, v21, v25
	v_min_i32_e32 v25, v28, v26
	v_min_i32_e32 v57, v67, v56
	v_min_i32_e32 v53, v30, v31
	v_max_i32_e32 v29, v28, v26
	v_max_i32_e32 v26, v21, v25
	v_min_i32_e32 v21, v21, v25
	v_max_i32_e32 v25, v67, v56
	v_max_i32_e32 v28, v30, v31
	v_min_i32_e32 v58, v57, v53
	v_max_i32_e32 v33, v55, v32
	v_min_i32_e32 v32, v55, v32
	v_max_i32_e32 v50, v27, v29
	v_min_i32_e32 v27, v27, v29
	v_max_i32_e32 v29, v25, v28
	v_min_i32_e32 v25, v25, v28
	v_max_i32_e32 v28, v57, v53
	v_sub_u32_e32 v30, v33, v87
	v_sub_u32_e32 v31, v32, v87
	v_sub_u32_e32 v24, v24, v87
	v_sub_u32_e32 v20, v20, v87
	v_sub_u32_e32 v23, v23, v87
	v_sub_u32_e32 v22, v22, v87
	v_sub_u32_e32 v19, v19, v87
	v_sub_u32_e32 v18, v18, v87
	v_sub_u32_e32 v32, v50, v87
	v_sub_u32_e32 v27, v27, v87
	v_sub_u32_e32 v26, v26, v87
	v_sub_u32_e32 v21, v21, v87
	v_sub_u32_e32 v29, v29, v87
	v_sub_u32_e32 v25, v25, v87
	v_sub_u32_e32 v28, v28, v87
	v_sub_u32_e32 v33, v58, v87
	ds_bpermute_b32 v50, v123, v30
	ds_bpermute_b32 v51, v123, v31
	ds_bpermute_b32 v52, v123, v24
	ds_bpermute_b32 v53, v123, v20
	ds_bpermute_b32 v54, v123, v23
	ds_bpermute_b32 v55, v123, v22
	ds_bpermute_b32 v56, v123, v19
	ds_bpermute_b32 v57, v123, v18
	ds_bpermute_b32 v58, v123, v32
	ds_bpermute_b32 v59, v123, v27
	ds_bpermute_b32 v60, v123, v26
	ds_bpermute_b32 v61, v123, v33
	ds_bpermute_b32 v62, v123, v28
	ds_bpermute_b32 v63, v123, v25
	ds_bpermute_b32 v64, v123, v29
	ds_bpermute_b32 v65, v123, v21
	s_waitcnt lgkmcnt(4)
	v_max_i32_e32 v30, v30, v61
	s_waitcnt lgkmcnt(3)
	v_max_i32_e32 v31, v31, v62
	s_waitcnt lgkmcnt(2)
	v_max_i32_e32 v24, v24, v63
	s_waitcnt lgkmcnt(1)
	v_max_i32_e32 v20, v20, v64
	s_waitcnt lgkmcnt(0)
	v_max_i32_e32 v23, v23, v65
	v_max_i32_e32 v22, v22, v60
	v_max_i32_e32 v19, v19, v59
	v_max_i32_e32 v18, v18, v58
	v_max_i32_e32 v32, v32, v57
	v_max_i32_e32 v27, v27, v56
	v_max_i32_e32 v26, v26, v55
	v_max_i32_e32 v21, v21, v54
	v_max_i32_e32 v29, v29, v53
	v_max_i32_e32 v25, v25, v52
	v_max_i32_e32 v28, v28, v51
	v_max_i32_e32 v33, v33, v50
	v_max_i32_e32 v50, v30, v32
	v_min_i32_e32 v30, v30, v32
	v_max_i32_e32 v32, v31, v27
	v_min_i32_e32 v27, v31, v27
	v_max_i32_e32 v31, v24, v26
	v_min_i32_e32 v24, v24, v26
	v_max_i32_e32 v26, v20, v21
	v_min_i32_e32 v20, v20, v21
	v_max_i32_e32 v21, v23, v29
	v_min_i32_e32 v23, v23, v29
	v_max_i32_e32 v29, v22, v25
	v_min_i32_e32 v22, v22, v25
	v_max_i32_e32 v25, v19, v28
	v_min_i32_e32 v19, v19, v28
	v_max_i32_e32 v28, v18, v33
	v_min_i32_e32 v18, v18, v33
	v_max_i32_e32 v33, v50, v21
	v_min_i32_e32 v21, v50, v21
	v_max_i32_e32 v50, v32, v29
	v_min_i32_e32 v29, v32, v29
	v_max_i32_e32 v32, v31, v25
	v_min_i32_e32 v25, v31, v25
	v_max_i32_e32 v31, v26, v28
	v_max_i32_e32 v64, v50, v31
	v_min_i32_e32 v67, v50, v31
	ds_read_b128 v[50:53], v94 offset:18432
	ds_read_b128 v[54:57], v94 offset:18464
	v_min_i32_e32 v26, v26, v28
	v_max_i32_e32 v28, v30, v23
	v_min_i32_e32 v58, v30, v23
	v_max_i32_e32 v23, v27, v22
	v_min_i32_e32 v59, v27, v22
	v_max_i32_e32 v22, v24, v19
	v_min_i32_e32 v60, v24, v19
	v_max_i32_e32 v19, v20, v18
	v_min_i32_e32 v61, v20, v18
	v_max_i32_e32 v62, v33, v32
	v_min_i32_e32 v66, v33, v32
	v_max_i32_e32 v68, v21, v25
	v_min_i32_e32 v69, v21, v25
	v_max_i32_e32 v70, v29, v26
	v_min_i32_e32 v71, v29, v26
	v_max_i32_e32 v72, v28, v22
	v_min_i32_e32 v73, v28, v22
	v_max_i32_e32 v74, v23, v19
	v_min_i32_e32 v75, v23, v19
	s_waitcnt vmcnt(3) lgkmcnt(1)
	v_mfma_f32_32x32x16_bf16 v[18:33], v[50:53], v[46:49], v[2:17]
	ds_read_b128 v[50:53], v94 offset:18496
	v_max_i32_e32 v76, v58, v60
	v_min_i32_e32 v77, v58, v60
	v_max_i32_e32 v78, v59, v61
	v_min_i32_e32 v79, v59, v61
	v_max_i32_e32 v63, v62, v64
	v_min_i32_e32 v65, v62, v64
	s_waitcnt vmcnt(2) lgkmcnt(1)
	v_mfma_f32_32x32x16_bf16 v[18:33], v[54:57], v[42:45], v[18:33]
	v_max_i32_e32 v64, v66, v67
	v_min_i32_e32 v62, v66, v67
	v_max_i32_e32 v61, v68, v70
	v_min_i32_e32 v60, v68, v70
	v_max_i32_e32 v59, v69, v71
	v_min_i32_e32 v57, v69, v71
	ds_read_b128 v[66:69], v94 offset:18528
	s_waitcnt vmcnt(1) lgkmcnt(1)
	v_mfma_f32_32x32x16_bf16 v[18:33], v[50:53], v[38:41], v[18:33]
	v_max_i32_e32 v55, v72, v74
	v_min_i32_e32 v58, v72, v74
	v_max_i32_e32 v56, v73, v75
	v_min_i32_e32 v54, v73, v75
	v_max_i32_e32 v53, v76, v78
	v_min_i32_e32 v52, v76, v78
	v_max_i32_e32 v51, v77, v79
	s_waitcnt vmcnt(0) lgkmcnt(0)
; #define LAS __attribute__((address_space(3)))
; #define MFMA32(a, b, c) __builtin_amdgcn_mfma_f32_32x32x16_bf16((a), (b), (c), 0, 0, 0)
; #define CE_(a, b) ce_desc(v[a], v[b])
; __device__ __forceinline__ void sort16_desc(int (&v)[16]) {
;     ...
;     CE_(0,13); CE_(1,12); CE_(2,15); CE_(3,14); CE_(4,8); CE_(5,6); CE_(7,11); CE_(9,10);
;     CE_(0,5); CE_(1,7); CE_(2,9); CE_(3,4); CE_(6,13); CE_(8,14); CE_(10,15); CE_(11,12);
;     CE_(0,1); CE_(2,3); CE_(4,5); CE_(6,8); CE_(7,9); CE_(10,11); CE_(12,13); CE_(14,15);
;     CE_(0,2); CE_(1,3); CE_(4,10); CE_(5,11); CE_(6,7); CE_(8,9); CE_(12,14); CE_(13,15);
;     CE_(1,2); CE_(3,12); CE_(4,6); CE_(5,7); CE_(8,10); CE_(9,11); CE_(13,14);
;     CE_(1,4); CE_(2,6); CE_(5,8); CE_(7,10); CE_(9,13); CE_(11,14);
;     CE_(2,4); CE_(3,6); CE_(9,12); CE_(11,13);
;     CE_(3,5); CE_(6,8); CE_(7,9); CE_(10,12);
;     CE_(3,4); CE_(5,6); CE_(7,8); CE_(9,10); CE_(11,12);
;     CE_(6,7); CE_(8,9);
;     ...
; }
; __device__ __forceinline__ void route_task(int task, int tl0, const bf16* QP  , const LAS bf16* KHL, LAS unsigned short* EL, LAS float* GL, int lane) {
;     ...
;         for (int kt = 0; kt < 4; ++kt) {
;             f32x16 X;
; #pragma unroll
;             for (int i = 0; i < 16; ++i) X[i] = 8.f;
;             const LAS bf16* khp = KHL + (half * 128 + 32 * kt + r) * 72 + 8 * hi;
; #pragma unroll
;             for (int ks = 0; ks < 4; ++ks) {
;                 const bf16x8 kh = lds8(khp + 16 * ks);
;                 X = MFMA32(kh, qa[half][ks], X);
;             }
;             int grp[16];
; #pragma unroll
;             for (int i = 0; i < 16; ++i) grp[i] = (int)((__float_as_uint(X[i]) | 127u) - (unsigned)(32 * kt + (i & 3) + 8 * (i >> 2)));
;             sort16_desc(grp);
;             if (kt == 0) {
; #pragma unroll
;                 for (int i = 0; i < 16; ++i) cur[i] = grp[i];
;             } else merge16_desc(cur, grp);
	v_or_b32_e32 v146, s10, v88
	v_mov_b32_e32 v147, v83
	v_lshl_add_u64 v[148:149], v[146:147], 1, s[80:81]
	global_load_dwordx4 v[150:153], v[148:149], off
	global_load_dwordx4 v[154:157], v[148:149], off offset:32
	global_load_dwordx4 v[158:161], v[148:149], off offset:64
	global_load_dwordx4 v[162:165], v[148:149], off offset:96
	global_load_dwordx4 v[166:169], v[148:149], off offset:128
	global_load_dwordx4 v[170:173], v[148:149], off offset:160
	global_load_dwordx4 v[174:177], v[148:149], off offset:192
	global_load_dwordx4 v[178:181], v[148:149], off offset:224
	v_mfma_f32_32x32x16_bf16 v[18:33], v[66:69], v[34:37], v[18:33]
	v_min_i32_e32 v50, v77, v79
	s_nop 10
	v_bitop3_b32 v21, v21, s42, 3 bitop3:0x56
	v_bitop3_b32 v32, v32, s42, 26 bitop3:0x56
	v_bitop3_b32 v22, v22, s42, 8 bitop3:0x56
	v_bitop3_b32 v26, v26, s42, 16 bitop3:0x56
	v_bitop3_b32 v31, v31, s42, 25 bitop3:0x56
	v_bitop3_b32 v23, v23, s42, 9 bitop3:0x56
	v_bitop3_b32 v24, v24, s42, 10 bitop3:0x56
	v_bitop3_b32 v27, v27, s42, 17 bitop3:0x56
	v_bitop3_b32 v28, v28, s42, 18 bitop3:0x56
	v_bitop3_b32 v20, v20, s42, 2 bitop3:0x56
	v_bitop3_b32 v33, v33, s42, 27 bitop3:0x56
	v_bitop3_b32 v25, v25, s42, 11 bitop3:0x56
	v_bitop3_b32 v29, v29, s42, 19 bitop3:0x56
	v_bitop3_b32 v19, v19, s42, 1 bitop3:0x56
	v_bitop3_b32 v30, v30, s42, 24 bitop3:0x56
	v_or_b32_e32 v18, 0x7f, v18
	v_max_i32_e32 v66, v21, v32
	v_max_i32_e32 v67, v22, v26
	v_max_i32_e32 v69, v18, v31
	v_max_i32_e32 v70, v23, v24
	v_min_i32_e32 v73, v27, v28
	v_min_i32_e32 v74, v20, v33
	v_min_i32_e32 v76, v25, v29
	v_min_i32_e32 v77, v19, v30
	v_min_i32_e32 v23, v23, v24
	v_min_i32_e32 v18, v18, v31
	v_min_i32_e32 v22, v22, v26
	v_min_i32_e32 v21, v21, v32
	v_max_i32_e32 v19, v19, v30
	v_max_i32_e32 v25, v25, v29
	v_max_i32_e32 v20, v20, v33
	v_max_i32_e32 v27, v27, v28
	v_max_i32_e32 v24, v23, v18
	v_max_i32_e32 v26, v22, v21
	v_min_i32_e32 v29, v19, v25
	v_min_i32_e32 v28, v20, v27
	v_max_i32_e32 v31, v24, v26
	v_min_i32_e32 v24, v24, v26
	v_min_i32_e32 v26, v29, v28
	v_min_i32_e32 v68, v66, v67
	v_min_i32_e32 v71, v69, v70
	v_max_i32_e32 v75, v73, v74
	v_max_i32_e32 v78, v76, v77
	v_max_i32_e32 v30, v29, v28
	v_max_i32_e32 v28, v24, v26
	v_min_i32_e32 v81, v24, v26
	v_min_i32_e32 v24, v76, v77
	v_min_i32_e32 v18, v23, v18
	v_min_i32_e32 v21, v22, v21
	v_min_i32_e32 v22, v73, v74
	v_min_i32_e32 v72, v68, v71
	v_min_i32_e32 v79, v75, v78
	v_min_i32_e32 v76, v24, v18
	v_min_i32_e32 v74, v21, v22
	v_max_i32_e32 v18, v24, v18
	v_max_i32_e32 v21, v21, v22
	v_max_i32_e32 v23, v69, v70
	v_max_i32_e32 v19, v19, v25
	v_max_i32_e32 v20, v20, v27
	v_max_i32_e32 v25, v66, v67
	v_max_i32_e32 v80, v72, v79
	v_max_i32_e32 v29, v68, v71
	v_max_i32_e32 v68, v75, v78
	v_min_i32_e32 v79, v72, v79
	v_max_i32_e32 v77, v76, v74
	v_min_i32_e32 v124, v18, v21
	v_min_i32_e32 v24, v23, v19
	v_min_i32_e32 v26, v20, v25
	v_min_i32_e32 v32, v31, v30
	v_min_i32_e32 v71, v29, v68
	v_max_i32_e32 v82, v81, v79
	v_max_i32_e32 v125, v77, v124
	v_min_i32_e32 v27, v24, v26
	v_max_i32_e32 v18, v18, v21
	v_min_i32_e32 v33, v80, v32
	v_min_i32_e32 v75, v28, v71
	v_max_i32_e32 v22, v82, v125
	v_min_i32_e32 v21, v27, v18
	v_max_i32_e32 v78, v33, v75
	v_max_i32_e32 v66, v22, v21
	v_max_i32_e32 v70, v78, v66
	v_max_i32_e32 v131, v29, v68
	v_min_i32_e32 v78, v78, v66
	ds_read_b128 v[66:69], v97
	v_max_i32_e32 v127, v23, v19
	v_max_i32_e32 v128, v20, v25
	v_max_i32_e32 v126, v24, v26
	v_min_i32_e32 v129, v127, v128
	v_max_i32_e32 v132, v31, v30
	v_min_i32_e32 v130, v126, v129
	v_min_i32_e32 v133, v131, v132
	v_max_i32_e32 v18, v27, v18
	v_min_i32_e32 v19, v130, v133
	v_max_i32_e32 v23, v80, v32
	v_max_i32_e32 v24, v28, v71
	v_min_i32_e32 v20, v18, v19
	v_min_i32_e32 v25, v23, v24
	v_min_i32_e32 v26, v20, v25
	v_min_i32_e32 v80, v70, v26
	v_max_i32_e32 v143, v70, v26
	ds_read_b128 v[70:73], v97 offset:32
	v_min_i32_e32 v75, v33, v75
	v_min_i32_e32 v134, v22, v21
	v_max_i32_e32 v138, v18, v19
	v_max_i32_e32 v139, v23, v24
	v_max_i32_e32 v141, v20, v25
	s_waitcnt lgkmcnt(1)
	v_mfma_f32_32x32x16_bf16 v[18:33], v[66:69], v[46:49], v[2:17]
	ds_read_b128 v[66:69], v97 offset:64
	v_max_i32_e32 v135, v75, v134
	v_max_i32_e32 v136, v78, v135
	v_min_i32_e32 v79, v81, v79
	v_min_i32_e32 v77, v77, v124
	v_min_i32_e32 v78, v78, v135
	v_max_i32_e32 v130, v130, v133
	s_waitcnt lgkmcnt(1)
	v_mfma_f32_32x32x16_bf16 v[18:33], v[70:73], v[42:45], v[18:33]
	ds_read_b128 v[70:73], v97 offset:96
	v_max_i32_e32 v126, v126, v129
	v_min_i32_e32 v74, v76, v74
	v_min_i32_e32 v140, v138, v139
	v_max_i32_e32 v81, v79, v77
	v_min_i32_e32 v82, v82, v125
	v_min_i32_e32 v75, v75, v134
	s_waitcnt lgkmcnt(1)
	v_mfma_f32_32x32x16_bf16 v[18:33], v[66:69], v[38:41], v[18:33]
	v_max_i32_e32 v66, v131, v132
	v_max_i32_e32 v134, v138, v139
	v_min_i32_e32 v77, v79, v77
	v_max_i32_e32 v124, v81, v82
	v_min_i32_e32 v81, v81, v82
	v_min_i32_e32 v67, v126, v66
	v_min_i32_e32 v142, v140, v141
	s_waitcnt lgkmcnt(0)
; #define LAS __attribute__((address_space(3)))
; #define MFMA32(a, b, c) __builtin_amdgcn_mfma_f32_32x32x16_bf16((a), (b), (c), 0, 0, 0)
; #define CE_(a, b) ce_desc(v[a], v[b])
; __device__ __forceinline__ void sort16_desc(int (&v)[16]) {
;     ...
;     CE_(0,13); CE_(1,12); CE_(2,15); CE_(3,14); CE_(4,8); CE_(5,6); CE_(7,11); CE_(9,10);
;     CE_(0,5); CE_(1,7); CE_(2,9); CE_(3,4); CE_(6,13); CE_(8,14); CE_(10,15); CE_(11,12);
;     CE_(0,1); CE_(2,3); CE_(4,5); CE_(6,8); CE_(7,9); CE_(10,11); CE_(12,13); CE_(14,15);
;     CE_(0,2); CE_(1,3); CE_(4,10); CE_(5,11); CE_(6,7); CE_(8,9); CE_(12,14); CE_(13,15);
;     CE_(1,2); CE_(3,12); CE_(4,6); CE_(5,7); CE_(8,10); CE_(9,11); CE_(13,14);
;     CE_(1,4); CE_(2,6); CE_(5,8); CE_(7,10); CE_(9,13); CE_(11,14);
;     CE_(2,4); CE_(3,6); CE_(9,12); CE_(11,13);
;     CE_(3,5); CE_(6,8); CE_(7,9); CE_(10,12);
;     CE_(3,4); CE_(5,6); CE_(7,8); CE_(9,10); CE_(11,12);
;     CE_(6,7); CE_(8,9);
;     ...
; }
; __device__ __forceinline__ void merge16_desc(int (&a)[16], const int (&b)[16]) {
; #pragma unroll
;     for (int i = 0; i < 16; ++i) a[i] = a[i] > b[15 - i] ? a[i] : b[15 - i];
; #pragma unroll
;     for (int j = 8; j > 0; j >>= 1)
; #pragma unroll
;         for (int i = 0; i < 16; ++i) { const int l = i ^ j; if (l > i) ce_desc(a[i], a[l]); }
; }
; __device__ __forceinline__ void route_task(int task, int tl0, const bf16* QP  , const LAS bf16* KHL, LAS unsigned short* EL, LAS float* GL, int lane) {
;     ...
;         for (int kt = 0; kt < 4; ++kt) {
;             f32x16 X;
; #pragma unroll
;             for (int i = 0; i < 16; ++i) X[i] = 8.f;
;             const LAS bf16* khp = KHL + (half * 128 + 32 * kt + r) * 72 + 8 * hi;
; #pragma unroll
;             for (int ks = 0; ks < 4; ++ks) {
;                 const bf16x8 kh = lds8(khp + 16 * ks);
;                 X = MFMA32(kh, qa[half][ks], X);
;             }
;             int grp[16];
; #pragma unroll
;             for (int i = 0; i < 16; ++i) grp[i] = (int)((__float_as_uint(X[i]) | 127u) - (unsigned)(32 * kt + (i & 3) + 8 * (i >> 2)));
;             sort16_desc(grp);
;             if (kt == 0) {
; #pragma unroll
;                 for (int i = 0; i < 16; ++i) cur[i] = grp[i];
;             } else merge16_desc(cur, grp);
	v_mfma_f32_32x32x16_bf16 v[18:33], v[70:73], v[34:37], v[18:33]
	v_min_i32_e32 v68, v130, v67
	v_min_i32_e32 v137, v80, v136
	v_min_i32_e32 v144, v142, v143
	v_min_i32_e32 v125, v124, v75
	v_min_i32_e32 v69, v134, v68
	s_nop 6
	v_bitop3_b32 v21, v21, s42, 35 bitop3:0x56
	v_bitop3_b32 v32, v32, s42, 58 bitop3:0x56
	v_bitop3_b32 v22, v22, s42, 40 bitop3:0x56
	v_bitop3_b32 v26, v26, s42, 48 bitop3:0x56
	v_bitop3_b32 v18, v18, s42, 32 bitop3:0x56
	v_bitop3_b32 v31, v31, s42, 57 bitop3:0x56
	v_bitop3_b32 v23, v23, s42, 41 bitop3:0x56
	v_bitop3_b32 v24, v24, s42, 42 bitop3:0x56
	v_bitop3_b32 v27, v27, s42, 49 bitop3:0x56
	v_bitop3_b32 v28, v28, s42, 50 bitop3:0x56
	v_bitop3_b32 v20, v20, s42, 34 bitop3:0x56
	v_bitop3_b32 v33, v33, s42, 59 bitop3:0x56
	v_bitop3_b32 v25, v25, s42, 43 bitop3:0x56
	v_bitop3_b32 v29, v29, s42, 51 bitop3:0x56
	v_bitop3_b32 v19, v19, s42, 33 bitop3:0x56
	v_bitop3_b32 v30, v30, s42, 56 bitop3:0x56
	v_max_i32_e32 v70, v21, v32
	v_max_i32_e32 v71, v22, v26
	v_max_i32_e32 v73, v18, v31
	v_max_i32_e32 v76, v23, v24
	v_min_i32_e32 v129, v27, v28
	v_min_i32_e32 v131, v20, v33
	v_min_i32_e32 v133, v25, v29
	v_min_i32_e32 v135, v19, v30
	v_min_i32_e32 v23, v23, v24
	v_min_i32_e32 v18, v18, v31
	v_min_i32_e32 v22, v22, v26
	v_min_i32_e32 v21, v21, v32
	v_max_i32_e32 v19, v19, v30
	v_max_i32_e32 v25, v25, v29
	v_max_i32_e32 v20, v20, v33
	v_max_i32_e32 v27, v27, v28
	v_min_i32_e32 v72, v70, v71
	v_min_i32_e32 v79, v73, v76
	v_max_i32_e32 v132, v129, v131
	v_max_i32_e32 v138, v133, v135
	v_max_i32_e32 v24, v23, v18
	v_max_i32_e32 v26, v22, v21
	v_min_i32_e32 v29, v19, v25
	v_min_i32_e32 v28, v20, v27
	v_min_i32_e32 v133, v133, v135
	v_min_i32_e32 v18, v23, v18
	v_min_i32_e32 v21, v22, v21
	v_min_i32_e32 v22, v129, v131
	v_max_i32_e32 v73, v73, v76
	v_max_i32_e32 v19, v19, v25
	v_max_i32_e32 v20, v20, v27
	v_max_i32_e32 v27, v70, v71
	v_min_i32_e32 v82, v72, v79
	v_min_i32_e32 v139, v132, v138
	v_max_i32_e32 v31, v24, v26
	v_max_i32_e32 v30, v29, v28
	v_min_i32_e32 v24, v24, v26
	v_min_i32_e32 v26, v29, v28
	v_max_i32_e32 v29, v72, v79
	v_max_i32_e32 v72, v132, v138
	v_min_i32_e32 v23, v133, v18
	v_min_i32_e32 v129, v21, v22
	v_max_i32_e32 v18, v133, v18
	v_max_i32_e32 v21, v21, v22
	v_min_i32_e32 v25, v73, v19
	v_min_i32_e32 v70, v20, v27
	v_max_i32_e32 v19, v73, v19
	v_max_i32_e32 v20, v20, v27
	v_min_i32_e32 v32, v31, v30
	v_max_i32_e32 v28, v24, v26
	v_min_i32_e32 v79, v29, v72
	v_min_i32_e32 v24, v24, v26
	v_min_i32_e32 v26, v82, v139
	v_max_i32_e32 v131, v23, v129
	v_min_i32_e32 v22, v18, v21
	v_min_i32_e32 v71, v25, v70
	v_max_i32_e32 v25, v25, v70
	v_min_i32_e32 v27, v19, v20
	v_max_i32_e32 v29, v29, v72
	v_max_i32_e32 v30, v31, v30
	v_max_i32_e32 v145, v82, v139
	v_max_i32_e32 v82, v24, v26
	v_max_i32_e32 v133, v131, v22
	v_max_i32_e32 v18, v18, v21
	v_min_i32_e32 v70, v25, v27
	v_min_i32_e32 v31, v29, v30
	v_min_i32_e32 v33, v145, v32
	v_min_i32_e32 v132, v28, v79
	v_max_i32_e32 v135, v82, v133
	v_min_i32_e32 v21, v71, v18
	v_max_i32_e32 v18, v71, v18
	v_min_i32_e32 v71, v70, v31
	v_max_i32_e32 v32, v145, v32
	v_max_i32_e32 v28, v28, v79
	v_max_i32_e32 v138, v33, v132
	v_max_i32_e32 v76, v135, v21
	v_min_i32_e32 v72, v18, v71
	v_min_i32_e32 v73, v32, v28
	v_min_i32_e32 v33, v33, v132
	v_min_i32_e32 v21, v135, v21
	v_max_i32_e32 v18, v18, v71
	v_max_i32_e32 v28, v32, v28
	v_min_i32_e32 v24, v24, v26
	v_min_i32_e32 v22, v131, v22
	v_max_i32_e32 v25, v25, v27
	v_max_i32_e32 v27, v29, v30
	v_max_i32_e32 v139, v138, v76
	v_min_i32_e32 v79, v72, v73
	v_min_i32_e32 v76, v138, v76
	v_max_i32_e32 v132, v33, v21
	v_min_i32_e32 v32, v18, v28
	v_max_i32_e32 v71, v72, v73
	v_max_i32_e32 v26, v24, v22
	v_min_i32_e32 v82, v82, v133
	v_max_i32_e32 v18, v18, v28
	v_max_i32_e32 v28, v70, v31
	v_min_i32_e32 v29, v25, v27
	v_min_i32_e32 v145, v139, v79
	v_max_i32_e32 v135, v76, v132
	v_min_i32_e32 v72, v32, v71
	v_max_i32_e32 v73, v139, v79
	v_max_i32_e32 v131, v26, v82
	v_min_i32_e32 v21, v33, v21
	v_min_i32_e32 v30, v28, v29
	v_min_i32_e32 v138, v145, v135
	v_min_i32_e32 v79, v72, v73
	v_min_i32_e32 v33, v131, v21
	v_min_i32_e32 v76, v76, v132
	v_min_i32_e32 v31, v18, v30
	v_min_i32_e32 v26, v26, v82
	v_min_i32_e32 v22, v24, v22
	v_min_i32_e32 v23, v23, v129
	v_max3_i32 v23, v127, v128, v23
	v_max3_i32 v22, v126, v66, v22
	v_max3_i32 v24, v130, v67, v26
	v_max3_i32 v26, v134, v68, v33
	v_max3_i32 v21, v69, v131, v21
	v_max3_i32 v33, v140, v141, v76
	v_max3_i32 v66, v142, v143, v138
	v_max3_i32 v67, v144, v145, v135
	v_max3_i32 v68, v80, v136, v79
	v_max3_i32 v69, v137, v72, v73
	v_max3_i32 v32, v78, v32, v71
	v_max3_i32 v31, v124, v75, v31
	v_max3_i32 v18, v125, v18, v30
	v_max3_i32 v28, v81, v28, v29
	v_max3_i32 v25, v77, v25, v27
	v_max3_i32 v19, v74, v19, v20
	v_max_i32_e32 v20, v23, v68
	v_min_i32_e32 v23, v23, v68
	v_max_i32_e32 v27, v22, v69
	v_min_i32_e32 v22, v22, v69
	v_max_i32_e32 v29, v24, v32
	v_min_i32_e32 v24, v24, v32
	v_max_i32_e32 v30, v26, v31
	v_min_i32_e32 v26, v26, v31
	v_max_i32_e32 v31, v21, v18
	v_min_i32_e32 v18, v21, v18
	v_max_i32_e32 v21, v33, v28
	v_min_i32_e32 v28, v33, v28
	v_max_i32_e32 v32, v66, v25
	v_min_i32_e32 v25, v66, v25
	v_max_i32_e32 v33, v67, v19
	v_min_i32_e32 v19, v67, v19
	ds_read_b128 v[66:69], v94 offset:27648
	v_max_i32_e32 v70, v20, v31
	v_min_i32_e32 v74, v20, v31
	v_max_i32_e32 v20, v27, v21
	v_min_i32_e32 v75, v27, v21
	v_max_i32_e32 v21, v29, v32
	v_max_i32_e32 v27, v30, v33
	v_max_i32_e32 v127, v70, v21
	v_min_i32_e32 v128, v70, v21
	ds_read_b128 v[70:73], v94 offset:27680
	v_min_i32_e32 v76, v29, v32
	v_min_i32_e32 v77, v30, v33
	v_max_i32_e32 v78, v23, v18
	v_min_i32_e32 v79, v23, v18
	v_max_i32_e32 v80, v22, v28
	v_min_i32_e32 v81, v22, v28
	v_max_i32_e32 v82, v24, v25
	v_min_i32_e32 v124, v24, v25
	v_max_i32_e32 v125, v26, v19
	v_min_i32_e32 v126, v26, v19
	v_max_i32_e32 v129, v20, v27
	v_min_i32_e32 v130, v20, v27
	s_waitcnt lgkmcnt(1)
; #define LAS __attribute__((address_space(3)))
; #define MFMA32(a, b, c) __builtin_amdgcn_mfma_f32_32x32x16_bf16((a), (b), (c), 0, 0, 0)
; #define CE_(a, b) ce_desc(v[a], v[b])
; __device__ __forceinline__ void sort16_desc(int (&v)[16]) {
;     ...
;     CE_(0,13); CE_(1,12); CE_(2,15); CE_(3,14); CE_(4,8); CE_(5,6); CE_(7,11); CE_(9,10);
;     CE_(0,5); CE_(1,7); CE_(2,9); CE_(3,4); CE_(6,13); CE_(8,14); CE_(10,15); CE_(11,12);
;     CE_(0,1); CE_(2,3); CE_(4,5); CE_(6,8); CE_(7,9); CE_(10,11); CE_(12,13); CE_(14,15);
;     CE_(0,2); CE_(1,3); CE_(4,10); CE_(5,11); CE_(6,7); CE_(8,9); CE_(12,14); CE_(13,15);
;     CE_(1,2); CE_(3,12); CE_(4,6); CE_(5,7); CE_(8,10); CE_(9,11); CE_(13,14);
;     CE_(1,4); CE_(2,6); CE_(5,8); CE_(7,10); CE_(9,13); CE_(11,14);
;     CE_(2,4); CE_(3,6); CE_(9,12); CE_(11,13);
;     CE_(3,5); CE_(6,8); CE_(7,9); CE_(10,12);
;     CE_(3,4); CE_(5,6); CE_(7,8); CE_(9,10); CE_(11,12);
;     CE_(6,7); CE_(8,9);
;     ...
; }
; __device__ __forceinline__ void merge16_desc(int (&a)[16], const int (&b)[16]) {
; #pragma unroll
;     for (int i = 0; i < 16; ++i) a[i] = a[i] > b[15 - i] ? a[i] : b[15 - i];
; #pragma unroll
;     for (int j = 8; j > 0; j >>= 1)
; #pragma unroll
;         for (int i = 0; i < 16; ++i) { const int l = i ^ j; if (l > i) ce_desc(a[i], a[l]); }
; }
; __device__ __forceinline__ void route_task(int task, int tl0, const bf16* QP  , const LAS bf16* KHL, LAS unsigned short* EL, LAS float* GL, int lane) {
;     ...
;         for (int kt = 0; kt < 4; ++kt) {
;             f32x16 X;
; #pragma unroll
;             for (int i = 0; i < 16; ++i) X[i] = 8.f;
;             const LAS bf16* khp = KHL + (half * 128 + 32 * kt + r) * 72 + 8 * hi;
; #pragma unroll
;             for (int ks = 0; ks < 4; ++ks) {
;                 const bf16x8 kh = lds8(khp + 16 * ks);
;                 X = MFMA32(kh, qa[half][ks], X);
;             }
;             int grp[16];
; #pragma unroll
;             for (int i = 0; i < 16; ++i) grp[i] = (int)((__float_as_uint(X[i]) | 127u) - (unsigned)(32 * kt + (i & 3) + 8 * (i >> 2)));
;             sort16_desc(grp);
;             if (kt == 0) {
; #pragma unroll
;                 for (int i = 0; i < 16; ++i) cur[i] = grp[i];
;             } else merge16_desc(cur, grp);
	v_mfma_f32_32x32x16_bf16 v[18:33], v[66:69], v[46:49], v[2:17]
	ds_read_b128 v[66:69], v94 offset:27712
	v_max_i32_e32 v131, v74, v76
	v_min_i32_e32 v74, v74, v76
	v_max_i32_e32 v76, v75, v77
	v_min_i32_e32 v75, v75, v77
	v_max_i32_e32 v77, v78, v82
	v_min_i32_e32 v78, v78, v82
	s_waitcnt lgkmcnt(1)
	v_mfma_f32_32x32x16_bf16 v[18:33], v[70:73], v[42:45], v[18:33]
	ds_read_b128 v[70:73], v94 offset:27744
	v_max_i32_e32 v82, v80, v125
	v_min_i32_e32 v80, v80, v125
	v_max_i32_e32 v125, v79, v124
	v_min_i32_e32 v79, v79, v124
	v_max_i32_e32 v124, v81, v126
	v_min_i32_e32 v81, v81, v126
	s_waitcnt lgkmcnt(1)
	v_mfma_f32_32x32x16_bf16 v[18:33], v[66:69], v[38:41], v[18:33]
	v_min_i32_e32 v126, v127, v129
	v_min_i32_e32 v66, v128, v130
	v_min_i32_e32 v67, v131, v76
	v_min_i32_e32 v69, v77, v82
	v_min_i32_e32 v132, v78, v80
	v_min_i32_e32 v133, v125, v124
	v_min_i32_e32 v68, v74, v75
	s_waitcnt lgkmcnt(0)
	v_mfma_f32_32x32x16_bf16 v[18:33], v[70:73], v[34:37], v[18:33]
	v_min_i32_e32 v134, v79, v81
	s_nop 10
	v_and_or_b32 v21, v21, s43, 60
	v_and_or_b32 v32, v32, s43, 37
	v_and_or_b32 v22, v22, s43, 55
	v_and_or_b32 v26, v26, s43, 47
	v_bitop3_b32 v18, v18, s42, 64 bitop3:0x56
	v_and_or_b32 v31, v31, s43, 38
	v_and_or_b32 v23, v23, s43, 54
	v_and_or_b32 v24, v24, s43, 53
	v_and_or_b32 v27, v27, s43, 46
	v_and_or_b32 v28, v28, s43, 45
	v_and_or_b32 v20, v20, s43, 61
	v_and_or_b32 v33, v33, s43, 36
	v_and_or_b32 v25, v25, s43, 52
	v_and_or_b32 v29, v29, s43, 44
	v_and_or_b32 v19, v19, s43, 62
	v_and_or_b32 v30, v30, s43, 39
	v_max_i32_e32 v70, v21, v32
	v_max_i32_e32 v71, v22, v26
	v_max_i32_e32 v73, v18, v31
	v_max_i32_e32 v135, v23, v24
	v_min_i32_e32 v138, v27, v28
	v_min_i32_e32 v139, v20, v33
	v_min_i32_e32 v141, v25, v29
	v_min_i32_e32 v142, v19, v30
	v_min_i32_e32 v23, v23, v24
	v_min_i32_e32 v18, v18, v31
	v_min_i32_e32 v22, v22, v26
	v_min_i32_e32 v21, v21, v32
	v_max_i32_e32 v19, v19, v30
	v_max_i32_e32 v25, v25, v29
	v_max_i32_e32 v20, v20, v33
	v_max_i32_e32 v27, v27, v28
	v_min_i32_e32 v72, v70, v71
	v_min_i32_e32 v136, v73, v135
	v_max_i32_e32 v140, v138, v139
	v_max_i32_e32 v143, v141, v142
	v_max_i32_e32 v24, v23, v18
	v_max_i32_e32 v26, v22, v21
	v_min_i32_e32 v29, v19, v25
	v_min_i32_e32 v28, v20, v27
	v_min_i32_e32 v141, v141, v142
	v_min_i32_e32 v18, v23, v18
	v_min_i32_e32 v21, v22, v21
	v_min_i32_e32 v22, v138, v139
	v_max_i32_e32 v73, v73, v135
	v_max_i32_e32 v19, v19, v25
	v_max_i32_e32 v20, v20, v27
	v_max_i32_e32 v27, v70, v71
	v_min_i32_e32 v137, v72, v136
	v_min_i32_e32 v144, v140, v143
	v_max_i32_e32 v31, v24, v26
	v_max_i32_e32 v30, v29, v28
	v_min_i32_e32 v24, v24, v26
	v_min_i32_e32 v26, v29, v28
	v_max_i32_e32 v29, v72, v136
	v_max_i32_e32 v72, v140, v143
	v_min_i32_e32 v23, v141, v18
	v_min_i32_e32 v138, v21, v22
	v_max_i32_e32 v18, v141, v18
	v_max_i32_e32 v21, v21, v22
	v_min_i32_e32 v25, v73, v19
	v_min_i32_e32 v70, v20, v27
	v_max_i32_e32 v19, v73, v19
	v_max_i32_e32 v20, v20, v27
	v_min_i32_e32 v32, v31, v30
	v_max_i32_e32 v28, v24, v26
	v_min_i32_e32 v136, v29, v72
	v_min_i32_e32 v24, v24, v26
	v_min_i32_e32 v26, v137, v144
	v_max_i32_e32 v139, v23, v138
	v_min_i32_e32 v22, v18, v21
	v_min_i32_e32 v71, v25, v70
	v_max_i32_e32 v25, v25, v70
	v_min_i32_e32 v27, v19, v20
	v_max_i32_e32 v29, v29, v72
	v_max_i32_e32 v30, v31, v30
	v_max_i32_e32 v145, v137, v144
	v_max_i32_e32 v137, v24, v26
	v_max_i32_e32 v141, v139, v22
	v_max_i32_e32 v18, v18, v21
	v_min_i32_e32 v70, v25, v27
	v_min_i32_e32 v31, v29, v30
	v_min_i32_e32 v33, v145, v32
	v_min_i32_e32 v140, v28, v136
	v_max_i32_e32 v142, v137, v141
	v_min_i32_e32 v21, v71, v18
	v_max_i32_e32 v18, v71, v18
	v_min_i32_e32 v71, v70, v31
	v_max_i32_e32 v32, v145, v32
	v_max_i32_e32 v28, v28, v136
	v_max_i32_e32 v143, v33, v140
	v_max_i32_e32 v135, v142, v21
	v_min_i32_e32 v72, v18, v71
	v_min_i32_e32 v73, v32, v28
	v_min_i32_e32 v33, v33, v140
	v_min_i32_e32 v21, v142, v21
	v_max_i32_e32 v18, v18, v71
	v_max_i32_e32 v28, v32, v28
	v_min_i32_e32 v24, v24, v26
	v_min_i32_e32 v22, v139, v22
	v_max_i32_e32 v25, v25, v27
	v_max_i32_e32 v27, v29, v30
	v_max_i32_e32 v144, v143, v135
	v_min_i32_e32 v136, v72, v73
	v_min_i32_e32 v135, v143, v135
	v_max_i32_e32 v140, v33, v21
	v_min_i32_e32 v32, v18, v28
	v_max_i32_e32 v71, v72, v73
	v_max_i32_e32 v26, v24, v22
	v_min_i32_e32 v137, v137, v141
	v_max_i32_e32 v18, v18, v28
	v_max_i32_e32 v28, v70, v31
	v_min_i32_e32 v29, v25, v27
	v_min_i32_e32 v145, v144, v136
	v_max_i32_e32 v142, v135, v140
	v_min_i32_e32 v72, v32, v71
	v_max_i32_e32 v73, v144, v136
	v_max_i32_e32 v139, v26, v137
	v_min_i32_e32 v21, v33, v21
	v_min_i32_e32 v30, v28, v29
	v_min_i32_e32 v143, v145, v142
	v_min_i32_e32 v136, v72, v73
	v_min_i32_e32 v33, v139, v21
	v_max_i32_e32 v21, v139, v21
	v_min_i32_e32 v135, v135, v140
	v_max_i32_e32 v32, v32, v71
	v_min_i32_e32 v31, v18, v30
	v_max_i32_e32 v18, v18, v30
	v_min_i32_e32 v26, v26, v137
	v_min_i32_e32 v22, v24, v22
	v_max_i32_e32 v24, v25, v27
	v_min_i32_e32 v23, v23, v138
	v_max3_i32 v23, v127, v129, v23
	v_max_i32_e32 v22, v126, v22
	v_max3_i32 v25, v128, v130, v26
	v_max_i32_e32 v26, v66, v33
	v_max3_i32 v21, v131, v76, v21
	v_max_i32_e32 v27, v67, v135
	v_max3_i32 v30, v74, v75, v143
	v_max3_i32 v66, v77, v82, v136
	v_max3_i32 v67, v69, v72, v73
	v_max3_i32 v32, v78, v80, v32
	v_max_i32_e32 v31, v132, v31
	v_max3_i32 v18, v125, v124, v18
	v_max3_i32 v28, v133, v28, v29
	v_max3_i32 v24, v79, v81, v24
	v_max3_i32 v33, v68, v145, v142
	v_max3_i32 v19, v134, v19, v20
	v_max_i32_e32 v20, v23, v66
	v_min_i32_e32 v23, v23, v66
	v_max_i32_e32 v29, v22, v67
	v_max_i32_e32 v66, v25, v32
	v_min_i32_e32 v25, v25, v32
	v_max_i32_e32 v32, v26, v31
	v_min_i32_e32 v26, v26, v31
	v_max_i32_e32 v31, v21, v18
	v_min_i32_e32 v18, v21, v18
	v_max_i32_e32 v21, v27, v28
	v_min_i32_e32 v27, v27, v28
	v_max_i32_e32 v28, v30, v24
	v_min_i32_e32 v22, v22, v67
	v_min_i32_e32 v24, v30, v24
	v_max_i32_e32 v30, v33, v19
	v_min_i32_e32 v19, v33, v19
	v_max_i32_e32 v33, v20, v31
	v_min_i32_e32 v74, v20, v31
	v_max_i32_e32 v20, v29, v21
	v_min_i32_e32 v75, v29, v21
	v_max_i32_e32 v21, v66, v28
	v_min_i32_e32 v76, v66, v28
	ds_read_b128 v[66:69], v98
	ds_read_b128 v[70:73], v98 offset:32
	v_max_i32_e32 v28, v32, v30
	v_min_i32_e32 v77, v32, v30
	v_max_i32_e32 v78, v23, v18
	v_min_i32_e32 v79, v23, v18
	v_max_i32_e32 v80, v22, v27
	v_min_i32_e32 v81, v22, v27
	v_max_i32_e32 v82, v25, v24
	v_min_i32_e32 v124, v25, v24
	v_max_i32_e32 v125, v26, v19
	v_min_i32_e32 v126, v26, v19
	v_max_i32_e32 v127, v33, v21
	v_min_i32_e32 v128, v33, v21
	v_max_i32_e32 v129, v20, v28
	v_min_i32_e32 v130, v20, v28
	s_waitcnt lgkmcnt(1)
; #define LAS __attribute__((address_space(3)))
; #define MFMA32(a, b, c) __builtin_amdgcn_mfma_f32_32x32x16_bf16((a), (b), (c), 0, 0, 0)
; #define CE_(a, b) ce_desc(v[a], v[b])
; __device__ __forceinline__ void sort16_desc(int (&v)[16]) {
;     ...
;     CE_(0,13); CE_(1,12); CE_(2,15); CE_(3,14); CE_(4,8); CE_(5,6); CE_(7,11); CE_(9,10);
;     CE_(0,5); CE_(1,7); CE_(2,9); CE_(3,4); CE_(6,13); CE_(8,14); CE_(10,15); CE_(11,12);
;     CE_(0,1); CE_(2,3); CE_(4,5); CE_(6,8); CE_(7,9); CE_(10,11); CE_(12,13); CE_(14,15);
;     CE_(0,2); CE_(1,3); CE_(4,10); CE_(5,11); CE_(6,7); CE_(8,9); CE_(12,14); CE_(13,15);
;     CE_(1,2); CE_(3,12); CE_(4,6); CE_(5,7); CE_(8,10); CE_(9,11); CE_(13,14);
;     CE_(1,4); CE_(2,6); CE_(5,8); CE_(7,10); CE_(9,13); CE_(11,14);
;     CE_(2,4); CE_(3,6); CE_(9,12); CE_(11,13);
;     CE_(3,5); CE_(6,8); CE_(7,9); CE_(10,12);
;     CE_(3,4); CE_(5,6); CE_(7,8); CE_(9,10); CE_(11,12);
;     CE_(6,7); CE_(8,9);
;     ...
; }
; __device__ __forceinline__ void merge16_desc(int (&a)[16], const int (&b)[16]) {
; #pragma unroll
;     for (int i = 0; i < 16; ++i) a[i] = a[i] > b[15 - i] ? a[i] : b[15 - i];
; #pragma unroll
;     for (int j = 8; j > 0; j >>= 1)
; #pragma unroll
;         for (int i = 0; i < 16; ++i) { const int l = i ^ j; if (l > i) ce_desc(a[i], a[l]); }
; }
; __device__ __forceinline__ void route_task(int task, int tl0, const bf16* QP  , const LAS bf16* KHL, LAS unsigned short* EL, LAS float* GL, int lane) {
;     ...
;         for (int kt = 0; kt < 4; ++kt) {
;             f32x16 X;
; #pragma unroll
;             for (int i = 0; i < 16; ++i) X[i] = 8.f;
;             const LAS bf16* khp = KHL + (half * 128 + 32 * kt + r) * 72 + 8 * hi;
; #pragma unroll
;             for (int ks = 0; ks < 4; ++ks) {
;                 const bf16x8 kh = lds8(khp + 16 * ks);
;                 X = MFMA32(kh, qa[half][ks], X);
;             }
;             int grp[16];
; #pragma unroll
;             for (int i = 0; i < 16; ++i) grp[i] = (int)((__float_as_uint(X[i]) | 127u) - (unsigned)(32 * kt + (i & 3) + 8 * (i >> 2)));
;             sort16_desc(grp);
;             if (kt == 0) {
; #pragma unroll
;                 for (int i = 0; i < 16; ++i) cur[i] = grp[i];
;             } else merge16_desc(cur, grp);
	v_mfma_f32_32x32x16_bf16 v[18:33], v[66:69], v[46:49], v[2:17]
	ds_read_b128 v[46:49], v98 offset:64
	v_max_i32_e32 v67, v75, v77
	v_min_i32_e32 v68, v75, v77
	v_max_i32_e32 v75, v80, v125
	v_max_i32_e32 v131, v74, v76
	v_min_i32_e32 v66, v74, v76
	v_max_i32_e32 v69, v78, v82
	s_waitcnt lgkmcnt(1)
	v_mfma_f32_32x32x16_bf16 v[18:33], v[70:73], v[42:45], v[18:33]
	ds_read_b128 v[42:45], v98 offset:96
	v_min_i32_e32 v70, v80, v125
	v_max_i32_e32 v71, v79, v124
	v_min_i32_e32 v72, v79, v124
	v_min_i32_e32 v74, v78, v82
	v_max_i32_e32 v73, v81, v126
	v_min_i32_e32 v76, v81, v126
	s_waitcnt lgkmcnt(1)
	v_mfma_f32_32x32x16_bf16 v[18:33], v[46:49], v[38:41], v[18:33]
	v_min_i32_e32 v77, v127, v129
	v_min_i32_e32 v38, v128, v130
	v_min_i32_e32 v39, v131, v67
	v_min_i32_e32 v40, v66, v68
	v_min_i32_e32 v41, v69, v75
	v_min_i32_e32 v46, v74, v70
	v_min_i32_e32 v47, v71, v73
	s_waitcnt lgkmcnt(0)
	v_mfma_f32_32x32x16_bf16 v[18:33], v[42:45], v[34:37], v[18:33]
	v_min_i32_e32 v48, v72, v76
	s_nop 10
	v_and_or_b32 v25, v25, s43, 20
	v_and_or_b32 v29, v29, s43, 12
	v_and_or_b32 v19, v19, s43, 30
	v_and_or_b32 v30, v30, s43, 7
	v_and_or_b32 v23, v23, s43, 22
	v_and_or_b32 v24, v24, s43, 21
	v_and_or_b32 v18, v18, s43, 31
	v_and_or_b32 v31, v31, s43, 6
	v_and_or_b32 v22, v22, s43, 23
	v_and_or_b32 v26, v26, s43, 15
	v_and_or_b32 v21, v21, s43, 28
	v_and_or_b32 v32, v32, s43, 5
	v_and_or_b32 v27, v27, s43, 14
	v_and_or_b32 v28, v28, s43, 13
	v_and_or_b32 v20, v20, s43, 29
	v_and_or_b32 v33, v33, s43, 4
	v_min_i32_e32 v34, v25, v29
	v_min_i32_e32 v35, v19, v30
	v_min_i32_e32 v37, v23, v24
	v_min_i32_e32 v42, v18, v31
	v_min_i32_e32 v45, v22, v26
	v_min_i32_e32 v49, v21, v32
	v_min_i32_e32 v79, v27, v28
	v_min_i32_e32 v80, v20, v33
	v_max_i32_e32 v18, v18, v31
	v_max_i32_e32 v23, v23, v24
	v_max_i32_e32 v19, v19, v30
	v_max_i32_e32 v25, v25, v29
	v_max_i32_e32 v20, v20, v33
	v_max_i32_e32 v27, v27, v28
	v_max_i32_e32 v21, v21, v32
	v_max_i32_e32 v22, v22, v26
	v_max_i32_e32 v24, v18, v23
	v_max_i32_e32 v29, v19, v25
	v_max_i32_e32 v28, v20, v27
	v_max_i32_e32 v26, v21, v22
	v_min_i32_e32 v30, v24, v29
	v_min_i32_e32 v31, v28, v26
	v_min_i32_e32 v43, v37, v42
	v_min_i32_e32 v32, v30, v31
	v_max_i32_e32 v30, v30, v31
	v_min_i32_e32 v21, v21, v22
	v_min_i32_e32 v18, v18, v23
	v_max_i32_e32 v23, v79, v80
	v_max_i32_e32 v31, v34, v35
	v_max_i32_e32 v37, v37, v42
	v_max_i32_e32 v42, v45, v49
	v_min_i32_e32 v19, v19, v25
	v_min_i32_e32 v20, v20, v27
	v_min_i32_e32 v36, v34, v35
	v_min_i32_e32 v78, v45, v49
	v_min_i32_e32 v81, v79, v80
	v_max_i32_e32 v22, v21, v18
	v_max_i32_e32 v45, v37, v42
	v_max_i32_e32 v25, v19, v20
	v_min_i32_e32 v18, v21, v18
	v_min_i32_e32 v21, v23, v31
	v_min_i32_e32 v44, v36, v43
	v_min_i32_e32 v82, v78, v81
	v_max_i32_e32 v33, v36, v43
	v_max_i32_e32 v36, v78, v81
	v_max_i32_e32 v24, v24, v29
	v_max_i32_e32 v26, v28, v26
	v_max_i32_e32 v34, v23, v31
	v_max_i32_e32 v27, v45, v25
	v_max_i32_e32 v23, v18, v21
	v_min_i32_e32 v25, v45, v25
	v_min_i32_e32 v37, v37, v42
	v_min_i32_e32 v19, v19, v20
	v_max_i32_e32 v43, v33, v36
	v_min_i32_e32 v28, v24, v26
	v_max_i32_e32 v35, v22, v34
	v_max_i32_e32 v31, v23, v25
	v_max_i32_e32 v20, v37, v19
	v_min_i32_e32 v23, v23, v25
	v_min_i32_e32 v19, v37, v19
	v_min_i32_e32 v18, v18, v21
	v_max_i32_e32 v25, v44, v82
	v_min_i32_e32 v33, v33, v36
	v_min_i32_e32 v29, v30, v28
	v_min_i32_e32 v49, v35, v27
	v_min_i32_e32 v22, v22, v34
	v_max_i32_e32 v21, v19, v18
	v_max_i32_e32 v36, v25, v33
	v_max_i32_e32 v78, v32, v43
	v_min_i32_e32 v79, v29, v49
	v_max_i32_e32 v34, v20, v22
	v_min_i32_e32 v20, v20, v22
	v_max_i32_e32 v37, v21, v36
	v_min_i32_e32 v32, v32, v43
	v_max_i32_e32 v80, v78, v79
	v_max_i32_e32 v42, v31, v34
	v_min_i32_e32 v78, v78, v79
	v_min_i32_e32 v31, v31, v34
	v_max_i32_e32 v22, v23, v20
	v_max_i32_e32 v43, v37, v32
	v_min_i32_e32 v18, v19, v18
	v_min_i32_e32 v19, v25, v33
	v_min_i32_e32 v20, v23, v20
	v_min_i32_e32 v23, v37, v32
	v_max_i32_e32 v28, v30, v28
	v_max_i32_e32 v27, v35, v27
	v_min_i32_e32 v124, v44, v82
	v_min_i32_e32 v45, v80, v42
	v_max_i32_e32 v34, v78, v31
	v_max_i32_e32 v44, v22, v43
	v_min_i32_e32 v31, v78, v31
	v_max_i32_e32 v25, v18, v19
	v_min_i32_e32 v21, v21, v36
	v_min_i32_e32 v32, v20, v23
	v_max_i32_e32 v29, v29, v49
	v_min_i32_e32 v30, v28, v27
	v_min_i32_e32 v22, v22, v43
	v_max_i32_e32 v20, v20, v23
	v_min_i32_e32 v79, v45, v34
	v_max_i32_e32 v78, v44, v31
	v_max_i32_e32 v33, v25, v21
	v_max_i32_e32 v37, v80, v42
	v_min_i32_e32 v35, v29, v30
	v_min_i32_e32 v31, v44, v31
	v_max_i32_e32 v23, v22, v20
	v_min_i32_e32 v81, v79, v78
	v_max_i32_e32 v36, v33, v32
	v_max_i32_e32 v42, v37, v35
	v_min_i32_e32 v21, v25, v21
	v_max_i32_e32 v25, v45, v34
	v_min_i32_e32 v43, v31, v23
	v_max_i32_e32 v27, v28, v27
	v_min_i32_e32 v18, v18, v19
	v_min_i32_e32 v20, v22, v20
	v_min_i32_e32 v32, v33, v32
	v_min_i32_e32 v33, v37, v35
	v_max3_i32 v124, v127, v129, v124
	v_max3_i32 v69, v69, v75, v81
	v_max3_i32 v36, v131, v67, v36
	v_max3_i32 v42, v71, v73, v42
	v_max3_i32 v21, v128, v130, v21
	v_max3_i32 v25, v74, v70, v25
	v_max3_i32 v43, v66, v68, v43
	v_max3_i32 v27, v72, v76, v27
	v_max_i32_e32 v18, v77, v18
	v_max3_i32 v19, v41, v79, v78
	v_max_i32_e32 v20, v39, v20
	v_max3_i32 v22, v47, v29, v30
	v_max_i32_e32 v32, v38, v32
	v_max_i32_e32 v33, v46, v33
	v_max3_i32 v23, v40, v31, v23
	v_max3_i32 v24, v48, v24, v26
	v_min_i32_e32 v49, v36, v42
	v_min_i32_e32 v34, v21, v25
	v_min_i32_e32 v41, v18, v19
	v_min_i32_e32 v29, v20, v22
	v_min_i32_e32 v26, v23, v24
	v_max_i32_e32 v39, v124, v69
	v_max_i32_e32 v36, v36, v42
	v_max_i32_e32 v21, v21, v25
	v_max_i32_e32 v25, v43, v27
; __device__ __forceinline__ void route_task(int task, int tl0, const bf16* QP  , const LAS bf16* KHL, LAS unsigned short* EL, LAS float* GL, int lane) {
;     ...
;             } else merge16_desc(cur, grp);
;         }
;         { const unsigned h4 = 4u * (unsigned)hi;
; #pragma unroll
;           for (int i = 0; i < 16; ++i) cur[i] -= (int)h4; }
;         int oth[16];
; #pragma unroll
;         for (int i = 0; i < 16; ++i) oth[i] = __shfl_xor(cur[i], 32);
;         merge16_desc(cur, oth);
; #pragma unroll
;         for (int i = 0; i < 16; ++i) top[half][i] = cur[i];
;     }
;     unsigned P1[4], P2[4];
; #pragma unroll
;     for (int q = 0; q < 4; ++q) { P1[q] = 0u; P2[q] = 0u;
; #pragma unroll
;         for (int s = 0; s < 4; ++s) { P1[q] |= (127u - ((unsigned)top[0][4 * q + s] & 127u)) << (8 * s); P2[q] |= (127u - ((unsigned)top[1][4 * q + s] & 127u)) << (8 * s); } }
	v_max_i32_e32 v18, v18, v19
	v_max_i32_e32 v19, v20, v22
	v_max_i32_e32 v22, v32, v33
	v_max_i32_e32 v23, v23, v24
	v_min_i32_e32 v28, v43, v27
	v_max_i32_e32 v40, v39, v36
	v_max_i32_e32 v27, v21, v25
	v_max_i32_e32 v20, v18, v19
	v_max_i32_e32 v24, v22, v23
	v_min_i32_e32 v35, v32, v33
	v_max_i32_e32 v42, v40, v27
	v_max_i32_e32 v32, v20, v24
	v_min_i32_e32 v27, v40, v27
	v_min_i32_e32 v20, v20, v24
	v_max_i32_e32 v24, v27, v20
	v_min_i32_e32 v20, v27, v20
	v_min_i32_e32 v27, v39, v36
	v_min_i32_e32 v21, v21, v25
	v_min_i32_e32 v18, v18, v19
	v_min_i32_e32 v19, v22, v23
	v_min_i32_e32 v75, v124, v69
	v_max_i32_e32 v25, v27, v21
	v_max_i32_e32 v22, v18, v19
	v_min_i32_e32 v21, v27, v21
	v_min_i32_e32 v18, v18, v19
	v_min_i32_e32 v44, v34, v28
	v_min_i32_e32 v31, v35, v26
	v_max_i32_e32 v23, v25, v22
	v_min_i32_e32 v22, v25, v22
	v_max_i32_e32 v19, v21, v18
	v_min_i32_e32 v18, v21, v18
	v_max_i32_e32 v21, v75, v49
	v_max_i32_e32 v25, v34, v28
	v_max_i32_e32 v28, v41, v29
	v_max_i32_e32 v26, v35, v26
	v_min_i32_e32 v67, v75, v49
	v_min_i32_e32 v30, v41, v29
	v_max_i32_e32 v27, v21, v25
	v_min_i32_e32 v21, v21, v25
	v_min_i32_e32 v25, v28, v26
	v_min_i32_e32 v45, v67, v44
	v_min_i32_e32 v37, v30, v31
	v_max_i32_e32 v29, v28, v26
	v_max_i32_e32 v26, v21, v25
	v_min_i32_e32 v21, v21, v25
	v_max_i32_e32 v25, v67, v44
	v_max_i32_e32 v28, v30, v31
	v_min_i32_e32 v38, v45, v37
	v_max_i32_e32 v33, v42, v32
	v_min_i32_e32 v32, v42, v32
	v_max_i32_e32 v34, v27, v29
	v_min_i32_e32 v27, v27, v29
	v_max_i32_e32 v29, v25, v28
	v_min_i32_e32 v25, v25, v28
	v_max_i32_e32 v28, v45, v37
	v_sub_u32_e32 v30, v33, v87
	v_sub_u32_e32 v31, v32, v87
	v_sub_u32_e32 v24, v24, v87
	v_sub_u32_e32 v20, v20, v87
	v_sub_u32_e32 v23, v23, v87
	v_sub_u32_e32 v22, v22, v87
	v_sub_u32_e32 v19, v19, v87
	v_sub_u32_e32 v18, v18, v87
	v_sub_u32_e32 v32, v34, v87
	v_sub_u32_e32 v27, v27, v87
	v_sub_u32_e32 v26, v26, v87
	v_sub_u32_e32 v21, v21, v87
	v_sub_u32_e32 v29, v29, v87
	v_sub_u32_e32 v25, v25, v87
	v_sub_u32_e32 v28, v28, v87
	v_sub_u32_e32 v33, v38, v87
	ds_bpermute_b32 v34, v123, v30
	ds_bpermute_b32 v35, v123, v31
	ds_bpermute_b32 v36, v123, v24
	ds_bpermute_b32 v37, v123, v20
	ds_bpermute_b32 v38, v123, v23
	ds_bpermute_b32 v39, v123, v22
	ds_bpermute_b32 v40, v123, v19
	ds_bpermute_b32 v41, v123, v18
	ds_bpermute_b32 v42, v123, v32
	ds_bpermute_b32 v43, v123, v27
	ds_bpermute_b32 v44, v123, v26
	ds_bpermute_b32 v45, v123, v33
	ds_bpermute_b32 v46, v123, v28
	ds_bpermute_b32 v47, v123, v25
	ds_bpermute_b32 v48, v123, v29
	ds_bpermute_b32 v49, v123, v21
	s_waitcnt lgkmcnt(4)
	v_max_i32_e32 v30, v30, v45
	s_waitcnt lgkmcnt(3)
	v_max_i32_e32 v31, v31, v46
	s_waitcnt lgkmcnt(2)
	v_max_i32_e32 v24, v24, v47
	s_waitcnt lgkmcnt(1)
	v_max_i32_e32 v20, v20, v48
	s_waitcnt lgkmcnt(0)
	v_max_i32_e32 v23, v23, v49
	v_max_i32_e32 v22, v22, v44
	v_max_i32_e32 v19, v19, v43
	v_max_i32_e32 v18, v18, v42
	v_max_i32_e32 v32, v32, v41
	v_max_i32_e32 v27, v27, v40
	v_max_i32_e32 v26, v26, v39
	v_max_i32_e32 v21, v21, v38
	v_max_i32_e32 v29, v29, v37
	v_max_i32_e32 v25, v25, v36
	v_max_i32_e32 v28, v28, v35
	v_max_i32_e32 v33, v33, v34
	v_max_i32_e32 v34, v30, v32
	v_min_i32_e32 v30, v30, v32
	v_max_i32_e32 v32, v31, v27
	v_min_i32_e32 v27, v31, v27
	v_max_i32_e32 v31, v24, v26
	v_min_i32_e32 v24, v24, v26
	v_max_i32_e32 v26, v20, v21
	v_min_i32_e32 v20, v20, v21
	v_max_i32_e32 v21, v23, v29
	v_min_i32_e32 v23, v23, v29
	v_max_i32_e32 v29, v22, v25
	v_min_i32_e32 v22, v22, v25
	v_max_i32_e32 v25, v19, v28
	v_min_i32_e32 v19, v19, v28
	v_max_i32_e32 v28, v18, v33
	v_min_i32_e32 v18, v18, v33
	v_max_i32_e32 v33, v34, v21
	v_min_i32_e32 v21, v34, v21
	v_max_i32_e32 v34, v32, v29
	v_min_i32_e32 v29, v32, v29
	v_max_i32_e32 v32, v31, v25
	v_min_i32_e32 v25, v31, v25
	v_max_i32_e32 v31, v26, v28
	v_min_i32_e32 v26, v26, v28
	v_max_i32_e32 v28, v30, v23
	v_min_i32_e32 v23, v30, v23
	v_max_i32_e32 v30, v27, v22
	v_min_i32_e32 v22, v27, v22
	v_max_i32_e32 v27, v24, v19
	v_min_i32_e32 v19, v24, v19
	v_max_i32_e32 v24, v20, v18
	v_min_i32_e32 v18, v20, v18
	v_max_i32_e32 v20, v33, v32
	v_min_i32_e32 v32, v33, v32
	v_max_i32_e32 v33, v34, v31
	v_min_i32_e32 v31, v34, v31
	v_max_i32_e32 v34, v21, v25
	v_min_i32_e32 v21, v21, v25
	v_max_i32_e32 v25, v29, v26
	v_min_i32_e32 v29, v29, v26
	v_max_i32_e32 v35, v28, v27
	v_min_i32_e32 v27, v28, v27
	v_max_i32_e32 v28, v30, v24
	v_min_i32_e32 v24, v30, v24
	v_max_i32_e32 v30, v23, v19
	v_min_i32_e32 v19, v23, v19
	v_max_i32_e32 v23, v22, v18
	v_min_i32_e32 v18, v22, v18
	v_max_i32_e32 v26, v20, v33
	v_min_i32_e32 v33, v20, v33
	v_lshlrev_b32_e32 v20, 8, v65
	v_lshlrev_b32_e32 v22, 16, v64
	v_max_i32_e32 v36, v32, v31
	v_max_i32_e32 v40, v19, v18
	v_min_i32_e32 v41, v19, v18
	v_and_b32_e32 v18, 0x7f, v63
	v_and_b32_e32 v20, 0x7f00, v20
	v_and_b32_e32 v22, 0x7f0000, v22
	v_max_i32_e32 v37, v21, v29
	v_min_i32_e32 v29, v21, v29
	v_lshlrev_b32_e32 v21, 8, v33
	v_or3_b32 v18, v20, v18, v22
	v_lshlrev_b32_e32 v20, 16, v36
	v_and_b32_e32 v19, 0x7f, v26
	v_and_b32_e32 v21, 0x7f00, v21
	v_and_b32_e32 v20, 0x7f0000, v20
	v_or3_b32 v20, v21, v19, v20
	v_lshlrev_b32_e32 v19, 24, v62
	v_min_i32_e32 v31, v32, v31
	v_and_b32_e32 v19, 0x7f000000, v19
	v_bitop3_b32 v19, v18, s68, v19 bitop3:0x36
	v_lshlrev_b32_e32 v18, 24, v31
	v_max_i32_e32 v38, v35, v28
	v_min_i32_e32 v28, v35, v28
	v_max_i32_e32 v35, v27, v24
	v_min_i32_e32 v27, v27, v24
	v_and_b32_e32 v18, 0x7f000000, v18
	v_lshlrev_b32_e32 v22, 8, v60
	v_lshlrev_b32_e32 v24, 16, v59
	v_max_i32_e32 v32, v34, v25
	v_min_i32_e32 v34, v34, v25
	v_bitop3_b32 v18, v20, s68, v18 bitop3:0x36
	v_and_b32_e32 v20, 0x7f, v61
; __device__ __forceinline__ void route_task(int task, int tl0, const bf16* QP  , const LAS bf16* KHL, LAS unsigned short* EL, LAS float* GL, int lane) {
;     ...
;     unsigned P1[4], P2[4];
; #pragma unroll
;     for (int q = 0; q < 4; ++q) { P1[q] = 0u; P2[q] = 0u;
; #pragma unroll
;         for (int s = 0; s < 4; ++s) { P1[q] |= (127u - ((unsigned)top[0][4 * q + s] & 127u)) << (8 * s); P2[q] |= (127u - ((unsigned)top[1][4 * q + s] & 127u)) << (8 * s); } }
;     int bk[16];
;     {
;         int hi2 = hi; asm volatile("" : "+v"(hi2));
;         const bool h1 = hi2 != 0;
;         constexpr int A1[16] = {1, 1, 1, 1, 1, 1, 1, 1, 2, 2, 2, 2, 2, 3, 3, 3}, B1[16] = {0, 1, 2, 3, 4, 5, 6, 7, 0, 1, 2, 3, 4, 0, 1, 2};
; #pragma unroll
;         for (int i = 0; i < 16; ++i) { const float ta = __int_as_float(h1 ? top[0][A1[i]] : top[0][0]), tb = __int_as_float(h1 ? top[1][B1[i]] : top[1][i]); const unsigned code = h1 ? (unsigned)(A1[i] * 16 + B1[i]) : (unsigned)i;
;             bk[i] = (int)((__float_as_uint(ta + tb) | 255u) - code); }
;         sort16_desc(bk);
	v_and_b32_e32 v22, 0x7f00, v22
	v_and_b32_e32 v24, 0x7f0000, v24
	v_max_i32_e32 v39, v30, v23
	v_min_i32_e32 v30, v30, v23
	v_lshlrev_b32_e32 v23, 8, v34
	v_or3_b32 v20, v22, v20, v24
	v_lshlrev_b32_e32 v22, 16, v37
	v_and_b32_e32 v21, 0x7f, v32
	v_and_b32_e32 v23, 0x7f00, v23
	v_and_b32_e32 v22, 0x7f0000, v22
	v_or3_b32 v22, v23, v21, v22
	v_lshlrev_b32_e32 v21, 24, v57
	v_and_b32_e32 v21, 0x7f000000, v21
	v_bitop3_b32 v21, v20, s68, v21 bitop3:0x36
	v_lshlrev_b32_e32 v20, 24, v29
	v_and_b32_e32 v20, 0x7f000000, v20
	v_lshlrev_b32_e32 v24, 8, v58
	v_lshlrev_b32_e32 v42, 16, v56
	v_bitop3_b32 v20, v22, s68, v20 bitop3:0x36
	v_and_b32_e32 v22, 0x7f, v55
	v_and_b32_e32 v24, 0x7f00, v24
	v_and_b32_e32 v42, 0x7f0000, v42
	v_lshlrev_b32_e32 v25, 8, v28
	v_or3_b32 v22, v24, v22, v42
	v_lshlrev_b32_e32 v24, 16, v35
	v_and_b32_e32 v23, 0x7f, v38
	v_and_b32_e32 v25, 0x7f00, v25
	v_and_b32_e32 v24, 0x7f0000, v24
	v_or3_b32 v24, v25, v23, v24
	v_lshlrev_b32_e32 v23, 24, v54
	v_and_b32_e32 v23, 0x7f000000, v23
	v_bitop3_b32 v23, v22, s68, v23 bitop3:0x36
	v_lshlrev_b32_e32 v22, 24, v27
	v_and_b32_e32 v22, 0x7f000000, v22
	v_lshlrev_b32_e32 v42, 8, v52
	v_lshlrev_b32_e32 v44, 16, v51
	v_bitop3_b32 v22, v24, s68, v22 bitop3:0x36
	v_and_b32_e32 v24, 0x7f, v53
	v_and_b32_e32 v42, 0x7f00, v42
	v_and_b32_e32 v44, 0x7f0000, v44
	v_lshlrev_b32_e32 v43, 8, v30
	v_or3_b32 v24, v42, v24, v44
	v_lshlrev_b32_e32 v42, 16, v40
	v_and_b32_e32 v25, 0x7f, v39
	v_and_b32_e32 v43, 0x7f00, v43
	v_and_b32_e32 v42, 0x7f0000, v42
	v_or3_b32 v42, v43, v25, v42
	v_lshlrev_b32_e32 v25, 24, v50
	v_and_b32_e32 v25, 0x7f000000, v25
	v_bitop3_b32 v25, v24, s68, v25 bitop3:0x36
	v_lshlrev_b32_e32 v24, 24, v41
	v_and_b32_e32 v24, 0x7f000000, v24
	v_bitop3_b32 v24, v42, s68, v24 bitop3:0x36
	v_mov_b32_e32 v42, v86
	v_add_f32_e32 v55, v55, v26
	v_cmp_eq_u32_e32 vcc, 0, v42
	v_add_f32_e32 v56, v56, v26
	v_add_f32_e32 v54, v54, v26
	v_cndmask_b32_e32 v42, v65, v63, vcc
	v_add_f32_e32 v44, v42, v26
	v_cndmask_b32_e64 v43, -16, 0, vcc
	v_or_b32_e32 v44, 0xff, v44
	v_add_f32_e32 v45, v42, v33
	v_add_u32_e32 v43, v44, v43
	v_cndmask_b32_e64 v44, v99, -1, vcc
	v_or_b32_e32 v45, 0xff, v45
	v_add_f32_e32 v46, v42, v36
	v_add_u32_e32 v44, v45, v44
	v_cndmask_b32_e64 v45, v100, -2, vcc
	v_or_b32_e32 v46, 0xff, v46
	v_add_f32_e32 v47, v42, v31
	v_add_u32_e32 v45, v46, v45
	v_cndmask_b32_e64 v46, v101, -3, vcc
	v_or_b32_e32 v47, 0xff, v47
	v_add_f32_e32 v48, v42, v32
	v_add_u32_e32 v46, v47, v46
	v_cndmask_b32_e64 v47, v102, -4, vcc
	v_or_b32_e32 v48, 0xff, v48
	v_add_f32_e32 v34, v42, v34
	v_add_f32_e32 v37, v42, v37
	v_add_f32_e32 v29, v42, v29
	v_cndmask_b32_e32 v42, v64, v63, vcc
	v_cndmask_b32_e32 v32, v32, v39, vcc
	v_add_u32_e32 v47, v48, v47
	v_cndmask_b32_e64 v48, v103, -5, vcc
	v_or_b32_e32 v34, 0xff, v34
	v_add_f32_e32 v32, v42, v32
	v_add_u32_e32 v34, v34, v48
	v_cndmask_b32_e64 v48, v104, -6, vcc
	v_or_b32_e32 v37, 0xff, v37
	v_cndmask_b32_e32 v38, v26, v38, vcc
	v_cndmask_b32_e64 v39, v116, -12, vcc
	v_or_b32_e32 v32, 0xff, v32
	v_add_u32_e32 v37, v37, v48
	v_cndmask_b32_e64 v48, v105, -7, vcc
	v_or_b32_e32 v29, 0xff, v29
	v_add_f32_e32 v38, v42, v38
	v_cndmask_b32_e32 v28, v33, v28, vcc
	v_add_u32_e32 v32, v32, v39
	v_cndmask_b32_e32 v39, v62, v63, vcc
	v_cndmask_b32_e32 v30, v26, v30, vcc
	v_add_u32_e32 v29, v29, v48
	v_cndmask_b32_e64 v48, v106, -8, vcc
	v_or_b32_e32 v38, 0xff, v38
	v_add_f32_e32 v28, v42, v28
	v_cndmask_b32_e32 v35, v36, v35, vcc
	v_cndmask_b32_e32 v27, v31, v27, vcc
	v_add_f32_e32 v30, v39, v30
	v_cndmask_b32_e32 v40, v33, v40, vcc
	v_add_u32_e32 v38, v38, v48
	v_cndmask_b32_e64 v48, v107, -9, vcc
	v_or_b32_e32 v28, 0xff, v28
	v_add_f32_e32 v35, v42, v35
	v_add_f32_e32 v27, v42, v27
	v_cndmask_b32_e64 v42, v117, -13, vcc
	v_or_b32_e32 v30, 0xff, v30
	v_add_f32_e32 v40, v39, v40
	v_cndmask_b32_e32 v41, v36, v41, vcc
	v_add_u32_e32 v28, v28, v48
	v_cndmask_b32_e64 v48, v114, -10, vcc
	v_or_b32_e32 v35, 0xff, v35
	v_add_u32_e32 v30, v30, v42
	v_cndmask_b32_e64 v42, v118, -14, vcc
	v_or_b32_e32 v40, 0xff, v40
	v_add_f32_e32 v39, v39, v41
	v_add_u32_e32 v35, v35, v48
	v_cndmask_b32_e64 v48, v115, -11, vcc
	v_or_b32_e32 v27, 0xff, v27
	v_add_u32_e32 v40, v40, v42
	v_cndmask_b32_e64 v42, v119, -15, vcc
	v_or_b32_e32 v39, 0xff, v39
	v_add_u32_e32 v27, v27, v48
	v_add_u32_e32 v39, v39, v42
	v_max_i32_e32 v41, v43, v30
	v_min_i32_e32 v30, v43, v30
	v_max_i32_e32 v42, v44, v32
	v_min_i32_e32 v32, v44, v32
	v_max_i32_e32 v43, v45, v39
	v_min_i32_e32 v39, v45, v39
	v_max_i32_e32 v44, v46, v40
	v_min_i32_e32 v40, v46, v40
	v_max_i32_e32 v45, v47, v38
	v_min_i32_e32 v38, v47, v38
	v_max_i32_e32 v46, v34, v37
	v_min_i32_e32 v34, v34, v37
	v_max_i32_e32 v37, v29, v27
	v_min_i32_e32 v27, v29, v27
	v_max_i32_e32 v29, v28, v35
	v_min_i32_e32 v28, v28, v35
	v_max_i32_e32 v35, v41, v46
	v_min_i32_e32 v41, v41, v46
	v_max_i32_e32 v46, v42, v37
	v_min_i32_e32 v37, v42, v37
	v_max_i32_e32 v42, v43, v29
	v_min_i32_e32 v29, v43, v29
	v_max_i32_e32 v43, v44, v45
	v_min_i32_e32 v44, v44, v45
	v_max_i32_e32 v45, v34, v30
	v_min_i32_e32 v30, v34, v30
	v_max_i32_e32 v34, v38, v40
	v_min_i32_e32 v38, v38, v40
	v_max_i32_e32 v40, v28, v39
	v_min_i32_e32 v28, v28, v39
	v_max_i32_e32 v39, v27, v32
	v_min_i32_e32 v27, v27, v32
	v_max_i32_e32 v32, v35, v46
	v_min_i32_e32 v35, v35, v46
	v_max_i32_e32 v46, v42, v43
	v_min_i32_e32 v42, v42, v43
	v_max_i32_e32 v43, v44, v41
	v_min_i32_e32 v41, v44, v41
	v_max_i32_e32 v44, v45, v34
	v_min_i32_e32 v34, v45, v34
	v_max_i32_e32 v45, v37, v29
	v_min_i32_e32 v29, v37, v29
	v_max_i32_e32 v37, v40, v39
	v_min_i32_e32 v39, v40, v39
	v_max_i32_e32 v40, v27, v30
; #define CAND(a, b) (int)((__float_as_uint(__int_as_float(top[0][a]) + __int_as_float(top[1][b])) | 255u) - (unsigned)((a) * 16 + (b)))
; __device__ __forceinline__ void route_task(int task, int tl0, const bf16* QP  , const LAS bf16* KHL, LAS unsigned short* EL, LAS float* GL, int lane) {
;     ...
;         sort16_desc(bk);
;         int oth[16];
; #pragma unroll
;         for (int i = 0; i < 16; ++i) oth[i] = __shfl_xor(bk[i], 32);
;         merge16_desc(bk, oth);
;     }
;     ...
;     {
;         int gk[16];
;         gk[0] = CAND(3, 3); gk[1] = CAND(4, 0); gk[2] = CAND(4, 1); gk[3] = CAND(4, 2); gk[4] = CAND(5, 0); gk[5] = CAND(5, 1); gk[6] = CAND(6, 0); gk[7] = CAND(6, 1);
;         gk[8] = CAND(7, 0); gk[9] = CAND(7, 1); gk[10] = CAND(8, 0); gk[11] = CAND(9, 0); gk[12] = CAND(10, 0); gk[13] = CAND(11, 0); gk[14] = CAND(12, 0); gk[15] = CAND(13, 0);
;         sort16_desc(gk);
	v_min_i32_e32 v27, v27, v30
	v_max_i32_e32 v30, v38, v28
	v_min_i32_e32 v28, v38, v28
	v_max_i32_e32 v38, v32, v46
	v_min_i32_e32 v32, v32, v46
	v_max_i32_e32 v46, v35, v42
	v_min_i32_e32 v35, v35, v42
	v_max_i32_e32 v42, v43, v37
	v_min_i32_e32 v37, v43, v37
	v_max_i32_e32 v43, v41, v39
	v_min_i32_e32 v39, v41, v39
	v_max_i32_e32 v41, v44, v45
	v_min_i32_e32 v44, v44, v45
	v_max_i32_e32 v45, v34, v29
	v_min_i32_e32 v29, v34, v29
	v_max_i32_e32 v34, v40, v30
	v_min_i32_e32 v30, v40, v30
	v_max_i32_e32 v40, v27, v28
	v_min_i32_e32 v27, v27, v28
	v_max_i32_e32 v28, v46, v32
	v_min_i32_e32 v32, v46, v32
	v_max_i32_e32 v46, v35, v34
	v_min_i32_e32 v34, v35, v34
	v_max_i32_e32 v35, v42, v41
	v_min_i32_e32 v41, v42, v41
	v_max_i32_e32 v42, v43, v44
	v_min_i32_e32 v43, v43, v44
	v_max_i32_e32 v44, v45, v37
	v_min_i32_e32 v37, v45, v37
	v_max_i32_e32 v45, v29, v39
	v_min_i32_e32 v29, v29, v39
	v_max_i32_e32 v39, v40, v30
	v_min_i32_e32 v30, v40, v30
	v_max_i32_e32 v40, v28, v35
	v_min_i32_e32 v28, v28, v35
	v_max_i32_e32 v35, v32, v41
	v_min_i32_e32 v32, v32, v41
	v_max_i32_e32 v41, v42, v44
	v_min_i32_e32 v42, v42, v44
	v_max_i32_e32 v44, v43, v37
	v_min_i32_e32 v37, v43, v37
	v_max_i32_e32 v43, v45, v39
	v_min_i32_e32 v39, v45, v39
	v_max_i32_e32 v45, v29, v30
	v_min_i32_e32 v29, v29, v30
	v_max_i32_e32 v30, v35, v28
	v_min_i32_e32 v28, v35, v28
	v_max_i32_e32 v35, v46, v32
	v_min_i32_e32 v32, v46, v32
	v_max_i32_e32 v46, v43, v34
	v_min_i32_e32 v34, v43, v34
	v_max_i32_e32 v43, v45, v39
	v_min_i32_e32 v39, v45, v39
	v_max_i32_e32 v45, v35, v41
	v_min_i32_e32 v35, v35, v41
	v_max_i32_e32 v41, v32, v42
	v_min_i32_e32 v32, v32, v42
	v_max_i32_e32 v42, v44, v46
	v_min_i32_e32 v44, v44, v46
	v_max_i32_e32 v46, v37, v34
	v_min_i32_e32 v34, v37, v34
	v_max_i32_e32 v37, v45, v28
	v_min_i32_e32 v28, v45, v28
	v_max_i32_e32 v45, v35, v41
	v_min_i32_e32 v35, v35, v41
	v_max_i32_e32 v41, v42, v32
	v_min_i32_e32 v32, v42, v32
	v_max_i32_e32 v42, v44, v46
	v_min_i32_e32 v44, v44, v46
	v_max_i32_e32 v46, v43, v34
	v_min_i32_e32 v34, v43, v34
	v_max_i32_e32 v43, v35, v41
	v_min_i32_e32 v35, v35, v41
	v_max_i32_e32 v41, v32, v42
	v_min_i32_e32 v32, v32, v42
	ds_bpermute_b32 v67, v123, v41
	ds_bpermute_b32 v68, v123, v32
	ds_bpermute_b32 v69, v123, v44
	ds_bpermute_b32 v64, v123, v45
	ds_bpermute_b32 v65, v123, v43
	ds_bpermute_b32 v66, v123, v35
	s_waitcnt lgkmcnt(4)
	v_max_i32_e32 v43, v43, v68
	s_waitcnt lgkmcnt(3)
	v_max_i32_e32 v45, v45, v69
	v_max_i32_e32 v35, v35, v67
	v_add_f32_e32 v31, v62, v31
	v_add_f32_e32 v62, v61, v26
	v_add_f32_e32 v67, v61, v33
	v_add_f32_e32 v36, v61, v36
	v_add_f32_e32 v61, v60, v26
	v_add_f32_e32 v60, v60, v33
	v_add_f32_e32 v68, v59, v26
	v_add_f32_e32 v59, v59, v33
	v_add_f32_e32 v69, v57, v26
	v_add_f32_e32 v33, v57, v33
	v_add_f32_e32 v57, v58, v26
	v_add_f32_e32 v53, v53, v26
	v_add_f32_e32 v52, v52, v26
	ds_bpermute_b32 v70, v123, v27
	v_or_b32_e32 v31, 0xff, v31
	v_or_b32_e32 v62, 0xff, v62
	v_or_b32_e32 v67, 0xff, v67
	v_or_b32_e32 v36, 0xff, v36
	v_or_b32_e32 v61, 0xff, v61
	v_or_b32_e32 v60, 0xff, v60
	v_or_b32_e32 v68, 0xff, v68
	v_or_b32_e32 v59, 0xff, v59
	v_or_b32_e32 v69, 0xff, v69
	v_or_b32_e32 v33, 0xff, v33
	v_or_b32_e32 v55, 0xff, v55
	v_or_b32_e32 v57, 0xff, v57
	v_or_b32_e32 v56, 0xff, v56
	v_or_b32_e32 v54, 0xff, v54
	v_or_b32_e32 v53, 0xff, v53
	v_or_b32_e32 v52, 0xff, v52
	v_subrev_u32_e32 v31, 51, v31
	v_subrev_u32_e32 v62, 64, v62
	v_add_u32_e32 v67, 0xffffffbf, v67
	v_add_u32_e32 v36, 0xffffffbe, v36
	v_add_u32_e32 v61, 0xffffffb0, v61
	v_add_u32_e32 v60, 0xffffffaf, v60
	v_add_u32_e32 v68, 0xffffffa0, v68
	v_add_u32_e32 v59, 0xffffff9f, v59
	v_add_u32_e32 v69, 0xffffff90, v69
	v_add_u32_e32 v33, 0xffffff8f, v33
	v_add_u32_e32 v55, 0xffffff80, v55
	v_add_u32_e32 v57, 0xffffff70, v57
	v_add_u32_e32 v56, 0xffffff60, v56
	v_add_u32_e32 v54, 0xffffff50, v54
	v_add_u32_e32 v53, 0xffffff40, v53
	v_add_u32_e32 v52, 0xffffff30, v52
	ds_bpermute_b32 v42, v123, v38
	ds_bpermute_b32 v47, v123, v40
	ds_bpermute_b32 v48, v123, v30
	ds_bpermute_b32 v49, v123, v37
	ds_bpermute_b32 v63, v123, v28
	ds_bpermute_b32 v71, v123, v29
	ds_bpermute_b32 v72, v123, v39
	ds_bpermute_b32 v73, v123, v34
	ds_bpermute_b32 v74, v123, v46
	v_max_i32_e32 v58, v31, v54
	v_min_i32_e32 v31, v31, v54
	v_max_i32_e32 v54, v62, v56
	v_min_i32_e32 v56, v62, v56
	v_max_i32_e32 v62, v67, v52
	v_min_i32_e32 v52, v67, v52
	v_max_i32_e32 v67, v36, v53
	v_min_i32_e32 v36, v36, v53
	v_max_i32_e32 v53, v61, v69
	v_min_i32_e32 v61, v61, v69
	v_max_i32_e32 v69, v60, v68
	v_min_i32_e32 v60, v60, v68
	v_max_i32_e32 v68, v59, v57
	v_min_i32_e32 v57, v59, v57
	v_max_i32_e32 v59, v33, v55
	v_min_i32_e32 v33, v33, v55
	v_max_i32_e32 v55, v58, v69
	v_min_i32_e32 v58, v58, v69
	v_max_i32_e32 v69, v54, v68
	v_min_i32_e32 v54, v54, v68
	v_max_i32_e32 v68, v62, v59
	v_min_i32_e32 v59, v62, v59
	v_max_i32_e32 v62, v67, v53
	v_min_i32_e32 v53, v67, v53
	v_max_i32_e32 v67, v60, v31
	v_min_i32_e32 v31, v60, v31
	v_max_i32_e32 v60, v61, v36
	v_min_i32_e32 v36, v61, v36
	v_max_i32_e32 v61, v33, v52
	v_min_i32_e32 v33, v33, v52
	v_max_i32_e32 v52, v57, v56
	v_min_i32_e32 v56, v57, v56
	v_max_i32_e32 v57, v55, v69
	v_min_i32_e32 v55, v55, v69
	v_max_i32_e32 v69, v68, v62
	v_min_i32_e32 v62, v68, v62
	v_max_i32_e32 v68, v53, v58
	v_min_i32_e32 v53, v53, v58
	v_max_i32_e32 v58, v67, v60
	v_min_i32_e32 v60, v67, v60
	v_max_i32_e32 v67, v54, v59
	v_min_i32_e32 v54, v54, v59
	v_max_i32_e32 v59, v61, v52
	v_min_i32_e32 v52, v61, v52
	v_max_i32_e32 v61, v56, v31
	v_min_i32_e32 v31, v56, v31
	v_max_i32_e32 v56, v36, v33
	v_min_i32_e32 v33, v36, v33
	s_waitcnt lgkmcnt(9)
; #define CAND(a, b) (int)((__float_as_uint(__int_as_float(top[0][a]) + __int_as_float(top[1][b])) | 255u) - (unsigned)((a) * 16 + (b)))
; __device__ __forceinline__ void route_task(int task, int tl0, const bf16* QP  , const LAS bf16* KHL, LAS unsigned short* EL, LAS float* GL, int lane) {
;     ...
;         sort16_desc(bk);
;         int oth[16];
; #pragma unroll
;         for (int i = 0; i < 16; ++i) oth[i] = __shfl_xor(bk[i], 32);
;         merge16_desc(bk, oth);
;     }
;     ...
;     {
;         int gk[16];
;         gk[0] = CAND(3, 3); gk[1] = CAND(4, 0); gk[2] = CAND(4, 1); gk[3] = CAND(4, 2); gk[4] = CAND(5, 0); gk[5] = CAND(5, 1); gk[6] = CAND(6, 0); gk[7] = CAND(6, 1);
;         gk[8] = CAND(7, 0); gk[9] = CAND(7, 1); gk[10] = CAND(8, 0); gk[11] = CAND(9, 0); gk[12] = CAND(10, 0); gk[13] = CAND(11, 0); gk[14] = CAND(12, 0); gk[15] = CAND(13, 0);
;         sort16_desc(gk);
;         merge16_desc(bk, gk);
;     }
	v_max_i32_e32 v38, v38, v70
	v_min_i32_e32 v36, v57, v69
	v_max_i32_e32 v70, v55, v62
	v_min_i32_e32 v55, v55, v62
	v_max_i32_e32 v62, v68, v59
	v_min_i32_e32 v59, v68, v59
	v_max_i32_e32 v68, v53, v52
	v_min_i32_e32 v52, v53, v52
	v_max_i32_e32 v53, v58, v67
	v_min_i32_e32 v58, v58, v67
	v_max_i32_e32 v67, v60, v54
	v_min_i32_e32 v54, v60, v54
	v_max_i32_e32 v60, v61, v56
	v_min_i32_e32 v56, v61, v56
	v_max_i32_e32 v61, v31, v33
	v_min_i32_e32 v31, v31, v33
	v_max_i32_e32 v33, v70, v36
	v_min_i32_e32 v36, v70, v36
	v_max_i32_e32 v70, v55, v60
	v_min_i32_e32 v55, v55, v60
	v_max_i32_e32 v60, v62, v53
	v_min_i32_e32 v53, v62, v53
	v_max_i32_e32 v62, v68, v58
	v_min_i32_e32 v58, v68, v58
	v_max_i32_e32 v68, v67, v59
	v_min_i32_e32 v59, v67, v59
	v_max_i32_e32 v67, v54, v52
	v_min_i32_e32 v52, v54, v52
	v_max_i32_e32 v54, v61, v56
	s_waitcnt lgkmcnt(3)
	v_max_i32_e32 v40, v40, v71
	s_waitcnt lgkmcnt(2)
	v_max_i32_e32 v30, v30, v72
	s_waitcnt lgkmcnt(1)
	v_max_i32_e32 v37, v37, v73
	s_waitcnt lgkmcnt(0)
	v_max_i32_e32 v28, v28, v74
	v_max_i32_e32 v41, v41, v66
	v_max_i32_e32 v32, v32, v65
	v_max_i32_e32 v44, v44, v64
	v_max_i32_e32 v46, v46, v63
	v_max_i32_e32 v34, v34, v49
	v_max_i32_e32 v39, v39, v48
	v_max_i32_e32 v29, v29, v47
	v_max_i32_e32 v27, v27, v42
	v_min_i32_e32 v56, v61, v56
	v_max_i32_e32 v61, v33, v60
	v_min_i32_e32 v33, v33, v60
	v_max_i32_e32 v60, v36, v53
	v_min_i32_e32 v36, v36, v53
	v_max_i32_e32 v53, v62, v68
	v_min_i32_e32 v62, v62, v68
	v_max_i32_e32 v68, v58, v59
	v_min_i32_e32 v58, v58, v59
	v_max_i32_e32 v59, v67, v54
	v_max_i32_e32 v42, v38, v41
	v_min_i32_e32 v38, v38, v41
	v_max_i32_e32 v41, v40, v32
	v_min_i32_e32 v32, v40, v32
	v_max_i32_e32 v40, v30, v44
	v_min_i32_e32 v30, v30, v44
	v_max_i32_e32 v44, v37, v46
	v_min_i32_e32 v37, v37, v46
	v_max_i32_e32 v46, v28, v34
	v_min_i32_e32 v28, v28, v34
	v_max_i32_e32 v34, v45, v39
	v_min_i32_e32 v39, v45, v39
	v_max_i32_e32 v45, v43, v29
	v_min_i32_e32 v29, v43, v29
	v_max_i32_e32 v43, v35, v27
	v_min_i32_e32 v27, v35, v27
	v_min_i32_e32 v54, v67, v54
	v_max_i32_e32 v67, v52, v56
	v_max_i32_e32 v71, v70, v36
	v_min_i32_e32 v36, v70, v36
	v_max_i32_e32 v70, v59, v55
	v_min_i32_e32 v55, v59, v55
	v_max_i32_e32 v35, v42, v46
	v_min_i32_e32 v42, v42, v46
	v_max_i32_e32 v46, v41, v34
	v_min_i32_e32 v34, v41, v34
	v_max_i32_e32 v41, v40, v45
	v_min_i32_e32 v40, v40, v45
	v_max_i32_e32 v45, v44, v43
	v_min_i32_e32 v43, v44, v43
	v_max_i32_e32 v44, v38, v28
	v_min_i32_e32 v28, v38, v28
	v_max_i32_e32 v38, v32, v39
	v_min_i32_e32 v32, v32, v39
	v_max_i32_e32 v39, v30, v29
	v_min_i32_e32 v29, v30, v29
	v_max_i32_e32 v30, v37, v27
	v_min_i32_e32 v27, v37, v27
	v_min_i32_e32 v52, v52, v56
	v_min_i32_e32 v56, v60, v33
	v_max_i32_e32 v59, v67, v54
	v_min_i32_e32 v54, v67, v54
	v_max_i32_e32 v67, v71, v53
	v_min_i32_e32 v53, v71, v53
	v_max_i32_e32 v71, v36, v62
	v_min_i32_e32 v36, v36, v62
	v_max_i32_e32 v62, v68, v70
	v_min_i32_e32 v68, v68, v70
	v_max_i32_e32 v70, v58, v55
	v_max_i32_e32 v37, v35, v41
	v_min_i32_e32 v35, v35, v41
	v_max_i32_e32 v41, v46, v45
	v_min_i32_e32 v45, v46, v45
	v_max_i32_e32 v46, v42, v40
	v_min_i32_e32 v40, v42, v40
	v_max_i32_e32 v42, v34, v43
	v_min_i32_e32 v34, v34, v43
	v_max_i32_e32 v43, v44, v39
	v_min_i32_e32 v39, v44, v39
	v_max_i32_e32 v44, v38, v30
	v_min_i32_e32 v30, v38, v30
	v_max_i32_e32 v38, v28, v29
	v_min_i32_e32 v28, v28, v29
	v_max_i32_e32 v29, v32, v27
	v_min_i32_e32 v27, v32, v27
	v_min_i32_e32 v55, v58, v55
	v_max_i32_e32 v58, v67, v56
	v_min_i32_e32 v56, v67, v56
	v_max_i32_e32 v67, v53, v71
	v_min_i32_e32 v53, v53, v71
	v_max_i32_e32 v71, v62, v36
	v_min_i32_e32 v36, v62, v36
	v_max_i32_e32 v62, v68, v70
	v_min_i32_e32 v32, v37, v41
	v_min_i32_e32 v47, v35, v45
	v_min_i32_e32 v48, v46, v42
	v_min_i32_e32 v49, v40, v34
	v_min_i32_e32 v63, v43, v44
	v_min_i32_e32 v64, v39, v30
	v_min_i32_e32 v65, v38, v29
	v_min_i32_e32 v66, v28, v27
	v_min_i32_e32 v68, v68, v70
	v_max_i32_e32 v70, v59, v55
	v_min_i32_e32 v55, v59, v55
	v_min_i32_e32 v59, v53, v71
	v_min_i32_e32 v72, v36, v62
	v_max3_i32 v31, v37, v41, v31
	v_max_i32_e32 v32, v32, v52
	v_max3_i32 v35, v35, v45, v54
	v_max_i32_e32 v37, v47, v55
	v_max3_i32 v41, v46, v42, v70
	v_max_i32_e32 v42, v48, v68
	v_max3_i32 v34, v40, v34, v72
	v_max3_i32 v36, v49, v36, v62
	v_max3_i32 v40, v43, v44, v59
	v_max3_i32 v43, v63, v53, v71
	v_max3_i32 v30, v39, v30, v67
	v_max_i32_e32 v39, v64, v56
	v_max3_i32 v29, v38, v29, v58
	v_max3_i32 v33, v65, v60, v33
	v_max3_i32 v27, v28, v27, v61
	v_max3_i32 v28, v66, v57, v69
	v_max_i32_e32 v38, v31, v40
	v_min_i32_e32 v31, v31, v40
	v_max_i32_e32 v40, v32, v43
	v_min_i32_e32 v32, v32, v43
	v_max_i32_e32 v43, v35, v30
	v_min_i32_e32 v30, v35, v30
	v_max_i32_e32 v35, v37, v39
	v_min_i32_e32 v37, v37, v39
	v_max_i32_e32 v39, v41, v29
	v_min_i32_e32 v29, v41, v29
	v_max_i32_e32 v41, v42, v33
	v_min_i32_e32 v33, v42, v33
	v_max_i32_e32 v42, v34, v27
	v_min_i32_e32 v27, v34, v27
	v_max_i32_e32 v34, v36, v28
	v_min_i32_e32 v28, v36, v28
	v_max_i32_e32 v36, v38, v39
	v_min_i32_e32 v38, v38, v39
	v_max_i32_e32 v39, v40, v41
	v_min_i32_e32 v40, v40, v41
	v_max_i32_e32 v41, v43, v42
	v_min_i32_e32 v42, v43, v42
	v_max_i32_e32 v43, v35, v34
	v_min_i32_e32 v34, v35, v34
	v_max_i32_e32 v35, v31, v29
	v_min_i32_e32 v29, v31, v29
	v_max_i32_e32 v31, v32, v33
	v_min_i32_e32 v32, v32, v33
	v_max_i32_e32 v33, v30, v27
	v_min_i32_e32 v27, v30, v27
	v_max_i32_e32 v30, v37, v28
	v_min_i32_e32 v28, v37, v28
	v_max_i32_e32 v37, v36, v41
	v_min_i32_e32 v36, v36, v41
	v_max_i32_e32 v41, v39, v43
	v_min_i32_e32 v39, v39, v43
	v_max_i32_e32 v43, v38, v42
	v_min_i32_e32 v38, v38, v42
; #define CAND(a, b) (int)((__float_as_uint(__int_as_float(top[0][a]) + __int_as_float(top[1][b])) | 255u) - (unsigned)((a) * 16 + (b)))
; __device__ __forceinline__ void route_task(int task, int tl0, const bf16* QP  , const LAS bf16* KHL, LAS unsigned short* EL, LAS float* GL, int lane) {
;     ...
;         merge16_desc(bk, gk);
;     }
;     {
;         const int c14 = CAND(14, 0), c15 = CAND(15, 0);
;         const int n14 = max(bk[14], c14), n15 = max(min(bk[14], c14), max(bk[15], c15));
;         bk[14] = n14; bk[15] = n15;
;     }
;     ...
;     int my[8];
; #pragma unroll
;     for (int i = 0; i < 8; ++i) { int lo_ = bk[i], hi_ = bk[8 + i]; asm volatile("" : "+v"(lo_), "+v"(hi_)); my[i] = hi ? hi_ : lo_; }
;     int bv[8];
; #pragma unroll
;     for (int i = 0; i < 8; ++i) {
;         const unsigned cd = 255u - ((unsigned)my[i] & 255u), ca = cd >> 4, cb = cd & 15u;
;         const unsigned wa = (ca >> 2) == 0u ? P1[0] : (ca >> 2) == 1u ? P1[1] : (ca >> 2) == 2u ? P1[2] : P1[3];
;         const unsigned wb = (cb >> 2) == 0u ? P2[0] : (cb >> 2) == 1u ? P2[1] : (cb >> 2) == 2u ? P2[2] : P2[3];
;         bv[i] = (int)((((wa >> (8u * (ca & 3u))) & 255u) << 7) | ((wb >> (8u * (cb & 3u))) & 255u));
;     }
	v_max_i32_e32 v42, v40, v34
	v_min_i32_e32 v34, v40, v34
	v_max_i32_e32 v40, v35, v33
	v_min_i32_e32 v33, v35, v33
	v_max_i32_e32 v35, v31, v30
	v_min_i32_e32 v30, v31, v30
	v_max_i32_e32 v31, v29, v27
	v_min_i32_e32 v27, v29, v27
	v_max_i32_e32 v29, v32, v28
	v_min_i32_e32 v28, v32, v28
	v_max_i32_e32 v32, v37, v41
	v_min_i32_e32 v37, v37, v41
	v_max_i32_e32 v41, v36, v39
	v_min_i32_e32 v36, v36, v39
	v_max_i32_e32 v39, v43, v42
	v_min_i32_e32 v42, v43, v42
	v_max_i32_e32 v43, v38, v34
	v_min_i32_e32 v34, v38, v34
	v_max_i32_e32 v38, v40, v35
	v_min_i32_e32 v35, v40, v35
	v_max_i32_e32 v40, v33, v30
	v_min_i32_e32 v30, v33, v30
	v_max_i32_e32 v33, v31, v29
	v_min_i32_e32 v29, v31, v29
	v_max_i32_e32 v31, v27, v28
	v_min_i32_e32 v27, v27, v28
	v_add_f32_e32 v28, v51, v26
	v_or_b32_e32 v28, 0xff, v28
	v_add_f32_e32 v26, v50, v26
	v_add_u32_e32 v28, 0xffffff20, v28
	v_or_b32_e32 v26, 0xff, v26
	v_add_u32_e32 v26, 0xffffff10, v26
	v_max_i32_e32 v44, v31, v28
	v_min_i32_e32 v28, v31, v28
	v_max3_i32 v26, v28, v27, v26
	v_mov_b32_e32 v27, v32
	s_nop 0
	v_cndmask_b32_e64 v27, v38, v27, s[6:7]
	v_not_b32_e32 v28, v27
	v_bfe_u32 v45, v28, 6, 2
	v_cmp_eq_u32_e32 vcc, 2, v45
	v_cndmask_b32_e64 v34, v26, v34, s[6:7]
	v_bitop3_b32 v26, v27, s3, v27 bitop3:0xc
	v_cndmask_b32_e32 v46, v25, v23, vcc
	v_cmp_eq_u32_e32 vcc, 1, v45
	v_cndmask_b32_e64 v31, v35, v37, s[6:7]
	v_not_b32_e32 v35, v31
	v_cndmask_b32_e32 v45, v46, v21, vcc
	v_cmp_gt_u32_e32 vcc, 64, v26
	v_cndmask_b32_e64 v37, v40, v41, s[6:7]
	v_cndmask_b32_e64 v41, v44, v43, s[6:7]
	v_cndmask_b32_e32 v26, v45, v19, vcc
	v_bfe_u32 v45, v28, 2, 2
	v_cmp_eq_u32_e32 vcc, 2, v45
	v_bitop3_b32 v44, v27, 15, v27 bitop3:0xc
	v_bfe_u32 v47, v35, 6, 2
	v_cndmask_b32_e32 v46, v24, v22, vcc
	v_cmp_eq_u32_e32 vcc, 1, v45
	v_not_b32_e32 v38, v37
	v_bfe_u32 v49, v38, 6, 2
	v_cndmask_b32_e32 v45, v46, v20, vcc
	v_cmp_gt_u32_e32 vcc, 4, v44
	v_bitop3_b32 v46, v31, 15, v31 bitop3:0xc
	v_cndmask_b32_e64 v30, v30, v36, s[6:7]
	v_cndmask_b32_e32 v44, v45, v18, vcc
	v_cmp_eq_u32_e32 vcc, 2, v47
	v_bitop3_b32 v45, v31, s3, v31 bitop3:0xc
	v_not_b32_e32 v36, v30
	v_cndmask_b32_e32 v48, v25, v23, vcc
	v_cmp_eq_u32_e32 vcc, 1, v47
	v_bfe_u32 v51, v36, 6, 2
	v_cndmask_b32_e64 v33, v33, v39, s[6:7]
	v_cndmask_b32_e32 v47, v48, v21, vcc
	v_cmp_gt_u32_e32 vcc, 64, v45
	v_not_b32_e32 v39, v33
	v_bfe_u32 v53, v39, 6, 2
	v_cndmask_b32_e32 v45, v47, v19, vcc
	v_bfe_u32 v47, v35, 2, 2
	v_cmp_eq_u32_e32 vcc, 2, v47
	v_cndmask_b32_e64 v29, v29, v42, s[6:7]
	v_not_b32_e32 v40, v29
	v_cndmask_b32_e32 v48, v24, v22, vcc
	v_cmp_eq_u32_e32 vcc, 1, v47
	v_bfe_u32 v55, v40, 6, 2
	v_not_b32_e32 v42, v41
	v_cndmask_b32_e32 v47, v48, v20, vcc
	v_cmp_gt_u32_e32 vcc, 4, v46
	v_bitop3_b32 v48, v37, 15, v37 bitop3:0xc
	v_bfe_u32 v57, v42, 6, 2
	v_cndmask_b32_e32 v46, v47, v18, vcc
	v_cmp_eq_u32_e32 vcc, 2, v49
	v_bitop3_b32 v47, v37, s3, v37 bitop3:0xc
	v_not_b32_e32 v43, v34
	v_cndmask_b32_e32 v50, v25, v23, vcc
	v_cmp_eq_u32_e32 vcc, 1, v49
	v_bfe_u32 v59, v43, 6, 2
	v_or_b32_e32 v82, s10, v88
	v_cndmask_b32_e32 v49, v50, v21, vcc
	v_cmp_gt_u32_e32 vcc, 64, v47
	s_nop 1
	v_cndmask_b32_e32 v47, v49, v19, vcc
	v_bfe_u32 v49, v38, 2, 2
	v_cmp_eq_u32_e32 vcc, 2, v49
	s_nop 1
	v_cndmask_b32_e32 v50, v24, v22, vcc
	v_cmp_eq_u32_e32 vcc, 1, v49
	s_nop 1
	v_cndmask_b32_e32 v49, v50, v20, vcc
	v_cmp_gt_u32_e32 vcc, 4, v48
	v_bitop3_b32 v50, v30, 15, v30 bitop3:0xc
	s_nop 0
	v_cndmask_b32_e32 v48, v49, v18, vcc
	v_cmp_eq_u32_e32 vcc, 2, v51
	v_bitop3_b32 v49, v30, s3, v30 bitop3:0xc
	s_nop 0
	v_cndmask_b32_e32 v52, v25, v23, vcc
	v_cmp_eq_u32_e32 vcc, 1, v51
	s_nop 1
	v_cndmask_b32_e32 v51, v52, v21, vcc
	v_cmp_gt_u32_e32 vcc, 64, v49
	s_nop 1
	v_cndmask_b32_e32 v49, v51, v19, vcc
	v_bfe_u32 v51, v36, 2, 2
	v_cmp_eq_u32_e32 vcc, 2, v51
	s_nop 1
	v_cndmask_b32_e32 v52, v24, v22, vcc
	v_cmp_eq_u32_e32 vcc, 1, v51
	s_nop 1
	v_cndmask_b32_e32 v51, v52, v20, vcc
	v_cmp_gt_u32_e32 vcc, 4, v50
	v_bitop3_b32 v52, v33, 15, v33 bitop3:0xc
	s_nop 0
	v_cndmask_b32_e32 v50, v51, v18, vcc
	v_cmp_eq_u32_e32 vcc, 2, v53
	v_bitop3_b32 v51, v33, s3, v33 bitop3:0xc
	s_nop 0
	v_cndmask_b32_e32 v54, v25, v23, vcc
	v_cmp_eq_u32_e32 vcc, 1, v53
	s_nop 1
	v_cndmask_b32_e32 v53, v54, v21, vcc
	v_cmp_gt_u32_e32 vcc, 64, v51
	s_nop 1
	v_cndmask_b32_e32 v51, v53, v19, vcc
	v_bfe_u32 v53, v39, 2, 2
	v_cmp_eq_u32_e32 vcc, 2, v53
	s_nop 1
	v_cndmask_b32_e32 v54, v24, v22, vcc
	v_cmp_eq_u32_e32 vcc, 1, v53
	s_nop 1
	v_cndmask_b32_e32 v53, v54, v20, vcc
	v_cmp_gt_u32_e32 vcc, 4, v52
	v_bitop3_b32 v54, v29, 15, v29 bitop3:0xc
	s_nop 0
	v_cndmask_b32_e32 v52, v53, v18, vcc
	v_cmp_eq_u32_e32 vcc, 2, v55
	v_bitop3_b32 v53, v29, s3, v29 bitop3:0xc
	s_nop 0
	v_cndmask_b32_e32 v56, v25, v23, vcc
	v_cmp_eq_u32_e32 vcc, 1, v55
	s_nop 1
	v_cndmask_b32_e32 v55, v56, v21, vcc
	v_cmp_gt_u32_e32 vcc, 64, v53
	s_nop 1
	v_cndmask_b32_e32 v53, v55, v19, vcc
	v_bfe_u32 v55, v40, 2, 2
	v_cmp_eq_u32_e32 vcc, 2, v55
	s_nop 1
	v_cndmask_b32_e32 v56, v24, v22, vcc
	v_cmp_eq_u32_e32 vcc, 1, v55
	s_nop 1
	v_cndmask_b32_e32 v55, v56, v20, vcc
	v_cmp_gt_u32_e32 vcc, 4, v54
	v_bitop3_b32 v56, v41, 15, v41 bitop3:0xc
	s_nop 0
	v_cndmask_b32_e32 v54, v55, v18, vcc
	v_cmp_eq_u32_e32 vcc, 2, v57
	v_bitop3_b32 v55, v41, s3, v41 bitop3:0xc
	s_nop 0
	v_cndmask_b32_e32 v58, v25, v23, vcc
	v_cmp_eq_u32_e32 vcc, 1, v57
	s_nop 1
	v_cndmask_b32_e32 v57, v58, v21, vcc
	v_cmp_gt_u32_e32 vcc, 64, v55
	s_nop 1
	v_cndmask_b32_e32 v55, v57, v19, vcc
	v_bfe_u32 v57, v42, 2, 2
	v_cmp_eq_u32_e32 vcc, 2, v57
	s_nop 1
	v_cndmask_b32_e32 v58, v24, v22, vcc
	v_cmp_eq_u32_e32 vcc, 1, v57
	s_nop 1
	v_cndmask_b32_e32 v57, v58, v20, vcc
; #define LAS __attribute__((address_space(3)))
; __device__ __forceinline__ void route_task(int task, int tl0, const bf16* QP  , const LAS bf16* KHL, LAS unsigned short* EL, LAS float* GL, int lane) {
;     ...
;     { unsigned qo = (unsigned)t * (unsigned)D + (unsigned)(head * 128 + 8 * hi); asm volatile("" : "+v"(qo)); const bf16* qp = QP + qo;
; #pragma unroll
;       for (int hf = 0; hf < 2; ++hf)
; #pragma unroll
;         for (int ks = 0; ks < 4; ++ks) qa[hf][ks] = ldg8(qp + 64 * hf + 16 * ks); }
;     ...
;     for (int i = 0; i < 8; ++i) {
;         const unsigned cd = 255u - ((unsigned)my[i] & 255u), ca = cd >> 4, cb = cd & 15u;
;         const unsigned wa = (ca >> 2) == 0u ? P1[0] : (ca >> 2) == 1u ? P1[1] : (ca >> 2) == 2u ? P1[2] : P1[3];
;         const unsigned wb = (cb >> 2) == 0u ? P2[0] : (cb >> 2) == 1u ? P2[1] : (cb >> 2) == 2u ? P2[2] : P2[3];
;         bv[i] = (int)((((wa >> (8u * (ca & 3u))) & 255u) << 7) | ((wb >> (8u * (cb & 3u))) & 255u));
;     }
;     float e[8], se = 0.f;
; #pragma unroll
;     for (int i = 0; i < 8; ++i) { e[i] = __expf(__int_as_float(my[i]) - __int_as_float(bk[0])); se += e[i]; }
;     se += __shfl_xor(se, 32);
;     const float inv = 1.f / se;
;     {
;         int l2 = lane; asm volatile("" : "+v"(l2));
;         const int o2 = (tl0 + ((l2 & 31) >> 3)) * 128 + (l2 & 7) * 16 + 8 * (l2 >> 5);
;         LAS v4u* ip = (LAS v4u*)(EL + o2); typedef float f4v __attribute__((ext_vector_type(4))); LAS f4v* gp = (LAS f4v*)(GL + o2);
;         ip[0] = (v4u){(unsigned)bv[0] | ((unsigned)bv[1] << 16), (unsigned)bv[2] | ((unsigned)bv[3] << 16), (unsigned)bv[4] | ((unsigned)bv[5] << 16), (unsigned)bv[6] | ((unsigned)bv[7] << 16)};
;         gp[0] = (f4v){e[0] * inv, e[1] * inv, e[2] * inv, e[3] * inv}; gp[1] = (f4v){e[4] * inv, e[5] * inv, e[6] * inv, e[7] * inv};
;     }
	v_cmp_gt_u32_e32 vcc, 4, v56
	v_bitop3_b32 v58, v34, 15, v34 bitop3:0xc
	s_nop 0
	v_cndmask_b32_e32 v56, v57, v18, vcc
	v_cmp_eq_u32_e32 vcc, 2, v59
	v_bitop3_b32 v57, v34, s3, v34 bitop3:0xc
	s_nop 0
	v_cndmask_b32_e32 v23, v25, v23, vcc
	v_cmp_eq_u32_e32 vcc, 1, v59
	v_sub_f32_e32 v25, v30, v32
	v_mul_f32_e32 v25, 0x3fb8aa3b, v25
	v_cndmask_b32_e32 v21, v23, v21, vcc
	v_cmp_gt_u32_e32 vcc, 64, v57
	v_lshrrev_b32_e32 v23, 1, v39
	v_and_b32_e32 v23, 24, v23
	v_cndmask_b32_e32 v19, v21, v19, vcc
	v_bfe_u32 v21, v43, 2, 2
	v_cmp_eq_u32_e32 vcc, 2, v21
	v_lshrrev_b32_e32 v23, v23, v51
	v_lshlrev_b32_e32 v23, 7, v23
	v_cndmask_b32_e32 v22, v24, v22, vcc
	v_cmp_eq_u32_e32 vcc, 1, v21
	v_lshrrev_b32_e32 v21, 1, v42
	v_and_b32_e32 v21, 24, v21
	v_cndmask_b32_e32 v20, v22, v20, vcc
	v_cmp_gt_u32_e32 vcc, 4, v58
	v_lshrrev_b32_e32 v21, v21, v55
	v_lshrrev_b32_e32 v22, 1, v40
	v_cndmask_b32_e32 v18, v20, v18, vcc
	v_lshlrev_b32_e32 v20, 3, v42
	v_lshlrev_b32_e32 v21, 7, v21
	v_and_b32_e32 v22, 24, v22
	v_lshrrev_b32_e32 v20, v20, v56
	v_and_b32_e32 v21, 0x7f80, v21
	v_lshrrev_b32_e32 v22, v22, v53
	v_and_or_b32 v21, v20, s3, v21
	v_lshlrev_b32_e32 v20, 3, v40
	v_lshlrev_b32_e32 v22, 7, v22
	v_lshrrev_b32_e32 v20, v20, v54
	v_and_b32_e32 v22, 0x7f80, v22
	v_and_or_b32 v20, v20, s3, v22
	v_lshlrev_b32_e32 v22, 3, v39
	v_lshrrev_b32_e32 v22, v22, v52
	v_and_b32_e32 v23, 0x7f80, v23
	v_and_or_b32 v39, v22, s3, v23
	v_lshrrev_b32_e32 v23, 1, v36
	v_and_b32_e32 v23, 24, v23
	v_lshrrev_b32_e32 v23, v23, v49
	v_lshlrev_b32_e32 v22, 3, v36
	v_lshlrev_b32_e32 v23, 7, v23
	v_lshrrev_b32_e32 v22, v22, v50
	v_and_b32_e32 v23, 0x7f80, v23
	v_and_or_b32 v36, v22, s3, v23
	v_lshrrev_b32_e32 v23, 1, v38
	v_and_b32_e32 v23, 24, v23
	v_lshrrev_b32_e32 v23, v23, v47
	v_lshlrev_b32_e32 v22, 3, v38
	v_lshlrev_b32_e32 v23, 7, v23
	v_lshrrev_b32_e32 v22, v22, v48
	v_and_b32_e32 v23, 0x7f80, v23
	v_and_or_b32 v38, v22, s3, v23
	v_lshrrev_b32_e32 v23, 1, v35
	v_and_b32_e32 v23, 24, v23
	v_lshrrev_b32_e32 v23, v23, v45
	v_lshlrev_b32_e32 v22, 3, v35
	v_lshlrev_b32_e32 v23, 7, v23
	v_lshrrev_b32_e32 v22, v22, v46
	v_and_b32_e32 v23, 0x7f80, v23
	v_and_or_b32 v35, v22, s3, v23
	v_lshrrev_b32_e32 v23, 1, v28
	v_and_b32_e32 v23, 24, v23
	v_lshrrev_b32_e32 v23, v23, v26
	v_lshlrev_b32_e32 v22, 3, v28
	v_lshlrev_b32_e32 v23, 7, v23
	v_lshrrev_b32_e32 v22, v22, v44
	v_and_b32_e32 v23, 0x7f80, v23
	v_and_or_b32 v40, v22, s3, v23
	v_sub_f32_e32 v22, v27, v32
	v_mul_f32_e32 v22, 0x3fb8aa3b, v22
	v_sub_f32_e32 v23, v31, v32
	v_exp_f32_e32 v22, v22
	v_mul_f32_e32 v23, 0x3fb8aa3b, v23
	v_sub_f32_e32 v24, v37, v32
	v_exp_f32_e32 v23, v23
	v_mul_f32_e32 v24, 0x3fb8aa3b, v24
	v_exp_f32_e32 v24, v24
	v_exp_f32_e32 v25, v25
	v_add_f32_e32 v26, 0, v22
	v_add_f32_e32 v26, v23, v26
	v_add_f32_e32 v26, v24, v26
	v_add_f32_e32 v30, v25, v26
	v_sub_f32_e32 v26, v33, v32
	v_mul_f32_e32 v26, 0x3fb8aa3b, v26
	v_sub_f32_e32 v27, v29, v32
	v_exp_f32_e32 v26, v26
	v_mul_f32_e32 v27, 0x3fb8aa3b, v27
	v_sub_f32_e32 v28, v41, v32
	v_exp_f32_e32 v27, v27
	v_mul_f32_e32 v28, 0x3fb8aa3b, v28
	v_sub_f32_e32 v29, v34, v32
	v_exp_f32_e32 v28, v28
	v_mul_f32_e32 v29, 0x3fb8aa3b, v29
	v_exp_f32_e32 v29, v29
	v_add_f32_e32 v30, v26, v30
	v_add_f32_e32 v30, v27, v30
	v_add_f32_e32 v30, v28, v30
	v_add_f32_e32 v30, v29, v30
	ds_bpermute_b32 v31, v123, v30
	v_lshrrev_b32_e32 v42, 1, v43
	v_and_b32_e32 v32, 24, v42
	v_lshrrev_b32_e32 v19, v32, v19
	v_lshlrev_b32_e32 v19, 7, v19
	s_waitcnt lgkmcnt(0)
	v_add_f32_e32 v30, v30, v31
	v_div_scale_f32 v31, s[12:13], v30, v30, 1.0
	v_rcp_f32_e32 v32, v31
	v_lshlrev_b32_e32 v33, 3, v43
	v_and_b32_e32 v19, 0x7f80, v19
	v_lshrrev_b32_e32 v18, v33, v18
	v_and_or_b32 v33, v18, s3, v19
	v_fma_f32 v18, -v31, v32, 1.0
	v_fmac_f32_e32 v32, v18, v32
	v_div_scale_f32 v18, vcc, 1.0, v30, 1.0
	v_mul_f32_e32 v19, v18, v32
	v_fma_f32 v34, -v31, v19, v18
	v_fmac_f32_e32 v19, v34, v32
	v_fma_f32 v18, -v31, v19, v18
	v_div_fmas_f32 v18, v18, v32, v19
	v_div_fixup_f32 v30, v18, v30, 1.0
	v_mov_b32_e32 v18, v1
	v_lshl_or_b32 v20, v20, 16, v39
	v_lshrrev_b32_e32 v19, 3, v18
	v_and_or_b32 v19, v19, 3, s55
	v_lshlrev_b32_e32 v31, 4, v18
	v_ashrrev_i32_e32 v18, 2, v18
	v_lshlrev_b32_e32 v19, 7, v19
	v_and_b32_e32 v31, 0x70, v31
	v_and_b32_e32 v18, -8, v18
	v_add3_u32 v18, v18, v31, v19
	v_lshl_add_u32 v31, v18, 1, s11
	v_lshl_add_u32 v32, v18, 2, s69
	v_lshl_or_b32 v18, v35, 16, v40
	v_lshl_or_b32 v19, v36, 16, v38
	v_lshl_or_b32 v21, v33, 16, v21
	ds_write_b128 v31, v[18:21]
	v_pk_mul_f32 v[20:21], v[24:25], v[30:31] op_sel_hi:[1,0]
	v_pk_mul_f32 v[18:19], v[22:23], v[30:31] op_sel_hi:[1,0]
	ds_write_b128 v32, v[18:21]
	v_pk_mul_f32 v[20:21], v[28:29], v[30:31] op_sel_hi:[1,0]
	v_pk_mul_f32 v[18:19], v[26:27], v[30:31] op_sel_hi:[1,0]
	ds_write_b128 v32, v[18:21] offset:16
	v_mov_b64_e32 v[32:33], s[30:31]
	v_lshl_add_u64 v[128:129], v[82:83], 1, s[80:81]
	s_waitcnt vmcnt(4)
	v_mov_b32_e32 v78, v150
	v_mov_b32_e32 v79, v151
	v_mov_b32_e32 v80, v152
	v_mov_b32_e32 v81, v153
	v_mov_b32_e32 v74, v154
	v_mov_b32_e32 v75, v155
	v_mov_b32_e32 v76, v156
	v_mov_b32_e32 v77, v157
	v_mov_b32_e32 v70, v158
	v_mov_b32_e32 v71, v159
	v_mov_b32_e32 v72, v160
	v_mov_b32_e32 v73, v161
	v_mov_b32_e32 v66, v162
	v_mov_b32_e32 v67, v163
	v_mov_b32_e32 v68, v164
	v_mov_b32_e32 v69, v165
	ds_read_b128 v[50:53], v94
	ds_read_b128 v[54:57], v94 offset:32
	v_mov_b64_e32 v[30:31], s[28:29]
	v_mov_b64_e32 v[28:29], s[26:27]
	v_mov_b64_e32 v[26:27], s[24:25]
	v_mov_b64_e32 v[24:25], s[22:23]
	v_mov_b64_e32 v[22:23], s[20:21]
	v_mov_b64_e32 v[20:21], s[18:19]
	v_mov_b64_e32 v[18:19], s[16:17]
	s_waitcnt vmcnt(3) lgkmcnt(1)
; #define LAS __attribute__((address_space(3)))
; #define MFMA32(a, b, c) __builtin_amdgcn_mfma_f32_32x32x16_bf16((a), (b), (c), 0, 0, 0)
; #define CE_(a, b) ce_desc(v[a], v[b])
; __device__ __forceinline__ void sort16_desc(int (&v)[16]) {
;     ...
;     CE_(0,13); CE_(1,12); CE_(2,15); CE_(3,14); CE_(4,8); CE_(5,6); CE_(7,11); CE_(9,10);
;     CE_(0,5); CE_(1,7); CE_(2,9); CE_(3,4); CE_(6,13); CE_(8,14); CE_(10,15); CE_(11,12);
;     CE_(0,1); CE_(2,3); CE_(4,5); CE_(6,8); CE_(7,9); CE_(10,11); CE_(12,13); CE_(14,15);
;     CE_(0,2); CE_(1,3); CE_(4,10); CE_(5,11); CE_(6,7); CE_(8,9); CE_(12,14); CE_(13,15);
;     CE_(1,2); CE_(3,12); CE_(4,6); CE_(5,7); CE_(8,10); CE_(9,11); CE_(13,14);
;     CE_(1,4); CE_(2,6); CE_(5,8); CE_(7,10); CE_(9,13); CE_(11,14);
;     CE_(2,4); CE_(3,6); CE_(9,12); CE_(11,13);
;     CE_(3,5); CE_(6,8); CE_(7,9); CE_(10,12);
;     CE_(3,4); CE_(5,6); CE_(7,8); CE_(9,10); CE_(11,12);
;     CE_(6,7); CE_(8,9);
;     ...
; }
; __device__ __forceinline__ void merge16_desc(int (&a)[16], const int (&b)[16]) {
; #pragma unroll
;     for (int i = 0; i < 16; ++i) a[i] = a[i] > b[15 - i] ? a[i] : b[15 - i];
; #pragma unroll
;     for (int j = 8; j > 0; j >>= 1)
; #pragma unroll
;         for (int i = 0; i < 16; ++i) { const int l = i ^ j; if (l > i) ce_desc(a[i], a[l]); }
; }
; __device__ __forceinline__ void route_task(int task, int tl0, const bf16* QP  , const LAS bf16* KHL, LAS unsigned short* EL, LAS float* GL, int lane) {
;     ...
;         for (int kt = 0; kt < 4; ++kt) {
;             f32x16 X;
; #pragma unroll
;             for (int i = 0; i < 16; ++i) X[i] = 8.f;
;             const LAS bf16* khp = KHL + (half * 128 + 32 * kt + r) * 72 + 8 * hi;
; #pragma unroll
;             for (int ks = 0; ks < 4; ++ks) {
;                 const bf16x8 kh = lds8(khp + 16 * ks);
;                 X = MFMA32(kh, qa[half][ks], X);
;             }
;             int grp[16];
; #pragma unroll
;             for (int i = 0; i < 16; ++i) grp[i] = (int)((__float_as_uint(X[i]) | 127u) - (unsigned)(32 * kt + (i & 3) + 8 * (i >> 2)));
;             sort16_desc(grp);
;             if (kt == 0) {
; #pragma unroll
;                 for (int i = 0; i < 16; ++i) cur[i] = grp[i];
;             } else merge16_desc(cur, grp);
	s_nop 0
	v_mfma_f32_32x32x16_bf16 v[34:49], v[50:53], v[78:81], v[18:33]
	ds_read_b128 v[50:53], v94 offset:64
	ds_read_b128 v[124:127], v94 offset:96
	s_waitcnt vmcnt(2) lgkmcnt(2)
	v_mfma_f32_32x32x16_bf16 v[34:49], v[54:57], v[74:77], v[34:49]
	s_waitcnt vmcnt(1) lgkmcnt(1)
	v_mfma_f32_32x32x16_bf16 v[34:49], v[50:53], v[70:73], v[34:49]
	s_waitcnt vmcnt(0)
	v_mov_b32_e32 v62, v166
	v_mov_b32_e32 v63, v167
	v_mov_b32_e32 v64, v168
	v_mov_b32_e32 v65, v169
	v_mov_b32_e32 v58, v170
	v_mov_b32_e32 v59, v171
	v_mov_b32_e32 v60, v172
	v_mov_b32_e32 v61, v173
	v_mov_b32_e32 v54, v174
	v_mov_b32_e32 v55, v175
	v_mov_b32_e32 v56, v176
	v_mov_b32_e32 v57, v177
	v_mov_b32_e32 v50, v178
	v_mov_b32_e32 v51, v179
	v_mov_b32_e32 v52, v180
	v_mov_b32_e32 v53, v181
	s_waitcnt vmcnt(4) lgkmcnt(0)
	v_mfma_f32_32x32x16_bf16 v[34:49], v[124:127], v[66:69], v[34:49]
	s_nop 11
	v_bitop3_b32 v37, v37, s42, 3 bitop3:0x56
	v_bitop3_b32 v48, v48, s42, 26 bitop3:0x56
	v_bitop3_b32 v38, v38, s42, 8 bitop3:0x56
	v_bitop3_b32 v42, v42, s42, 16 bitop3:0x56
	v_bitop3_b32 v47, v47, s42, 25 bitop3:0x56
	v_bitop3_b32 v39, v39, s42, 9 bitop3:0x56
	v_bitop3_b32 v40, v40, s42, 10 bitop3:0x56
	v_bitop3_b32 v43, v43, s42, 17 bitop3:0x56
	v_bitop3_b32 v44, v44, s42, 18 bitop3:0x56
	v_bitop3_b32 v36, v36, s42, 2 bitop3:0x56
	v_bitop3_b32 v49, v49, s42, 27 bitop3:0x56
	v_bitop3_b32 v41, v41, s42, 11 bitop3:0x56
	v_bitop3_b32 v45, v45, s42, 19 bitop3:0x56
	v_bitop3_b32 v35, v35, s42, 1 bitop3:0x56
	v_bitop3_b32 v46, v46, s42, 24 bitop3:0x56
	v_or_b32_e32 v34, 0x7f, v34
	v_max_i32_e32 v82, v37, v48
	v_max_i32_e32 v124, v38, v42
	v_max_i32_e32 v126, v34, v47
	v_max_i32_e32 v127, v39, v40
	v_min_i32_e32 v130, v43, v44
	v_min_i32_e32 v131, v36, v49
	v_min_i32_e32 v133, v41, v45
	v_min_i32_e32 v134, v35, v46
	v_min_i32_e32 v39, v39, v40
	v_min_i32_e32 v34, v34, v47
	v_min_i32_e32 v38, v38, v42
	v_min_i32_e32 v37, v37, v48
	v_max_i32_e32 v35, v35, v46
	v_max_i32_e32 v41, v41, v45
	v_max_i32_e32 v36, v36, v49
	v_max_i32_e32 v43, v43, v44
	v_min_i32_e32 v125, v82, v124
	v_min_i32_e32 v128, v126, v127
	v_max_i32_e32 v132, v130, v131
	v_max_i32_e32 v135, v133, v134
	v_max_i32_e32 v40, v39, v34
	v_max_i32_e32 v42, v38, v37
	v_min_i32_e32 v45, v35, v41
	v_min_i32_e32 v44, v36, v43
	v_min_i32_e32 v129, v125, v128
	v_max_i32_e32 v47, v40, v42
	v_max_i32_e32 v46, v45, v44
	v_min_i32_e32 v40, v40, v42
	v_min_i32_e32 v42, v45, v44
	v_max_i32_e32 v45, v125, v128
	v_max_i32_e32 v125, v132, v135
	v_min_i32_e32 v128, v45, v125
	v_min_i32_e32 v34, v39, v34
	v_max_i32_e32 v39, v126, v127
	v_max_i32_e32 v35, v35, v41
	v_max_i32_e32 v41, v82, v124
	v_max_i32_e32 v148, v45, v125
	ds_read_b128 v[124:127], v95
	v_max_i32_e32 v44, v40, v42
	v_min_i32_e32 v138, v40, v42
	v_min_i32_e32 v40, v133, v134
	v_min_i32_e32 v37, v38, v37
	v_min_i32_e32 v38, v130, v131
	v_max_i32_e32 v36, v36, v43
	v_min_i32_e32 v136, v132, v135
	v_min_i32_e32 v133, v40, v34
	v_min_i32_e32 v134, v37, v38
	v_max_i32_e32 v34, v40, v34
	v_max_i32_e32 v37, v37, v38
	v_min_i32_e32 v40, v39, v35
	v_min_i32_e32 v42, v36, v41
	v_max_i32_e32 v144, v39, v35
	v_max_i32_e32 v145, v36, v41
	v_max_i32_e32 v137, v129, v136
	v_min_i32_e32 v136, v129, v136
	v_max_i32_e32 v140, v133, v134
	v_min_i32_e32 v141, v34, v37
	v_max_i32_e32 v143, v40, v42
	v_min_i32_e32 v146, v144, v145
	v_max_i32_e32 v149, v47, v46
	v_min_i32_e32 v48, v47, v46
	v_max_i32_e32 v139, v138, v136
	v_max_i32_e32 v142, v140, v141
	v_min_i32_e32 v43, v40, v42
	v_max_i32_e32 v34, v34, v37
	v_min_i32_e32 v147, v143, v146
	v_min_i32_e32 v150, v148, v149
	v_min_i32_e32 v49, v137, v48
	v_min_i32_e32 v132, v44, v128
	v_max_i32_e32 v38, v139, v142
	v_min_i32_e32 v37, v43, v34
	v_max_i32_e32 v34, v43, v34
	v_min_i32_e32 v35, v147, v150
	v_max_i32_e32 v39, v137, v48
	v_max_i32_e32 v40, v44, v128
	v_max_i32_e32 v135, v49, v132
	v_max_i32_e32 v82, v38, v37
	v_min_i32_e32 v36, v34, v35
	v_min_i32_e32 v41, v39, v40
	v_max_i32_e32 v129, v135, v82
	v_min_i32_e32 v42, v36, v41
	v_min_i32_e32 v137, v129, v42
	v_max_i32_e32 v159, v129, v42
	ds_read_b128 v[128:131], v95 offset:32
	v_min_i32_e32 v82, v135, v82
	v_min_i32_e32 v132, v49, v132
	v_min_i32_e32 v135, v38, v37
	v_max_i32_e32 v154, v34, v35
	v_max_i32_e32 v155, v39, v40
	v_max_i32_e32 v157, v36, v41
	s_waitcnt lgkmcnt(1)
	v_mfma_f32_32x32x16_bf16 v[34:49], v[124:127], v[78:81], v[18:33]
	ds_read_b128 v[124:127], v95 offset:64
	v_max_i32_e32 v151, v132, v135
	v_max_i32_e32 v152, v82, v151
	v_min_i32_e32 v136, v138, v136
	v_min_i32_e32 v138, v140, v141
	v_min_i32_e32 v82, v82, v151
	v_max_i32_e32 v147, v147, v150
	s_waitcnt lgkmcnt(1)
	v_mfma_f32_32x32x16_bf16 v[34:49], v[128:131], v[74:77], v[34:49]
	ds_read_b128 v[128:131], v95 offset:96
	v_max_i32_e32 v143, v143, v146
	v_min_i32_e32 v133, v133, v134
	v_min_i32_e32 v156, v154, v155
	v_max_i32_e32 v140, v136, v138
	v_min_i32_e32 v139, v139, v142
	v_max_i32_e32 v142, v154, v155
	s_waitcnt lgkmcnt(1)
	v_mfma_f32_32x32x16_bf16 v[34:49], v[124:127], v[70:73], v[34:49]
	v_max_i32_e32 v124, v148, v149
	v_min_i32_e32 v136, v136, v138
	v_max_i32_e32 v141, v140, v139
	v_min_i32_e32 v139, v140, v139
	v_min_i32_e32 v125, v143, v124
	v_min_i32_e32 v158, v156, v157
	v_min_i32_e32 v132, v132, v135
	s_waitcnt lgkmcnt(0)
; #define LAS __attribute__((address_space(3)))
; #define MFMA32(a, b, c) __builtin_amdgcn_mfma_f32_32x32x16_bf16((a), (b), (c), 0, 0, 0)
; #define CE_(a, b) ce_desc(v[a], v[b])
; __device__ __forceinline__ void sort16_desc(int (&v)[16]) {
;     ...
;     CE_(0,13); CE_(1,12); CE_(2,15); CE_(3,14); CE_(4,8); CE_(5,6); CE_(7,11); CE_(9,10);
;     CE_(0,5); CE_(1,7); CE_(2,9); CE_(3,4); CE_(6,13); CE_(8,14); CE_(10,15); CE_(11,12);
;     CE_(0,1); CE_(2,3); CE_(4,5); CE_(6,8); CE_(7,9); CE_(10,11); CE_(12,13); CE_(14,15);
;     CE_(0,2); CE_(1,3); CE_(4,10); CE_(5,11); CE_(6,7); CE_(8,9); CE_(12,14); CE_(13,15);
;     CE_(1,2); CE_(3,12); CE_(4,6); CE_(5,7); CE_(8,10); CE_(9,11); CE_(13,14);
;     CE_(1,4); CE_(2,6); CE_(5,8); CE_(7,10); CE_(9,13); CE_(11,14);
;     CE_(2,4); CE_(3,6); CE_(9,12); CE_(11,13);
;     CE_(3,5); CE_(6,8); CE_(7,9); CE_(10,12);
;     CE_(3,4); CE_(5,6); CE_(7,8); CE_(9,10); CE_(11,12);
;     CE_(6,7); CE_(8,9);
;     ...
; }
; __device__ __forceinline__ void merge16_desc(int (&a)[16], const int (&b)[16]) {
; #pragma unroll
;     for (int i = 0; i < 16; ++i) a[i] = a[i] > b[15 - i] ? a[i] : b[15 - i];
; #pragma unroll
;     for (int j = 8; j > 0; j >>= 1)
; #pragma unroll
;         for (int i = 0; i < 16; ++i) { const int l = i ^ j; if (l > i) ce_desc(a[i], a[l]); }
; }
; __device__ __forceinline__ void route_task(int task, int tl0, const bf16* QP  , const LAS bf16* KHL, LAS unsigned short* EL, LAS float* GL, int lane) {
;     ...
;         for (int kt = 0; kt < 4; ++kt) {
;             f32x16 X;
; #pragma unroll
;             for (int i = 0; i < 16; ++i) X[i] = 8.f;
;             const LAS bf16* khp = KHL + (half * 128 + 32 * kt + r) * 72 + 8 * hi;
; #pragma unroll
;             for (int ks = 0; ks < 4; ++ks) {
;                 const bf16x8 kh = lds8(khp + 16 * ks);
;                 X = MFMA32(kh, qa[half][ks], X);
;             }
;             int grp[16];
; #pragma unroll
;             for (int i = 0; i < 16; ++i) grp[i] = (int)((__float_as_uint(X[i]) | 127u) - (unsigned)(32 * kt + (i & 3) + 8 * (i >> 2)));
;             sort16_desc(grp);
;             if (kt == 0) {
; #pragma unroll
;                 for (int i = 0; i < 16; ++i) cur[i] = grp[i];
;             } else merge16_desc(cur, grp);
	v_mfma_f32_32x32x16_bf16 v[34:49], v[128:131], v[66:69], v[34:49]
	v_min_i32_e32 v126, v147, v125
	v_min_i32_e32 v153, v137, v152
	v_min_i32_e32 v160, v158, v159
	v_min_i32_e32 v135, v141, v132
	v_min_i32_e32 v127, v142, v126
	s_nop 6
	v_bitop3_b32 v37, v37, s42, 35 bitop3:0x56
	v_bitop3_b32 v48, v48, s42, 58 bitop3:0x56
	v_bitop3_b32 v38, v38, s42, 40 bitop3:0x56
	v_bitop3_b32 v42, v42, s42, 48 bitop3:0x56
	v_bitop3_b32 v34, v34, s42, 32 bitop3:0x56
	v_bitop3_b32 v47, v47, s42, 57 bitop3:0x56
	v_bitop3_b32 v39, v39, s42, 41 bitop3:0x56
	v_bitop3_b32 v40, v40, s42, 42 bitop3:0x56
	v_bitop3_b32 v43, v43, s42, 49 bitop3:0x56
	v_bitop3_b32 v44, v44, s42, 50 bitop3:0x56
	v_bitop3_b32 v36, v36, s42, 34 bitop3:0x56
	v_bitop3_b32 v49, v49, s42, 59 bitop3:0x56
	v_bitop3_b32 v41, v41, s42, 43 bitop3:0x56
	v_bitop3_b32 v45, v45, s42, 51 bitop3:0x56
	v_bitop3_b32 v35, v35, s42, 33 bitop3:0x56
	v_bitop3_b32 v46, v46, s42, 56 bitop3:0x56
	v_max_i32_e32 v128, v37, v48
	v_max_i32_e32 v129, v38, v42
	v_max_i32_e32 v131, v34, v47
	v_max_i32_e32 v134, v39, v40
	v_min_i32_e32 v146, v43, v44
	v_min_i32_e32 v148, v36, v49
	v_min_i32_e32 v150, v41, v45
	v_min_i32_e32 v151, v35, v46
	v_min_i32_e32 v39, v39, v40
	v_min_i32_e32 v34, v34, v47
	v_min_i32_e32 v38, v38, v42
	v_min_i32_e32 v37, v37, v48
	v_max_i32_e32 v35, v35, v46
	v_max_i32_e32 v41, v41, v45
	v_max_i32_e32 v36, v36, v49
	v_max_i32_e32 v43, v43, v44
	v_min_i32_e32 v130, v128, v129
	v_min_i32_e32 v138, v131, v134
	v_max_i32_e32 v149, v146, v148
	v_max_i32_e32 v154, v150, v151
	v_max_i32_e32 v40, v39, v34
	v_max_i32_e32 v42, v38, v37
	v_min_i32_e32 v45, v35, v41
	v_min_i32_e32 v44, v36, v43
	v_min_i32_e32 v150, v150, v151
	v_min_i32_e32 v34, v39, v34
	v_min_i32_e32 v37, v38, v37
	v_min_i32_e32 v38, v146, v148
	v_max_i32_e32 v131, v131, v134
	v_max_i32_e32 v35, v35, v41
	v_max_i32_e32 v36, v36, v43
	v_max_i32_e32 v43, v128, v129
	v_min_i32_e32 v140, v130, v138
	v_min_i32_e32 v155, v149, v154
	v_max_i32_e32 v47, v40, v42
	v_max_i32_e32 v46, v45, v44
	v_min_i32_e32 v40, v40, v42
	v_min_i32_e32 v42, v45, v44
	v_max_i32_e32 v45, v130, v138
	v_max_i32_e32 v130, v149, v154
	v_min_i32_e32 v39, v150, v34
	v_min_i32_e32 v146, v37, v38
	v_max_i32_e32 v34, v150, v34
	v_max_i32_e32 v37, v37, v38
	v_min_i32_e32 v41, v131, v35
	v_min_i32_e32 v128, v36, v43
	v_max_i32_e32 v35, v131, v35
	v_max_i32_e32 v36, v36, v43
	v_min_i32_e32 v48, v47, v46
	v_max_i32_e32 v44, v40, v42
	v_min_i32_e32 v138, v45, v130
	v_min_i32_e32 v40, v40, v42
	v_min_i32_e32 v42, v140, v155
	v_max_i32_e32 v148, v39, v146
	v_min_i32_e32 v38, v34, v37
	v_min_i32_e32 v129, v41, v128
	v_max_i32_e32 v41, v41, v128
	v_min_i32_e32 v43, v35, v36
	v_max_i32_e32 v45, v45, v130
	v_max_i32_e32 v46, v47, v46
	v_max_i32_e32 v161, v140, v155
	v_max_i32_e32 v140, v40, v42
	v_max_i32_e32 v150, v148, v38
	v_max_i32_e32 v34, v34, v37
	v_min_i32_e32 v128, v41, v43
	v_min_i32_e32 v47, v45, v46
	v_min_i32_e32 v49, v161, v48
	v_min_i32_e32 v149, v44, v138
	v_max_i32_e32 v151, v140, v150
	v_min_i32_e32 v37, v129, v34
	v_max_i32_e32 v34, v129, v34
	v_min_i32_e32 v129, v128, v47
	v_max_i32_e32 v48, v161, v48
	v_max_i32_e32 v44, v44, v138
	v_max_i32_e32 v154, v49, v149
	v_max_i32_e32 v134, v151, v37
	v_min_i32_e32 v130, v34, v129
	v_min_i32_e32 v131, v48, v44
	v_min_i32_e32 v49, v49, v149
	v_min_i32_e32 v37, v151, v37
	v_max_i32_e32 v34, v34, v129
	v_max_i32_e32 v44, v48, v44
	v_min_i32_e32 v40, v40, v42
	v_min_i32_e32 v38, v148, v38
	v_max_i32_e32 v41, v41, v43
	v_max_i32_e32 v43, v45, v46
	v_max_i32_e32 v155, v154, v134
	v_min_i32_e32 v138, v130, v131
	v_min_i32_e32 v134, v154, v134
	v_max_i32_e32 v149, v49, v37
	v_min_i32_e32 v48, v34, v44
	v_max_i32_e32 v129, v130, v131
	v_max_i32_e32 v42, v40, v38
	v_min_i32_e32 v140, v140, v150
	v_max_i32_e32 v34, v34, v44
	v_max_i32_e32 v44, v128, v47
	v_min_i32_e32 v45, v41, v43
	v_min_i32_e32 v161, v155, v138
	v_max_i32_e32 v151, v134, v149
	v_min_i32_e32 v130, v48, v129
	v_max_i32_e32 v131, v155, v138
	v_max_i32_e32 v148, v42, v140
	v_min_i32_e32 v37, v49, v37
	v_min_i32_e32 v46, v44, v45
	v_min_i32_e32 v154, v161, v151
	v_min_i32_e32 v138, v130, v131
	v_min_i32_e32 v49, v148, v37
	v_min_i32_e32 v134, v134, v149
	v_min_i32_e32 v47, v34, v46
	v_min_i32_e32 v42, v42, v140
	v_min_i32_e32 v38, v40, v38
	v_min_i32_e32 v39, v39, v146
	v_max3_i32 v39, v144, v145, v39
	v_max3_i32 v38, v143, v124, v38
	v_max3_i32 v40, v147, v125, v42
	v_max3_i32 v42, v142, v126, v49
	v_max3_i32 v37, v127, v148, v37
	v_max3_i32 v49, v156, v157, v134
	v_max3_i32 v124, v158, v159, v154
	v_max3_i32 v125, v160, v161, v151
	v_max3_i32 v126, v137, v152, v138
	v_max3_i32 v127, v153, v130, v131
	v_max3_i32 v48, v82, v48, v129
	v_max3_i32 v47, v141, v132, v47
	v_max3_i32 v34, v135, v34, v46
	v_max3_i32 v44, v139, v44, v45
	v_max3_i32 v41, v136, v41, v43
	v_max3_i32 v35, v133, v35, v36
	v_max_i32_e32 v36, v39, v126
	v_min_i32_e32 v39, v39, v126
	v_max_i32_e32 v43, v38, v127
	v_min_i32_e32 v38, v38, v127
	v_max_i32_e32 v45, v40, v48
	v_min_i32_e32 v40, v40, v48
	v_max_i32_e32 v46, v42, v47
	v_min_i32_e32 v42, v42, v47
	v_max_i32_e32 v47, v37, v34
	v_min_i32_e32 v34, v37, v34
	v_max_i32_e32 v37, v49, v44
	v_min_i32_e32 v44, v49, v44
	v_max_i32_e32 v48, v124, v41
	v_min_i32_e32 v41, v124, v41
	v_max_i32_e32 v49, v125, v35
	v_min_i32_e32 v35, v125, v35
	ds_read_b128 v[124:127], v94 offset:9216
	ds_read_b128 v[128:131], v94 offset:9248
	v_max_i32_e32 v82, v36, v47
	v_min_i32_e32 v132, v36, v47
	v_max_i32_e32 v36, v43, v37
	v_min_i32_e32 v133, v43, v37
	v_max_i32_e32 v37, v45, v48
	v_max_i32_e32 v43, v46, v49
	v_min_i32_e32 v134, v45, v48
	v_min_i32_e32 v135, v46, v49
	v_max_i32_e32 v136, v39, v34
	v_min_i32_e32 v137, v39, v34
	v_max_i32_e32 v138, v38, v44
	v_min_i32_e32 v139, v38, v44
	v_max_i32_e32 v140, v40, v41
	v_min_i32_e32 v141, v40, v41
	v_max_i32_e32 v142, v42, v35
	v_min_i32_e32 v143, v42, v35
	v_max_i32_e32 v144, v82, v37
	v_min_i32_e32 v82, v82, v37
	v_max_i32_e32 v145, v36, v43
	v_min_i32_e32 v146, v36, v43
	s_waitcnt lgkmcnt(1)
; #define LAS __attribute__((address_space(3)))
; #define MFMA32(a, b, c) __builtin_amdgcn_mfma_f32_32x32x16_bf16((a), (b), (c), 0, 0, 0)
; #define CE_(a, b) ce_desc(v[a], v[b])
; __device__ __forceinline__ void sort16_desc(int (&v)[16]) {
;     ...
;     CE_(0,13); CE_(1,12); CE_(2,15); CE_(3,14); CE_(4,8); CE_(5,6); CE_(7,11); CE_(9,10);
;     CE_(0,5); CE_(1,7); CE_(2,9); CE_(3,4); CE_(6,13); CE_(8,14); CE_(10,15); CE_(11,12);
;     CE_(0,1); CE_(2,3); CE_(4,5); CE_(6,8); CE_(7,9); CE_(10,11); CE_(12,13); CE_(14,15);
;     CE_(0,2); CE_(1,3); CE_(4,10); CE_(5,11); CE_(6,7); CE_(8,9); CE_(12,14); CE_(13,15);
;     CE_(1,2); CE_(3,12); CE_(4,6); CE_(5,7); CE_(8,10); CE_(9,11); CE_(13,14);
;     CE_(1,4); CE_(2,6); CE_(5,8); CE_(7,10); CE_(9,13); CE_(11,14);
;     CE_(2,4); CE_(3,6); CE_(9,12); CE_(11,13);
;     CE_(3,5); CE_(6,8); CE_(7,9); CE_(10,12);
;     CE_(3,4); CE_(5,6); CE_(7,8); CE_(9,10); CE_(11,12);
;     CE_(6,7); CE_(8,9);
;     ...
; }
; __device__ __forceinline__ void merge16_desc(int (&a)[16], const int (&b)[16]) {
; #pragma unroll
;     for (int i = 0; i < 16; ++i) a[i] = a[i] > b[15 - i] ? a[i] : b[15 - i];
; #pragma unroll
;     for (int j = 8; j > 0; j >>= 1)
; #pragma unroll
;         for (int i = 0; i < 16; ++i) { const int l = i ^ j; if (l > i) ce_desc(a[i], a[l]); }
; }
; __device__ __forceinline__ void route_task(int task, int tl0, const bf16* QP  , const LAS bf16* KHL, LAS unsigned short* EL, LAS float* GL, int lane) {
;     ...
;         for (int kt = 0; kt < 4; ++kt) {
;             f32x16 X;
; #pragma unroll
;             for (int i = 0; i < 16; ++i) X[i] = 8.f;
;             const LAS bf16* khp = KHL + (half * 128 + 32 * kt + r) * 72 + 8 * hi;
; #pragma unroll
;             for (int ks = 0; ks < 4; ++ks) {
;                 const bf16x8 kh = lds8(khp + 16 * ks);
;                 X = MFMA32(kh, qa[half][ks], X);
;             }
;             int grp[16];
; #pragma unroll
;             for (int i = 0; i < 16; ++i) grp[i] = (int)((__float_as_uint(X[i]) | 127u) - (unsigned)(32 * kt + (i & 3) + 8 * (i >> 2)));
;             sort16_desc(grp);
;             if (kt == 0) {
; #pragma unroll
;                 for (int i = 0; i < 16; ++i) cur[i] = grp[i];
;             } else merge16_desc(cur, grp);
	v_mfma_f32_32x32x16_bf16 v[34:49], v[124:127], v[78:81], v[18:33]
	ds_read_b128 v[124:127], v94 offset:9280
	v_max_i32_e32 v147, v132, v134
	v_min_i32_e32 v132, v132, v134
	v_max_i32_e32 v134, v133, v135
	v_min_i32_e32 v133, v133, v135
	v_max_i32_e32 v135, v136, v140
	v_min_i32_e32 v136, v136, v140
	s_waitcnt lgkmcnt(1)
	v_mfma_f32_32x32x16_bf16 v[34:49], v[128:131], v[74:77], v[34:49]
	ds_read_b128 v[128:131], v94 offset:9312
	v_max_i32_e32 v140, v138, v142
	v_min_i32_e32 v138, v138, v142
	v_max_i32_e32 v142, v137, v141
	v_min_i32_e32 v137, v137, v141
	v_max_i32_e32 v141, v139, v143
	v_min_i32_e32 v139, v139, v143
	s_waitcnt lgkmcnt(1)
	v_mfma_f32_32x32x16_bf16 v[34:49], v[124:127], v[70:73], v[34:49]
	v_min_i32_e32 v143, v144, v145
	v_min_i32_e32 v124, v82, v146
	v_min_i32_e32 v127, v135, v140
	v_min_i32_e32 v125, v147, v134
	v_min_i32_e32 v126, v132, v133
	v_min_i32_e32 v149, v142, v141
	v_min_i32_e32 v148, v136, v138
	s_waitcnt lgkmcnt(0)
	v_mfma_f32_32x32x16_bf16 v[34:49], v[128:131], v[66:69], v[34:49]
	v_min_i32_e32 v150, v137, v139
	s_nop 10
	v_and_or_b32 v37, v37, s43, 60
	v_and_or_b32 v48, v48, s43, 37
	v_and_or_b32 v38, v38, s43, 55
	v_and_or_b32 v42, v42, s43, 47
	v_bitop3_b32 v34, v34, s42, 64 bitop3:0x56
	v_and_or_b32 v47, v47, s43, 38
	v_and_or_b32 v39, v39, s43, 54
	v_and_or_b32 v40, v40, s43, 53
	v_and_or_b32 v43, v43, s43, 46
	v_and_or_b32 v44, v44, s43, 45
	v_and_or_b32 v36, v36, s43, 61
	v_and_or_b32 v49, v49, s43, 36
	v_and_or_b32 v41, v41, s43, 52
	v_and_or_b32 v45, v45, s43, 44
	v_and_or_b32 v35, v35, s43, 62
	v_and_or_b32 v46, v46, s43, 39
	v_max_i32_e32 v128, v37, v48
	v_max_i32_e32 v129, v38, v42
	v_max_i32_e32 v131, v34, v47
	v_max_i32_e32 v151, v39, v40
	v_min_i32_e32 v154, v43, v44
	v_min_i32_e32 v155, v36, v49
	v_min_i32_e32 v157, v41, v45
	v_min_i32_e32 v158, v35, v46
	v_min_i32_e32 v39, v39, v40
	v_min_i32_e32 v34, v34, v47
	v_min_i32_e32 v38, v38, v42
	v_min_i32_e32 v37, v37, v48
	v_max_i32_e32 v35, v35, v46
	v_max_i32_e32 v41, v41, v45
	v_max_i32_e32 v36, v36, v49
	v_max_i32_e32 v43, v43, v44
	v_min_i32_e32 v130, v128, v129
	v_min_i32_e32 v152, v131, v151
	v_max_i32_e32 v156, v154, v155
	v_max_i32_e32 v159, v157, v158
	v_max_i32_e32 v40, v39, v34
	v_max_i32_e32 v42, v38, v37
	v_min_i32_e32 v45, v35, v41
	v_min_i32_e32 v44, v36, v43
	v_min_i32_e32 v157, v157, v158
	v_min_i32_e32 v34, v39, v34
	v_min_i32_e32 v37, v38, v37
	v_min_i32_e32 v38, v154, v155
	v_max_i32_e32 v131, v131, v151
	v_max_i32_e32 v35, v35, v41
	v_max_i32_e32 v36, v36, v43
	v_max_i32_e32 v43, v128, v129
	v_min_i32_e32 v153, v130, v152
	v_min_i32_e32 v160, v156, v159
	v_max_i32_e32 v47, v40, v42
	v_max_i32_e32 v46, v45, v44
	v_min_i32_e32 v40, v40, v42
	v_min_i32_e32 v42, v45, v44
	v_max_i32_e32 v45, v130, v152
	v_max_i32_e32 v130, v156, v159
	v_min_i32_e32 v39, v157, v34
	v_min_i32_e32 v154, v37, v38
	v_max_i32_e32 v34, v157, v34
	v_max_i32_e32 v37, v37, v38
	v_min_i32_e32 v41, v131, v35
	v_min_i32_e32 v128, v36, v43
	v_max_i32_e32 v35, v131, v35
	v_max_i32_e32 v36, v36, v43
	v_min_i32_e32 v48, v47, v46
	v_max_i32_e32 v44, v40, v42
	v_min_i32_e32 v152, v45, v130
	v_min_i32_e32 v40, v40, v42
	v_min_i32_e32 v42, v153, v160
	v_max_i32_e32 v155, v39, v154
	v_min_i32_e32 v38, v34, v37
	v_min_i32_e32 v129, v41, v128
	v_max_i32_e32 v41, v41, v128
	v_min_i32_e32 v43, v35, v36
	v_max_i32_e32 v45, v45, v130
	v_max_i32_e32 v46, v47, v46
	v_max_i32_e32 v161, v153, v160
	v_max_i32_e32 v153, v40, v42
	v_max_i32_e32 v157, v155, v38
	v_max_i32_e32 v34, v34, v37
	v_min_i32_e32 v128, v41, v43
	v_min_i32_e32 v47, v45, v46
	v_min_i32_e32 v49, v161, v48
	v_min_i32_e32 v156, v44, v152
	v_max_i32_e32 v158, v153, v157
	v_min_i32_e32 v37, v129, v34
	v_max_i32_e32 v34, v129, v34
	v_min_i32_e32 v129, v128, v47
	v_max_i32_e32 v48, v161, v48
	v_max_i32_e32 v44, v44, v152
	v_min_i32_e32 v40, v40, v42
	v_min_i32_e32 v38, v155, v38
	v_max_i32_e32 v159, v49, v156
	v_max_i32_e32 v151, v158, v37
	v_min_i32_e32 v130, v34, v129
	v_min_i32_e32 v131, v48, v44
	v_min_i32_e32 v49, v49, v156
	v_min_i32_e32 v37, v158, v37
	v_max_i32_e32 v34, v34, v129
	v_max_i32_e32 v44, v48, v44
	v_max_i32_e32 v42, v40, v38
	v_min_i32_e32 v153, v153, v157
	v_max_i32_e32 v160, v159, v151
	v_min_i32_e32 v152, v130, v131
	v_max_i32_e32 v156, v49, v37
	v_min_i32_e32 v48, v34, v44
	v_max_i32_e32 v129, v130, v131
	v_max_i32_e32 v155, v42, v153
	v_min_i32_e32 v37, v49, v37
	v_min_i32_e32 v151, v159, v151
	v_min_i32_e32 v130, v48, v129
	v_max_i32_e32 v131, v160, v152
	v_min_i32_e32 v49, v155, v37
	v_max_i32_e32 v41, v41, v43
	v_max_i32_e32 v43, v45, v46
	v_min_i32_e32 v42, v42, v153
	v_min_i32_e32 v38, v40, v38
	v_min_i32_e32 v161, v160, v152
	v_max_i32_e32 v158, v151, v156
	v_min_i32_e32 v151, v151, v156
	v_max_i32_e32 v34, v34, v44
	v_max_i32_e32 v44, v128, v47
	v_min_i32_e32 v45, v41, v43
	v_max_i32_e32 v40, v41, v43
	v_max_i32_e32 v38, v143, v38
	v_max3_i32 v41, v82, v146, v42
	v_max_i32_e32 v42, v124, v49
	v_max3_i32 v124, v127, v130, v131
	v_min_i32_e32 v46, v44, v45
	v_max_i32_e32 v43, v125, v151
	v_max3_i32 v49, v126, v161, v158
	v_max3_i32 v44, v149, v44, v45
	v_max_i32_e32 v45, v38, v124
	v_min_i32_e32 v38, v38, v124
	ds_read_b128 v[124:127], v96
	v_min_i32_e32 v159, v161, v158
	v_min_i32_e32 v152, v130, v131
	v_max_i32_e32 v37, v155, v37
	v_max_i32_e32 v48, v48, v129
	v_min_i32_e32 v47, v34, v46
	v_max_i32_e32 v34, v34, v46
	v_min_i32_e32 v39, v39, v154
	v_max3_i32 v39, v144, v145, v39
	v_max3_i32 v37, v147, v134, v37
	v_max3_i32 v46, v132, v133, v159
	v_max3_i32 v82, v135, v140, v152
	v_max3_i32 v48, v136, v138, v48
	v_max_i32_e32 v47, v148, v47
	v_max3_i32 v34, v142, v141, v34
	v_max3_i32 v40, v137, v139, v40
	v_max3_i32 v35, v150, v35, v36
	v_max_i32_e32 v36, v39, v82
	v_min_i32_e32 v39, v39, v82
	v_max_i32_e32 v82, v41, v48
	v_min_i32_e32 v41, v41, v48
	v_max_i32_e32 v48, v42, v47
	v_min_i32_e32 v42, v42, v47
	v_max_i32_e32 v47, v37, v34
	v_min_i32_e32 v34, v37, v34
	v_max_i32_e32 v37, v43, v44
	v_min_i32_e32 v43, v43, v44
	v_max_i32_e32 v44, v46, v40
	v_min_i32_e32 v40, v46, v40
	v_max_i32_e32 v46, v49, v35
	v_min_i32_e32 v35, v49, v35
	v_max_i32_e32 v49, v36, v47
	v_min_i32_e32 v132, v36, v47
	v_max_i32_e32 v36, v45, v37
	v_min_i32_e32 v133, v45, v37
	v_max_i32_e32 v37, v82, v44
	v_min_i32_e32 v82, v82, v44
	v_max_i32_e32 v44, v48, v46
	ds_read_b128 v[128:131], v96 offset:32
	v_min_i32_e32 v134, v48, v46
	v_max_i32_e32 v135, v39, v34
	v_min_i32_e32 v136, v39, v34
	v_max_i32_e32 v137, v38, v43
	v_min_i32_e32 v138, v38, v43
	v_max_i32_e32 v139, v41, v40
	v_min_i32_e32 v140, v41, v40
	v_max_i32_e32 v141, v42, v35
	v_min_i32_e32 v142, v42, v35
	v_max_i32_e32 v143, v49, v37
	v_min_i32_e32 v144, v49, v37
	v_max_i32_e32 v145, v36, v44
	v_min_i32_e32 v146, v36, v44
	s_waitcnt lgkmcnt(1)
; #define LAS __attribute__((address_space(3)))
; #define MFMA32(a, b, c) __builtin_amdgcn_mfma_f32_32x32x16_bf16((a), (b), (c), 0, 0, 0)
; #define CE_(a, b) ce_desc(v[a], v[b])
; __device__ __forceinline__ void sort16_desc(int (&v)[16]) {
;     ...
;     CE_(0,13); CE_(1,12); CE_(2,15); CE_(3,14); CE_(4,8); CE_(5,6); CE_(7,11); CE_(9,10);
;     CE_(0,5); CE_(1,7); CE_(2,9); CE_(3,4); CE_(6,13); CE_(8,14); CE_(10,15); CE_(11,12);
;     CE_(0,1); CE_(2,3); CE_(4,5); CE_(6,8); CE_(7,9); CE_(10,11); CE_(12,13); CE_(14,15);
;     CE_(0,2); CE_(1,3); CE_(4,10); CE_(5,11); CE_(6,7); CE_(8,9); CE_(12,14); CE_(13,15);
;     CE_(1,2); CE_(3,12); CE_(4,6); CE_(5,7); CE_(8,10); CE_(9,11); CE_(13,14);
;     CE_(1,4); CE_(2,6); CE_(5,8); CE_(7,10); CE_(9,13); CE_(11,14);
;     CE_(2,4); CE_(3,6); CE_(9,12); CE_(11,13);
;     CE_(3,5); CE_(6,8); CE_(7,9); CE_(10,12);
;     CE_(3,4); CE_(5,6); CE_(7,8); CE_(9,10); CE_(11,12);
;     CE_(6,7); CE_(8,9);
;     ...
; }
; __device__ __forceinline__ void merge16_desc(int (&a)[16], const int (&b)[16]) {
; #pragma unroll
;     for (int i = 0; i < 16; ++i) a[i] = a[i] > b[15 - i] ? a[i] : b[15 - i];
; #pragma unroll
;     for (int j = 8; j > 0; j >>= 1)
; #pragma unroll
;         for (int i = 0; i < 16; ++i) { const int l = i ^ j; if (l > i) ce_desc(a[i], a[l]); }
; }
; __device__ __forceinline__ void route_task(int task, int tl0, const bf16* QP  , const LAS bf16* KHL, LAS unsigned short* EL, LAS float* GL, int lane) {
;     ...
;         for (int kt = 0; kt < 4; ++kt) {
;             f32x16 X;
; #pragma unroll
;             for (int i = 0; i < 16; ++i) X[i] = 8.f;
;             const LAS bf16* khp = KHL + (half * 128 + 32 * kt + r) * 72 + 8 * hi;
; #pragma unroll
;             for (int ks = 0; ks < 4; ++ks) {
;                 const bf16x8 kh = lds8(khp + 16 * ks);
;                 X = MFMA32(kh, qa[half][ks], X);
;             }
;             int grp[16];
; #pragma unroll
;             for (int i = 0; i < 16; ++i) grp[i] = (int)((__float_as_uint(X[i]) | 127u) - (unsigned)(32 * kt + (i & 3) + 8 * (i >> 2)));
;             sort16_desc(grp);
;             if (kt == 0) {
; #pragma unroll
;                 for (int i = 0; i < 16; ++i) cur[i] = grp[i];
;             } else merge16_desc(cur, grp);
	v_mfma_f32_32x32x16_bf16 v[34:49], v[124:127], v[78:81], v[18:33]
	ds_read_b128 v[78:81], v96 offset:64
	v_max_i32_e32 v147, v132, v82
	v_min_i32_e32 v82, v132, v82
	v_max_i32_e32 v132, v137, v141
	v_max_i32_e32 v124, v133, v134
	v_min_i32_e32 v125, v133, v134
	v_max_i32_e32 v126, v135, v139
	s_waitcnt lgkmcnt(1)
	v_mfma_f32_32x32x16_bf16 v[34:49], v[128:131], v[74:77], v[34:49]
	ds_read_b128 v[74:77], v96 offset:96
	v_min_i32_e32 v128, v137, v141
	v_max_i32_e32 v129, v136, v140
	v_min_i32_e32 v130, v136, v140
	v_min_i32_e32 v127, v135, v139
	v_max_i32_e32 v131, v138, v142
	v_min_i32_e32 v133, v138, v142
	s_waitcnt lgkmcnt(1)
	v_mfma_f32_32x32x16_bf16 v[34:49], v[78:81], v[70:73], v[34:49]
	v_min_i32_e32 v134, v143, v145
	v_min_i32_e32 v70, v144, v146
	v_min_i32_e32 v71, v147, v124
	v_min_i32_e32 v72, v82, v125
	v_min_i32_e32 v73, v126, v132
	v_min_i32_e32 v78, v127, v128
	v_min_i32_e32 v79, v129, v131
	s_waitcnt lgkmcnt(0)
	v_mfma_f32_32x32x16_bf16 v[34:49], v[74:77], v[66:69], v[34:49]
	v_min_i32_e32 v80, v130, v133
	s_nop 10
	v_and_or_b32 v41, v41, s43, 20
	v_and_or_b32 v45, v45, s43, 12
	v_and_or_b32 v35, v35, s43, 30
	v_and_or_b32 v46, v46, s43, 7
	v_and_or_b32 v39, v39, s43, 22
	v_and_or_b32 v40, v40, s43, 21
	v_and_or_b32 v34, v34, s43, 31
	v_and_or_b32 v47, v47, s43, 6
	v_and_or_b32 v38, v38, s43, 23
	v_and_or_b32 v42, v42, s43, 15
	v_and_or_b32 v37, v37, s43, 28
	v_and_or_b32 v48, v48, s43, 5
	v_and_or_b32 v43, v43, s43, 14
	v_and_or_b32 v44, v44, s43, 13
	v_and_or_b32 v36, v36, s43, 29
	v_and_or_b32 v49, v49, s43, 4
	v_min_i32_e32 v66, v41, v45
	v_min_i32_e32 v67, v35, v46
	v_min_i32_e32 v69, v39, v40
	v_min_i32_e32 v74, v34, v47
	v_min_i32_e32 v77, v38, v42
	v_min_i32_e32 v81, v37, v48
	v_min_i32_e32 v136, v43, v44
	v_min_i32_e32 v137, v36, v49
	v_max_i32_e32 v34, v34, v47
	v_max_i32_e32 v39, v39, v40
	v_max_i32_e32 v35, v35, v46
	v_max_i32_e32 v41, v41, v45
	v_max_i32_e32 v36, v36, v49
	v_max_i32_e32 v43, v43, v44
	v_max_i32_e32 v37, v37, v48
	v_max_i32_e32 v38, v38, v42
	v_max_i32_e32 v40, v34, v39
	v_max_i32_e32 v45, v35, v41
	v_max_i32_e32 v44, v36, v43
	v_max_i32_e32 v42, v37, v38
	v_min_i32_e32 v46, v40, v45
	v_min_i32_e32 v47, v44, v42
	v_min_i32_e32 v75, v69, v74
	v_min_i32_e32 v48, v46, v47
	v_max_i32_e32 v46, v46, v47
	v_min_i32_e32 v37, v37, v38
	v_min_i32_e32 v34, v34, v39
	v_max_i32_e32 v39, v136, v137
	v_max_i32_e32 v47, v66, v67
	v_max_i32_e32 v69, v69, v74
	v_max_i32_e32 v74, v77, v81
	v_min_i32_e32 v35, v35, v41
	v_min_i32_e32 v36, v36, v43
	v_min_i32_e32 v68, v66, v67
	v_min_i32_e32 v135, v77, v81
	v_min_i32_e32 v138, v136, v137
	v_max_i32_e32 v38, v37, v34
	v_max_i32_e32 v77, v69, v74
	v_max_i32_e32 v41, v35, v36
	v_min_i32_e32 v34, v37, v34
	v_min_i32_e32 v37, v39, v47
	v_min_i32_e32 v76, v68, v75
	v_min_i32_e32 v139, v135, v138
	v_max_i32_e32 v49, v68, v75
	v_max_i32_e32 v68, v135, v138
	v_max_i32_e32 v40, v40, v45
	v_max_i32_e32 v42, v44, v42
	v_max_i32_e32 v66, v39, v47
	v_max_i32_e32 v43, v77, v41
	v_max_i32_e32 v39, v34, v37
	v_min_i32_e32 v41, v77, v41
	v_min_i32_e32 v69, v69, v74
	v_min_i32_e32 v35, v35, v36
	v_max_i32_e32 v75, v49, v68
	v_min_i32_e32 v44, v40, v42
	v_max_i32_e32 v67, v38, v66
	v_max_i32_e32 v47, v39, v41
	v_max_i32_e32 v36, v69, v35
	v_min_i32_e32 v39, v39, v41
	v_min_i32_e32 v35, v69, v35
	v_min_i32_e32 v34, v34, v37
	v_max_i32_e32 v41, v76, v139
	v_min_i32_e32 v49, v49, v68
	v_min_i32_e32 v45, v46, v44
	v_min_i32_e32 v81, v67, v43
	v_min_i32_e32 v38, v38, v66
	v_max_i32_e32 v37, v35, v34
	v_max_i32_e32 v68, v41, v49
	v_max_i32_e32 v135, v48, v75
	v_min_i32_e32 v136, v45, v81
	v_max_i32_e32 v66, v36, v38
	v_min_i32_e32 v36, v36, v38
	v_max_i32_e32 v69, v37, v68
	v_min_i32_e32 v48, v48, v75
	v_max_i32_e32 v137, v135, v136
	v_max_i32_e32 v74, v47, v66
	v_min_i32_e32 v135, v135, v136
	v_min_i32_e32 v47, v47, v66
	v_max_i32_e32 v38, v39, v36
	v_max_i32_e32 v75, v69, v48
	v_min_i32_e32 v34, v35, v34
	v_min_i32_e32 v35, v41, v49
	v_min_i32_e32 v36, v39, v36
	v_min_i32_e32 v39, v69, v48
	v_max_i32_e32 v44, v46, v44
	v_max_i32_e32 v43, v67, v43
	v_min_i32_e32 v140, v76, v139
	v_min_i32_e32 v77, v137, v74
	v_max_i32_e32 v66, v135, v47
	v_max_i32_e32 v76, v38, v75
	v_min_i32_e32 v47, v135, v47
	v_max_i32_e32 v41, v34, v35
	v_min_i32_e32 v37, v37, v68
	v_min_i32_e32 v48, v36, v39
	v_max_i32_e32 v45, v45, v81
	v_min_i32_e32 v46, v44, v43
	v_min_i32_e32 v38, v38, v75
	v_max_i32_e32 v36, v36, v39
	v_min_i32_e32 v136, v77, v66
	v_max_i32_e32 v135, v76, v47
	v_max_i32_e32 v49, v41, v37
	v_max_i32_e32 v69, v137, v74
	v_min_i32_e32 v67, v45, v46
	v_min_i32_e32 v47, v76, v47
	v_max_i32_e32 v39, v38, v36
	v_min_i32_e32 v138, v136, v135
	v_max_i32_e32 v68, v49, v48
	v_max_i32_e32 v74, v69, v67
	v_min_i32_e32 v37, v41, v37
	v_max_i32_e32 v41, v77, v66
	v_min_i32_e32 v75, v47, v39
	v_max_i32_e32 v43, v44, v43
	v_min_i32_e32 v34, v34, v35
	v_min_i32_e32 v36, v38, v36
	v_min_i32_e32 v48, v49, v48
	v_min_i32_e32 v49, v69, v67
	v_max3_i32 v140, v143, v145, v140
	v_max3_i32 v126, v126, v132, v138
	v_max3_i32 v68, v147, v124, v68
	v_max3_i32 v74, v129, v131, v74
	v_max3_i32 v37, v144, v146, v37
	v_max3_i32 v41, v127, v128, v41
	v_max3_i32 v75, v82, v125, v75
	v_max3_i32 v43, v130, v133, v43
	v_max_i32_e32 v34, v134, v34
	v_max3_i32 v35, v73, v136, v135
	v_max_i32_e32 v36, v71, v36
	v_max3_i32 v38, v79, v45, v46
	v_max_i32_e32 v48, v70, v48
	v_max_i32_e32 v49, v78, v49
	v_max3_i32 v39, v72, v47, v39
	v_max3_i32 v40, v80, v40, v42
	v_min_i32_e32 v81, v68, v74
	v_min_i32_e32 v66, v37, v41
	v_min_i32_e32 v73, v34, v35
	v_min_i32_e32 v45, v36, v38
	v_min_i32_e32 v42, v39, v40
	v_max_i32_e32 v71, v140, v126
; #define LAS __attribute__((address_space(3)))
; #define MFMA32(a, b, c) __builtin_amdgcn_mfma_f32_32x32x16_bf16((a), (b), (c), 0, 0, 0)
; __device__ __forceinline__ void route_task(int task, int tl0, const bf16* QP  , const LAS bf16* KHL, LAS unsigned short* EL, LAS float* GL, int lane) {
;     ...
;         for (int kt = 0; kt < 4; ++kt) {
;             f32x16 X;
; #pragma unroll
;             for (int i = 0; i < 16; ++i) X[i] = 8.f;
;             const LAS bf16* khp = KHL + (half * 128 + 32 * kt + r) * 72 + 8 * hi;
; #pragma unroll
;             for (int ks = 0; ks < 4; ++ks) {
;                 const bf16x8 kh = lds8(khp + 16 * ks);
;                 X = MFMA32(kh, qa[half][ks], X);
;             }
;             int grp[16];
; #pragma unroll
;             for (int i = 0; i < 16; ++i) grp[i] = (int)((__float_as_uint(X[i]) | 127u) - (unsigned)(32 * kt + (i & 3) + 8 * (i >> 2)));
;             sort16_desc(grp);
;             if (kt == 0) {
; #pragma unroll
;                 for (int i = 0; i < 16; ++i) cur[i] = grp[i];
;             } else merge16_desc(cur, grp);
;     ...
;         { const unsigned h4 = 4u * (unsigned)hi;
; #pragma unroll
;           for (int i = 0; i < 16; ++i) cur[i] -= (int)h4; }
;         int oth[16];
; #pragma unroll
;         for (int i = 0; i < 16; ++i) oth[i] = __shfl_xor(cur[i], 32);
;         merge16_desc(cur, oth);
	v_max_i32_e32 v68, v68, v74
	v_max_i32_e32 v37, v37, v41
	v_max_i32_e32 v41, v75, v43
	v_max_i32_e32 v34, v34, v35
	v_max_i32_e32 v35, v36, v38
	v_max_i32_e32 v38, v48, v49
	v_max_i32_e32 v39, v39, v40
	v_min_i32_e32 v44, v75, v43
	v_max_i32_e32 v72, v71, v68
	v_max_i32_e32 v43, v37, v41
	v_max_i32_e32 v36, v34, v35
	v_max_i32_e32 v40, v38, v39
	v_min_i32_e32 v67, v48, v49
	v_max_i32_e32 v74, v72, v43
	v_max_i32_e32 v48, v36, v40
	v_min_i32_e32 v43, v72, v43
	v_min_i32_e32 v36, v36, v40
	v_max_i32_e32 v40, v43, v36
	v_min_i32_e32 v36, v43, v36
	v_min_i32_e32 v43, v71, v68
	v_min_i32_e32 v37, v37, v41
	v_min_i32_e32 v34, v34, v35
	v_min_i32_e32 v35, v38, v39
	v_min_i32_e32 v132, v140, v126
	v_max_i32_e32 v41, v43, v37
	v_max_i32_e32 v38, v34, v35
	v_min_i32_e32 v37, v43, v37
	v_min_i32_e32 v34, v34, v35
	v_min_i32_e32 v76, v66, v44
	v_min_i32_e32 v47, v67, v42
	v_max_i32_e32 v39, v41, v38
	v_min_i32_e32 v38, v41, v38
	v_max_i32_e32 v35, v37, v34
	v_min_i32_e32 v34, v37, v34
	v_max_i32_e32 v37, v132, v81
	v_max_i32_e32 v41, v66, v44
	v_max_i32_e32 v44, v73, v45
	v_max_i32_e32 v42, v67, v42
	v_min_i32_e32 v124, v132, v81
	v_min_i32_e32 v46, v73, v45
	v_max_i32_e32 v43, v37, v41
	v_min_i32_e32 v37, v37, v41
	v_min_i32_e32 v41, v44, v42
	v_min_i32_e32 v77, v124, v76
	v_min_i32_e32 v69, v46, v47
	v_max_i32_e32 v45, v44, v42
	v_max_i32_e32 v42, v37, v41
	v_min_i32_e32 v37, v37, v41
	v_max_i32_e32 v41, v124, v76
	v_max_i32_e32 v44, v46, v47
	v_min_i32_e32 v70, v77, v69
	v_max_i32_e32 v49, v74, v48
	v_min_i32_e32 v48, v74, v48
	v_max_i32_e32 v66, v43, v45
	v_min_i32_e32 v43, v43, v45
	v_max_i32_e32 v45, v41, v44
	v_min_i32_e32 v41, v41, v44
	v_max_i32_e32 v44, v77, v69
	v_sub_u32_e32 v46, v49, v87
	v_sub_u32_e32 v47, v48, v87
	v_sub_u32_e32 v40, v40, v87
	v_sub_u32_e32 v36, v36, v87
	v_sub_u32_e32 v39, v39, v87
	v_sub_u32_e32 v38, v38, v87
	v_sub_u32_e32 v35, v35, v87
	v_sub_u32_e32 v34, v34, v87
	v_sub_u32_e32 v48, v66, v87
	v_sub_u32_e32 v43, v43, v87
	v_sub_u32_e32 v42, v42, v87
	v_sub_u32_e32 v37, v37, v87
	v_sub_u32_e32 v45, v45, v87
	v_sub_u32_e32 v41, v41, v87
	v_sub_u32_e32 v44, v44, v87
	v_sub_u32_e32 v49, v70, v87
	ds_bpermute_b32 v66, v123, v46
	ds_bpermute_b32 v67, v123, v47
	ds_bpermute_b32 v68, v123, v40
	ds_bpermute_b32 v69, v123, v36
	ds_bpermute_b32 v70, v123, v39
	ds_bpermute_b32 v71, v123, v38
	ds_bpermute_b32 v72, v123, v35
	ds_bpermute_b32 v73, v123, v34
	ds_bpermute_b32 v74, v123, v48
	ds_bpermute_b32 v75, v123, v43
	ds_bpermute_b32 v76, v123, v42
	ds_bpermute_b32 v77, v123, v49
	ds_bpermute_b32 v78, v123, v44
	ds_bpermute_b32 v79, v123, v41
	ds_bpermute_b32 v80, v123, v45
	ds_bpermute_b32 v81, v123, v37
	s_waitcnt lgkmcnt(4)
	v_max_i32_e32 v46, v46, v77
	s_waitcnt lgkmcnt(3)
	v_max_i32_e32 v47, v47, v78
	s_waitcnt lgkmcnt(2)
	v_max_i32_e32 v40, v40, v79
	s_waitcnt lgkmcnt(1)
	v_max_i32_e32 v36, v36, v80
	s_waitcnt lgkmcnt(0)
	v_max_i32_e32 v39, v39, v81
	v_max_i32_e32 v38, v38, v76
	v_max_i32_e32 v35, v35, v75
	v_max_i32_e32 v34, v34, v74
	v_max_i32_e32 v48, v48, v73
	v_max_i32_e32 v43, v43, v72
	v_max_i32_e32 v42, v42, v71
	v_max_i32_e32 v37, v37, v70
	v_max_i32_e32 v45, v45, v69
	v_max_i32_e32 v41, v41, v68
	v_max_i32_e32 v44, v44, v67
	v_max_i32_e32 v49, v49, v66
	v_max_i32_e32 v66, v46, v48
	v_min_i32_e32 v46, v46, v48
	v_max_i32_e32 v48, v47, v43
	v_min_i32_e32 v43, v47, v43
	v_max_i32_e32 v47, v40, v42
	v_min_i32_e32 v40, v40, v42
	v_max_i32_e32 v42, v36, v37
	v_min_i32_e32 v36, v36, v37
	v_max_i32_e32 v37, v39, v45
	v_min_i32_e32 v39, v39, v45
	v_max_i32_e32 v45, v38, v41
	v_min_i32_e32 v38, v38, v41
	v_max_i32_e32 v41, v35, v44
	v_min_i32_e32 v35, v35, v44
	v_max_i32_e32 v44, v34, v49
	v_min_i32_e32 v34, v34, v49
	v_max_i32_e32 v49, v66, v37
	v_min_i32_e32 v37, v66, v37
	v_max_i32_e32 v66, v48, v45
	v_min_i32_e32 v45, v48, v45
	v_max_i32_e32 v48, v47, v41
	v_min_i32_e32 v41, v47, v41
	v_max_i32_e32 v47, v42, v44
	v_max_i32_e32 v80, v66, v47
	v_min_i32_e32 v124, v66, v47
	ds_read_b128 v[66:69], v94 offset:18432
	ds_read_b128 v[70:73], v94 offset:18464
	v_min_i32_e32 v42, v42, v44
	v_max_i32_e32 v44, v46, v39
	v_min_i32_e32 v74, v46, v39
	v_max_i32_e32 v39, v43, v38
	v_min_i32_e32 v75, v43, v38
	v_max_i32_e32 v38, v40, v35
	v_min_i32_e32 v76, v40, v35
	v_max_i32_e32 v35, v36, v34
	v_min_i32_e32 v77, v36, v34
	v_max_i32_e32 v78, v49, v48
	v_min_i32_e32 v82, v49, v48
	v_max_i32_e32 v125, v37, v41
	v_min_i32_e32 v126, v37, v41
	v_max_i32_e32 v127, v45, v42
	v_min_i32_e32 v128, v45, v42
	v_max_i32_e32 v129, v44, v38
	v_min_i32_e32 v130, v44, v38
	v_max_i32_e32 v131, v39, v35
	v_min_i32_e32 v132, v39, v35
	s_waitcnt vmcnt(3) lgkmcnt(1)
	v_mfma_f32_32x32x16_bf16 v[34:49], v[66:69], v[62:65], v[18:33]
	ds_read_b128 v[66:69], v94 offset:18496
	v_max_i32_e32 v133, v74, v76
	v_min_i32_e32 v134, v74, v76
	v_max_i32_e32 v135, v75, v77
	v_min_i32_e32 v136, v75, v77
	v_max_i32_e32 v79, v78, v80
	v_min_i32_e32 v81, v78, v80
	s_waitcnt vmcnt(2) lgkmcnt(1)
	v_mfma_f32_32x32x16_bf16 v[34:49], v[70:73], v[58:61], v[34:49]
	v_max_i32_e32 v80, v82, v124
	v_min_i32_e32 v78, v82, v124
	v_max_i32_e32 v77, v125, v127
	v_min_i32_e32 v76, v125, v127
	v_max_i32_e32 v75, v126, v128
	v_min_i32_e32 v73, v126, v128
	ds_read_b128 v[124:127], v94 offset:18528
	s_waitcnt vmcnt(1) lgkmcnt(1)
	v_mfma_f32_32x32x16_bf16 v[34:49], v[66:69], v[54:57], v[34:49]
	v_max_i32_e32 v71, v129, v131
	v_min_i32_e32 v74, v129, v131
	v_max_i32_e32 v72, v130, v132
	v_min_i32_e32 v70, v130, v132
	v_max_i32_e32 v69, v133, v135
	v_min_i32_e32 v68, v133, v135
	v_max_i32_e32 v67, v134, v136
	s_waitcnt vmcnt(0) lgkmcnt(0)
; #define LAS __attribute__((address_space(3)))
; #define MFMA32(a, b, c) __builtin_amdgcn_mfma_f32_32x32x16_bf16((a), (b), (c), 0, 0, 0)
; #define CE_(a, b) ce_desc(v[a], v[b])
; __device__ __forceinline__ void sort16_desc(int (&v)[16]) {
;     ...
;     CE_(0,13); CE_(1,12); CE_(2,15); CE_(3,14); CE_(4,8); CE_(5,6); CE_(7,11); CE_(9,10);
;     CE_(0,5); CE_(1,7); CE_(2,9); CE_(3,4); CE_(6,13); CE_(8,14); CE_(10,15); CE_(11,12);
;     CE_(0,1); CE_(2,3); CE_(4,5); CE_(6,8); CE_(7,9); CE_(10,11); CE_(12,13); CE_(14,15);
;     CE_(0,2); CE_(1,3); CE_(4,10); CE_(5,11); CE_(6,7); CE_(8,9); CE_(12,14); CE_(13,15);
;     CE_(1,2); CE_(3,12); CE_(4,6); CE_(5,7); CE_(8,10); CE_(9,11); CE_(13,14);
;     CE_(1,4); CE_(2,6); CE_(5,8); CE_(7,10); CE_(9,13); CE_(11,14);
;     CE_(2,4); CE_(3,6); CE_(9,12); CE_(11,13);
;     CE_(3,5); CE_(6,8); CE_(7,9); CE_(10,12);
;     CE_(3,4); CE_(5,6); CE_(7,8); CE_(9,10); CE_(11,12);
;     CE_(6,7); CE_(8,9);
;     ...
; }
; __device__ __forceinline__ void merge16_desc(int (&a)[16], const int (&b)[16]) {
; #pragma unroll
;     for (int i = 0; i < 16; ++i) a[i] = a[i] > b[15 - i] ? a[i] : b[15 - i];
; #pragma unroll
;     for (int j = 8; j > 0; j >>= 1)
; #pragma unroll
;         for (int i = 0; i < 16; ++i) { const int l = i ^ j; if (l > i) ce_desc(a[i], a[l]); }
; }
; __device__ __forceinline__ void route_task(int task, int tl0, const bf16* QP  , const LAS bf16* KHL, LAS unsigned short* EL, LAS float* GL, int lane) {
;     ...
;         for (int kt = 0; kt < 4; ++kt) {
;             f32x16 X;
; #pragma unroll
;             for (int i = 0; i < 16; ++i) X[i] = 8.f;
;             const LAS bf16* khp = KHL + (half * 128 + 32 * kt + r) * 72 + 8 * hi;
; #pragma unroll
;             for (int ks = 0; ks < 4; ++ks) {
;                 const bf16x8 kh = lds8(khp + 16 * ks);
;                 X = MFMA32(kh, qa[half][ks], X);
;             }
;             int grp[16];
; #pragma unroll
;             for (int i = 0; i < 16; ++i) grp[i] = (int)((__float_as_uint(X[i]) | 127u) - (unsigned)(32 * kt + (i & 3) + 8 * (i >> 2)));
;             sort16_desc(grp);
;             if (kt == 0) {
; #pragma unroll
;                 for (int i = 0; i < 16; ++i) cur[i] = grp[i];
;             } else merge16_desc(cur, grp);
	v_mfma_f32_32x32x16_bf16 v[34:49], v[124:127], v[50:53], v[34:49]
	v_min_i32_e32 v66, v134, v136
	s_nop 10
	v_bitop3_b32 v37, v37, s42, 3 bitop3:0x56
	v_bitop3_b32 v48, v48, s42, 26 bitop3:0x56
	v_bitop3_b32 v38, v38, s42, 8 bitop3:0x56
	v_bitop3_b32 v42, v42, s42, 16 bitop3:0x56
	v_bitop3_b32 v47, v47, s42, 25 bitop3:0x56
	v_bitop3_b32 v39, v39, s42, 9 bitop3:0x56
	v_bitop3_b32 v40, v40, s42, 10 bitop3:0x56
	v_bitop3_b32 v43, v43, s42, 17 bitop3:0x56
	v_bitop3_b32 v44, v44, s42, 18 bitop3:0x56
	v_bitop3_b32 v36, v36, s42, 2 bitop3:0x56
	v_bitop3_b32 v49, v49, s42, 27 bitop3:0x56
	v_bitop3_b32 v41, v41, s42, 11 bitop3:0x56
	v_bitop3_b32 v45, v45, s42, 19 bitop3:0x56
	v_bitop3_b32 v35, v35, s42, 1 bitop3:0x56
	v_bitop3_b32 v46, v46, s42, 24 bitop3:0x56
	v_or_b32_e32 v34, 0x7f, v34
	v_max_i32_e32 v82, v37, v48
	v_max_i32_e32 v124, v38, v42
	v_max_i32_e32 v126, v34, v47
	v_max_i32_e32 v127, v39, v40
	v_min_i32_e32 v130, v43, v44
	v_min_i32_e32 v131, v36, v49
	v_min_i32_e32 v133, v41, v45
	v_min_i32_e32 v134, v35, v46
	v_min_i32_e32 v39, v39, v40
	v_min_i32_e32 v34, v34, v47
	v_min_i32_e32 v38, v38, v42
	v_min_i32_e32 v37, v37, v48
	v_max_i32_e32 v35, v35, v46
	v_max_i32_e32 v41, v41, v45
	v_max_i32_e32 v36, v36, v49
	v_max_i32_e32 v43, v43, v44
	v_min_i32_e32 v125, v82, v124
	v_min_i32_e32 v128, v126, v127
	v_max_i32_e32 v132, v130, v131
	v_max_i32_e32 v135, v133, v134
	v_max_i32_e32 v40, v39, v34
	v_max_i32_e32 v42, v38, v37
	v_min_i32_e32 v45, v35, v41
	v_min_i32_e32 v44, v36, v43
	v_min_i32_e32 v129, v125, v128
	v_max_i32_e32 v47, v40, v42
	v_max_i32_e32 v46, v45, v44
	v_min_i32_e32 v40, v40, v42
	v_min_i32_e32 v42, v45, v44
	v_max_i32_e32 v45, v125, v128
	v_max_i32_e32 v125, v132, v135
	v_min_i32_e32 v128, v45, v125
	v_min_i32_e32 v34, v39, v34
	v_max_i32_e32 v39, v126, v127
	v_max_i32_e32 v35, v35, v41
	v_max_i32_e32 v41, v82, v124
	v_max_i32_e32 v148, v45, v125
	ds_read_b128 v[124:127], v97
	v_max_i32_e32 v44, v40, v42
	v_min_i32_e32 v138, v40, v42
	v_min_i32_e32 v40, v133, v134
	v_min_i32_e32 v37, v38, v37
	v_min_i32_e32 v38, v130, v131
	v_max_i32_e32 v36, v36, v43
	v_min_i32_e32 v136, v132, v135
	v_min_i32_e32 v133, v40, v34
	v_min_i32_e32 v134, v37, v38
	v_max_i32_e32 v34, v40, v34
	v_max_i32_e32 v37, v37, v38
	v_min_i32_e32 v40, v39, v35
	v_min_i32_e32 v42, v36, v41
	v_max_i32_e32 v144, v39, v35
	v_max_i32_e32 v145, v36, v41
	v_max_i32_e32 v137, v129, v136
	v_min_i32_e32 v136, v129, v136
	v_max_i32_e32 v140, v133, v134
	v_min_i32_e32 v141, v34, v37
	v_max_i32_e32 v143, v40, v42
	v_min_i32_e32 v146, v144, v145
	v_max_i32_e32 v149, v47, v46
	v_min_i32_e32 v48, v47, v46
	v_max_i32_e32 v139, v138, v136
	v_max_i32_e32 v142, v140, v141
	v_min_i32_e32 v43, v40, v42
	v_max_i32_e32 v34, v34, v37
	v_min_i32_e32 v147, v143, v146
	v_min_i32_e32 v150, v148, v149
	v_min_i32_e32 v49, v137, v48
	v_min_i32_e32 v132, v44, v128
	v_max_i32_e32 v38, v139, v142
	v_min_i32_e32 v37, v43, v34
	v_max_i32_e32 v34, v43, v34
	v_min_i32_e32 v35, v147, v150
	v_max_i32_e32 v39, v137, v48
	v_max_i32_e32 v40, v44, v128
	v_max_i32_e32 v135, v49, v132
	v_max_i32_e32 v82, v38, v37
	v_min_i32_e32 v36, v34, v35
	v_min_i32_e32 v41, v39, v40
	v_max_i32_e32 v129, v135, v82
	v_min_i32_e32 v42, v36, v41
	v_min_i32_e32 v137, v129, v42
	v_max_i32_e32 v159, v129, v42
	ds_read_b128 v[128:131], v97 offset:32
	v_min_i32_e32 v82, v135, v82
	v_min_i32_e32 v132, v49, v132
	v_min_i32_e32 v135, v38, v37
	v_max_i32_e32 v154, v34, v35
	v_max_i32_e32 v155, v39, v40
	v_max_i32_e32 v157, v36, v41
	s_waitcnt lgkmcnt(1)
	v_mfma_f32_32x32x16_bf16 v[34:49], v[124:127], v[62:65], v[18:33]
	ds_read_b128 v[124:127], v97 offset:64
	v_max_i32_e32 v151, v132, v135
	v_max_i32_e32 v152, v82, v151
	v_min_i32_e32 v136, v138, v136
	v_min_i32_e32 v138, v140, v141
	v_min_i32_e32 v82, v82, v151
	v_max_i32_e32 v147, v147, v150
	s_waitcnt lgkmcnt(1)
	v_mfma_f32_32x32x16_bf16 v[34:49], v[128:131], v[58:61], v[34:49]
	ds_read_b128 v[128:131], v97 offset:96
	v_max_i32_e32 v143, v143, v146
	v_min_i32_e32 v133, v133, v134
	v_min_i32_e32 v156, v154, v155
	v_max_i32_e32 v140, v136, v138
	v_min_i32_e32 v139, v139, v142
	v_max_i32_e32 v142, v154, v155
	s_waitcnt lgkmcnt(1)
	v_mfma_f32_32x32x16_bf16 v[34:49], v[124:127], v[54:57], v[34:49]
	v_max_i32_e32 v124, v148, v149
	v_min_i32_e32 v136, v136, v138
	v_max_i32_e32 v141, v140, v139
	v_min_i32_e32 v139, v140, v139
	v_min_i32_e32 v125, v143, v124
	v_min_i32_e32 v158, v156, v157
	v_min_i32_e32 v132, v132, v135
	s_waitcnt lgkmcnt(0)
; #define LAS __attribute__((address_space(3)))
; #define MFMA32(a, b, c) __builtin_amdgcn_mfma_f32_32x32x16_bf16((a), (b), (c), 0, 0, 0)
; #define CE_(a, b) ce_desc(v[a], v[b])
; __device__ __forceinline__ void sort16_desc(int (&v)[16]) {
;     ...
;     CE_(0,13); CE_(1,12); CE_(2,15); CE_(3,14); CE_(4,8); CE_(5,6); CE_(7,11); CE_(9,10);
;     CE_(0,5); CE_(1,7); CE_(2,9); CE_(3,4); CE_(6,13); CE_(8,14); CE_(10,15); CE_(11,12);
;     CE_(0,1); CE_(2,3); CE_(4,5); CE_(6,8); CE_(7,9); CE_(10,11); CE_(12,13); CE_(14,15);
;     CE_(0,2); CE_(1,3); CE_(4,10); CE_(5,11); CE_(6,7); CE_(8,9); CE_(12,14); CE_(13,15);
;     CE_(1,2); CE_(3,12); CE_(4,6); CE_(5,7); CE_(8,10); CE_(9,11); CE_(13,14);
;     CE_(1,4); CE_(2,6); CE_(5,8); CE_(7,10); CE_(9,13); CE_(11,14);
;     CE_(2,4); CE_(3,6); CE_(9,12); CE_(11,13);
;     CE_(3,5); CE_(6,8); CE_(7,9); CE_(10,12);
;     CE_(3,4); CE_(5,6); CE_(7,8); CE_(9,10); CE_(11,12);
;     CE_(6,7); CE_(8,9);
;     ...
; }
; __device__ __forceinline__ void merge16_desc(int (&a)[16], const int (&b)[16]) {
; #pragma unroll
;     for (int i = 0; i < 16; ++i) a[i] = a[i] > b[15 - i] ? a[i] : b[15 - i];
; #pragma unroll
;     for (int j = 8; j > 0; j >>= 1)
; #pragma unroll
;         for (int i = 0; i < 16; ++i) { const int l = i ^ j; if (l > i) ce_desc(a[i], a[l]); }
; }
; __device__ __forceinline__ void route_task(int task, int tl0, const bf16* QP  , const LAS bf16* KHL, LAS unsigned short* EL, LAS float* GL, int lane) {
;     ...
;         for (int kt = 0; kt < 4; ++kt) {
;             f32x16 X;
; #pragma unroll
;             for (int i = 0; i < 16; ++i) X[i] = 8.f;
;             const LAS bf16* khp = KHL + (half * 128 + 32 * kt + r) * 72 + 8 * hi;
; #pragma unroll
;             for (int ks = 0; ks < 4; ++ks) {
;                 const bf16x8 kh = lds8(khp + 16 * ks);
;                 X = MFMA32(kh, qa[half][ks], X);
;             }
;             int grp[16];
; #pragma unroll
;             for (int i = 0; i < 16; ++i) grp[i] = (int)((__float_as_uint(X[i]) | 127u) - (unsigned)(32 * kt + (i & 3) + 8 * (i >> 2)));
;             sort16_desc(grp);
;             if (kt == 0) {
; #pragma unroll
;                 for (int i = 0; i < 16; ++i) cur[i] = grp[i];
;             } else merge16_desc(cur, grp);
	v_mfma_f32_32x32x16_bf16 v[34:49], v[128:131], v[50:53], v[34:49]
	v_min_i32_e32 v126, v147, v125
	v_min_i32_e32 v153, v137, v152
	v_min_i32_e32 v160, v158, v159
	v_min_i32_e32 v135, v141, v132
	v_min_i32_e32 v127, v142, v126
	s_nop 6
	v_bitop3_b32 v37, v37, s42, 35 bitop3:0x56
	v_bitop3_b32 v48, v48, s42, 58 bitop3:0x56
	v_bitop3_b32 v38, v38, s42, 40 bitop3:0x56
	v_bitop3_b32 v42, v42, s42, 48 bitop3:0x56
	v_bitop3_b32 v34, v34, s42, 32 bitop3:0x56
	v_bitop3_b32 v47, v47, s42, 57 bitop3:0x56
	v_bitop3_b32 v39, v39, s42, 41 bitop3:0x56
	v_bitop3_b32 v40, v40, s42, 42 bitop3:0x56
	v_bitop3_b32 v43, v43, s42, 49 bitop3:0x56
	v_bitop3_b32 v44, v44, s42, 50 bitop3:0x56
	v_bitop3_b32 v36, v36, s42, 34 bitop3:0x56
	v_bitop3_b32 v49, v49, s42, 59 bitop3:0x56
	v_bitop3_b32 v41, v41, s42, 43 bitop3:0x56
	v_bitop3_b32 v45, v45, s42, 51 bitop3:0x56
	v_bitop3_b32 v35, v35, s42, 33 bitop3:0x56
	v_bitop3_b32 v46, v46, s42, 56 bitop3:0x56
	v_max_i32_e32 v128, v37, v48
	v_max_i32_e32 v129, v38, v42
	v_max_i32_e32 v131, v34, v47
	v_max_i32_e32 v134, v39, v40
	v_min_i32_e32 v146, v43, v44
	v_min_i32_e32 v148, v36, v49
	v_min_i32_e32 v150, v41, v45
	v_min_i32_e32 v151, v35, v46
	v_min_i32_e32 v39, v39, v40
	v_min_i32_e32 v34, v34, v47
	v_min_i32_e32 v38, v38, v42
	v_min_i32_e32 v37, v37, v48
	v_max_i32_e32 v35, v35, v46
	v_max_i32_e32 v41, v41, v45
	v_max_i32_e32 v36, v36, v49
	v_max_i32_e32 v43, v43, v44
	v_min_i32_e32 v130, v128, v129
	v_min_i32_e32 v138, v131, v134
	v_max_i32_e32 v149, v146, v148
	v_max_i32_e32 v154, v150, v151
	v_max_i32_e32 v40, v39, v34
	v_max_i32_e32 v42, v38, v37
	v_min_i32_e32 v45, v35, v41
	v_min_i32_e32 v44, v36, v43
	v_min_i32_e32 v150, v150, v151
	v_min_i32_e32 v34, v39, v34
	v_min_i32_e32 v37, v38, v37
	v_min_i32_e32 v38, v146, v148
	v_max_i32_e32 v131, v131, v134
	v_max_i32_e32 v35, v35, v41
	v_max_i32_e32 v36, v36, v43
	v_max_i32_e32 v43, v128, v129
	v_min_i32_e32 v140, v130, v138
	v_min_i32_e32 v155, v149, v154
	v_max_i32_e32 v47, v40, v42
	v_max_i32_e32 v46, v45, v44
	v_min_i32_e32 v40, v40, v42
	v_min_i32_e32 v42, v45, v44
	v_max_i32_e32 v45, v130, v138
	v_max_i32_e32 v130, v149, v154
	v_min_i32_e32 v39, v150, v34
	v_min_i32_e32 v146, v37, v38
	v_max_i32_e32 v34, v150, v34
	v_max_i32_e32 v37, v37, v38
	v_min_i32_e32 v41, v131, v35
	v_min_i32_e32 v128, v36, v43
	v_max_i32_e32 v35, v131, v35
	v_max_i32_e32 v36, v36, v43
	v_min_i32_e32 v48, v47, v46
	v_max_i32_e32 v44, v40, v42
	v_min_i32_e32 v138, v45, v130
	v_min_i32_e32 v40, v40, v42
	v_min_i32_e32 v42, v140, v155
	v_max_i32_e32 v148, v39, v146
	v_min_i32_e32 v38, v34, v37
	v_min_i32_e32 v129, v41, v128
	v_max_i32_e32 v41, v41, v128
	v_min_i32_e32 v43, v35, v36
	v_max_i32_e32 v45, v45, v130
	v_max_i32_e32 v46, v47, v46
	v_max_i32_e32 v161, v140, v155
	v_max_i32_e32 v140, v40, v42
	v_max_i32_e32 v150, v148, v38
	v_max_i32_e32 v34, v34, v37
	v_min_i32_e32 v128, v41, v43
	v_min_i32_e32 v47, v45, v46
	v_min_i32_e32 v49, v161, v48
	v_min_i32_e32 v149, v44, v138
	v_max_i32_e32 v151, v140, v150
	v_min_i32_e32 v37, v129, v34
	v_max_i32_e32 v34, v129, v34
	v_min_i32_e32 v129, v128, v47
	v_max_i32_e32 v48, v161, v48
	v_max_i32_e32 v44, v44, v138
	v_max_i32_e32 v154, v49, v149
	v_max_i32_e32 v134, v151, v37
	v_min_i32_e32 v130, v34, v129
	v_min_i32_e32 v131, v48, v44
	v_min_i32_e32 v49, v49, v149
	v_min_i32_e32 v37, v151, v37
	v_max_i32_e32 v34, v34, v129
	v_max_i32_e32 v44, v48, v44
	v_min_i32_e32 v40, v40, v42
	v_min_i32_e32 v38, v148, v38
	v_max_i32_e32 v41, v41, v43
	v_max_i32_e32 v43, v45, v46
	v_max_i32_e32 v155, v154, v134
	v_min_i32_e32 v138, v130, v131
	v_min_i32_e32 v134, v154, v134
	v_max_i32_e32 v149, v49, v37
	v_min_i32_e32 v48, v34, v44
	v_max_i32_e32 v129, v130, v131
	v_max_i32_e32 v42, v40, v38
	v_min_i32_e32 v140, v140, v150
	v_max_i32_e32 v34, v34, v44
	v_max_i32_e32 v44, v128, v47
	v_min_i32_e32 v45, v41, v43
	v_min_i32_e32 v161, v155, v138
	v_max_i32_e32 v151, v134, v149
	v_min_i32_e32 v130, v48, v129
	v_max_i32_e32 v131, v155, v138
	v_max_i32_e32 v148, v42, v140
	v_min_i32_e32 v37, v49, v37
	v_min_i32_e32 v46, v44, v45
	v_min_i32_e32 v154, v161, v151
	v_min_i32_e32 v138, v130, v131
	v_min_i32_e32 v49, v148, v37
	v_min_i32_e32 v134, v134, v149
	v_min_i32_e32 v47, v34, v46
	v_min_i32_e32 v42, v42, v140
	v_min_i32_e32 v38, v40, v38
	v_min_i32_e32 v39, v39, v146
	v_max3_i32 v39, v144, v145, v39
	v_max3_i32 v38, v143, v124, v38
	v_max3_i32 v40, v147, v125, v42
	v_max3_i32 v42, v142, v126, v49
	v_max3_i32 v37, v127, v148, v37
	v_max3_i32 v49, v156, v157, v134
	v_max3_i32 v124, v158, v159, v154
	v_max3_i32 v125, v160, v161, v151
	v_max3_i32 v126, v137, v152, v138
	v_max3_i32 v127, v153, v130, v131
	v_max3_i32 v48, v82, v48, v129
	v_max3_i32 v47, v141, v132, v47
	v_max3_i32 v34, v135, v34, v46
	v_max3_i32 v44, v139, v44, v45
	v_max3_i32 v41, v136, v41, v43
	v_max3_i32 v35, v133, v35, v36
	v_max_i32_e32 v36, v39, v126
	v_min_i32_e32 v39, v39, v126
	v_max_i32_e32 v43, v38, v127
	v_min_i32_e32 v38, v38, v127
	v_max_i32_e32 v45, v40, v48
	v_min_i32_e32 v40, v40, v48
	v_max_i32_e32 v46, v42, v47
	v_min_i32_e32 v42, v42, v47
	v_max_i32_e32 v47, v37, v34
	v_min_i32_e32 v34, v37, v34
	v_max_i32_e32 v37, v49, v44
	v_min_i32_e32 v44, v49, v44
	v_max_i32_e32 v48, v124, v41
	v_min_i32_e32 v41, v124, v41
	v_max_i32_e32 v49, v125, v35
	v_min_i32_e32 v35, v125, v35
	ds_read_b128 v[124:127], v94 offset:27648
	ds_read_b128 v[128:131], v94 offset:27680
	v_max_i32_e32 v82, v36, v47
	v_min_i32_e32 v132, v36, v47
	v_max_i32_e32 v36, v43, v37
	v_min_i32_e32 v133, v43, v37
	v_max_i32_e32 v37, v45, v48
	v_max_i32_e32 v43, v46, v49
	v_min_i32_e32 v134, v45, v48
	v_min_i32_e32 v135, v46, v49
	v_max_i32_e32 v136, v39, v34
	v_min_i32_e32 v137, v39, v34
	v_max_i32_e32 v138, v38, v44
	v_min_i32_e32 v139, v38, v44
	v_max_i32_e32 v140, v40, v41
	v_min_i32_e32 v141, v40, v41
	v_max_i32_e32 v142, v42, v35
	v_min_i32_e32 v143, v42, v35
	v_max_i32_e32 v144, v82, v37
	v_min_i32_e32 v82, v82, v37
	v_max_i32_e32 v145, v36, v43
	v_min_i32_e32 v146, v36, v43
	s_waitcnt lgkmcnt(1)
; #define LAS __attribute__((address_space(3)))
; #define MFMA32(a, b, c) __builtin_amdgcn_mfma_f32_32x32x16_bf16((a), (b), (c), 0, 0, 0)
; #define CE_(a, b) ce_desc(v[a], v[b])
; __device__ __forceinline__ void sort16_desc(int (&v)[16]) {
;     ...
;     CE_(0,13); CE_(1,12); CE_(2,15); CE_(3,14); CE_(4,8); CE_(5,6); CE_(7,11); CE_(9,10);
;     CE_(0,5); CE_(1,7); CE_(2,9); CE_(3,4); CE_(6,13); CE_(8,14); CE_(10,15); CE_(11,12);
;     CE_(0,1); CE_(2,3); CE_(4,5); CE_(6,8); CE_(7,9); CE_(10,11); CE_(12,13); CE_(14,15);
;     CE_(0,2); CE_(1,3); CE_(4,10); CE_(5,11); CE_(6,7); CE_(8,9); CE_(12,14); CE_(13,15);
;     CE_(1,2); CE_(3,12); CE_(4,6); CE_(5,7); CE_(8,10); CE_(9,11); CE_(13,14);
;     CE_(1,4); CE_(2,6); CE_(5,8); CE_(7,10); CE_(9,13); CE_(11,14);
;     CE_(2,4); CE_(3,6); CE_(9,12); CE_(11,13);
;     CE_(3,5); CE_(6,8); CE_(7,9); CE_(10,12);
;     CE_(3,4); CE_(5,6); CE_(7,8); CE_(9,10); CE_(11,12);
;     CE_(6,7); CE_(8,9);
;     ...
; }
; __device__ __forceinline__ void merge16_desc(int (&a)[16], const int (&b)[16]) {
; #pragma unroll
;     for (int i = 0; i < 16; ++i) a[i] = a[i] > b[15 - i] ? a[i] : b[15 - i];
; #pragma unroll
;     for (int j = 8; j > 0; j >>= 1)
; #pragma unroll
;         for (int i = 0; i < 16; ++i) { const int l = i ^ j; if (l > i) ce_desc(a[i], a[l]); }
; }
; __device__ __forceinline__ void route_task(int task, int tl0, const bf16* QP  , const LAS bf16* KHL, LAS unsigned short* EL, LAS float* GL, int lane) {
;     ...
;         for (int kt = 0; kt < 4; ++kt) {
;             f32x16 X;
; #pragma unroll
;             for (int i = 0; i < 16; ++i) X[i] = 8.f;
;             const LAS bf16* khp = KHL + (half * 128 + 32 * kt + r) * 72 + 8 * hi;
; #pragma unroll
;             for (int ks = 0; ks < 4; ++ks) {
;                 const bf16x8 kh = lds8(khp + 16 * ks);
;                 X = MFMA32(kh, qa[half][ks], X);
;             }
;             int grp[16];
; #pragma unroll
;             for (int i = 0; i < 16; ++i) grp[i] = (int)((__float_as_uint(X[i]) | 127u) - (unsigned)(32 * kt + (i & 3) + 8 * (i >> 2)));
;             sort16_desc(grp);
;             if (kt == 0) {
; #pragma unroll
;                 for (int i = 0; i < 16; ++i) cur[i] = grp[i];
;             } else merge16_desc(cur, grp);
	v_mfma_f32_32x32x16_bf16 v[34:49], v[124:127], v[62:65], v[18:33]
	ds_read_b128 v[124:127], v94 offset:27712
	v_max_i32_e32 v147, v132, v134
	v_min_i32_e32 v132, v132, v134
	v_max_i32_e32 v134, v133, v135
	v_min_i32_e32 v133, v133, v135
	v_max_i32_e32 v135, v136, v140
	v_min_i32_e32 v136, v136, v140
	s_waitcnt lgkmcnt(1)
	v_mfma_f32_32x32x16_bf16 v[34:49], v[128:131], v[58:61], v[34:49]
	ds_read_b128 v[128:131], v94 offset:27744
	v_max_i32_e32 v140, v138, v142
	v_min_i32_e32 v138, v138, v142
	v_max_i32_e32 v142, v137, v141
	v_min_i32_e32 v137, v137, v141
	v_max_i32_e32 v141, v139, v143
	v_min_i32_e32 v139, v139, v143
	s_waitcnt lgkmcnt(1)
	v_mfma_f32_32x32x16_bf16 v[34:49], v[124:127], v[54:57], v[34:49]
	v_min_i32_e32 v143, v144, v145
	v_min_i32_e32 v124, v82, v146
	v_min_i32_e32 v127, v135, v140
	v_min_i32_e32 v125, v147, v134
	v_min_i32_e32 v126, v132, v133
	v_min_i32_e32 v149, v142, v141
	v_min_i32_e32 v148, v136, v138
	s_waitcnt lgkmcnt(0)
	v_mfma_f32_32x32x16_bf16 v[34:49], v[128:131], v[50:53], v[34:49]
	v_min_i32_e32 v150, v137, v139
	s_nop 10
	v_and_or_b32 v37, v37, s43, 60
	v_and_or_b32 v48, v48, s43, 37
	v_and_or_b32 v38, v38, s43, 55
	v_and_or_b32 v42, v42, s43, 47
	v_bitop3_b32 v34, v34, s42, 64 bitop3:0x56
	v_and_or_b32 v47, v47, s43, 38
	v_and_or_b32 v39, v39, s43, 54
	v_and_or_b32 v40, v40, s43, 53
	v_and_or_b32 v43, v43, s43, 46
	v_and_or_b32 v44, v44, s43, 45
	v_and_or_b32 v36, v36, s43, 61
	v_and_or_b32 v49, v49, s43, 36
	v_and_or_b32 v41, v41, s43, 52
	v_and_or_b32 v45, v45, s43, 44
	v_and_or_b32 v35, v35, s43, 62
	v_and_or_b32 v46, v46, s43, 39
	v_max_i32_e32 v128, v37, v48
	v_max_i32_e32 v129, v38, v42
	v_max_i32_e32 v131, v34, v47
	v_max_i32_e32 v151, v39, v40
	v_min_i32_e32 v154, v43, v44
	v_min_i32_e32 v155, v36, v49
	v_min_i32_e32 v157, v41, v45
	v_min_i32_e32 v158, v35, v46
	v_min_i32_e32 v39, v39, v40
	v_min_i32_e32 v34, v34, v47
	v_min_i32_e32 v38, v38, v42
	v_min_i32_e32 v37, v37, v48
	v_max_i32_e32 v35, v35, v46
	v_max_i32_e32 v41, v41, v45
	v_max_i32_e32 v36, v36, v49
	v_max_i32_e32 v43, v43, v44
	v_min_i32_e32 v130, v128, v129
	v_min_i32_e32 v152, v131, v151
	v_max_i32_e32 v156, v154, v155
	v_max_i32_e32 v159, v157, v158
	v_max_i32_e32 v40, v39, v34
	v_max_i32_e32 v42, v38, v37
	v_min_i32_e32 v45, v35, v41
	v_min_i32_e32 v44, v36, v43
	v_min_i32_e32 v157, v157, v158
	v_min_i32_e32 v34, v39, v34
	v_min_i32_e32 v37, v38, v37
	v_min_i32_e32 v38, v154, v155
	v_max_i32_e32 v131, v131, v151
	v_max_i32_e32 v35, v35, v41
	v_max_i32_e32 v36, v36, v43
	v_max_i32_e32 v43, v128, v129
	v_min_i32_e32 v153, v130, v152
	v_min_i32_e32 v160, v156, v159
	v_max_i32_e32 v47, v40, v42
	v_max_i32_e32 v46, v45, v44
	v_min_i32_e32 v40, v40, v42
	v_min_i32_e32 v42, v45, v44
	v_max_i32_e32 v45, v130, v152
	v_max_i32_e32 v130, v156, v159
	v_min_i32_e32 v39, v157, v34
	v_min_i32_e32 v154, v37, v38
	v_max_i32_e32 v34, v157, v34
	v_max_i32_e32 v37, v37, v38
	v_min_i32_e32 v41, v131, v35
	v_min_i32_e32 v128, v36, v43
	v_max_i32_e32 v35, v131, v35
	v_max_i32_e32 v36, v36, v43
	v_min_i32_e32 v48, v47, v46
	v_max_i32_e32 v44, v40, v42
	v_min_i32_e32 v152, v45, v130
	v_min_i32_e32 v40, v40, v42
	v_min_i32_e32 v42, v153, v160
	v_max_i32_e32 v155, v39, v154
	v_min_i32_e32 v38, v34, v37
	v_min_i32_e32 v129, v41, v128
	v_max_i32_e32 v41, v41, v128
	v_min_i32_e32 v43, v35, v36
	v_max_i32_e32 v45, v45, v130
	v_max_i32_e32 v46, v47, v46
	v_max_i32_e32 v161, v153, v160
	v_max_i32_e32 v153, v40, v42
	v_max_i32_e32 v157, v155, v38
	v_max_i32_e32 v34, v34, v37
	v_min_i32_e32 v128, v41, v43
	v_min_i32_e32 v47, v45, v46
	v_min_i32_e32 v49, v161, v48
	v_min_i32_e32 v156, v44, v152
	v_max_i32_e32 v158, v153, v157
	v_min_i32_e32 v37, v129, v34
	v_max_i32_e32 v34, v129, v34
	v_min_i32_e32 v129, v128, v47
	v_max_i32_e32 v48, v161, v48
	v_max_i32_e32 v44, v44, v152
	v_min_i32_e32 v40, v40, v42
	v_min_i32_e32 v38, v155, v38
	v_max_i32_e32 v159, v49, v156
	v_max_i32_e32 v151, v158, v37
	v_min_i32_e32 v130, v34, v129
	v_min_i32_e32 v131, v48, v44
	v_min_i32_e32 v49, v49, v156
	v_min_i32_e32 v37, v158, v37
	v_max_i32_e32 v34, v34, v129
	v_max_i32_e32 v44, v48, v44
	v_max_i32_e32 v42, v40, v38
	v_min_i32_e32 v153, v153, v157
	v_max_i32_e32 v160, v159, v151
	v_min_i32_e32 v152, v130, v131
	v_max_i32_e32 v156, v49, v37
	v_min_i32_e32 v48, v34, v44
	v_max_i32_e32 v129, v130, v131
	v_max_i32_e32 v155, v42, v153
	v_min_i32_e32 v37, v49, v37
	v_min_i32_e32 v151, v159, v151
	v_min_i32_e32 v130, v48, v129
	v_max_i32_e32 v131, v160, v152
	v_min_i32_e32 v49, v155, v37
	v_max_i32_e32 v41, v41, v43
	v_max_i32_e32 v43, v45, v46
	v_min_i32_e32 v42, v42, v153
	v_min_i32_e32 v38, v40, v38
	v_min_i32_e32 v161, v160, v152
	v_max_i32_e32 v158, v151, v156
	v_min_i32_e32 v151, v151, v156
	v_max_i32_e32 v34, v34, v44
	v_max_i32_e32 v44, v128, v47
	v_min_i32_e32 v45, v41, v43
	v_max_i32_e32 v40, v41, v43
	v_max_i32_e32 v38, v143, v38
	v_max3_i32 v41, v82, v146, v42
	v_max_i32_e32 v42, v124, v49
	v_max3_i32 v124, v127, v130, v131
	v_min_i32_e32 v46, v44, v45
	v_max_i32_e32 v43, v125, v151
	v_max3_i32 v49, v126, v161, v158
	v_max3_i32 v44, v149, v44, v45
	v_max_i32_e32 v45, v38, v124
	v_min_i32_e32 v38, v38, v124
	ds_read_b128 v[124:127], v98
	v_min_i32_e32 v159, v161, v158
	v_min_i32_e32 v152, v130, v131
	v_max_i32_e32 v37, v155, v37
	v_max_i32_e32 v48, v48, v129
	v_min_i32_e32 v47, v34, v46
	v_max_i32_e32 v34, v34, v46
	v_min_i32_e32 v39, v39, v154
	v_max3_i32 v39, v144, v145, v39
	v_max3_i32 v37, v147, v134, v37
	v_max3_i32 v46, v132, v133, v159
	v_max3_i32 v82, v135, v140, v152
	v_max3_i32 v48, v136, v138, v48
	v_max_i32_e32 v47, v148, v47
	v_max3_i32 v34, v142, v141, v34
	v_max3_i32 v40, v137, v139, v40
	v_max3_i32 v35, v150, v35, v36
	v_max_i32_e32 v36, v39, v82
	v_min_i32_e32 v39, v39, v82
	v_max_i32_e32 v82, v41, v48
	v_min_i32_e32 v41, v41, v48
	v_max_i32_e32 v48, v42, v47
	v_min_i32_e32 v42, v42, v47
	v_max_i32_e32 v47, v37, v34
	v_min_i32_e32 v34, v37, v34
	v_max_i32_e32 v37, v43, v44
	v_min_i32_e32 v43, v43, v44
	v_max_i32_e32 v44, v46, v40
	v_min_i32_e32 v40, v46, v40
	v_max_i32_e32 v46, v49, v35
	v_min_i32_e32 v35, v49, v35
	v_max_i32_e32 v49, v36, v47
	v_min_i32_e32 v132, v36, v47
	v_max_i32_e32 v36, v45, v37
	v_min_i32_e32 v133, v45, v37
	v_max_i32_e32 v37, v82, v44
	v_min_i32_e32 v82, v82, v44
	v_max_i32_e32 v44, v48, v46
	ds_read_b128 v[128:131], v98 offset:32
	v_min_i32_e32 v134, v48, v46
	v_max_i32_e32 v135, v39, v34
	v_min_i32_e32 v136, v39, v34
	v_max_i32_e32 v137, v38, v43
	v_min_i32_e32 v138, v38, v43
	v_max_i32_e32 v139, v41, v40
	v_min_i32_e32 v140, v41, v40
	v_max_i32_e32 v141, v42, v35
	v_min_i32_e32 v142, v42, v35
	v_max_i32_e32 v143, v49, v37
	v_min_i32_e32 v144, v49, v37
	v_max_i32_e32 v145, v36, v44
	v_min_i32_e32 v146, v36, v44
	s_waitcnt lgkmcnt(1)
; #define LAS __attribute__((address_space(3)))
; #define MFMA32(a, b, c) __builtin_amdgcn_mfma_f32_32x32x16_bf16((a), (b), (c), 0, 0, 0)
; #define CE_(a, b) ce_desc(v[a], v[b])
; __device__ __forceinline__ void sort16_desc(int (&v)[16]) {
;     ...
;     CE_(0,13); CE_(1,12); CE_(2,15); CE_(3,14); CE_(4,8); CE_(5,6); CE_(7,11); CE_(9,10);
;     CE_(0,5); CE_(1,7); CE_(2,9); CE_(3,4); CE_(6,13); CE_(8,14); CE_(10,15); CE_(11,12);
;     CE_(0,1); CE_(2,3); CE_(4,5); CE_(6,8); CE_(7,9); CE_(10,11); CE_(12,13); CE_(14,15);
;     CE_(0,2); CE_(1,3); CE_(4,10); CE_(5,11); CE_(6,7); CE_(8,9); CE_(12,14); CE_(13,15);
;     CE_(1,2); CE_(3,12); CE_(4,6); CE_(5,7); CE_(8,10); CE_(9,11); CE_(13,14);
;     CE_(1,4); CE_(2,6); CE_(5,8); CE_(7,10); CE_(9,13); CE_(11,14);
;     CE_(2,4); CE_(3,6); CE_(9,12); CE_(11,13);
;     CE_(3,5); CE_(6,8); CE_(7,9); CE_(10,12);
;     CE_(3,4); CE_(5,6); CE_(7,8); CE_(9,10); CE_(11,12);
;     CE_(6,7); CE_(8,9);
;     ...
; }
; __device__ __forceinline__ void merge16_desc(int (&a)[16], const int (&b)[16]) {
; #pragma unroll
;     for (int i = 0; i < 16; ++i) a[i] = a[i] > b[15 - i] ? a[i] : b[15 - i];
; #pragma unroll
;     for (int j = 8; j > 0; j >>= 1)
; #pragma unroll
;         for (int i = 0; i < 16; ++i) { const int l = i ^ j; if (l > i) ce_desc(a[i], a[l]); }
; }
; __device__ __forceinline__ void route_task(int task, int tl0, const bf16* QP  , const LAS bf16* KHL, LAS unsigned short* EL, LAS float* GL, int lane) {
;     ...
;         for (int kt = 0; kt < 4; ++kt) {
;             f32x16 X;
; #pragma unroll
;             for (int i = 0; i < 16; ++i) X[i] = 8.f;
;             const LAS bf16* khp = KHL + (half * 128 + 32 * kt + r) * 72 + 8 * hi;
; #pragma unroll
;             for (int ks = 0; ks < 4; ++ks) {
;                 const bf16x8 kh = lds8(khp + 16 * ks);
;                 X = MFMA32(kh, qa[half][ks], X);
;             }
;             int grp[16];
; #pragma unroll
;             for (int i = 0; i < 16; ++i) grp[i] = (int)((__float_as_uint(X[i]) | 127u) - (unsigned)(32 * kt + (i & 3) + 8 * (i >> 2)));
;             sort16_desc(grp);
;             if (kt == 0) {
; #pragma unroll
;                 for (int i = 0; i < 16; ++i) cur[i] = grp[i];
;             } else merge16_desc(cur, grp);
	v_mfma_f32_32x32x16_bf16 v[34:49], v[124:127], v[62:65], v[18:33]
	v_max_i32_e32 v147, v132, v82
	s_nop 5
	ds_read_b128 v[18:21], v98 offset:64
	ds_read_b128 v[22:25], v98 offset:96
	s_waitcnt lgkmcnt(2)
	v_mfma_f32_32x32x16_bf16 v[34:49], v[128:131], v[58:61], v[34:49]
	v_min_i32_e32 v26, v132, v82
	v_max_i32_e32 v27, v133, v134
	v_min_i32_e32 v30, v135, v139
	v_min_i32_e32 v32, v137, v141
	v_max_i32_e32 v33, v136, v140
	v_max_i32_e32 v59, v138, v142
	v_min_i32_e32 v28, v133, v134
	s_waitcnt lgkmcnt(1)
	v_mfma_f32_32x32x16_bf16 v[34:49], v[18:21], v[54:57], v[34:49]
	v_min_i32_e32 v19, v147, v27
	v_min_i32_e32 v54, v30, v32
	v_min_i32_e32 v55, v33, v59
	v_max_i32_e32 v29, v135, v139
	v_max_i32_e32 v31, v137, v141
	v_min_i32_e32 v58, v136, v140
	v_min_i32_e32 v60, v138, v142
	s_waitcnt lgkmcnt(0)
	v_mfma_f32_32x32x16_bf16 v[34:49], v[22:25], v[50:53], v[34:49]
	v_min_i32_e32 v18, v144, v146
	v_min_i32_e32 v61, v143, v145
	v_min_i32_e32 v20, v26, v28
	v_min_i32_e32 v21, v29, v31
	v_min_i32_e32 v56, v58, v60
	s_nop 6
	v_or_b32_e32 v22, 0x7f, v41
	v_or_b32_e32 v23, 0x7f, v45
	v_or_b32_e32 v25, 0x7f, v35
	v_or_b32_e32 v35, 0x7f, v46
	v_and_or_b32 v39, v39, s43, 22
	v_and_or_b32 v40, v40, s43, 21
	v_and_or_b32 v34, v34, s43, 31
	v_and_or_b32 v47, v47, s43, 6
	v_and_or_b32 v38, v38, s43, 23
	v_and_or_b32 v42, v42, s43, 15
	v_and_or_b32 v37, v37, s43, 28
	v_and_or_b32 v48, v48, s43, 5
	v_and_or_b32 v43, v43, s43, 14
	v_and_or_b32 v44, v44, s43, 13
	v_and_or_b32 v36, v36, s43, 29
	v_and_or_b32 v49, v49, s43, 4
	v_add_u32_e32 v22, 0xffffff95, v22
	v_add_u32_e32 v23, 0xffffff8d, v23
	v_add_u32_e32 v25, 0xffffff9f, v25
	v_add_u32_e32 v35, 0xffffff88, v35
	v_min_i32_e32 v24, v22, v23
	v_min_i32_e32 v41, v25, v35
	v_min_i32_e32 v46, v39, v40
	v_min_i32_e32 v50, v34, v47
	v_min_i32_e32 v53, v38, v42
	v_min_i32_e32 v57, v37, v48
	v_min_i32_e32 v63, v43, v44
	v_min_i32_e32 v64, v36, v49
	v_max_i32_e32 v34, v34, v47
	v_max_i32_e32 v39, v39, v40
	v_max_i32_e32 v25, v25, v35
	v_max_i32_e32 v22, v22, v23
	v_max_i32_e32 v36, v36, v49
	v_max_i32_e32 v43, v43, v44
	v_max_i32_e32 v37, v37, v48
	v_max_i32_e32 v38, v38, v42
	v_min_i32_e32 v45, v24, v41
	v_min_i32_e32 v51, v46, v50
	v_max_i32_e32 v40, v34, v39
	v_max_i32_e32 v23, v25, v22
	v_max_i32_e32 v44, v36, v43
	v_max_i32_e32 v42, v37, v38
	v_min_i32_e32 v37, v37, v38
	v_min_i32_e32 v34, v34, v39
	v_max_i32_e32 v39, v63, v64
	v_max_i32_e32 v24, v24, v41
	v_max_i32_e32 v46, v46, v50
	v_max_i32_e32 v50, v53, v57
	v_min_i32_e32 v22, v25, v22
	v_min_i32_e32 v25, v36, v43
	v_min_i32_e32 v62, v53, v57
	v_min_i32_e32 v65, v63, v64
	v_min_i32_e32 v35, v40, v23
	v_min_i32_e32 v47, v44, v42
	v_max_i32_e32 v23, v40, v23
	v_max_i32_e32 v40, v44, v42
	v_max_i32_e32 v38, v37, v34
	v_max_i32_e32 v41, v39, v24
	v_max_i32_e32 v53, v46, v50
	v_max_i32_e32 v36, v22, v25
	v_min_i32_e32 v46, v46, v50
	v_min_i32_e32 v22, v22, v25
	v_min_i32_e32 v52, v45, v51
	v_min_i32_e32 v82, v62, v65
	v_min_i32_e32 v48, v35, v47
	v_max_i32_e32 v45, v45, v51
	v_max_i32_e32 v49, v62, v65
	v_max_i32_e32 v35, v35, v47
	v_min_i32_e32 v42, v23, v40
	v_max_i32_e32 v47, v38, v41
	v_max_i32_e32 v43, v53, v36
	v_min_i32_e32 v34, v37, v34
	v_min_i32_e32 v24, v39, v24
	v_max_i32_e32 v25, v46, v22
	v_min_i32_e32 v38, v38, v41
	v_max_i32_e32 v51, v45, v49
	v_min_i32_e32 v44, v35, v42
	v_min_i32_e32 v57, v47, v43
	v_max_i32_e32 v37, v34, v24
	v_min_i32_e32 v36, v53, v36
	v_max_i32_e32 v41, v25, v38
	v_min_i32_e32 v25, v25, v38
	v_min_i32_e32 v22, v46, v22
	v_min_i32_e32 v24, v34, v24
	v_max_i32_e32 v38, v52, v82
	v_min_i32_e32 v45, v45, v49
	v_max_i32_e32 v62, v48, v51
	v_min_i32_e32 v63, v44, v57
	v_max_i32_e32 v39, v37, v36
	v_max_i32_e32 v34, v22, v24
	v_max_i32_e32 v46, v38, v45
	v_max_i32_e32 v64, v62, v63
	v_max_i32_e32 v50, v39, v41
	v_min_i32_e32 v62, v62, v63
	v_min_i32_e32 v39, v39, v41
	v_min_i32_e32 v36, v37, v36
	v_max_i32_e32 v49, v34, v46
	v_min_i32_e32 v48, v48, v51
	v_min_i32_e32 v22, v22, v24
	v_min_i32_e32 v24, v38, v45
	v_min_i32_e32 v53, v64, v50
	v_max_i32_e32 v41, v62, v39
	v_max_i32_e32 v37, v36, v25
	v_max_i32_e32 v51, v49, v48
	v_max_i32_e32 v38, v22, v24
	v_min_i32_e32 v34, v34, v46
	v_min_i32_e32 v25, v36, v25
	v_min_i32_e32 v36, v49, v48
	v_min_i32_e32 v124, v52, v82
	v_max_i32_e32 v52, v37, v51
	v_min_i32_e32 v39, v62, v39
	v_max_i32_e32 v45, v38, v34
	v_min_i32_e32 v46, v25, v36
	v_max_i32_e32 v35, v35, v42
	v_max_i32_e32 v42, v47, v43
	v_min_i32_e32 v34, v38, v34
	v_max_i32_e32 v38, v53, v41
	v_min_i32_e32 v37, v37, v51
	v_max_i32_e32 v25, v25, v36
	v_max_i32_e32 v48, v45, v46
	v_max_i32_e32 v44, v44, v57
	v_min_i32_e32 v43, v35, v42
	v_max3_i32 v30, v30, v32, v38
	v_min_i32_e32 v38, v52, v39
	v_max_i32_e32 v36, v37, v25
	v_min_i32_e32 v25, v37, v25
	v_min_i32_e32 v63, v53, v41
	v_max_i32_e32 v62, v52, v39
	v_max3_i32 v27, v147, v27, v48
	v_max_i32_e32 v48, v64, v50
	v_min_i32_e32 v47, v44, v43
	v_min_i32_e32 v39, v38, v36
	v_max_i32_e32 v19, v19, v25
	v_max3_i32 v25, v55, v44, v43
	v_min_i32_e32 v43, v45, v46
	v_min_i32_e32 v65, v63, v62
	v_max_i32_e32 v49, v48, v47
	v_max3_i32 v26, v26, v28, v39
	v_max_i32_e32 v28, v35, v42
	v_min_i32_e32 v22, v22, v24
	v_max_i32_e32 v18, v18, v43
	v_min_i32_e32 v43, v48, v47
	v_max3_i32 v124, v143, v145, v124
	v_max3_i32 v29, v29, v31, v65
	v_max3_i32 v33, v33, v59, v49
	v_max3_i32 v34, v144, v146, v34
	v_max3_i32 v28, v58, v60, v28
	v_max_i32_e32 v22, v61, v22
	v_max3_i32 v21, v21, v63, v62
	v_max_i32_e32 v43, v54, v43
	v_max3_i32 v20, v20, v38, v36
	v_max3_i32 v23, v56, v23, v40
	v_min_i32_e32 v31, v124, v29
	v_min_i32_e32 v49, v27, v33
	v_min_i32_e32 v32, v34, v30
	v_min_i32_e32 v35, v26, v28
; __device__ __forceinline__ void route_task(int task, int tl0, const bf16* QP  , const LAS bf16* KHL, LAS unsigned short* EL, LAS float* GL, int lane) {
;     ...
;             } else merge16_desc(cur, grp);
;         }
;         { const unsigned h4 = 4u * (unsigned)hi;
; #pragma unroll
;           for (int i = 0; i < 16; ++i) cur[i] -= (int)h4; }
;         int oth[16];
; #pragma unroll
;         for (int i = 0; i < 16; ++i) oth[i] = __shfl_xor(cur[i], 32);
;         merge16_desc(cur, oth);
; #pragma unroll
;         for (int i = 0; i < 16; ++i) top[half][i] = cur[i];
;     }
;     unsigned P1[4], P2[4];
; #pragma unroll
;     for (int q = 0; q < 4; ++q) { P1[q] = 0u; P2[q] = 0u;
; #pragma unroll
;         for (int s = 0; s < 4; ++s) { P1[q] |= (127u - ((unsigned)top[0][4 * q + s] & 127u)) << (8 * s); P2[q] |= (127u - ((unsigned)top[1][4 * q + s] & 127u)) << (8 * s); } }
	v_min_i32_e32 v24, v22, v21
	v_min_i32_e32 v37, v19, v25
	v_min_i32_e32 v44, v18, v43
	v_min_i32_e32 v36, v20, v23
	v_max_i32_e32 v29, v124, v29
	v_max_i32_e32 v27, v27, v33
	v_max_i32_e32 v30, v34, v30
	v_max_i32_e32 v26, v26, v28
	v_max_i32_e32 v21, v22, v21
	v_max_i32_e32 v19, v19, v25
	v_max_i32_e32 v18, v18, v43
	v_max_i32_e32 v20, v20, v23
	v_max_i32_e32 v33, v29, v27
	v_max_i32_e32 v28, v30, v26
	v_max_i32_e32 v22, v21, v19
	v_max_i32_e32 v23, v18, v20
	v_max_i32_e32 v34, v33, v28
	v_max_i32_e32 v25, v22, v23
	v_min_i32_e32 v28, v33, v28
	v_min_i32_e32 v22, v22, v23
	v_min_i32_e32 v27, v29, v27
	v_min_i32_e32 v26, v30, v26
	v_min_i32_e32 v19, v21, v19
	v_min_i32_e32 v18, v18, v20
	v_max_i32_e32 v23, v28, v22
	v_min_i32_e32 v22, v28, v22
	v_max_i32_e32 v28, v27, v26
	v_max_i32_e32 v20, v19, v18
	v_min_i32_e32 v26, v27, v26
	v_min_i32_e32 v18, v19, v18
	v_min_i32_e32 v42, v24, v37
	v_max_i32_e32 v19, v26, v18
	v_min_i32_e32 v18, v26, v18
	v_max_i32_e32 v26, v31, v49
	v_max_i32_e32 v27, v32, v35
	v_max_i32_e32 v24, v24, v37
	v_max_i32_e32 v29, v44, v36
	v_min_i32_e32 v50, v31, v49
	v_min_i32_e32 v39, v32, v35
	v_min_i32_e32 v38, v44, v36
	v_max_i32_e32 v21, v28, v20
	v_min_i32_e32 v20, v28, v20
	v_max_i32_e32 v28, v26, v27
	v_max_i32_e32 v30, v24, v29
	v_min_i32_e32 v26, v26, v27
	v_min_i32_e32 v24, v24, v29
	v_min_i32_e32 v41, v50, v39
	v_min_i32_e32 v40, v42, v38
	v_max_i32_e32 v27, v26, v24
	v_min_i32_e32 v24, v26, v24
	v_max_i32_e32 v26, v50, v39
	v_max_i32_e32 v29, v42, v38
	v_min_i32_e32 v45, v41, v40
	v_max_i32_e32 v43, v34, v25
	v_min_i32_e32 v25, v34, v25
	v_max_i32_e32 v31, v28, v30
	v_min_i32_e32 v28, v28, v30
	v_max_i32_e32 v30, v26, v29
	v_min_i32_e32 v26, v26, v29
	v_max_i32_e32 v29, v41, v40
	v_sub_u32_e32 v32, v43, v87
	v_sub_u32_e32 v25, v25, v87
	v_sub_u32_e32 v23, v23, v87
	v_sub_u32_e32 v22, v22, v87
	v_sub_u32_e32 v21, v21, v87
	v_sub_u32_e32 v20, v20, v87
	v_sub_u32_e32 v19, v19, v87
	v_sub_u32_e32 v18, v18, v87
	v_sub_u32_e32 v31, v31, v87
	v_sub_u32_e32 v28, v28, v87
	v_sub_u32_e32 v27, v27, v87
	v_sub_u32_e32 v24, v24, v87
	v_sub_u32_e32 v30, v30, v87
	v_sub_u32_e32 v26, v26, v87
	v_sub_u32_e32 v29, v29, v87
	v_sub_u32_e32 v33, v45, v87
	ds_bpermute_b32 v34, v123, v32
	ds_bpermute_b32 v35, v123, v25
	ds_bpermute_b32 v36, v123, v23
	ds_bpermute_b32 v37, v123, v22
	ds_bpermute_b32 v38, v123, v21
	ds_bpermute_b32 v39, v123, v20
	ds_bpermute_b32 v40, v123, v19
	ds_bpermute_b32 v41, v123, v18
	ds_bpermute_b32 v42, v123, v31
	ds_bpermute_b32 v43, v123, v28
	ds_bpermute_b32 v44, v123, v27
	ds_bpermute_b32 v45, v123, v33
	ds_bpermute_b32 v46, v123, v29
	ds_bpermute_b32 v47, v123, v26
	ds_bpermute_b32 v48, v123, v30
	ds_bpermute_b32 v49, v123, v24
	s_waitcnt lgkmcnt(4)
	v_max_i32_e32 v32, v32, v45
	s_waitcnt lgkmcnt(3)
	v_max_i32_e32 v25, v25, v46
	s_waitcnt lgkmcnt(2)
	v_max_i32_e32 v23, v23, v47
	s_waitcnt lgkmcnt(1)
	v_max_i32_e32 v22, v22, v48
	s_waitcnt lgkmcnt(0)
	v_max_i32_e32 v21, v21, v49
	v_max_i32_e32 v20, v20, v44
	v_max_i32_e32 v19, v19, v43
	v_max_i32_e32 v18, v18, v42
	v_max_i32_e32 v31, v31, v41
	v_max_i32_e32 v28, v28, v40
	v_max_i32_e32 v27, v27, v39
	v_max_i32_e32 v24, v24, v38
	v_max_i32_e32 v30, v30, v37
	v_max_i32_e32 v26, v26, v36
	v_max_i32_e32 v29, v29, v35
	v_max_i32_e32 v33, v33, v34
	v_max_i32_e32 v34, v32, v31
	v_min_i32_e32 v31, v32, v31
	v_max_i32_e32 v32, v25, v28
	v_min_i32_e32 v25, v25, v28
	v_max_i32_e32 v28, v23, v27
	v_min_i32_e32 v23, v23, v27
	v_max_i32_e32 v27, v22, v24
	v_min_i32_e32 v22, v22, v24
	v_max_i32_e32 v24, v21, v30
	v_min_i32_e32 v21, v21, v30
	v_max_i32_e32 v30, v20, v26
	v_min_i32_e32 v20, v20, v26
	v_max_i32_e32 v26, v19, v29
	v_min_i32_e32 v19, v19, v29
	v_max_i32_e32 v29, v18, v33
	v_min_i32_e32 v18, v18, v33
	v_max_i32_e32 v33, v34, v24
	v_min_i32_e32 v24, v34, v24
	v_max_i32_e32 v34, v32, v30
	v_min_i32_e32 v30, v32, v30
	v_max_i32_e32 v32, v28, v26
	v_min_i32_e32 v26, v28, v26
	v_max_i32_e32 v28, v27, v29
	v_min_i32_e32 v27, v27, v29
	v_max_i32_e32 v29, v31, v21
	v_min_i32_e32 v21, v31, v21
	v_max_i32_e32 v31, v25, v20
	v_min_i32_e32 v20, v25, v20
	v_max_i32_e32 v25, v23, v19
	v_min_i32_e32 v19, v23, v19
	v_max_i32_e32 v23, v22, v18
	v_min_i32_e32 v18, v22, v18
	v_max_i32_e32 v22, v33, v32
	v_min_i32_e32 v32, v33, v32
	v_max_i32_e32 v33, v34, v28
	v_min_i32_e32 v28, v34, v28
	v_max_i32_e32 v34, v24, v26
	v_min_i32_e32 v24, v24, v26
	v_max_i32_e32 v35, v30, v27
	v_min_i32_e32 v27, v30, v27
	v_max_i32_e32 v30, v29, v25
	v_min_i32_e32 v25, v29, v25
	v_max_i32_e32 v29, v31, v23
	v_min_i32_e32 v23, v31, v23
	v_max_i32_e32 v31, v21, v19
	v_min_i32_e32 v19, v21, v19
	v_max_i32_e32 v21, v20, v18
	v_min_i32_e32 v18, v20, v18
	v_max_i32_e32 v26, v22, v33
	v_min_i32_e32 v33, v22, v33
	v_lshlrev_b32_e32 v20, 8, v81
	v_lshlrev_b32_e32 v22, 16, v80
	v_max_i32_e32 v36, v32, v28
	v_max_i32_e32 v40, v19, v18
	v_min_i32_e32 v41, v19, v18
	v_and_b32_e32 v18, 0x7f, v79
	v_and_b32_e32 v20, 0x7f00, v20
	v_and_b32_e32 v22, 0x7f0000, v22
	v_max_i32_e32 v39, v31, v21
	v_min_i32_e32 v31, v31, v21
	v_lshlrev_b32_e32 v21, 8, v33
	v_or3_b32 v18, v20, v18, v22
	v_lshlrev_b32_e32 v20, 16, v36
	v_and_b32_e32 v19, 0x7f, v26
	v_and_b32_e32 v21, 0x7f00, v21
	v_and_b32_e32 v20, 0x7f0000, v20
	v_or3_b32 v20, v21, v19, v20
	v_lshlrev_b32_e32 v19, 24, v78
	v_min_i32_e32 v28, v32, v28
	v_and_b32_e32 v19, 0x7f000000, v19
	v_bitop3_b32 v19, v18, s68, v19 bitop3:0x36
	v_lshlrev_b32_e32 v18, 24, v28
	v_max_i32_e32 v32, v34, v35
	v_min_i32_e32 v34, v34, v35
	v_max_i32_e32 v35, v24, v27
	v_min_i32_e32 v27, v24, v27
	v_and_b32_e32 v18, 0x7f000000, v18
	v_lshlrev_b32_e32 v22, 8, v76
	v_lshlrev_b32_e32 v24, 16, v75
; __device__ __forceinline__ void route_task(int task, int tl0, const bf16* QP  , const LAS bf16* KHL, LAS unsigned short* EL, LAS float* GL, int lane) {
;     ...
;     unsigned P1[4], P2[4];
; #pragma unroll
;     for (int q = 0; q < 4; ++q) { P1[q] = 0u; P2[q] = 0u;
; #pragma unroll
;         for (int s = 0; s < 4; ++s) { P1[q] |= (127u - ((unsigned)top[0][4 * q + s] & 127u)) << (8 * s); P2[q] |= (127u - ((unsigned)top[1][4 * q + s] & 127u)) << (8 * s); } }
;     int bk[16];
;     {
;         int hi2 = hi; asm volatile("" : "+v"(hi2));
;         const bool h1 = hi2 != 0;
;         constexpr int A1[16] = {1, 1, 1, 1, 1, 1, 1, 1, 2, 2, 2, 2, 2, 3, 3, 3}, B1[16] = {0, 1, 2, 3, 4, 5, 6, 7, 0, 1, 2, 3, 4, 0, 1, 2};
; #pragma unroll
;         for (int i = 0; i < 16; ++i) { const float ta = __int_as_float(h1 ? top[0][A1[i]] : top[0][0]), tb = __int_as_float(h1 ? top[1][B1[i]] : top[1][i]); const unsigned code = h1 ? (unsigned)(A1[i] * 16 + B1[i]) : (unsigned)i;
;             bk[i] = (int)((__float_as_uint(ta + tb) | 255u) - code); }
;         sort16_desc(bk);
	v_bitop3_b32 v18, v20, s68, v18 bitop3:0x36
	v_and_b32_e32 v20, 0x7f, v77
	v_and_b32_e32 v22, 0x7f00, v22
	v_and_b32_e32 v24, 0x7f0000, v24
	v_max_i32_e32 v37, v30, v29
	v_min_i32_e32 v29, v30, v29
	v_max_i32_e32 v30, v25, v23
	v_min_i32_e32 v38, v25, v23
	v_lshlrev_b32_e32 v23, 8, v34
	v_or3_b32 v20, v22, v20, v24
	v_lshlrev_b32_e32 v22, 16, v35
	v_and_b32_e32 v21, 0x7f, v32
	v_and_b32_e32 v23, 0x7f00, v23
	v_and_b32_e32 v22, 0x7f0000, v22
	v_or3_b32 v22, v23, v21, v22
	v_lshlrev_b32_e32 v21, 24, v73
	v_and_b32_e32 v21, 0x7f000000, v21
	v_bitop3_b32 v21, v20, s68, v21 bitop3:0x36
	v_lshlrev_b32_e32 v20, 24, v27
	v_and_b32_e32 v20, 0x7f000000, v20
	v_lshlrev_b32_e32 v24, 8, v74
	v_lshlrev_b32_e32 v42, 16, v72
	v_bitop3_b32 v20, v22, s68, v20 bitop3:0x36
	v_and_b32_e32 v22, 0x7f, v71
	v_and_b32_e32 v24, 0x7f00, v24
	v_and_b32_e32 v42, 0x7f0000, v42
	v_lshlrev_b32_e32 v25, 8, v29
	v_or3_b32 v22, v24, v22, v42
	v_lshlrev_b32_e32 v24, 16, v30
	v_and_b32_e32 v23, 0x7f, v37
	v_and_b32_e32 v25, 0x7f00, v25
	v_and_b32_e32 v24, 0x7f0000, v24
	v_or3_b32 v24, v25, v23, v24
	v_lshlrev_b32_e32 v23, 24, v70
	v_and_b32_e32 v23, 0x7f000000, v23
	v_bitop3_b32 v23, v22, s68, v23 bitop3:0x36
	v_lshlrev_b32_e32 v22, 24, v38
	v_and_b32_e32 v22, 0x7f000000, v22
	v_lshlrev_b32_e32 v42, 8, v68
	v_lshlrev_b32_e32 v44, 16, v67
	v_bitop3_b32 v22, v24, s68, v22 bitop3:0x36
	v_and_b32_e32 v24, 0x7f, v69
	v_and_b32_e32 v42, 0x7f00, v42
	v_and_b32_e32 v44, 0x7f0000, v44
	v_lshlrev_b32_e32 v43, 8, v31
	v_or3_b32 v24, v42, v24, v44
	v_lshlrev_b32_e32 v42, 16, v40
	v_and_b32_e32 v25, 0x7f, v39
	v_and_b32_e32 v43, 0x7f00, v43
	v_and_b32_e32 v42, 0x7f0000, v42
	v_or3_b32 v42, v43, v25, v42
	v_lshlrev_b32_e32 v25, 24, v66
	v_and_b32_e32 v25, 0x7f000000, v25
	v_bitop3_b32 v25, v24, s68, v25 bitop3:0x36
	v_lshlrev_b32_e32 v24, 24, v41
	v_and_b32_e32 v24, 0x7f000000, v24
	v_bitop3_b32 v24, v42, s68, v24 bitop3:0x36
	v_mov_b32_e32 v42, v86
	v_add_f32_e32 v62, v74, v26
	v_cmp_eq_u32_e32 vcc, 0, v42
	v_add_f32_e32 v63, v72, v26
	v_add_f32_e32 v64, v70, v26
	v_cndmask_b32_e32 v42, v81, v79, vcc
	v_add_f32_e32 v44, v42, v26
	v_cndmask_b32_e64 v43, -16, 0, vcc
	v_or_b32_e32 v44, 0xff, v44
	v_add_f32_e32 v45, v42, v33
	v_add_u32_e32 v43, v44, v43
	v_cndmask_b32_e64 v44, v99, -1, vcc
	v_or_b32_e32 v45, 0xff, v45
	v_add_f32_e32 v46, v42, v36
	v_add_u32_e32 v44, v45, v44
	v_cndmask_b32_e64 v45, v100, -2, vcc
	v_or_b32_e32 v46, 0xff, v46
	v_add_f32_e32 v47, v42, v28
	v_add_u32_e32 v45, v46, v45
	v_cndmask_b32_e64 v46, v101, -3, vcc
	v_or_b32_e32 v47, 0xff, v47
	v_add_f32_e32 v48, v42, v32
	v_add_u32_e32 v46, v47, v46
	v_cndmask_b32_e64 v47, v102, -4, vcc
	v_or_b32_e32 v48, 0xff, v48
	v_add_f32_e32 v34, v42, v34
	v_add_f32_e32 v35, v42, v35
	v_add_f32_e32 v27, v42, v27
	v_cndmask_b32_e32 v42, v80, v79, vcc
	v_cndmask_b32_e32 v32, v32, v39, vcc
	v_add_u32_e32 v47, v48, v47
	v_cndmask_b32_e64 v48, v103, -5, vcc
	v_or_b32_e32 v34, 0xff, v34
	v_add_f32_e32 v32, v42, v32
	v_add_u32_e32 v34, v34, v48
	v_cndmask_b32_e64 v48, v104, -6, vcc
	v_or_b32_e32 v35, 0xff, v35
	v_cndmask_b32_e32 v37, v26, v37, vcc
	v_cndmask_b32_e64 v39, v116, -12, vcc
	v_or_b32_e32 v32, 0xff, v32
	v_add_u32_e32 v35, v35, v48
	v_cndmask_b32_e64 v48, v105, -7, vcc
	v_or_b32_e32 v27, 0xff, v27
	v_add_f32_e32 v37, v42, v37
	v_cndmask_b32_e32 v29, v33, v29, vcc
	v_add_u32_e32 v32, v32, v39
	v_cndmask_b32_e32 v39, v78, v79, vcc
	v_cndmask_b32_e32 v31, v26, v31, vcc
	v_add_u32_e32 v27, v27, v48
	v_cndmask_b32_e64 v48, v106, -8, vcc
	v_or_b32_e32 v37, 0xff, v37
	v_add_f32_e32 v29, v42, v29
	v_cndmask_b32_e32 v30, v36, v30, vcc
	v_cndmask_b32_e32 v38, v28, v38, vcc
	v_add_f32_e32 v31, v39, v31
	v_cndmask_b32_e32 v40, v33, v40, vcc
	v_add_u32_e32 v37, v37, v48
	v_cndmask_b32_e64 v48, v107, -9, vcc
	v_or_b32_e32 v29, 0xff, v29
	v_add_f32_e32 v30, v42, v30
	v_add_f32_e32 v38, v42, v38
	v_cndmask_b32_e64 v42, v117, -13, vcc
	v_or_b32_e32 v31, 0xff, v31
	v_add_f32_e32 v40, v39, v40
	v_cndmask_b32_e32 v41, v36, v41, vcc
	v_add_u32_e32 v29, v29, v48
	v_cndmask_b32_e64 v48, v114, -10, vcc
	v_or_b32_e32 v30, 0xff, v30
	v_add_u32_e32 v31, v31, v42
	v_cndmask_b32_e64 v42, v118, -14, vcc
	v_or_b32_e32 v40, 0xff, v40
	v_add_f32_e32 v39, v39, v41
	v_add_u32_e32 v30, v30, v48
	v_cndmask_b32_e64 v48, v115, -11, vcc
	v_or_b32_e32 v38, 0xff, v38
	v_add_u32_e32 v40, v40, v42
	v_cndmask_b32_e64 v42, v119, -15, vcc
	v_or_b32_e32 v39, 0xff, v39
	v_add_u32_e32 v38, v38, v48
	v_add_u32_e32 v39, v39, v42
	v_max_i32_e32 v41, v43, v31
	v_min_i32_e32 v31, v43, v31
	v_max_i32_e32 v42, v44, v32
	v_min_i32_e32 v32, v44, v32
	v_max_i32_e32 v43, v45, v39
	v_min_i32_e32 v39, v45, v39
	v_max_i32_e32 v44, v46, v40
	v_min_i32_e32 v40, v46, v40
	v_max_i32_e32 v45, v47, v37
	v_min_i32_e32 v37, v47, v37
	v_max_i32_e32 v46, v34, v35
	v_min_i32_e32 v34, v34, v35
	v_max_i32_e32 v35, v27, v38
	v_min_i32_e32 v27, v27, v38
	v_max_i32_e32 v38, v29, v30
	v_min_i32_e32 v29, v29, v30
	v_max_i32_e32 v30, v41, v46
	v_min_i32_e32 v41, v41, v46
	v_max_i32_e32 v46, v42, v35
	v_min_i32_e32 v35, v42, v35
	v_max_i32_e32 v42, v43, v38
	v_min_i32_e32 v38, v43, v38
	v_max_i32_e32 v43, v44, v45
	v_min_i32_e32 v44, v44, v45
	v_max_i32_e32 v45, v34, v31
	v_min_i32_e32 v31, v34, v31
	v_max_i32_e32 v34, v37, v40
	v_min_i32_e32 v37, v37, v40
	v_max_i32_e32 v40, v29, v39
	v_min_i32_e32 v29, v29, v39
	v_max_i32_e32 v39, v27, v32
	v_min_i32_e32 v27, v27, v32
	v_max_i32_e32 v32, v30, v46
	v_min_i32_e32 v30, v30, v46
	v_max_i32_e32 v46, v42, v43
	v_min_i32_e32 v42, v42, v43
	v_max_i32_e32 v43, v44, v41
	v_min_i32_e32 v41, v44, v41
	v_max_i32_e32 v44, v45, v34
	v_min_i32_e32 v34, v45, v34
; #define CAND(a, b) (int)((__float_as_uint(__int_as_float(top[0][a]) + __int_as_float(top[1][b])) | 255u) - (unsigned)((a) * 16 + (b)))
; __device__ __forceinline__ void route_task(int task, int tl0, const bf16* QP  , const LAS bf16* KHL, LAS unsigned short* EL, LAS float* GL, int lane) {
;     ...
;         sort16_desc(bk);
;         int oth[16];
; #pragma unroll
;         for (int i = 0; i < 16; ++i) oth[i] = __shfl_xor(bk[i], 32);
;         merge16_desc(bk, oth);
;     }
;     ...
;     {
;         int gk[16];
;         gk[0] = CAND(3, 3); gk[1] = CAND(4, 0); gk[2] = CAND(4, 1); gk[3] = CAND(4, 2); gk[4] = CAND(5, 0); gk[5] = CAND(5, 1); gk[6] = CAND(6, 0); gk[7] = CAND(6, 1);
;         gk[8] = CAND(7, 0); gk[9] = CAND(7, 1); gk[10] = CAND(8, 0); gk[11] = CAND(9, 0); gk[12] = CAND(10, 0); gk[13] = CAND(11, 0); gk[14] = CAND(12, 0); gk[15] = CAND(13, 0);
;         sort16_desc(gk);
	v_max_i32_e32 v45, v35, v38
	v_min_i32_e32 v35, v35, v38
	v_max_i32_e32 v38, v40, v39
	v_min_i32_e32 v39, v40, v39
	v_max_i32_e32 v40, v27, v31
	v_min_i32_e32 v27, v27, v31
	v_max_i32_e32 v31, v37, v29
	v_min_i32_e32 v29, v37, v29
	v_max_i32_e32 v37, v32, v46
	v_min_i32_e32 v32, v32, v46
	v_max_i32_e32 v46, v30, v42
	v_min_i32_e32 v30, v30, v42
	v_max_i32_e32 v42, v43, v38
	v_min_i32_e32 v38, v43, v38
	v_max_i32_e32 v43, v41, v39
	v_min_i32_e32 v39, v41, v39
	v_max_i32_e32 v41, v44, v45
	v_min_i32_e32 v44, v44, v45
	v_max_i32_e32 v45, v34, v35
	v_min_i32_e32 v34, v34, v35
	v_max_i32_e32 v35, v40, v31
	v_min_i32_e32 v31, v40, v31
	v_max_i32_e32 v40, v27, v29
	v_min_i32_e32 v27, v27, v29
	v_max_i32_e32 v29, v46, v32
	v_min_i32_e32 v32, v46, v32
	v_max_i32_e32 v46, v30, v35
	v_min_i32_e32 v30, v30, v35
	v_max_i32_e32 v35, v42, v41
	v_min_i32_e32 v41, v42, v41
	v_max_i32_e32 v42, v43, v44
	v_min_i32_e32 v43, v43, v44
	v_max_i32_e32 v44, v45, v38
	v_min_i32_e32 v38, v45, v38
	v_max_i32_e32 v45, v34, v39
	v_min_i32_e32 v34, v34, v39
	v_max_i32_e32 v39, v40, v31
	v_min_i32_e32 v31, v40, v31
	v_max_i32_e32 v40, v29, v35
	v_min_i32_e32 v29, v29, v35
	v_max_i32_e32 v35, v32, v41
	v_min_i32_e32 v32, v32, v41
	v_max_i32_e32 v41, v42, v44
	v_min_i32_e32 v42, v42, v44
	v_max_i32_e32 v44, v43, v38
	v_min_i32_e32 v38, v43, v38
	v_max_i32_e32 v43, v45, v39
	v_min_i32_e32 v39, v45, v39
	v_max_i32_e32 v45, v34, v31
	v_min_i32_e32 v31, v34, v31
	v_max_i32_e32 v34, v35, v29
	v_min_i32_e32 v29, v35, v29
	v_max_i32_e32 v35, v46, v32
	v_min_i32_e32 v32, v46, v32
	v_max_i32_e32 v46, v43, v30
	v_min_i32_e32 v30, v43, v30
	v_max_i32_e32 v43, v45, v39
	v_min_i32_e32 v39, v45, v39
	v_max_i32_e32 v45, v35, v41
	v_min_i32_e32 v35, v35, v41
	v_max_i32_e32 v41, v32, v42
	v_min_i32_e32 v32, v32, v42
	v_max_i32_e32 v42, v44, v46
	v_min_i32_e32 v44, v44, v46
	v_max_i32_e32 v46, v38, v30
	v_min_i32_e32 v30, v38, v30
	v_max_i32_e32 v38, v45, v29
	v_min_i32_e32 v29, v45, v29
	v_max_i32_e32 v45, v35, v41
	v_min_i32_e32 v35, v35, v41
	v_max_i32_e32 v41, v42, v32
	v_min_i32_e32 v32, v42, v32
	v_max_i32_e32 v42, v44, v46
	v_min_i32_e32 v44, v44, v46
	v_max_i32_e32 v46, v43, v30
	v_min_i32_e32 v30, v43, v30
	v_max_i32_e32 v43, v35, v41
	v_min_i32_e32 v35, v35, v41
	v_max_i32_e32 v41, v32, v42
	v_min_i32_e32 v32, v32, v42
	ds_bpermute_b32 v54, v123, v41
	ds_bpermute_b32 v55, v123, v32
	ds_bpermute_b32 v56, v123, v44
	ds_bpermute_b32 v57, v123, v27
	ds_bpermute_b32 v58, v123, v31
	ds_bpermute_b32 v59, v123, v39
	ds_bpermute_b32 v60, v123, v30
	ds_bpermute_b32 v61, v123, v46
	ds_bpermute_b32 v42, v123, v37
	ds_bpermute_b32 v47, v123, v40
	ds_bpermute_b32 v48, v123, v34
	ds_bpermute_b32 v49, v123, v38
	ds_bpermute_b32 v50, v123, v29
	ds_bpermute_b32 v51, v123, v45
	ds_bpermute_b32 v52, v123, v43
	ds_bpermute_b32 v53, v123, v35
	s_waitcnt lgkmcnt(12)
	v_max_i32_e32 v37, v37, v57
	s_waitcnt lgkmcnt(11)
	v_max_i32_e32 v40, v40, v58
	s_waitcnt lgkmcnt(10)
	v_max_i32_e32 v34, v34, v59
	s_waitcnt lgkmcnt(9)
	v_max_i32_e32 v38, v38, v60
	s_waitcnt lgkmcnt(8)
	v_max_i32_e32 v29, v29, v61
	v_max_i32_e32 v45, v45, v56
	v_max_i32_e32 v43, v43, v55
	v_max_i32_e32 v35, v35, v54
	v_add_f32_e32 v28, v78, v28
	v_add_f32_e32 v54, v77, v26
	v_add_f32_e32 v55, v77, v33
	v_add_f32_e32 v36, v77, v36
	v_add_f32_e32 v56, v76, v26
	v_add_f32_e32 v57, v76, v33
	v_add_f32_e32 v58, v75, v26
	v_add_f32_e32 v59, v75, v33
	v_add_f32_e32 v60, v73, v26
	v_add_f32_e32 v33, v73, v33
	v_add_f32_e32 v61, v71, v26
	v_add_f32_e32 v65, v69, v26
	v_add_f32_e32 v68, v68, v26
	v_or_b32_e32 v28, 0xff, v28
	v_or_b32_e32 v54, 0xff, v54
	v_or_b32_e32 v55, 0xff, v55
	v_or_b32_e32 v36, 0xff, v36
	v_or_b32_e32 v56, 0xff, v56
	v_or_b32_e32 v57, 0xff, v57
	v_or_b32_e32 v58, 0xff, v58
	v_or_b32_e32 v59, 0xff, v59
	v_or_b32_e32 v60, 0xff, v60
	v_or_b32_e32 v33, 0xff, v33
	v_or_b32_e32 v61, 0xff, v61
	v_or_b32_e32 v62, 0xff, v62
	v_or_b32_e32 v63, 0xff, v63
	v_or_b32_e32 v64, 0xff, v64
	v_or_b32_e32 v65, 0xff, v65
	v_or_b32_e32 v68, 0xff, v68
	v_subrev_u32_e32 v28, 51, v28
	v_subrev_u32_e32 v54, 64, v54
	v_add_u32_e32 v55, 0xffffffbf, v55
	v_add_u32_e32 v36, 0xffffffbe, v36
	v_add_u32_e32 v56, 0xffffffb0, v56
	v_add_u32_e32 v57, 0xffffffaf, v57
	v_add_u32_e32 v58, 0xffffffa0, v58
	v_add_u32_e32 v59, 0xffffff9f, v59
	v_add_u32_e32 v60, 0xffffff90, v60
	v_add_u32_e32 v33, 0xffffff8f, v33
	v_add_u32_e32 v61, 0xffffff80, v61
	v_add_u32_e32 v62, 0xffffff70, v62
	v_add_u32_e32 v63, 0xffffff60, v63
	v_add_u32_e32 v64, 0xffffff50, v64
	v_add_u32_e32 v65, 0xffffff40, v65
	v_add_u32_e32 v68, 0xffffff30, v68
	v_max_i32_e32 v69, v28, v64
	v_min_i32_e32 v28, v28, v64
	v_max_i32_e32 v64, v54, v63
	v_min_i32_e32 v54, v54, v63
	v_max_i32_e32 v63, v55, v68
	v_min_i32_e32 v55, v55, v68
	v_max_i32_e32 v68, v36, v65
	v_min_i32_e32 v36, v36, v65
	v_max_i32_e32 v65, v56, v60
	v_min_i32_e32 v56, v56, v60
	v_max_i32_e32 v60, v57, v58
	v_min_i32_e32 v57, v57, v58
	v_max_i32_e32 v58, v59, v62
	v_min_i32_e32 v59, v59, v62
	v_max_i32_e32 v62, v33, v61
	v_min_i32_e32 v33, v33, v61
	v_max_i32_e32 v61, v69, v60
	v_min_i32_e32 v60, v69, v60
	v_max_i32_e32 v69, v64, v58
	v_min_i32_e32 v58, v64, v58
	v_max_i32_e32 v64, v63, v62
	v_min_i32_e32 v62, v63, v62
	v_max_i32_e32 v63, v68, v65
	v_min_i32_e32 v65, v68, v65
	v_max_i32_e32 v68, v57, v28
	v_min_i32_e32 v28, v57, v28
	v_max_i32_e32 v57, v56, v36
	v_min_i32_e32 v36, v56, v36
	v_max_i32_e32 v56, v33, v55
	v_min_i32_e32 v33, v33, v55
	v_max_i32_e32 v55, v59, v54
	v_min_i32_e32 v54, v59, v54
	v_max_i32_e32 v59, v61, v69
	v_min_i32_e32 v61, v61, v69
	v_max_i32_e32 v69, v64, v63
	v_min_i32_e32 v63, v64, v63
	v_max_i32_e32 v64, v65, v60
	v_min_i32_e32 v60, v65, v60
	v_max_i32_e32 v65, v68, v57
	v_min_i32_e32 v57, v68, v57
	v_max_i32_e32 v68, v58, v62
	v_min_i32_e32 v58, v58, v62
	v_max_i32_e32 v62, v56, v55
	v_min_i32_e32 v55, v56, v55
	v_max_i32_e32 v56, v54, v28
	v_min_i32_e32 v28, v54, v28
	v_max_i32_e32 v54, v36, v33
	v_min_i32_e32 v33, v36, v33
	v_min_i32_e32 v36, v59, v69
	v_max_i32_e32 v70, v61, v63
	v_min_i32_e32 v61, v61, v63
	v_max_i32_e32 v63, v64, v62
	v_min_i32_e32 v62, v64, v62
	v_max_i32_e32 v64, v60, v55
	v_min_i32_e32 v55, v60, v55
	v_max_i32_e32 v60, v65, v68
	v_min_i32_e32 v65, v65, v68
	v_max_i32_e32 v68, v57, v58
	v_min_i32_e32 v57, v57, v58
	v_max_i32_e32 v58, v56, v54
	v_min_i32_e32 v54, v56, v54
	v_max_i32_e32 v56, v28, v33
	v_min_i32_e32 v28, v28, v33
	v_max_i32_e32 v33, v70, v36
	v_min_i32_e32 v36, v70, v36
	v_max_i32_e32 v70, v61, v58
	v_min_i32_e32 v58, v61, v58
	v_max_i32_e32 v61, v63, v60
	v_min_i32_e32 v60, v63, v60
	v_max_i32_e32 v63, v64, v65
	v_min_i32_e32 v64, v64, v65
	v_max_i32_e32 v65, v68, v62
	v_min_i32_e32 v62, v68, v62
	v_max_i32_e32 v68, v57, v55
	v_min_i32_e32 v55, v57, v55
	v_max_i32_e32 v57, v56, v54
	s_waitcnt lgkmcnt(0)
; #define CAND(a, b) (int)((__float_as_uint(__int_as_float(top[0][a]) + __int_as_float(top[1][b])) | 255u) - (unsigned)((a) * 16 + (b)))
; __device__ __forceinline__ void route_task(int task, int tl0, const bf16* QP  , const LAS bf16* KHL, LAS unsigned short* EL, LAS float* GL, int lane) {
;     ...
;         int oth[16];
; #pragma unroll
;         for (int i = 0; i < 16; ++i) oth[i] = __shfl_xor(bk[i], 32);
;         merge16_desc(bk, oth);
;     }
;     ...
;     {
;         int gk[16];
;         gk[0] = CAND(3, 3); gk[1] = CAND(4, 0); gk[2] = CAND(4, 1); gk[3] = CAND(4, 2); gk[4] = CAND(5, 0); gk[5] = CAND(5, 1); gk[6] = CAND(6, 0); gk[7] = CAND(6, 1);
;         gk[8] = CAND(7, 0); gk[9] = CAND(7, 1); gk[10] = CAND(8, 0); gk[11] = CAND(9, 0); gk[12] = CAND(10, 0); gk[13] = CAND(11, 0); gk[14] = CAND(12, 0); gk[15] = CAND(13, 0);
;         sort16_desc(gk);
;         merge16_desc(bk, gk);
;     }
;     {
;         const int c14 = CAND(14, 0), c15 = CAND(15, 0);
;         const int n14 = max(bk[14], c14), n15 = max(min(bk[14], c14), max(bk[15], c15));
;         bk[14] = n14; bk[15] = n15;
;     }
	v_max_i32_e32 v41, v41, v53
	v_max_i32_e32 v32, v32, v52
	v_max_i32_e32 v44, v44, v51
	v_max_i32_e32 v46, v46, v50
	v_max_i32_e32 v30, v30, v49
	v_max_i32_e32 v39, v39, v48
	v_max_i32_e32 v31, v31, v47
	v_max_i32_e32 v27, v27, v42
	v_min_i32_e32 v54, v56, v54
	v_max_i32_e32 v56, v33, v61
	v_min_i32_e32 v33, v33, v61
	v_max_i32_e32 v61, v36, v60
	v_min_i32_e32 v36, v36, v60
	v_max_i32_e32 v60, v63, v65
	v_min_i32_e32 v63, v63, v65
	v_max_i32_e32 v65, v64, v62
	v_min_i32_e32 v62, v64, v62
	v_max_i32_e32 v64, v68, v57
	v_max_i32_e32 v42, v37, v41
	v_min_i32_e32 v37, v37, v41
	v_max_i32_e32 v41, v40, v32
	v_min_i32_e32 v32, v40, v32
	v_max_i32_e32 v40, v34, v44
	v_min_i32_e32 v34, v34, v44
	v_max_i32_e32 v44, v38, v46
	v_min_i32_e32 v38, v38, v46
	v_max_i32_e32 v46, v29, v30
	v_min_i32_e32 v29, v29, v30
	v_max_i32_e32 v30, v45, v39
	v_min_i32_e32 v39, v45, v39
	v_max_i32_e32 v45, v43, v31
	v_min_i32_e32 v31, v43, v31
	v_max_i32_e32 v43, v35, v27
	v_min_i32_e32 v27, v35, v27
	v_min_i32_e32 v57, v68, v57
	v_max_i32_e32 v68, v55, v54
	v_max_i32_e32 v71, v70, v36
	v_min_i32_e32 v36, v70, v36
	v_max_i32_e32 v70, v64, v58
	v_min_i32_e32 v58, v64, v58
	v_max_i32_e32 v35, v42, v46
	v_min_i32_e32 v42, v42, v46
	v_max_i32_e32 v46, v41, v30
	v_min_i32_e32 v30, v41, v30
	v_max_i32_e32 v41, v40, v45
	v_min_i32_e32 v40, v40, v45
	v_max_i32_e32 v45, v44, v43
	v_min_i32_e32 v43, v44, v43
	v_max_i32_e32 v44, v37, v29
	v_min_i32_e32 v29, v37, v29
	v_max_i32_e32 v37, v32, v39
	v_min_i32_e32 v32, v32, v39
	v_max_i32_e32 v39, v34, v31
	v_min_i32_e32 v31, v34, v31
	v_max_i32_e32 v34, v38, v27
	v_min_i32_e32 v27, v38, v27
	v_min_i32_e32 v54, v55, v54
	v_min_i32_e32 v55, v61, v33
	v_max_i32_e32 v64, v68, v57
	v_min_i32_e32 v57, v68, v57
	v_max_i32_e32 v68, v71, v60
	v_min_i32_e32 v60, v71, v60
	v_max_i32_e32 v71, v36, v63
	v_min_i32_e32 v36, v36, v63
	v_max_i32_e32 v63, v65, v70
	v_min_i32_e32 v65, v65, v70
	v_max_i32_e32 v70, v62, v58
	v_max_i32_e32 v38, v35, v41
	v_min_i32_e32 v35, v35, v41
	v_max_i32_e32 v41, v46, v45
	v_min_i32_e32 v45, v46, v45
	v_max_i32_e32 v46, v42, v40
	v_min_i32_e32 v40, v42, v40
	v_max_i32_e32 v42, v30, v43
	v_min_i32_e32 v30, v30, v43
	v_max_i32_e32 v43, v44, v39
	v_min_i32_e32 v39, v44, v39
	v_max_i32_e32 v44, v37, v34
	v_min_i32_e32 v34, v37, v34
	v_max_i32_e32 v37, v29, v31
	v_min_i32_e32 v29, v29, v31
	v_max_i32_e32 v31, v32, v27
	v_min_i32_e32 v27, v32, v27
	v_min_i32_e32 v58, v62, v58
	v_max_i32_e32 v62, v68, v55
	v_min_i32_e32 v55, v68, v55
	v_max_i32_e32 v68, v60, v71
	v_min_i32_e32 v60, v60, v71
	v_max_i32_e32 v71, v63, v36
	v_min_i32_e32 v36, v63, v36
	v_max_i32_e32 v63, v65, v70
	v_min_i32_e32 v32, v38, v41
	v_min_i32_e32 v47, v35, v45
	v_min_i32_e32 v48, v46, v42
	v_min_i32_e32 v49, v40, v30
	v_min_i32_e32 v50, v43, v44
	v_min_i32_e32 v51, v39, v34
	v_min_i32_e32 v52, v37, v31
	v_min_i32_e32 v53, v29, v27
	v_min_i32_e32 v65, v65, v70
	v_max_i32_e32 v70, v64, v58
	v_min_i32_e32 v58, v64, v58
	v_min_i32_e32 v64, v60, v71
	v_min_i32_e32 v72, v36, v63
	v_max3_i32 v28, v38, v41, v28
	v_max_i32_e32 v32, v32, v54
	v_max3_i32 v35, v35, v45, v57
	v_max_i32_e32 v38, v47, v58
	v_max3_i32 v41, v46, v42, v70
	v_max_i32_e32 v42, v48, v65
	v_max3_i32 v30, v40, v30, v72
	v_max3_i32 v36, v49, v36, v63
	v_max3_i32 v40, v43, v44, v64
	v_max3_i32 v43, v50, v60, v71
	v_max3_i32 v34, v39, v34, v68
	v_max_i32_e32 v39, v51, v55
	v_max3_i32 v31, v37, v31, v62
	v_max3_i32 v33, v52, v61, v33
	v_max3_i32 v27, v29, v27, v56
	v_max3_i32 v29, v53, v59, v69
	v_max_i32_e32 v37, v28, v40
	v_min_i32_e32 v28, v28, v40
	v_max_i32_e32 v40, v32, v43
	v_min_i32_e32 v32, v32, v43
	v_max_i32_e32 v43, v35, v34
	v_min_i32_e32 v34, v35, v34
	v_max_i32_e32 v35, v38, v39
	v_min_i32_e32 v38, v38, v39
	v_max_i32_e32 v39, v41, v31
	v_min_i32_e32 v31, v41, v31
	v_max_i32_e32 v41, v42, v33
	v_min_i32_e32 v33, v42, v33
	v_max_i32_e32 v42, v30, v27
	v_min_i32_e32 v27, v30, v27
	v_max_i32_e32 v30, v36, v29
	v_min_i32_e32 v29, v36, v29
	v_max_i32_e32 v36, v37, v39
	v_min_i32_e32 v37, v37, v39
	v_max_i32_e32 v39, v40, v41
	v_min_i32_e32 v40, v40, v41
	v_max_i32_e32 v41, v43, v42
	v_min_i32_e32 v42, v43, v42
	v_max_i32_e32 v43, v35, v30
	v_min_i32_e32 v30, v35, v30
	v_max_i32_e32 v35, v28, v31
	v_min_i32_e32 v28, v28, v31
	v_max_i32_e32 v31, v32, v33
	v_min_i32_e32 v32, v32, v33
	v_max_i32_e32 v33, v34, v27
	v_min_i32_e32 v27, v34, v27
	v_max_i32_e32 v34, v38, v29
	v_min_i32_e32 v29, v38, v29
	v_max_i32_e32 v38, v36, v41
	v_min_i32_e32 v36, v36, v41
	v_max_i32_e32 v41, v39, v43
	v_min_i32_e32 v39, v39, v43
	v_max_i32_e32 v43, v37, v42
	v_min_i32_e32 v37, v37, v42
	v_max_i32_e32 v42, v40, v30
	v_min_i32_e32 v30, v40, v30
	v_max_i32_e32 v40, v35, v33
	v_min_i32_e32 v33, v35, v33
	v_max_i32_e32 v35, v31, v34
	v_min_i32_e32 v31, v31, v34
	v_max_i32_e32 v34, v28, v27
	v_min_i32_e32 v27, v28, v27
	v_max_i32_e32 v28, v32, v29
	v_min_i32_e32 v29, v32, v29
	v_max_i32_e32 v32, v38, v41
	v_min_i32_e32 v38, v38, v41
	v_max_i32_e32 v41, v36, v39
	v_min_i32_e32 v36, v36, v39
	v_max_i32_e32 v39, v43, v42
	v_min_i32_e32 v42, v43, v42
	v_max_i32_e32 v43, v37, v30
	v_min_i32_e32 v30, v37, v30
	v_max_i32_e32 v37, v40, v35
	v_min_i32_e32 v35, v40, v35
	v_max_i32_e32 v40, v33, v31
	v_min_i32_e32 v31, v33, v31
	v_max_i32_e32 v33, v34, v28
	v_min_i32_e32 v28, v34, v28
	v_max_i32_e32 v34, v27, v29
	v_min_i32_e32 v27, v27, v29
	v_add_f32_e32 v29, v67, v26
	v_or_b32_e32 v29, 0xff, v29
	v_add_f32_e32 v26, v66, v26
	v_add_u32_e32 v29, 0xffffff20, v29
	v_or_b32_e32 v26, 0xff, v26
	v_add_u32_e32 v26, 0xffffff10, v26
	v_max_i32_e32 v44, v34, v29
	v_min_i32_e32 v29, v34, v29
	v_max3_i32 v26, v29, v27, v26
; __device__ __forceinline__ void route_task(int task, int tl0, const bf16* QP  , const LAS bf16* KHL, LAS unsigned short* EL, LAS float* GL, int lane) {
;     ...
;     int my[8];
; #pragma unroll
;     for (int i = 0; i < 8; ++i) { int lo_ = bk[i], hi_ = bk[8 + i]; asm volatile("" : "+v"(lo_), "+v"(hi_)); my[i] = hi ? hi_ : lo_; }
;     int bv[8];
; #pragma unroll
;     for (int i = 0; i < 8; ++i) {
;         const unsigned cd = 255u - ((unsigned)my[i] & 255u), ca = cd >> 4, cb = cd & 15u;
;         const unsigned wa = (ca >> 2) == 0u ? P1[0] : (ca >> 2) == 1u ? P1[1] : (ca >> 2) == 2u ? P1[2] : P1[3];
;         const unsigned wb = (cb >> 2) == 0u ? P2[0] : (cb >> 2) == 1u ? P2[1] : (cb >> 2) == 2u ? P2[2] : P2[3];
;         bv[i] = (int)((((wa >> (8u * (ca & 3u))) & 255u) << 7) | ((wb >> (8u * (cb & 3u))) & 255u));
;     }
;     float e[8], se = 0.f;
; #pragma unroll
;     for (int i = 0; i < 8; ++i) { e[i] = __expf(__int_as_float(my[i]) - __int_as_float(bk[0])); se += e[i]; }
;     se += __shfl_xor(se, 32);
;     const float inv = 1.f / se;
	v_mov_b32_e32 v27, v32
	s_nop 0
	v_cndmask_b32_e64 v27, v37, v27, s[6:7]
	v_not_b32_e32 v29, v27
	v_bfe_u32 v45, v29, 6, 2
	v_cmp_eq_u32_e32 vcc, 2, v45
	v_cndmask_b32_e64 v30, v26, v30, s[6:7]
	v_bitop3_b32 v26, v27, s3, v27 bitop3:0xc
	v_cndmask_b32_e32 v46, v25, v23, vcc
	v_cmp_eq_u32_e32 vcc, 1, v45
	v_cndmask_b32_e64 v34, v35, v38, s[6:7]
	v_not_b32_e32 v35, v34
	v_cndmask_b32_e32 v45, v46, v21, vcc
	v_cmp_gt_u32_e32 vcc, 64, v26
	v_cndmask_b32_e64 v37, v40, v41, s[6:7]
	v_cndmask_b32_e64 v41, v44, v43, s[6:7]
	v_cndmask_b32_e32 v26, v45, v19, vcc
	v_bfe_u32 v45, v29, 2, 2
	v_cmp_eq_u32_e32 vcc, 2, v45
	v_bitop3_b32 v44, v27, 15, v27 bitop3:0xc
	v_bfe_u32 v47, v35, 6, 2
	v_cndmask_b32_e32 v46, v24, v22, vcc
	v_cmp_eq_u32_e32 vcc, 1, v45
	v_not_b32_e32 v38, v37
	v_bfe_u32 v49, v38, 6, 2
	v_cndmask_b32_e32 v45, v46, v20, vcc
	v_cmp_gt_u32_e32 vcc, 4, v44
	v_bitop3_b32 v46, v34, 15, v34 bitop3:0xc
	v_cndmask_b32_e64 v31, v31, v36, s[6:7]
	v_cndmask_b32_e32 v44, v45, v18, vcc
	v_cmp_eq_u32_e32 vcc, 2, v47
	v_bitop3_b32 v45, v34, s3, v34 bitop3:0xc
	v_not_b32_e32 v36, v31
	v_cndmask_b32_e32 v48, v25, v23, vcc
	v_cmp_eq_u32_e32 vcc, 1, v47
	v_bfe_u32 v51, v36, 6, 2
	v_cndmask_b32_e64 v33, v33, v39, s[6:7]
	v_cndmask_b32_e32 v47, v48, v21, vcc
	v_cmp_gt_u32_e32 vcc, 64, v45
	v_not_b32_e32 v39, v33
	v_bfe_u32 v53, v39, 6, 2
	v_cndmask_b32_e32 v45, v47, v19, vcc
	v_bfe_u32 v47, v35, 2, 2
	v_cmp_eq_u32_e32 vcc, 2, v47
	v_cndmask_b32_e64 v28, v28, v42, s[6:7]
	v_not_b32_e32 v40, v28
	v_cndmask_b32_e32 v48, v24, v22, vcc
	v_cmp_eq_u32_e32 vcc, 1, v47
	v_bfe_u32 v55, v40, 6, 2
	v_not_b32_e32 v42, v41
	v_cndmask_b32_e32 v47, v48, v20, vcc
	v_cmp_gt_u32_e32 vcc, 4, v46
	v_bitop3_b32 v48, v37, 15, v37 bitop3:0xc
	v_bfe_u32 v57, v42, 6, 2
	v_cndmask_b32_e32 v46, v47, v18, vcc
	v_cmp_eq_u32_e32 vcc, 2, v49
	v_bitop3_b32 v47, v37, s3, v37 bitop3:0xc
	v_not_b32_e32 v43, v30
	v_cndmask_b32_e32 v50, v25, v23, vcc
	v_cmp_eq_u32_e32 vcc, 1, v49
	v_bfe_u32 v59, v43, 6, 2
	s_nop 0
	v_cndmask_b32_e32 v49, v50, v21, vcc
	v_cmp_gt_u32_e32 vcc, 64, v47
	s_nop 1
	v_cndmask_b32_e32 v47, v49, v19, vcc
	v_bfe_u32 v49, v38, 2, 2
	v_cmp_eq_u32_e32 vcc, 2, v49
	s_nop 1
	v_cndmask_b32_e32 v50, v24, v22, vcc
	v_cmp_eq_u32_e32 vcc, 1, v49
	s_nop 1
	v_cndmask_b32_e32 v49, v50, v20, vcc
	v_cmp_gt_u32_e32 vcc, 4, v48
	v_bitop3_b32 v50, v31, 15, v31 bitop3:0xc
	s_nop 0
	v_cndmask_b32_e32 v48, v49, v18, vcc
	v_cmp_eq_u32_e32 vcc, 2, v51
	v_bitop3_b32 v49, v31, s3, v31 bitop3:0xc
	s_nop 0
	v_cndmask_b32_e32 v52, v25, v23, vcc
	v_cmp_eq_u32_e32 vcc, 1, v51
	s_nop 1
	v_cndmask_b32_e32 v51, v52, v21, vcc
	v_cmp_gt_u32_e32 vcc, 64, v49
	s_nop 1
	v_cndmask_b32_e32 v49, v51, v19, vcc
	v_bfe_u32 v51, v36, 2, 2
	v_cmp_eq_u32_e32 vcc, 2, v51
	s_nop 1
	v_cndmask_b32_e32 v52, v24, v22, vcc
	v_cmp_eq_u32_e32 vcc, 1, v51
	s_nop 1
	v_cndmask_b32_e32 v51, v52, v20, vcc
	v_cmp_gt_u32_e32 vcc, 4, v50
	v_bitop3_b32 v52, v33, 15, v33 bitop3:0xc
	s_nop 0
	v_cndmask_b32_e32 v50, v51, v18, vcc
	v_cmp_eq_u32_e32 vcc, 2, v53
	v_bitop3_b32 v51, v33, s3, v33 bitop3:0xc
	s_nop 0
	v_cndmask_b32_e32 v54, v25, v23, vcc
	v_cmp_eq_u32_e32 vcc, 1, v53
	s_nop 1
	v_cndmask_b32_e32 v53, v54, v21, vcc
	v_cmp_gt_u32_e32 vcc, 64, v51
	s_nop 1
	v_cndmask_b32_e32 v51, v53, v19, vcc
	v_bfe_u32 v53, v39, 2, 2
	v_cmp_eq_u32_e32 vcc, 2, v53
	s_nop 1
	v_cndmask_b32_e32 v54, v24, v22, vcc
	v_cmp_eq_u32_e32 vcc, 1, v53
	s_nop 1
	v_cndmask_b32_e32 v53, v54, v20, vcc
	v_cmp_gt_u32_e32 vcc, 4, v52
	v_bitop3_b32 v54, v28, 15, v28 bitop3:0xc
	s_nop 0
	v_cndmask_b32_e32 v52, v53, v18, vcc
	v_cmp_eq_u32_e32 vcc, 2, v55
	v_bitop3_b32 v53, v28, s3, v28 bitop3:0xc
	s_nop 0
	v_cndmask_b32_e32 v56, v25, v23, vcc
	v_cmp_eq_u32_e32 vcc, 1, v55
	s_nop 1
	v_cndmask_b32_e32 v55, v56, v21, vcc
	v_cmp_gt_u32_e32 vcc, 64, v53
	s_nop 1
	v_cndmask_b32_e32 v53, v55, v19, vcc
	v_bfe_u32 v55, v40, 2, 2
	v_cmp_eq_u32_e32 vcc, 2, v55
	s_nop 1
	v_cndmask_b32_e32 v56, v24, v22, vcc
	v_cmp_eq_u32_e32 vcc, 1, v55
	s_nop 1
	v_cndmask_b32_e32 v55, v56, v20, vcc
	v_cmp_gt_u32_e32 vcc, 4, v54
	v_bitop3_b32 v56, v41, 15, v41 bitop3:0xc
	s_nop 0
	v_cndmask_b32_e32 v54, v55, v18, vcc
	v_cmp_eq_u32_e32 vcc, 2, v57
	v_bitop3_b32 v55, v41, s3, v41 bitop3:0xc
	s_nop 0
	v_cndmask_b32_e32 v58, v25, v23, vcc
	v_cmp_eq_u32_e32 vcc, 1, v57
	s_nop 1
	v_cndmask_b32_e32 v57, v58, v21, vcc
	v_cmp_gt_u32_e32 vcc, 64, v55
	s_nop 1
	v_cndmask_b32_e32 v55, v57, v19, vcc
	v_bfe_u32 v57, v42, 2, 2
	v_cmp_eq_u32_e32 vcc, 2, v57
	s_nop 1
	v_cndmask_b32_e32 v58, v24, v22, vcc
	v_cmp_eq_u32_e32 vcc, 1, v57
	s_nop 1
	v_cndmask_b32_e32 v57, v58, v20, vcc
	v_cmp_gt_u32_e32 vcc, 4, v56
	v_bitop3_b32 v58, v30, 15, v30 bitop3:0xc
	s_nop 0
	v_cndmask_b32_e32 v56, v57, v18, vcc
	v_cmp_eq_u32_e32 vcc, 2, v59
	v_bitop3_b32 v57, v30, s3, v30 bitop3:0xc
	s_nop 0
	v_cndmask_b32_e32 v23, v25, v23, vcc
	v_cmp_eq_u32_e32 vcc, 1, v59
	v_sub_f32_e32 v25, v31, v32
	v_mul_f32_e32 v25, 0x3fb8aa3b, v25
	v_cndmask_b32_e32 v21, v23, v21, vcc
	v_cmp_gt_u32_e32 vcc, 64, v57
	v_lshrrev_b32_e32 v23, 1, v39
	v_and_b32_e32 v23, 24, v23
	v_cndmask_b32_e32 v19, v21, v19, vcc
	v_bfe_u32 v21, v43, 2, 2
	v_cmp_eq_u32_e32 vcc, 2, v21
	v_lshrrev_b32_e32 v23, v23, v51
	v_lshlrev_b32_e32 v23, 7, v23
	v_cndmask_b32_e32 v22, v24, v22, vcc
	v_cmp_eq_u32_e32 vcc, 1, v21
	v_lshrrev_b32_e32 v21, 1, v42
	v_and_b32_e32 v21, 24, v21
	v_cndmask_b32_e32 v20, v22, v20, vcc
	v_cmp_gt_u32_e32 vcc, 4, v58
	v_lshrrev_b32_e32 v21, v21, v55
	v_lshrrev_b32_e32 v22, 1, v40
	v_cndmask_b32_e32 v18, v20, v18, vcc
	v_lshlrev_b32_e32 v20, 3, v42
	v_lshlrev_b32_e32 v21, 7, v21
	v_and_b32_e32 v22, 24, v22
	v_lshrrev_b32_e32 v20, v20, v56
; #define LAS __attribute__((address_space(3)))
; __device__ __forceinline__ void peer_u_item(int p, int j, const LAS unsigned short* EL  , const unsigned char* __restrict__ XQ, const unsigned char* __restrict__ U8, LAS int* ACC  , int lane, int wave) {
;     asm volatile("" : "+v"(lane));
;     const int gidx = lane >> 3; const unsigned coff = (unsigned)(p * 128 + (lane & 7) * 16), toff = (unsigned)(p * (16384 * 128) + (lane & 7) * 16);
; #pragma unroll 1
;     for (int it = 0; it < 8; ++it) {
;         const int t = j * 64 + it * 8 + wave;
;         unsigned E[8];
;         { const LAS v4u* ep = (const LAS v4u*)(EL + (it * 8 + wave) * 128 + 16 * gidx); const v4u e0 = ep[0], e1 = ep[1];
;           E[0] = e0.x; E[1] = e0.y; E[2] = e0.z; E[3] = e0.w; E[4] = e1.x; E[5] = e1.y; E[6] = e1.z; E[7] = e1.w; }
;         uint4 uu[16];
; #pragma unroll
;         for (int i = 0; i < 16; ++i) uu[i] = *(const uint4*)(U8 + (size_t)(PE_ID(E, i) * 128u + toff));
;         const uint4 xh = *(const uint4*)(XQ + (size_t)t * 512 + coff), xl = *(const uint4*)(XQ + 8 * MiB + (size_t)t * 512 + coff);
;         int d[16];
; #pragma unroll
;         for (int i = 0; i < 16; ++i) {
;             int sh = __builtin_amdgcn_sdot8((int)uu[i].x, (int)xh.x, 0, false); sh = __builtin_amdgcn_sdot8((int)uu[i].y, (int)xh.y, sh, false);
; __device__ __forceinline__ void route_task(int task, int tl0, const bf16* QP  , const LAS bf16* KHL, LAS unsigned short* EL, LAS float* GL, int lane) {
;     ...
;     for (int i = 0; i < 8; ++i) { e[i] = __expf(__int_as_float(my[i]) - __int_as_float(bk[0])); se += e[i]; }
;     se += __shfl_xor(se, 32);
;     const float inv = 1.f / se;
;     {
;         int l2 = lane; asm volatile("" : "+v"(l2));
;         const int o2 = (tl0 + ((l2 & 31) >> 3)) * 128 + (l2 & 7) * 16 + 8 * (l2 >> 5);
;         LAS v4u* ip = (LAS v4u*)(EL + o2); typedef float f4v __attribute__((ext_vector_type(4))); LAS f4v* gp = (LAS f4v*)(GL + o2);
;         ip[0] = (v4u){(unsigned)bv[0] | ((unsigned)bv[1] << 16), (unsigned)bv[2] | ((unsigned)bv[3] << 16), (unsigned)bv[4] | ((unsigned)bv[5] << 16), (unsigned)bv[6] | ((unsigned)bv[7] << 16)};
;         gp[0] = (f4v){e[0] * inv, e[1] * inv, e[2] * inv, e[3] * inv}; gp[1] = (f4v){e[4] * inv, e[5] * inv, e[6] * inv, e[7] * inv};
;     }
	v_and_b32_e32 v21, 0x7f80, v21
	v_lshrrev_b32_e32 v22, v22, v53
	v_and_or_b32 v21, v20, s3, v21
	v_lshlrev_b32_e32 v20, 3, v40
	v_lshlrev_b32_e32 v22, 7, v22
	v_lshrrev_b32_e32 v20, v20, v54
	v_and_b32_e32 v22, 0x7f80, v22
	v_and_or_b32 v20, v20, s3, v22
	v_lshlrev_b32_e32 v22, 3, v39
	v_lshrrev_b32_e32 v22, v22, v52
	v_and_b32_e32 v23, 0x7f80, v23
	v_and_or_b32 v39, v22, s3, v23
	v_lshrrev_b32_e32 v23, 1, v36
	v_and_b32_e32 v23, 24, v23
	v_lshrrev_b32_e32 v23, v23, v49
	v_lshlrev_b32_e32 v22, 3, v36
	v_lshlrev_b32_e32 v23, 7, v23
	v_lshrrev_b32_e32 v22, v22, v50
	v_and_b32_e32 v23, 0x7f80, v23
	v_and_or_b32 v36, v22, s3, v23
	v_lshrrev_b32_e32 v23, 1, v38
	v_and_b32_e32 v23, 24, v23
	v_lshrrev_b32_e32 v23, v23, v47
	v_lshlrev_b32_e32 v22, 3, v38
	v_lshlrev_b32_e32 v23, 7, v23
	v_lshrrev_b32_e32 v22, v22, v48
	v_and_b32_e32 v23, 0x7f80, v23
	v_and_or_b32 v38, v22, s3, v23
	v_lshrrev_b32_e32 v23, 1, v35
	v_and_b32_e32 v23, 24, v23
	v_lshrrev_b32_e32 v23, v23, v45
	v_lshlrev_b32_e32 v22, 3, v35
	v_lshlrev_b32_e32 v23, 7, v23
	v_lshrrev_b32_e32 v22, v22, v46
	v_and_b32_e32 v23, 0x7f80, v23
	v_and_or_b32 v35, v22, s3, v23
	v_lshrrev_b32_e32 v23, 1, v29
	v_and_b32_e32 v23, 24, v23
	v_lshrrev_b32_e32 v23, v23, v26
	v_lshlrev_b32_e32 v22, 3, v29
	v_lshlrev_b32_e32 v23, 7, v23
	v_lshrrev_b32_e32 v22, v22, v44
	v_and_b32_e32 v23, 0x7f80, v23
	v_and_or_b32 v40, v22, s3, v23
	v_sub_f32_e32 v22, v27, v32
	v_mul_f32_e32 v22, 0x3fb8aa3b, v22
	v_sub_f32_e32 v23, v34, v32
	v_exp_f32_e32 v22, v22
	v_mul_f32_e32 v23, 0x3fb8aa3b, v23
	v_sub_f32_e32 v24, v37, v32
	v_exp_f32_e32 v23, v23
	v_mul_f32_e32 v24, 0x3fb8aa3b, v24
	v_exp_f32_e32 v24, v24
	v_exp_f32_e32 v25, v25
	v_add_f32_e32 v26, 0, v22
	v_add_f32_e32 v26, v23, v26
	v_add_f32_e32 v26, v24, v26
	v_add_f32_e32 v31, v25, v26
	v_sub_f32_e32 v26, v33, v32
	v_mul_f32_e32 v26, 0x3fb8aa3b, v26
	v_sub_f32_e32 v27, v28, v32
	v_exp_f32_e32 v26, v26
	v_mul_f32_e32 v27, 0x3fb8aa3b, v27
	v_sub_f32_e32 v28, v41, v32
	v_exp_f32_e32 v27, v27
	v_mul_f32_e32 v28, 0x3fb8aa3b, v28
	v_sub_f32_e32 v29, v30, v32
	v_exp_f32_e32 v28, v28
	v_mul_f32_e32 v29, 0x3fb8aa3b, v29
	v_exp_f32_e32 v29, v29
	v_add_f32_e32 v30, v26, v31
	v_add_f32_e32 v30, v27, v30
	v_add_f32_e32 v30, v28, v30
	v_add_f32_e32 v30, v29, v30
	ds_bpermute_b32 v31, v123, v30
	v_lshrrev_b32_e32 v42, 1, v43
	v_and_b32_e32 v32, 24, v42
	v_lshrrev_b32_e32 v19, v32, v19
	v_lshlrev_b32_e32 v19, 7, v19
	s_waitcnt lgkmcnt(0)
	v_add_f32_e32 v30, v30, v31
	v_div_scale_f32 v31, s[12:13], v30, v30, 1.0
	v_rcp_f32_e32 v32, v31
	v_lshlrev_b32_e32 v33, 3, v43
	v_and_b32_e32 v19, 0x7f80, v19
	v_lshrrev_b32_e32 v18, v33, v18
	v_and_or_b32 v33, v18, s3, v19
	v_fma_f32 v18, -v31, v32, 1.0
	v_fmac_f32_e32 v32, v18, v32
	v_div_scale_f32 v18, vcc, 1.0, v30, 1.0
	v_mul_f32_e32 v19, v18, v32
	v_fma_f32 v34, -v31, v19, v18
	v_fmac_f32_e32 v19, v34, v32
	v_fma_f32 v18, -v31, v19, v18
	v_div_fmas_f32 v18, v18, v32, v19
	v_div_fixup_f32 v30, v18, v30, 1.0
	v_mov_b32_e32 v18, v1
	v_lshl_or_b32 v20, v20, 16, v39
	v_lshrrev_b32_e32 v19, 3, v18
	v_and_or_b32 v19, v19, 3, s57
	v_lshlrev_b32_e32 v31, 4, v18
	v_ashrrev_i32_e32 v18, 2, v18
	v_lshlrev_b32_e32 v19, 7, v19
	v_and_b32_e32 v31, 0x70, v31
	v_and_b32_e32 v18, -8, v18
	v_add3_u32 v18, v18, v31, v19
	v_lshl_add_u32 v31, v18, 1, s11
	v_lshl_add_u32 v32, v18, 2, s69
	v_lshl_or_b32 v18, v35, 16, v40
	v_lshl_or_b32 v19, v36, 16, v38
	v_lshl_or_b32 v21, v33, 16, v21
	ds_write_b128 v31, v[18:21]
	v_pk_mul_f32 v[20:21], v[24:25], v[30:31] op_sel_hi:[1,0]
	v_pk_mul_f32 v[18:19], v[22:23], v[30:31] op_sel_hi:[1,0]
	ds_write_b128 v32, v[18:21]
	v_pk_mul_f32 v[20:21], v[28:29], v[30:31] op_sel_hi:[1,0]
	v_pk_mul_f32 v[18:19], v[26:27], v[30:31] op_sel_hi:[1,0]
	ds_write_b128 v32, v[18:21] offset:16
	v_xor_b32_e32 v18, 4, v112
	v_cmp_lt_i32_e32 vcc, v18, v122
	s_waitcnt lgkmcnt(0)
	s_barrier
	v_cndmask_b32_e32 v18, v112, v18, vcc
	v_lshlrev_b32_e32 v30, 2, v18
	v_xor_b32_e32 v18, 2, v112
	v_cmp_lt_i32_e32 vcc, v18, v122
	s_nop 1
	v_cndmask_b32_e32 v18, v112, v18, vcc
	v_lshlrev_b32_e32 v31, 2, v18
	v_xor_b32_e32 v18, 1, v112
	v_cmp_lt_i32_e32 vcc, v18, v122
	s_nop 1
	v_cndmask_b32_e32 v18, v112, v18, vcc
	v_lshlrev_b32_e32 v32, 2, v18
	v_lshlrev_b32_e32 v56, 4, v1
	v_and_b32_e32 v56, 0x70, v56
	v_lshrrev_b32_e32 v59, 3, v1
	v_lshlrev_b32_e32 v59, 5, v59
	v_add_u32_e32 v59, s66, v59
	v_add_u32_e32 v59, -16, v59
	v_lshl_add_u32 v60, v1, 3, s64
	v_and_b32_e32 v38, 4, v1
	v_cmp_ne_u32_e64 s[10:11], 0, v38
	v_and_b32_e32 v38, 2, v1
	v_cmp_ne_u32_e64 s[12:13], 0, v38
	v_and_b32_e32 v38, 1, v1
	v_cmp_ne_u32_e64 s[14:15], 0, v38
	s_movk_i32 s94, 0x80
	s_mov_b32 s42, 0
	s_mov_b32 s43, 0
	s_mov_b32 s44, 1
	s_mov_b32 s45, 0
	s_lshl_b32 s32, s42, 11
	v_add_u32_e32 v39, s32, v59
	ds_read_b128 v[202:205], v39
	ds_read_b128 v[206:209], v39 offset:16
	s_lshl_b32 s46, s42, 3
	s_add_i32 s46, s46, s40
	s_lshl_b32 s46, s46, 9
	s_lshl_b32 s32, s43, 7
	s_add_i32 s46, s46, s32
	v_add_u32_e32 v57, s46, v56
	global_load_dwordx4 v[186:189], v57, s[34:35]
	global_load_dwordx4 v[190:193], v57, s[36:37]
	v_mov_b32_e32 v58, v56
	s_waitcnt lgkmcnt(0)
	v_mad_u32_u16 v38, v202, s94, v58
	global_load_dwordx4 v[122:125], v38, s[96:97]
	v_mad_u32_u16 v38, v202, s94, v58 op_sel:[1,0,0,0]
	global_load_dwordx4 v[126:129], v38, s[96:97]
	v_mad_u32_u16 v38, v203, s94, v58
	global_load_dwordx4 v[130:133], v38, s[96:97]
	v_mad_u32_u16 v38, v203, s94, v58 op_sel:[1,0,0,0]
	global_load_dwordx4 v[134:137], v38, s[96:97]
	v_mad_u32_u16 v38, v204, s94, v58
	global_load_dwordx4 v[138:141], v38, s[96:97]
	v_mad_u32_u16 v38, v204, s94, v58 op_sel:[1,0,0,0]
	global_load_dwordx4 v[142:145], v38, s[96:97]
	v_mad_u32_u16 v38, v205, s94, v58
	global_load_dwordx4 v[146:149], v38, s[96:97]
	v_mad_u32_u16 v38, v205, s94, v58 op_sel:[1,0,0,0]
	global_load_dwordx4 v[150:153], v38, s[96:97]
	v_mad_u32_u16 v38, v206, s94, v58
	global_load_dwordx4 v[154:157], v38, s[96:97]
	v_mad_u32_u16 v38, v206, s94, v58 op_sel:[1,0,0,0]
	global_load_dwordx4 v[158:161], v38, s[96:97]
	v_mad_u32_u16 v38, v207, s94, v58
	global_load_dwordx4 v[162:165], v38, s[96:97]
	v_mad_u32_u16 v38, v207, s94, v58 op_sel:[1,0,0,0]
	global_load_dwordx4 v[166:169], v38, s[96:97]
	v_mad_u32_u16 v38, v208, s94, v58
	global_load_dwordx4 v[170:173], v38, s[96:97]
	v_mad_u32_u16 v38, v208, s94, v58 op_sel:[1,0,0,0]
	global_load_dwordx4 v[174:177], v38, s[96:97]
	v_mad_u32_u16 v38, v209, s94, v58
	global_load_dwordx4 v[178:181], v38, s[96:97]
	v_mad_u32_u16 v38, v209, s94, v58 op_sel:[1,0,0,0]
	global_load_dwordx4 v[182:185], v38, s[96:97]
	s_mov_b32 s47, 15
; #define LAS __attribute__((address_space(3)))
; __device__ __forceinline__ void peer_u_item(int p, int j, const LAS unsigned short* EL  , const unsigned char* __restrict__ XQ, const unsigned char* __restrict__ U8, LAS int* ACC  , int lane, int wave) {
;     ...
;     const int gidx = lane >> 3; const unsigned coff = (unsigned)(p * 128 + (lane & 7) * 16), toff = (unsigned)(p * (16384 * 128) + (lane & 7) * 16);
; #pragma unroll 1
;     for (int it = 0; it < 8; ++it) {
;         const int t = j * 64 + it * 8 + wave;
;         unsigned E[8];
;         { const LAS v4u* ep = (const LAS v4u*)(EL + (it * 8 + wave) * 128 + 16 * gidx); const v4u e0 = ep[0], e1 = ep[1];
;           E[0] = e0.x; E[1] = e0.y; E[2] = e0.z; E[3] = e0.w; E[4] = e1.x; E[5] = e1.y; E[6] = e1.z; E[7] = e1.w; }
;         uint4 uu[16];
; #pragma unroll
;         for (int i = 0; i < 16; ++i) uu[i] = *(const uint4*)(U8 + (size_t)(PE_ID(E, i) * 128u + toff));
;         const uint4 xh = *(const uint4*)(XQ + (size_t)t * 512 + coff), xl = *(const uint4*)(XQ + 8 * MiB + (size_t)t * 512 + coff);
;         int d[16];
; #pragma unroll
;         for (int i = 0; i < 16; ++i) {
;             int sh = __builtin_amdgcn_sdot8((int)uu[i].x, (int)xh.x, 0, false); sh = __builtin_amdgcn_sdot8((int)uu[i].y, (int)xh.y, sh, false);
;             sh = __builtin_amdgcn_sdot8((int)uu[i].z, (int)xh.z, sh, false); sh = __builtin_amdgcn_sdot8((int)uu[i].w, (int)xh.w, sh, false);
;             int sl = __builtin_amdgcn_sdot8((int)uu[i].x, (int)xl.x, 0, false); sl = __builtin_amdgcn_sdot8((int)uu[i].y, (int)xl.y, sl, false);
;             sl = __builtin_amdgcn_sdot8((int)uu[i].z, (int)xl.z, sl, false); sl = __builtin_amdgcn_sdot8((int)uu[i].w, (int)xl.w, sl, false);
;             d[i] = (sh << 4) + sl;
.Lpu_trip:
	s_lshl_b32 s32, s44, 11
	v_add_u32_e32 v39, s32, v59
	ds_read_b128 v[210:213], v39
	ds_read_b128 v[214:217], v39 offset:16
	s_lshl_b32 s32, s42, 12
	v_add_u32_e32 v61, s32, v60
	ds_read_b64 v[62:63], v61
	s_lshl_b32 s46, s44, 3
	s_add_i32 s46, s46, s40
	s_lshl_b32 s46, s46, 9
	s_lshl_b32 s32, s45, 7
	s_add_i32 s46, s46, s32
	v_add_u32_e32 v57, s46, v56
	global_load_dwordx4 v[194:197], v57, s[34:35]
	global_load_dwordx4 v[198:201], v57, s[36:37]
	s_lshl_b32 s32, s45, 21
	v_add_u32_e32 v58, s32, v56
	s_waitcnt lgkmcnt(0)
	s_waitcnt vmcnt(17)
	v_dot8_i32_i4 v34, v122, v186, 0
	v_dot8_i32_i4 v35, v122, v190, 0
	v_dot8_i32_i4 v34, v123, v187, v34
	v_dot8_i32_i4 v35, v123, v191, v35
	v_dot8_i32_i4 v34, v124, v188, v34
	v_dot8_i32_i4 v35, v124, v192, v35
	v_dot8_i32_i4 v34, v125, v189, v34
	v_dot8_i32_i4 v35, v125, v193, v35
	v_mad_u32_u16 v38, v210, s94, v58
	global_load_dwordx4 v[122:125], v38, s[96:97]
	s_waitcnt vmcnt(17)
	v_lshl_add_u32 v18, v34, 4, v35
	v_dot8_i32_i4 v36, v126, v186, 0
	v_dot8_i32_i4 v37, v126, v190, 0
	v_dot8_i32_i4 v36, v127, v187, v36
	v_dot8_i32_i4 v37, v127, v191, v37
	v_dot8_i32_i4 v36, v128, v188, v36
	v_dot8_i32_i4 v37, v128, v192, v37
	v_dot8_i32_i4 v36, v129, v189, v36
	v_dot8_i32_i4 v37, v129, v193, v37
	v_mad_u32_u16 v38, v210, s94, v58 op_sel:[1,0,0,0]
	global_load_dwordx4 v[126:129], v38, s[96:97]
	s_waitcnt vmcnt(17)
	v_lshl_add_u32 v19, v36, 4, v37
	v_dot8_i32_i4 v34, v130, v186, 0
	v_dot8_i32_i4 v35, v130, v190, 0
	v_dot8_i32_i4 v34, v131, v187, v34
	v_dot8_i32_i4 v35, v131, v191, v35
	v_dot8_i32_i4 v34, v132, v188, v34
	v_dot8_i32_i4 v35, v132, v192, v35
	v_dot8_i32_i4 v34, v133, v189, v34
	v_dot8_i32_i4 v35, v133, v193, v35
	v_mad_u32_u16 v38, v211, s94, v58
	global_load_dwordx4 v[130:133], v38, s[96:97]
	s_waitcnt vmcnt(17)
	v_lshl_add_u32 v20, v34, 4, v35
	v_dot8_i32_i4 v36, v134, v186, 0
	v_dot8_i32_i4 v37, v134, v190, 0
	v_dot8_i32_i4 v36, v135, v187, v36
	v_dot8_i32_i4 v37, v135, v191, v37
	v_dot8_i32_i4 v36, v136, v188, v36
	v_dot8_i32_i4 v37, v136, v192, v37
	v_dot8_i32_i4 v36, v137, v189, v36
	v_dot8_i32_i4 v37, v137, v193, v37
	v_mad_u32_u16 v38, v211, s94, v58 op_sel:[1,0,0,0]
	global_load_dwordx4 v[134:137], v38, s[96:97]
	s_waitcnt vmcnt(17)
	v_lshl_add_u32 v21, v36, 4, v37
	v_dot8_i32_i4 v34, v138, v186, 0
	v_dot8_i32_i4 v35, v138, v190, 0
	v_dot8_i32_i4 v34, v139, v187, v34
	v_dot8_i32_i4 v35, v139, v191, v35
	v_dot8_i32_i4 v34, v140, v188, v34
	v_dot8_i32_i4 v35, v140, v192, v35
	v_dot8_i32_i4 v34, v141, v189, v34
	v_dot8_i32_i4 v35, v141, v193, v35
	v_mad_u32_u16 v38, v212, s94, v58
	global_load_dwordx4 v[138:141], v38, s[96:97]
	s_waitcnt vmcnt(17)
	v_lshl_add_u32 v22, v34, 4, v35
	v_dot8_i32_i4 v36, v142, v186, 0
	v_dot8_i32_i4 v37, v142, v190, 0
	v_dot8_i32_i4 v36, v143, v187, v36
	v_dot8_i32_i4 v37, v143, v191, v37
	v_dot8_i32_i4 v36, v144, v188, v36
	v_dot8_i32_i4 v37, v144, v192, v37
	v_dot8_i32_i4 v36, v145, v189, v36
	v_dot8_i32_i4 v37, v145, v193, v37
	v_mad_u32_u16 v38, v212, s94, v58 op_sel:[1,0,0,0]
	global_load_dwordx4 v[142:145], v38, s[96:97]
	s_waitcnt vmcnt(17)
	v_lshl_add_u32 v23, v36, 4, v37
	v_dot8_i32_i4 v34, v146, v186, 0
	v_dot8_i32_i4 v35, v146, v190, 0
	v_dot8_i32_i4 v34, v147, v187, v34
	v_dot8_i32_i4 v35, v147, v191, v35
	v_dot8_i32_i4 v34, v148, v188, v34
	v_dot8_i32_i4 v35, v148, v192, v35
	v_dot8_i32_i4 v34, v149, v189, v34
	v_dot8_i32_i4 v35, v149, v193, v35
	v_mad_u32_u16 v38, v213, s94, v58
	global_load_dwordx4 v[146:149], v38, s[96:97]
	s_waitcnt vmcnt(17)
	v_lshl_add_u32 v24, v34, 4, v35
	v_dot8_i32_i4 v36, v150, v186, 0
	v_dot8_i32_i4 v37, v150, v190, 0
	v_dot8_i32_i4 v36, v151, v187, v36
	v_dot8_i32_i4 v37, v151, v191, v37
	v_dot8_i32_i4 v36, v152, v188, v36
	v_dot8_i32_i4 v37, v152, v192, v37
	v_dot8_i32_i4 v36, v153, v189, v36
	v_dot8_i32_i4 v37, v153, v193, v37
	v_mad_u32_u16 v38, v213, s94, v58 op_sel:[1,0,0,0]
	global_load_dwordx4 v[150:153], v38, s[96:97]
	s_waitcnt vmcnt(17)
	v_lshl_add_u32 v25, v36, 4, v37
	v_dot8_i32_i4 v34, v154, v186, 0
	v_dot8_i32_i4 v35, v154, v190, 0
	v_dot8_i32_i4 v34, v155, v187, v34
	v_dot8_i32_i4 v35, v155, v191, v35
	v_dot8_i32_i4 v34, v156, v188, v34
	v_dot8_i32_i4 v35, v156, v192, v35
	v_dot8_i32_i4 v34, v157, v189, v34
	v_dot8_i32_i4 v35, v157, v193, v35
	v_mad_u32_u16 v38, v214, s94, v58
	global_load_dwordx4 v[154:157], v38, s[96:97]
	s_waitcnt vmcnt(17)
	v_lshl_add_u32 v26, v34, 4, v35
	v_dot8_i32_i4 v36, v158, v186, 0
	v_dot8_i32_i4 v37, v158, v190, 0
	v_dot8_i32_i4 v36, v159, v187, v36
	v_dot8_i32_i4 v37, v159, v191, v37
	v_dot8_i32_i4 v36, v160, v188, v36
	v_dot8_i32_i4 v37, v160, v192, v37
	v_dot8_i32_i4 v36, v161, v189, v36
	v_dot8_i32_i4 v37, v161, v193, v37
	v_mad_u32_u16 v38, v214, s94, v58 op_sel:[1,0,0,0]
	global_load_dwordx4 v[158:161], v38, s[96:97]
	s_waitcnt vmcnt(17)
	v_lshl_add_u32 v27, v36, 4, v37
	v_dot8_i32_i4 v34, v162, v186, 0
	v_dot8_i32_i4 v35, v162, v190, 0
	v_dot8_i32_i4 v34, v163, v187, v34
	v_dot8_i32_i4 v35, v163, v191, v35
	v_dot8_i32_i4 v34, v164, v188, v34
	v_dot8_i32_i4 v35, v164, v192, v35
	v_dot8_i32_i4 v34, v165, v189, v34
	v_dot8_i32_i4 v35, v165, v193, v35
	v_mad_u32_u16 v38, v215, s94, v58
	global_load_dwordx4 v[162:165], v38, s[96:97]
	s_waitcnt vmcnt(17)
	v_lshl_add_u32 v28, v34, 4, v35
	v_dot8_i32_i4 v36, v166, v186, 0
	v_dot8_i32_i4 v37, v166, v190, 0
	v_dot8_i32_i4 v36, v167, v187, v36
	v_dot8_i32_i4 v37, v167, v191, v37
	v_dot8_i32_i4 v36, v168, v188, v36
	v_dot8_i32_i4 v37, v168, v192, v37
	v_dot8_i32_i4 v36, v169, v189, v36
	v_dot8_i32_i4 v37, v169, v193, v37
	v_mad_u32_u16 v38, v215, s94, v58 op_sel:[1,0,0,0]
	global_load_dwordx4 v[166:169], v38, s[96:97]
	s_waitcnt vmcnt(17)
; #define LAS __attribute__((address_space(3)))
; template <int M4, int M2, int M1> __device__ __forceinline__ void treduce16i(const int (&a)[16], int lane, int& r0, int& r1) {
;     int b[8], c[4];
;     { const bool hi = (lane & M4) != 0;
; #pragma unroll
;       for (int i = 0; i < 8; ++i) { const int send = hi ? a[i] : a[i + 8]; const int recv = __shfl_xor(send, M4); b[i] = (hi ? a[i + 8] : a[i]) + recv; } }
;     { const bool hi = (lane & M2) != 0;
; #pragma unroll
;       for (int i = 0; i < 4; ++i) { const int send = hi ? b[i] : b[i + 4]; const int recv = __shfl_xor(send, M2); c[i] = (hi ? b[i + 4] : b[i]) + recv; } }
;     { const bool hi = (lane & M1) != 0;
;       { const int send = hi ? c[0] : c[2]; const int recv = __shfl_xor(send, M1); r0 = (hi ? c[2] : c[0]) + recv; }
;       { const int send = hi ? c[1] : c[3]; const int recv = __shfl_xor(send, M1); r1 = (hi ? c[3] : c[1]) + recv; } }
; }
; __device__ __forceinline__ void treduce16i_hw(const int (&a)[16], int lane, int& r0, int& r1) {
;     int b[8], c[4];
; #pragma unroll
;     for (int i = 0; i < 8; ++i) { const auto r = __builtin_amdgcn_permlane32_swap((unsigned)a[i], (unsigned)a[i + 8], false, false); b[i] = (int)r[0] + (int)r[1]; }
; #pragma unroll
;     for (int i = 0; i < 4; ++i) { const auto r = __builtin_amdgcn_permlane16_swap((unsigned)b[i], (unsigned)b[i + 4], false, false); c[i] = (int)r[0] + (int)r[1]; }
;     const bool hi = (lane & 8) != 0;
;     { const int send = hi ? c[0] : c[2]; r0 = (hi ? c[2] : c[0]) + __builtin_amdgcn_update_dpp(0, send, 0x128, 0xf, 0xf, false); }
;     { const int send = hi ? c[1] : c[3]; r1 = (hi ? c[3] : c[1]) + __builtin_amdgcn_update_dpp(0, send, 0x128, 0xf, 0xf, false); }
; }
; __device__ __forceinline__ void peer_u_item(int p, int j, const LAS unsigned short* EL  , const unsigned char* __restrict__ XQ, const unsigned char* __restrict__ U8, LAS int* ACC  , int lane, int wave) {
;     asm volatile("" : "+v"(lane));
;     const int gidx = lane >> 3; const unsigned coff = (unsigned)(p * 128 + (lane & 7) * 16), toff = (unsigned)(p * (16384 * 128) + (lane & 7) * 16);
; #pragma unroll 1
;     for (int it = 0; it < 8; ++it) {
;         const int t = j * 64 + it * 8 + wave;
;         unsigned E[8];
;         { const LAS v4u* ep = (const LAS v4u*)(EL + (it * 8 + wave) * 128 + 16 * gidx); const v4u e0 = ep[0], e1 = ep[1];
	v_lshl_add_u32 v29, v36, 4, v37
	v_dot8_i32_i4 v34, v170, v186, 0
	v_dot8_i32_i4 v35, v170, v190, 0
	v_dot8_i32_i4 v34, v171, v187, v34
	v_dot8_i32_i4 v35, v171, v191, v35
	v_dot8_i32_i4 v34, v172, v188, v34
	v_dot8_i32_i4 v35, v172, v192, v35
	v_dot8_i32_i4 v34, v173, v189, v34
	v_dot8_i32_i4 v35, v173, v193, v35
	v_mad_u32_u16 v38, v216, s94, v58
	global_load_dwordx4 v[170:173], v38, s[96:97]
	s_waitcnt vmcnt(17)
	v_lshl_add_u32 v30, v34, 4, v35
	v_dot8_i32_i4 v36, v174, v186, 0
	v_dot8_i32_i4 v37, v174, v190, 0
	v_dot8_i32_i4 v36, v175, v187, v36
	v_dot8_i32_i4 v37, v175, v191, v37
	v_dot8_i32_i4 v36, v176, v188, v36
	v_dot8_i32_i4 v37, v176, v192, v37
	v_dot8_i32_i4 v36, v177, v189, v36
	v_dot8_i32_i4 v37, v177, v193, v37
	v_mad_u32_u16 v38, v216, s94, v58 op_sel:[1,0,0,0]
	global_load_dwordx4 v[174:177], v38, s[96:97]
	s_waitcnt vmcnt(17)
	v_lshl_add_u32 v31, v36, 4, v37
	v_dot8_i32_i4 v34, v178, v186, 0
	v_dot8_i32_i4 v35, v178, v190, 0
	v_dot8_i32_i4 v34, v179, v187, v34
	v_dot8_i32_i4 v35, v179, v191, v35
	v_dot8_i32_i4 v34, v180, v188, v34
	v_dot8_i32_i4 v35, v180, v192, v35
	v_dot8_i32_i4 v34, v181, v189, v34
	v_dot8_i32_i4 v35, v181, v193, v35
	v_mad_u32_u16 v38, v217, s94, v58
	global_load_dwordx4 v[178:181], v38, s[96:97]
	s_waitcnt vmcnt(17)
	v_lshl_add_u32 v32, v34, 4, v35
	v_dot8_i32_i4 v36, v182, v186, 0
	v_dot8_i32_i4 v37, v182, v190, 0
	v_dot8_i32_i4 v36, v183, v187, v36
	v_dot8_i32_i4 v37, v183, v191, v37
	v_dot8_i32_i4 v36, v184, v188, v36
	v_dot8_i32_i4 v37, v184, v192, v37
	v_dot8_i32_i4 v36, v185, v189, v36
	v_dot8_i32_i4 v37, v185, v193, v37
	v_mad_u32_u16 v38, v217, s94, v58 op_sel:[1,0,0,0]
	global_load_dwordx4 v[182:185], v38, s[96:97]
	s_nop 0
	v_lshl_add_u32 v33, v36, 4, v37
	v_add_u32_dpp v40, v26, v26 row_shr:4 row_mask:0xf bank_mask:0xa
	v_add_u32_dpp v40, v18, v18 row_shl:4 row_mask:0xf bank_mask:0x5
	v_add_u32_dpp v41, v27, v27 row_shr:4 row_mask:0xf bank_mask:0xa
	v_add_u32_dpp v41, v19, v19 row_shl:4 row_mask:0xf bank_mask:0x5
	v_add_u32_dpp v42, v28, v28 row_shr:4 row_mask:0xf bank_mask:0xa
	v_add_u32_dpp v42, v20, v20 row_shl:4 row_mask:0xf bank_mask:0x5
	v_add_u32_dpp v43, v29, v29 row_shr:4 row_mask:0xf bank_mask:0xa
	v_add_u32_dpp v43, v21, v21 row_shl:4 row_mask:0xf bank_mask:0x5
	v_add_u32_dpp v44, v30, v30 row_shr:4 row_mask:0xf bank_mask:0xa
	v_add_u32_dpp v44, v22, v22 row_shl:4 row_mask:0xf bank_mask:0x5
	v_add_u32_dpp v45, v31, v31 row_shr:4 row_mask:0xf bank_mask:0xa
	v_add_u32_dpp v45, v23, v23 row_shl:4 row_mask:0xf bank_mask:0x5
	v_add_u32_dpp v46, v32, v32 row_shr:4 row_mask:0xf bank_mask:0xa
	v_add_u32_dpp v46, v24, v24 row_shl:4 row_mask:0xf bank_mask:0x5
	v_add_u32_dpp v47, v33, v33 row_shr:4 row_mask:0xf bank_mask:0xa
	v_add_u32_dpp v47, v25, v25 row_shl:4 row_mask:0xf bank_mask:0x5
	v_cndmask_b32_e64 v18, v44, v40, s[12:13]
	v_cndmask_b32_e64 v22, v40, v44, s[12:13]
	v_cndmask_b32_e64 v19, v45, v41, s[12:13]
	v_cndmask_b32_e64 v23, v41, v45, s[12:13]
	v_cndmask_b32_e64 v20, v46, v42, s[12:13]
	v_cndmask_b32_e64 v24, v42, v46, s[12:13]
	v_cndmask_b32_e64 v21, v47, v43, s[12:13]
	v_cndmask_b32_e64 v25, v43, v47, s[12:13]
	s_nop 0
	v_add_u32_dpp v26, v18, v22 quad_perm:[2,3,0,1] row_mask:0xf bank_mask:0xf
	v_add_u32_dpp v27, v19, v23 quad_perm:[2,3,0,1] row_mask:0xf bank_mask:0xf
	v_add_u32_dpp v28, v20, v24 quad_perm:[2,3,0,1] row_mask:0xf bank_mask:0xf
	v_add_u32_dpp v29, v21, v25 quad_perm:[2,3,0,1] row_mask:0xf bank_mask:0xf
	v_cndmask_b32_e64 v40, v28, v26, s[14:15]
	v_cndmask_b32_e64 v48, v26, v28, s[14:15]
	v_cndmask_b32_e64 v41, v29, v27, s[14:15]
	v_cndmask_b32_e64 v49, v27, v29, s[14:15]
	s_nop 1
	v_add_u32_dpp v44, v40, v48 quad_perm:[1,0,3,2] row_mask:0xf bank_mask:0xf
	v_add_u32_dpp v45, v41, v49 quad_perm:[1,0,3,2] row_mask:0xf bank_mask:0xf
	s_cmp_eq_u32 s43, 0
	s_cselect_b32 s32, 0, -1
	v_and_b32_e32 v62, s32, v62
	v_and_b32_e32 v63, s32, v63
	v_add_u32_e32 v44, v44, v62
	v_add_u32_e32 v45, v45, v63
	ds_write_b64 v61, v[44:45]
	s_mov_b32 s42, s44
	s_mov_b32 s43, s45
	s_add_i32 s44, s44, 1
	s_and_b32 s44, s44, 7
	s_cmp_eq_u32 s44, 0
	s_cselect_b32 s32, 1, 0
	s_add_i32 s45, s45, s32
	s_and_b32 s45, s45, 3
	s_lshl_b32 s32, s44, 11
	v_add_u32_e32 v39, s32, v59
	ds_read_b128 v[202:205], v39
	ds_read_b128 v[206:209], v39 offset:16
	s_lshl_b32 s32, s42, 12
	v_add_u32_e32 v61, s32, v60
	ds_read_b64 v[62:63], v61
	s_lshl_b32 s46, s44, 3
	s_add_i32 s46, s46, s40
	s_lshl_b32 s46, s46, 9
	s_lshl_b32 s32, s45, 7
	s_add_i32 s46, s46, s32
	v_add_u32_e32 v57, s46, v56
	global_load_dwordx4 v[186:189], v57, s[34:35]
	global_load_dwordx4 v[190:193], v57, s[36:37]
	s_lshl_b32 s32, s45, 21
	v_add_u32_e32 v58, s32, v56
	s_waitcnt lgkmcnt(0)
	s_waitcnt vmcnt(17)
	v_dot8_i32_i4 v34, v122, v194, 0
	v_dot8_i32_i4 v35, v122, v198, 0
	v_dot8_i32_i4 v34, v123, v195, v34
	v_dot8_i32_i4 v35, v123, v199, v35
	v_dot8_i32_i4 v34, v124, v196, v34
	v_dot8_i32_i4 v35, v124, v200, v35
	v_dot8_i32_i4 v34, v125, v197, v34
	v_dot8_i32_i4 v35, v125, v201, v35
	v_mad_u32_u16 v38, v202, s94, v58
	global_load_dwordx4 v[122:125], v38, s[96:97]
	s_waitcnt vmcnt(17)
	v_lshl_add_u32 v18, v34, 4, v35
	v_dot8_i32_i4 v36, v126, v194, 0
	v_dot8_i32_i4 v37, v126, v198, 0
	v_dot8_i32_i4 v36, v127, v195, v36
	v_dot8_i32_i4 v37, v127, v199, v37
	v_dot8_i32_i4 v36, v128, v196, v36
	v_dot8_i32_i4 v37, v128, v200, v37
	v_dot8_i32_i4 v36, v129, v197, v36
	v_dot8_i32_i4 v37, v129, v201, v37
	v_mad_u32_u16 v38, v202, s94, v58 op_sel:[1,0,0,0]
	global_load_dwordx4 v[126:129], v38, s[96:97]
	s_waitcnt vmcnt(17)
; __device__ __forceinline__ void peer_u_item(int p, int j, const LAS unsigned short* EL  , const unsigned char* __restrict__ XQ, const unsigned char* __restrict__ U8, LAS int* ACC  , int lane, int wave) {
;     ...
;         for (int i = 0; i < 16; ++i) uu[i] = *(const uint4*)(U8 + (size_t)(PE_ID(E, i) * 128u + toff));
;         const uint4 xh = *(const uint4*)(XQ + (size_t)t * 512 + coff), xl = *(const uint4*)(XQ + 8 * MiB + (size_t)t * 512 + coff);
;         int d[16];
; #pragma unroll
;         for (int i = 0; i < 16; ++i) {
;             int sh = __builtin_amdgcn_sdot8((int)uu[i].x, (int)xh.x, 0, false); sh = __builtin_amdgcn_sdot8((int)uu[i].y, (int)xh.y, sh, false);
;             sh = __builtin_amdgcn_sdot8((int)uu[i].z, (int)xh.z, sh, false); sh = __builtin_amdgcn_sdot8((int)uu[i].w, (int)xh.w, sh, false);
;             int sl = __builtin_amdgcn_sdot8((int)uu[i].x, (int)xl.x, 0, false); sl = __builtin_amdgcn_sdot8((int)uu[i].y, (int)xl.y, sl, false);
;             sl = __builtin_amdgcn_sdot8((int)uu[i].z, (int)xl.z, sl, false); sl = __builtin_amdgcn_sdot8((int)uu[i].w, (int)xl.w, sl, false);
;             d[i] = (sh << 4) + sl;
	v_lshl_add_u32 v19, v36, 4, v37
	v_dot8_i32_i4 v34, v130, v194, 0
	v_dot8_i32_i4 v35, v130, v198, 0
	v_dot8_i32_i4 v34, v131, v195, v34
	v_dot8_i32_i4 v35, v131, v199, v35
	v_dot8_i32_i4 v34, v132, v196, v34
	v_dot8_i32_i4 v35, v132, v200, v35
	v_dot8_i32_i4 v34, v133, v197, v34
	v_dot8_i32_i4 v35, v133, v201, v35
	v_mad_u32_u16 v38, v203, s94, v58
	global_load_dwordx4 v[130:133], v38, s[96:97]
	s_waitcnt vmcnt(17)
	v_lshl_add_u32 v20, v34, 4, v35
	v_dot8_i32_i4 v36, v134, v194, 0
	v_dot8_i32_i4 v37, v134, v198, 0
	v_dot8_i32_i4 v36, v135, v195, v36
	v_dot8_i32_i4 v37, v135, v199, v37
	v_dot8_i32_i4 v36, v136, v196, v36
	v_dot8_i32_i4 v37, v136, v200, v37
	v_dot8_i32_i4 v36, v137, v197, v36
	v_dot8_i32_i4 v37, v137, v201, v37
	v_mad_u32_u16 v38, v203, s94, v58 op_sel:[1,0,0,0]
	global_load_dwordx4 v[134:137], v38, s[96:97]
	s_waitcnt vmcnt(17)
	v_lshl_add_u32 v21, v36, 4, v37
	v_dot8_i32_i4 v34, v138, v194, 0
	v_dot8_i32_i4 v35, v138, v198, 0
	v_dot8_i32_i4 v34, v139, v195, v34
	v_dot8_i32_i4 v35, v139, v199, v35
	v_dot8_i32_i4 v34, v140, v196, v34
	v_dot8_i32_i4 v35, v140, v200, v35
	v_dot8_i32_i4 v34, v141, v197, v34
	v_dot8_i32_i4 v35, v141, v201, v35
	v_mad_u32_u16 v38, v204, s94, v58
	global_load_dwordx4 v[138:141], v38, s[96:97]
	s_waitcnt vmcnt(17)
	v_lshl_add_u32 v22, v34, 4, v35
	v_dot8_i32_i4 v36, v142, v194, 0
	v_dot8_i32_i4 v37, v142, v198, 0
	v_dot8_i32_i4 v36, v143, v195, v36
	v_dot8_i32_i4 v37, v143, v199, v37
	v_dot8_i32_i4 v36, v144, v196, v36
	v_dot8_i32_i4 v37, v144, v200, v37
	v_dot8_i32_i4 v36, v145, v197, v36
	v_dot8_i32_i4 v37, v145, v201, v37
	v_mad_u32_u16 v38, v204, s94, v58 op_sel:[1,0,0,0]
	global_load_dwordx4 v[142:145], v38, s[96:97]
	s_waitcnt vmcnt(17)
	v_lshl_add_u32 v23, v36, 4, v37
	v_dot8_i32_i4 v34, v146, v194, 0
	v_dot8_i32_i4 v35, v146, v198, 0
	v_dot8_i32_i4 v34, v147, v195, v34
	v_dot8_i32_i4 v35, v147, v199, v35
	v_dot8_i32_i4 v34, v148, v196, v34
	v_dot8_i32_i4 v35, v148, v200, v35
	v_dot8_i32_i4 v34, v149, v197, v34
	v_dot8_i32_i4 v35, v149, v201, v35
	v_mad_u32_u16 v38, v205, s94, v58
	global_load_dwordx4 v[146:149], v38, s[96:97]
	s_waitcnt vmcnt(17)
	v_lshl_add_u32 v24, v34, 4, v35
	v_dot8_i32_i4 v36, v150, v194, 0
	v_dot8_i32_i4 v37, v150, v198, 0
	v_dot8_i32_i4 v36, v151, v195, v36
	v_dot8_i32_i4 v37, v151, v199, v37
	v_dot8_i32_i4 v36, v152, v196, v36
	v_dot8_i32_i4 v37, v152, v200, v37
	v_dot8_i32_i4 v36, v153, v197, v36
	v_dot8_i32_i4 v37, v153, v201, v37
	v_mad_u32_u16 v38, v205, s94, v58 op_sel:[1,0,0,0]
	global_load_dwordx4 v[150:153], v38, s[96:97]
	s_waitcnt vmcnt(17)
	v_lshl_add_u32 v25, v36, 4, v37
	v_dot8_i32_i4 v34, v154, v194, 0
	v_dot8_i32_i4 v35, v154, v198, 0
	v_dot8_i32_i4 v34, v155, v195, v34
	v_dot8_i32_i4 v35, v155, v199, v35
	v_dot8_i32_i4 v34, v156, v196, v34
	v_dot8_i32_i4 v35, v156, v200, v35
	v_dot8_i32_i4 v34, v157, v197, v34
	v_dot8_i32_i4 v35, v157, v201, v35
	v_mad_u32_u16 v38, v206, s94, v58
	global_load_dwordx4 v[154:157], v38, s[96:97]
	s_waitcnt vmcnt(17)
	v_lshl_add_u32 v26, v34, 4, v35
	v_dot8_i32_i4 v36, v158, v194, 0
	v_dot8_i32_i4 v37, v158, v198, 0
	v_dot8_i32_i4 v36, v159, v195, v36
	v_dot8_i32_i4 v37, v159, v199, v37
	v_dot8_i32_i4 v36, v160, v196, v36
	v_dot8_i32_i4 v37, v160, v200, v37
	v_dot8_i32_i4 v36, v161, v197, v36
	v_dot8_i32_i4 v37, v161, v201, v37
	v_mad_u32_u16 v38, v206, s94, v58 op_sel:[1,0,0,0]
	global_load_dwordx4 v[158:161], v38, s[96:97]
	s_waitcnt vmcnt(17)
	v_lshl_add_u32 v27, v36, 4, v37
	v_dot8_i32_i4 v34, v162, v194, 0
	v_dot8_i32_i4 v35, v162, v198, 0
	v_dot8_i32_i4 v34, v163, v195, v34
	v_dot8_i32_i4 v35, v163, v199, v35
	v_dot8_i32_i4 v34, v164, v196, v34
	v_dot8_i32_i4 v35, v164, v200, v35
	v_dot8_i32_i4 v34, v165, v197, v34
	v_dot8_i32_i4 v35, v165, v201, v35
	v_mad_u32_u16 v38, v207, s94, v58
	global_load_dwordx4 v[162:165], v38, s[96:97]
	s_waitcnt vmcnt(17)
	v_lshl_add_u32 v28, v34, 4, v35
	v_dot8_i32_i4 v36, v166, v194, 0
	v_dot8_i32_i4 v37, v166, v198, 0
	v_dot8_i32_i4 v36, v167, v195, v36
	v_dot8_i32_i4 v37, v167, v199, v37
	v_dot8_i32_i4 v36, v168, v196, v36
	v_dot8_i32_i4 v37, v168, v200, v37
	v_dot8_i32_i4 v36, v169, v197, v36
	v_dot8_i32_i4 v37, v169, v201, v37
	v_mad_u32_u16 v38, v207, s94, v58 op_sel:[1,0,0,0]
	global_load_dwordx4 v[166:169], v38, s[96:97]
	s_waitcnt vmcnt(17)
	v_lshl_add_u32 v29, v36, 4, v37
	v_dot8_i32_i4 v34, v170, v194, 0
	v_dot8_i32_i4 v35, v170, v198, 0
	v_dot8_i32_i4 v34, v171, v195, v34
	v_dot8_i32_i4 v35, v171, v199, v35
	v_dot8_i32_i4 v34, v172, v196, v34
	v_dot8_i32_i4 v35, v172, v200, v35
	v_dot8_i32_i4 v34, v173, v197, v34
	v_dot8_i32_i4 v35, v173, v201, v35
	v_mad_u32_u16 v38, v208, s94, v58
	global_load_dwordx4 v[170:173], v38, s[96:97]
	s_waitcnt vmcnt(17)
	v_lshl_add_u32 v30, v34, 4, v35
	v_dot8_i32_i4 v36, v174, v194, 0
	v_dot8_i32_i4 v37, v174, v198, 0
	v_dot8_i32_i4 v36, v175, v195, v36
	v_dot8_i32_i4 v37, v175, v199, v37
	v_dot8_i32_i4 v36, v176, v196, v36
	v_dot8_i32_i4 v37, v176, v200, v37
	v_dot8_i32_i4 v36, v177, v197, v36
	v_dot8_i32_i4 v37, v177, v201, v37
	v_mad_u32_u16 v38, v208, s94, v58 op_sel:[1,0,0,0]
	global_load_dwordx4 v[174:177], v38, s[96:97]
	s_waitcnt vmcnt(17)
	v_lshl_add_u32 v31, v36, 4, v37
	v_dot8_i32_i4 v34, v178, v194, 0
	v_dot8_i32_i4 v35, v178, v198, 0
	v_dot8_i32_i4 v34, v179, v195, v34
	v_dot8_i32_i4 v35, v179, v199, v35
	v_dot8_i32_i4 v34, v180, v196, v34
	v_dot8_i32_i4 v35, v180, v200, v35
	v_dot8_i32_i4 v34, v181, v197, v34
	v_dot8_i32_i4 v35, v181, v201, v35
	v_mad_u32_u16 v38, v209, s94, v58
	global_load_dwordx4 v[178:181], v38, s[96:97]
	s_waitcnt vmcnt(17)
; #define LAS __attribute__((address_space(3)))
; template <int M4, int M2, int M1> __device__ __forceinline__ void treduce16i(const int (&a)[16], int lane, int& r0, int& r1) {
;     int b[8], c[4];
;     { const bool hi = (lane & M4) != 0;
; #pragma unroll
;       for (int i = 0; i < 8; ++i) { const int send = hi ? a[i] : a[i + 8]; const int recv = __shfl_xor(send, M4); b[i] = (hi ? a[i + 8] : a[i]) + recv; } }
;     { const bool hi = (lane & M2) != 0;
; #pragma unroll
;       for (int i = 0; i < 4; ++i) { const int send = hi ? b[i] : b[i + 4]; const int recv = __shfl_xor(send, M2); c[i] = (hi ? b[i + 4] : b[i]) + recv; } }
;     { const bool hi = (lane & M1) != 0;
;       { const int send = hi ? c[0] : c[2]; const int recv = __shfl_xor(send, M1); r0 = (hi ? c[2] : c[0]) + recv; }
;       { const int send = hi ? c[1] : c[3]; const int recv = __shfl_xor(send, M1); r1 = (hi ? c[3] : c[1]) + recv; } }
; }
; __device__ __forceinline__ void treduce16i_hw(const int (&a)[16], int lane, int& r0, int& r1) {
;     int b[8], c[4];
; #pragma unroll
;     for (int i = 0; i < 8; ++i) { const auto r = __builtin_amdgcn_permlane32_swap((unsigned)a[i], (unsigned)a[i + 8], false, false); b[i] = (int)r[0] + (int)r[1]; }
; #pragma unroll
;     for (int i = 0; i < 4; ++i) { const auto r = __builtin_amdgcn_permlane16_swap((unsigned)b[i], (unsigned)b[i + 4], false, false); c[i] = (int)r[0] + (int)r[1]; }
;     const bool hi = (lane & 8) != 0;
;     { const int send = hi ? c[0] : c[2]; r0 = (hi ? c[2] : c[0]) + __builtin_amdgcn_update_dpp(0, send, 0x128, 0xf, 0xf, false); }
;     { const int send = hi ? c[1] : c[3]; r1 = (hi ? c[3] : c[1]) + __builtin_amdgcn_update_dpp(0, send, 0x128, 0xf, 0xf, false); }
; }
; __device__ __forceinline__ void peer_u_item(int p, int j, const LAS unsigned short* EL  , const unsigned char* __restrict__ XQ, const unsigned char* __restrict__ U8, LAS int* ACC  , int lane, int wave) {
;     asm volatile("" : "+v"(lane));
;     const int gidx = lane >> 3; const unsigned coff = (unsigned)(p * 128 + (lane & 7) * 16), toff = (unsigned)(p * (16384 * 128) + (lane & 7) * 16);
; #pragma unroll 1
;     for (int it = 0; it < 8; ++it) {
;         const int t = j * 64 + it * 8 + wave;
;         unsigned E[8];
;         { const LAS v4u* ep = (const LAS v4u*)(EL + (it * 8 + wave) * 128 + 16 * gidx); const v4u e0 = ep[0], e1 = ep[1];
	v_lshl_add_u32 v32, v34, 4, v35
	v_dot8_i32_i4 v36, v182, v194, 0
	v_dot8_i32_i4 v37, v182, v198, 0
	v_dot8_i32_i4 v36, v183, v195, v36
	v_dot8_i32_i4 v37, v183, v199, v37
	v_dot8_i32_i4 v36, v184, v196, v36
	v_dot8_i32_i4 v37, v184, v200, v37
	v_dot8_i32_i4 v36, v185, v197, v36
	v_dot8_i32_i4 v37, v185, v201, v37
	v_mad_u32_u16 v38, v209, s94, v58 op_sel:[1,0,0,0]
	global_load_dwordx4 v[182:185], v38, s[96:97]
	s_nop 0
	v_lshl_add_u32 v33, v36, 4, v37
	v_add_u32_dpp v40, v26, v26 row_shr:4 row_mask:0xf bank_mask:0xa
	v_add_u32_dpp v40, v18, v18 row_shl:4 row_mask:0xf bank_mask:0x5
	v_add_u32_dpp v41, v27, v27 row_shr:4 row_mask:0xf bank_mask:0xa
	v_add_u32_dpp v41, v19, v19 row_shl:4 row_mask:0xf bank_mask:0x5
	v_add_u32_dpp v42, v28, v28 row_shr:4 row_mask:0xf bank_mask:0xa
	v_add_u32_dpp v42, v20, v20 row_shl:4 row_mask:0xf bank_mask:0x5
	v_add_u32_dpp v43, v29, v29 row_shr:4 row_mask:0xf bank_mask:0xa
	v_add_u32_dpp v43, v21, v21 row_shl:4 row_mask:0xf bank_mask:0x5
	v_add_u32_dpp v44, v30, v30 row_shr:4 row_mask:0xf bank_mask:0xa
	v_add_u32_dpp v44, v22, v22 row_shl:4 row_mask:0xf bank_mask:0x5
	v_add_u32_dpp v45, v31, v31 row_shr:4 row_mask:0xf bank_mask:0xa
	v_add_u32_dpp v45, v23, v23 row_shl:4 row_mask:0xf bank_mask:0x5
	v_add_u32_dpp v46, v32, v32 row_shr:4 row_mask:0xf bank_mask:0xa
	v_add_u32_dpp v46, v24, v24 row_shl:4 row_mask:0xf bank_mask:0x5
	v_add_u32_dpp v47, v33, v33 row_shr:4 row_mask:0xf bank_mask:0xa
	v_add_u32_dpp v47, v25, v25 row_shl:4 row_mask:0xf bank_mask:0x5
	v_cndmask_b32_e64 v18, v44, v40, s[12:13]
	v_cndmask_b32_e64 v22, v40, v44, s[12:13]
	v_cndmask_b32_e64 v19, v45, v41, s[12:13]
	v_cndmask_b32_e64 v23, v41, v45, s[12:13]
	v_cndmask_b32_e64 v20, v46, v42, s[12:13]
	v_cndmask_b32_e64 v24, v42, v46, s[12:13]
	v_cndmask_b32_e64 v21, v47, v43, s[12:13]
	v_cndmask_b32_e64 v25, v43, v47, s[12:13]
	s_nop 0
	v_add_u32_dpp v26, v18, v22 quad_perm:[2,3,0,1] row_mask:0xf bank_mask:0xf
	v_add_u32_dpp v27, v19, v23 quad_perm:[2,3,0,1] row_mask:0xf bank_mask:0xf
	v_add_u32_dpp v28, v20, v24 quad_perm:[2,3,0,1] row_mask:0xf bank_mask:0xf
	v_add_u32_dpp v29, v21, v25 quad_perm:[2,3,0,1] row_mask:0xf bank_mask:0xf
	v_cndmask_b32_e64 v40, v28, v26, s[14:15]
	v_cndmask_b32_e64 v48, v26, v28, s[14:15]
	v_cndmask_b32_e64 v41, v29, v27, s[14:15]
	v_cndmask_b32_e64 v49, v27, v29, s[14:15]
	s_nop 1
	v_add_u32_dpp v44, v40, v48 quad_perm:[1,0,3,2] row_mask:0xf bank_mask:0xf
	v_add_u32_dpp v45, v41, v49 quad_perm:[1,0,3,2] row_mask:0xf bank_mask:0xf
	s_cmp_eq_u32 s43, 0
	s_cselect_b32 s32, 0, -1
	v_and_b32_e32 v62, s32, v62
	v_and_b32_e32 v63, s32, v63
	v_add_u32_e32 v44, v44, v62
	v_add_u32_e32 v45, v45, v63
	ds_write_b64 v61, v[44:45]
	s_mov_b32 s42, s44
	s_mov_b32 s43, s45
	s_add_i32 s44, s44, 1
	s_and_b32 s44, s44, 7
	s_cmp_eq_u32 s44, 0
	s_cselect_b32 s32, 1, 0
	s_add_i32 s45, s45, s32
	s_and_b32 s45, s45, 3
	s_add_i32 s47, s47, -1
	s_cmp_lg_u32 s47, 0
	s_cbranch_scc1 .Lpu_trip
	s_lshl_b32 s32, s44, 11
	v_add_u32_e32 v39, s32, v59
	ds_read_b128 v[210:213], v39
	ds_read_b128 v[214:217], v39 offset:16
	s_lshl_b32 s32, s42, 12
	v_add_u32_e32 v61, s32, v60
	ds_read_b64 v[62:63], v61
	s_lshl_b32 s46, s44, 3
	s_add_i32 s46, s46, s40
	s_lshl_b32 s46, s46, 9
	s_lshl_b32 s32, s45, 7
	s_add_i32 s46, s46, s32
	v_add_u32_e32 v57, s46, v56
	global_load_dwordx4 v[194:197], v57, s[34:35]
	global_load_dwordx4 v[198:201], v57, s[36:37]
	s_lshl_b32 s32, s45, 21
	v_add_u32_e32 v58, s32, v56
	s_waitcnt lgkmcnt(0)
	s_waitcnt vmcnt(17)
	v_dot8_i32_i4 v34, v122, v186, 0
	v_dot8_i32_i4 v35, v122, v190, 0
	v_dot8_i32_i4 v34, v123, v187, v34
	v_dot8_i32_i4 v35, v123, v191, v35
	v_dot8_i32_i4 v34, v124, v188, v34
	v_dot8_i32_i4 v35, v124, v192, v35
	v_dot8_i32_i4 v34, v125, v189, v34
	v_dot8_i32_i4 v35, v125, v193, v35
	v_mad_u32_u16 v38, v210, s94, v58
	global_load_dwordx4 v[122:125], v38, s[96:97]
	s_waitcnt vmcnt(17)
	v_lshl_add_u32 v18, v34, 4, v35
	v_dot8_i32_i4 v36, v126, v186, 0
	v_dot8_i32_i4 v37, v126, v190, 0
	v_dot8_i32_i4 v36, v127, v187, v36
	v_dot8_i32_i4 v37, v127, v191, v37
	v_dot8_i32_i4 v36, v128, v188, v36
	v_dot8_i32_i4 v37, v128, v192, v37
	v_dot8_i32_i4 v36, v129, v189, v36
	v_dot8_i32_i4 v37, v129, v193, v37
	v_mad_u32_u16 v38, v210, s94, v58 op_sel:[1,0,0,0]
	global_load_dwordx4 v[126:129], v38, s[96:97]
	s_waitcnt vmcnt(17)
	v_lshl_add_u32 v19, v36, 4, v37
	v_dot8_i32_i4 v34, v130, v186, 0
	v_dot8_i32_i4 v35, v130, v190, 0
	v_dot8_i32_i4 v34, v131, v187, v34
	v_dot8_i32_i4 v35, v131, v191, v35
	v_dot8_i32_i4 v34, v132, v188, v34
	v_dot8_i32_i4 v35, v132, v192, v35
	v_dot8_i32_i4 v34, v133, v189, v34
	v_dot8_i32_i4 v35, v133, v193, v35
	v_mad_u32_u16 v38, v211, s94, v58
	global_load_dwordx4 v[130:133], v38, s[96:97]
	s_waitcnt vmcnt(17)
	v_lshl_add_u32 v20, v34, 4, v35
	v_dot8_i32_i4 v36, v134, v186, 0
	v_dot8_i32_i4 v37, v134, v190, 0
	v_dot8_i32_i4 v36, v135, v187, v36
	v_dot8_i32_i4 v37, v135, v191, v37
	v_dot8_i32_i4 v36, v136, v188, v36
	v_dot8_i32_i4 v37, v136, v192, v37
	v_dot8_i32_i4 v36, v137, v189, v36
	v_dot8_i32_i4 v37, v137, v193, v37
	v_mad_u32_u16 v38, v211, s94, v58 op_sel:[1,0,0,0]
	global_load_dwordx4 v[134:137], v38, s[96:97]
	s_waitcnt vmcnt(17)
	v_lshl_add_u32 v21, v36, 4, v37
	v_dot8_i32_i4 v34, v138, v186, 0
	v_dot8_i32_i4 v35, v138, v190, 0
	v_dot8_i32_i4 v34, v139, v187, v34
	v_dot8_i32_i4 v35, v139, v191, v35
	v_dot8_i32_i4 v34, v140, v188, v34
	v_dot8_i32_i4 v35, v140, v192, v35
	v_dot8_i32_i4 v34, v141, v189, v34
	v_dot8_i32_i4 v35, v141, v193, v35
	v_mad_u32_u16 v38, v212, s94, v58
	global_load_dwordx4 v[138:141], v38, s[96:97]
	s_waitcnt vmcnt(17)
; __device__ __forceinline__ void peer_u_item(int p, int j, const LAS unsigned short* EL  , const unsigned char* __restrict__ XQ, const unsigned char* __restrict__ U8, LAS int* ACC  , int lane, int wave) {
;     ...
;         for (int i = 0; i < 16; ++i) uu[i] = *(const uint4*)(U8 + (size_t)(PE_ID(E, i) * 128u + toff));
;         const uint4 xh = *(const uint4*)(XQ + (size_t)t * 512 + coff), xl = *(const uint4*)(XQ + 8 * MiB + (size_t)t * 512 + coff);
;         int d[16];
; #pragma unroll
;         for (int i = 0; i < 16; ++i) {
;             int sh = __builtin_amdgcn_sdot8((int)uu[i].x, (int)xh.x, 0, false); sh = __builtin_amdgcn_sdot8((int)uu[i].y, (int)xh.y, sh, false);
;             sh = __builtin_amdgcn_sdot8((int)uu[i].z, (int)xh.z, sh, false); sh = __builtin_amdgcn_sdot8((int)uu[i].w, (int)xh.w, sh, false);
;             int sl = __builtin_amdgcn_sdot8((int)uu[i].x, (int)xl.x, 0, false); sl = __builtin_amdgcn_sdot8((int)uu[i].y, (int)xl.y, sl, false);
;             sl = __builtin_amdgcn_sdot8((int)uu[i].z, (int)xl.z, sl, false); sl = __builtin_amdgcn_sdot8((int)uu[i].w, (int)xl.w, sl, false);
;             d[i] = (sh << 4) + sl;
	v_lshl_add_u32 v22, v34, 4, v35
	v_dot8_i32_i4 v36, v142, v186, 0
	v_dot8_i32_i4 v37, v142, v190, 0
	v_dot8_i32_i4 v36, v143, v187, v36
	v_dot8_i32_i4 v37, v143, v191, v37
	v_dot8_i32_i4 v36, v144, v188, v36
	v_dot8_i32_i4 v37, v144, v192, v37
	v_dot8_i32_i4 v36, v145, v189, v36
	v_dot8_i32_i4 v37, v145, v193, v37
	v_mad_u32_u16 v38, v212, s94, v58 op_sel:[1,0,0,0]
	global_load_dwordx4 v[142:145], v38, s[96:97]
	s_waitcnt vmcnt(17)
	v_lshl_add_u32 v23, v36, 4, v37
	v_dot8_i32_i4 v34, v146, v186, 0
	v_dot8_i32_i4 v35, v146, v190, 0
	v_dot8_i32_i4 v34, v147, v187, v34
	v_dot8_i32_i4 v35, v147, v191, v35
	v_dot8_i32_i4 v34, v148, v188, v34
	v_dot8_i32_i4 v35, v148, v192, v35
	v_dot8_i32_i4 v34, v149, v189, v34
	v_dot8_i32_i4 v35, v149, v193, v35
	v_mad_u32_u16 v38, v213, s94, v58
	global_load_dwordx4 v[146:149], v38, s[96:97]
	s_waitcnt vmcnt(17)
	v_lshl_add_u32 v24, v34, 4, v35
	v_dot8_i32_i4 v36, v150, v186, 0
	v_dot8_i32_i4 v37, v150, v190, 0
	v_dot8_i32_i4 v36, v151, v187, v36
	v_dot8_i32_i4 v37, v151, v191, v37
	v_dot8_i32_i4 v36, v152, v188, v36
	v_dot8_i32_i4 v37, v152, v192, v37
	v_dot8_i32_i4 v36, v153, v189, v36
	v_dot8_i32_i4 v37, v153, v193, v37
	v_mad_u32_u16 v38, v213, s94, v58 op_sel:[1,0,0,0]
	global_load_dwordx4 v[150:153], v38, s[96:97]
	s_waitcnt vmcnt(17)
	v_lshl_add_u32 v25, v36, 4, v37
	v_dot8_i32_i4 v34, v154, v186, 0
	v_dot8_i32_i4 v35, v154, v190, 0
	v_dot8_i32_i4 v34, v155, v187, v34
	v_dot8_i32_i4 v35, v155, v191, v35
	v_dot8_i32_i4 v34, v156, v188, v34
	v_dot8_i32_i4 v35, v156, v192, v35
	v_dot8_i32_i4 v34, v157, v189, v34
	v_dot8_i32_i4 v35, v157, v193, v35
	v_mad_u32_u16 v38, v214, s94, v58
	global_load_dwordx4 v[154:157], v38, s[96:97]
	s_waitcnt vmcnt(17)
	v_lshl_add_u32 v26, v34, 4, v35
	v_dot8_i32_i4 v36, v158, v186, 0
	v_dot8_i32_i4 v37, v158, v190, 0
	v_dot8_i32_i4 v36, v159, v187, v36
	v_dot8_i32_i4 v37, v159, v191, v37
	v_dot8_i32_i4 v36, v160, v188, v36
	v_dot8_i32_i4 v37, v160, v192, v37
	v_dot8_i32_i4 v36, v161, v189, v36
	v_dot8_i32_i4 v37, v161, v193, v37
	v_mad_u32_u16 v38, v214, s94, v58 op_sel:[1,0,0,0]
	global_load_dwordx4 v[158:161], v38, s[96:97]
	s_waitcnt vmcnt(17)
	v_lshl_add_u32 v27, v36, 4, v37
	v_dot8_i32_i4 v34, v162, v186, 0
	v_dot8_i32_i4 v35, v162, v190, 0
	v_dot8_i32_i4 v34, v163, v187, v34
	v_dot8_i32_i4 v35, v163, v191, v35
	v_dot8_i32_i4 v34, v164, v188, v34
	v_dot8_i32_i4 v35, v164, v192, v35
	v_dot8_i32_i4 v34, v165, v189, v34
	v_dot8_i32_i4 v35, v165, v193, v35
	v_mad_u32_u16 v38, v215, s94, v58
	global_load_dwordx4 v[162:165], v38, s[96:97]
	s_waitcnt vmcnt(17)
	v_lshl_add_u32 v28, v34, 4, v35
	v_dot8_i32_i4 v36, v166, v186, 0
	v_dot8_i32_i4 v37, v166, v190, 0
	v_dot8_i32_i4 v36, v167, v187, v36
	v_dot8_i32_i4 v37, v167, v191, v37
	v_dot8_i32_i4 v36, v168, v188, v36
	v_dot8_i32_i4 v37, v168, v192, v37
	v_dot8_i32_i4 v36, v169, v189, v36
	v_dot8_i32_i4 v37, v169, v193, v37
	v_mad_u32_u16 v38, v215, s94, v58 op_sel:[1,0,0,0]
	global_load_dwordx4 v[166:169], v38, s[96:97]
	s_waitcnt vmcnt(17)
	v_lshl_add_u32 v29, v36, 4, v37
	v_dot8_i32_i4 v34, v170, v186, 0
	v_dot8_i32_i4 v35, v170, v190, 0
	v_dot8_i32_i4 v34, v171, v187, v34
	v_dot8_i32_i4 v35, v171, v191, v35
	v_dot8_i32_i4 v34, v172, v188, v34
	v_dot8_i32_i4 v35, v172, v192, v35
	v_dot8_i32_i4 v34, v173, v189, v34
	v_dot8_i32_i4 v35, v173, v193, v35
	v_mad_u32_u16 v38, v216, s94, v58
	global_load_dwordx4 v[170:173], v38, s[96:97]
	s_waitcnt vmcnt(17)
	v_lshl_add_u32 v30, v34, 4, v35
	v_dot8_i32_i4 v36, v174, v186, 0
	v_dot8_i32_i4 v37, v174, v190, 0
	v_dot8_i32_i4 v36, v175, v187, v36
	v_dot8_i32_i4 v37, v175, v191, v37
	v_dot8_i32_i4 v36, v176, v188, v36
	v_dot8_i32_i4 v37, v176, v192, v37
	v_dot8_i32_i4 v36, v177, v189, v36
	v_dot8_i32_i4 v37, v177, v193, v37
	v_mad_u32_u16 v38, v216, s94, v58 op_sel:[1,0,0,0]
	global_load_dwordx4 v[174:177], v38, s[96:97]
	s_waitcnt vmcnt(17)
	v_lshl_add_u32 v31, v36, 4, v37
	v_dot8_i32_i4 v34, v178, v186, 0
	v_dot8_i32_i4 v35, v178, v190, 0
	v_dot8_i32_i4 v34, v179, v187, v34
	v_dot8_i32_i4 v35, v179, v191, v35
	v_dot8_i32_i4 v34, v180, v188, v34
	v_dot8_i32_i4 v35, v180, v192, v35
	v_dot8_i32_i4 v34, v181, v189, v34
	v_dot8_i32_i4 v35, v181, v193, v35
	v_mad_u32_u16 v38, v217, s94, v58
	global_load_dwordx4 v[178:181], v38, s[96:97]
	s_waitcnt vmcnt(17)
; #define LAS __attribute__((address_space(3)))
; template <int M4, int M2, int M1> __device__ __forceinline__ void treduce16i(const int (&a)[16], int lane, int& r0, int& r1) {
;     int b[8], c[4];
;     { const bool hi = (lane & M4) != 0;
; #pragma unroll
;       for (int i = 0; i < 8; ++i) { const int send = hi ? a[i] : a[i + 8]; const int recv = __shfl_xor(send, M4); b[i] = (hi ? a[i + 8] : a[i]) + recv; } }
;     { const bool hi = (lane & M2) != 0;
; #pragma unroll
;       for (int i = 0; i < 4; ++i) { const int send = hi ? b[i] : b[i + 4]; const int recv = __shfl_xor(send, M2); c[i] = (hi ? b[i + 4] : b[i]) + recv; } }
;     { const bool hi = (lane & M1) != 0;
;       { const int send = hi ? c[0] : c[2]; const int recv = __shfl_xor(send, M1); r0 = (hi ? c[2] : c[0]) + recv; }
;       { const int send = hi ? c[1] : c[3]; const int recv = __shfl_xor(send, M1); r1 = (hi ? c[3] : c[1]) + recv; } }
; }
; __device__ __forceinline__ void treduce16i_hw(const int (&a)[16], int lane, int& r0, int& r1) {
;     int b[8], c[4];
; #pragma unroll
;     for (int i = 0; i < 8; ++i) { const auto r = __builtin_amdgcn_permlane32_swap((unsigned)a[i], (unsigned)a[i + 8], false, false); b[i] = (int)r[0] + (int)r[1]; }
; #pragma unroll
;     for (int i = 0; i < 4; ++i) { const auto r = __builtin_amdgcn_permlane16_swap((unsigned)b[i], (unsigned)b[i + 4], false, false); c[i] = (int)r[0] + (int)r[1]; }
;     const bool hi = (lane & 8) != 0;
;     { const int send = hi ? c[0] : c[2]; r0 = (hi ? c[2] : c[0]) + __builtin_amdgcn_update_dpp(0, send, 0x128, 0xf, 0xf, false); }
;     { const int send = hi ? c[1] : c[3]; r1 = (hi ? c[3] : c[1]) + __builtin_amdgcn_update_dpp(0, send, 0x128, 0xf, 0xf, false); }
; }
; __device__ __forceinline__ void peer_u_item(int p, int j, const LAS unsigned short* EL  , const unsigned char* __restrict__ XQ, const unsigned char* __restrict__ U8, LAS int* ACC  , int lane, int wave) {
;     asm volatile("" : "+v"(lane));
;     const int gidx = lane >> 3; const unsigned coff = (unsigned)(p * 128 + (lane & 7) * 16), toff = (unsigned)(p * (16384 * 128) + (lane & 7) * 16);
; #pragma unroll 1
;     for (int it = 0; it < 8; ++it) {
;         const int t = j * 64 + it * 8 + wave;
;         unsigned E[8];
;         { const LAS v4u* ep = (const LAS v4u*)(EL + (it * 8 + wave) * 128 + 16 * gidx); const v4u e0 = ep[0], e1 = ep[1];
	v_lshl_add_u32 v32, v34, 4, v35
	v_dot8_i32_i4 v36, v182, v186, 0
	v_dot8_i32_i4 v37, v182, v190, 0
	v_dot8_i32_i4 v36, v183, v187, v36
	v_dot8_i32_i4 v37, v183, v191, v37
	v_dot8_i32_i4 v36, v184, v188, v36
	v_dot8_i32_i4 v37, v184, v192, v37
	v_dot8_i32_i4 v36, v185, v189, v36
	v_dot8_i32_i4 v37, v185, v193, v37
	v_mad_u32_u16 v38, v217, s94, v58 op_sel:[1,0,0,0]
	global_load_dwordx4 v[182:185], v38, s[96:97]
	s_nop 0
	v_lshl_add_u32 v33, v36, 4, v37
	v_add_u32_dpp v40, v26, v26 row_shr:4 row_mask:0xf bank_mask:0xa
	v_add_u32_dpp v40, v18, v18 row_shl:4 row_mask:0xf bank_mask:0x5
	v_add_u32_dpp v41, v27, v27 row_shr:4 row_mask:0xf bank_mask:0xa
	v_add_u32_dpp v41, v19, v19 row_shl:4 row_mask:0xf bank_mask:0x5
	v_add_u32_dpp v42, v28, v28 row_shr:4 row_mask:0xf bank_mask:0xa
	v_add_u32_dpp v42, v20, v20 row_shl:4 row_mask:0xf bank_mask:0x5
	v_add_u32_dpp v43, v29, v29 row_shr:4 row_mask:0xf bank_mask:0xa
	v_add_u32_dpp v43, v21, v21 row_shl:4 row_mask:0xf bank_mask:0x5
	v_add_u32_dpp v44, v30, v30 row_shr:4 row_mask:0xf bank_mask:0xa
	v_add_u32_dpp v44, v22, v22 row_shl:4 row_mask:0xf bank_mask:0x5
	v_add_u32_dpp v45, v31, v31 row_shr:4 row_mask:0xf bank_mask:0xa
	v_add_u32_dpp v45, v23, v23 row_shl:4 row_mask:0xf bank_mask:0x5
	v_add_u32_dpp v46, v32, v32 row_shr:4 row_mask:0xf bank_mask:0xa
	v_add_u32_dpp v46, v24, v24 row_shl:4 row_mask:0xf bank_mask:0x5
	v_add_u32_dpp v47, v33, v33 row_shr:4 row_mask:0xf bank_mask:0xa
	v_add_u32_dpp v47, v25, v25 row_shl:4 row_mask:0xf bank_mask:0x5
	v_cndmask_b32_e64 v18, v44, v40, s[12:13]
	v_cndmask_b32_e64 v22, v40, v44, s[12:13]
	v_cndmask_b32_e64 v19, v45, v41, s[12:13]
	v_cndmask_b32_e64 v23, v41, v45, s[12:13]
	v_cndmask_b32_e64 v20, v46, v42, s[12:13]
	v_cndmask_b32_e64 v24, v42, v46, s[12:13]
	v_cndmask_b32_e64 v21, v47, v43, s[12:13]
	v_cndmask_b32_e64 v25, v43, v47, s[12:13]
	s_nop 0
	v_add_u32_dpp v26, v18, v22 quad_perm:[2,3,0,1] row_mask:0xf bank_mask:0xf
	v_add_u32_dpp v27, v19, v23 quad_perm:[2,3,0,1] row_mask:0xf bank_mask:0xf
	v_add_u32_dpp v28, v20, v24 quad_perm:[2,3,0,1] row_mask:0xf bank_mask:0xf
	v_add_u32_dpp v29, v21, v25 quad_perm:[2,3,0,1] row_mask:0xf bank_mask:0xf
	v_cndmask_b32_e64 v40, v28, v26, s[14:15]
	v_cndmask_b32_e64 v48, v26, v28, s[14:15]
	v_cndmask_b32_e64 v41, v29, v27, s[14:15]
	v_cndmask_b32_e64 v49, v27, v29, s[14:15]
	s_nop 1
	v_add_u32_dpp v44, v40, v48 quad_perm:[1,0,3,2] row_mask:0xf bank_mask:0xf
	v_add_u32_dpp v45, v41, v49 quad_perm:[1,0,3,2] row_mask:0xf bank_mask:0xf
	s_cmp_eq_u32 s43, 0
	s_cselect_b32 s32, 0, -1
	v_and_b32_e32 v62, s32, v62
	v_and_b32_e32 v63, s32, v63
	v_add_u32_e32 v44, v44, v62
	v_add_u32_e32 v45, v45, v63
	ds_write_b64 v61, v[44:45]
	s_mov_b32 s42, s44
	s_mov_b32 s43, s45
	s_add_i32 s44, s44, 1
	s_and_b32 s44, s44, 7
	s_cmp_eq_u32 s44, 0
	s_cselect_b32 s32, 1, 0
	s_add_i32 s45, s45, s32
	s_and_b32 s45, s45, 3
	s_lshl_b32 s32, s42, 12
	v_add_u32_e32 v61, s32, v60
	ds_read_b64 v[62:63], v61
	s_waitcnt lgkmcnt(0)
	s_waitcnt vmcnt(15)
	v_dot8_i32_i4 v34, v122, v194, 0
	v_dot8_i32_i4 v35, v122, v198, 0
	v_dot8_i32_i4 v34, v123, v195, v34
	v_dot8_i32_i4 v35, v123, v199, v35
	v_dot8_i32_i4 v34, v124, v196, v34
	v_dot8_i32_i4 v35, v124, v200, v35
	v_dot8_i32_i4 v34, v125, v197, v34
	v_dot8_i32_i4 v35, v125, v201, v35
	s_nop 2
	s_waitcnt vmcnt(14)
	v_lshl_add_u32 v18, v34, 4, v35
	v_dot8_i32_i4 v36, v126, v194, 0
	v_dot8_i32_i4 v37, v126, v198, 0
	v_dot8_i32_i4 v36, v127, v195, v36
	v_dot8_i32_i4 v37, v127, v199, v37
	v_dot8_i32_i4 v36, v128, v196, v36
	v_dot8_i32_i4 v37, v128, v200, v37
	v_dot8_i32_i4 v36, v129, v197, v36
	v_dot8_i32_i4 v37, v129, v201, v37
	s_nop 2
	s_waitcnt vmcnt(13)
	v_lshl_add_u32 v19, v36, 4, v37
	v_dot8_i32_i4 v34, v130, v194, 0
	v_dot8_i32_i4 v35, v130, v198, 0
	v_dot8_i32_i4 v34, v131, v195, v34
	v_dot8_i32_i4 v35, v131, v199, v35
	v_dot8_i32_i4 v34, v132, v196, v34
	v_dot8_i32_i4 v35, v132, v200, v35
	v_dot8_i32_i4 v34, v133, v197, v34
	v_dot8_i32_i4 v35, v133, v201, v35
	s_nop 2
	s_waitcnt vmcnt(12)
	v_lshl_add_u32 v20, v34, 4, v35
	v_dot8_i32_i4 v36, v134, v194, 0
	v_dot8_i32_i4 v37, v134, v198, 0
	v_dot8_i32_i4 v36, v135, v195, v36
	v_dot8_i32_i4 v37, v135, v199, v37
	v_dot8_i32_i4 v36, v136, v196, v36
	v_dot8_i32_i4 v37, v136, v200, v37
	v_dot8_i32_i4 v36, v137, v197, v36
	v_dot8_i32_i4 v37, v137, v201, v37
	s_nop 2
	s_waitcnt vmcnt(11)
	v_lshl_add_u32 v21, v36, 4, v37
	v_dot8_i32_i4 v34, v138, v194, 0
	v_dot8_i32_i4 v35, v138, v198, 0
	v_dot8_i32_i4 v34, v139, v195, v34
	v_dot8_i32_i4 v35, v139, v199, v35
	v_dot8_i32_i4 v34, v140, v196, v34
	v_dot8_i32_i4 v35, v140, v200, v35
	v_dot8_i32_i4 v34, v141, v197, v34
	v_dot8_i32_i4 v35, v141, v201, v35
	s_nop 2
	s_waitcnt vmcnt(10)
	v_lshl_add_u32 v22, v34, 4, v35
	v_dot8_i32_i4 v36, v142, v194, 0
	v_dot8_i32_i4 v37, v142, v198, 0
	v_dot8_i32_i4 v36, v143, v195, v36
	v_dot8_i32_i4 v37, v143, v199, v37
	v_dot8_i32_i4 v36, v144, v196, v36
	v_dot8_i32_i4 v37, v144, v200, v37
	v_dot8_i32_i4 v36, v145, v197, v36
	v_dot8_i32_i4 v37, v145, v201, v37
	s_nop 2
	s_waitcnt vmcnt(9)
	v_lshl_add_u32 v23, v36, 4, v37
	v_dot8_i32_i4 v34, v146, v194, 0
	v_dot8_i32_i4 v35, v146, v198, 0
	v_dot8_i32_i4 v34, v147, v195, v34
	v_dot8_i32_i4 v35, v147, v199, v35
	v_dot8_i32_i4 v34, v148, v196, v34
	v_dot8_i32_i4 v35, v148, v200, v35
	v_dot8_i32_i4 v34, v149, v197, v34
	v_dot8_i32_i4 v35, v149, v201, v35
	s_nop 2
	s_waitcnt vmcnt(8)
	v_lshl_add_u32 v24, v34, 4, v35
	v_dot8_i32_i4 v36, v150, v194, 0
	v_dot8_i32_i4 v37, v150, v198, 0
	v_dot8_i32_i4 v36, v151, v195, v36
	v_dot8_i32_i4 v37, v151, v199, v37
	v_dot8_i32_i4 v36, v152, v196, v36
	v_dot8_i32_i4 v37, v152, v200, v37
	v_dot8_i32_i4 v36, v153, v197, v36
	v_dot8_i32_i4 v37, v153, v201, v37
	s_nop 2
	s_waitcnt vmcnt(7)
; #define LAS __attribute__((address_space(3)))
; template <int M4, int M2, int M1> __device__ __forceinline__ void treduce16i(const int (&a)[16], int lane, int& r0, int& r1) {
;     int b[8], c[4];
;     { const bool hi = (lane & M4) != 0;
; #pragma unroll
;       for (int i = 0; i < 8; ++i) { const int send = hi ? a[i] : a[i + 8]; const int recv = __shfl_xor(send, M4); b[i] = (hi ? a[i + 8] : a[i]) + recv; } }
;     { const bool hi = (lane & M2) != 0;
; #pragma unroll
;       for (int i = 0; i < 4; ++i) { const int send = hi ? b[i] : b[i + 4]; const int recv = __shfl_xor(send, M2); c[i] = (hi ? b[i + 4] : b[i]) + recv; } }
;     { const bool hi = (lane & M1) != 0;
;       { const int send = hi ? c[0] : c[2]; const int recv = __shfl_xor(send, M1); r0 = (hi ? c[2] : c[0]) + recv; }
;       { const int send = hi ? c[1] : c[3]; const int recv = __shfl_xor(send, M1); r1 = (hi ? c[3] : c[1]) + recv; } }
; }
; __device__ __forceinline__ void treduce16i_hw(const int (&a)[16], int lane, int& r0, int& r1) {
;     int b[8], c[4];
; #pragma unroll
;     for (int i = 0; i < 8; ++i) { const auto r = __builtin_amdgcn_permlane32_swap((unsigned)a[i], (unsigned)a[i + 8], false, false); b[i] = (int)r[0] + (int)r[1]; }
; #pragma unroll
;     for (int i = 0; i < 4; ++i) { const auto r = __builtin_amdgcn_permlane16_swap((unsigned)b[i], (unsigned)b[i + 4], false, false); c[i] = (int)r[0] + (int)r[1]; }
;     const bool hi = (lane & 8) != 0;
;     { const int send = hi ? c[0] : c[2]; r0 = (hi ? c[2] : c[0]) + __builtin_amdgcn_update_dpp(0, send, 0x128, 0xf, 0xf, false); }
;     { const int send = hi ? c[1] : c[3]; r1 = (hi ? c[3] : c[1]) + __builtin_amdgcn_update_dpp(0, send, 0x128, 0xf, 0xf, false); }
; }
; __device__ __forceinline__ void peer_u_item(int p, int j, const LAS unsigned short* EL  , const unsigned char* __restrict__ XQ, const unsigned char* __restrict__ U8, LAS int* ACC  , int lane, int wave) {
;     asm volatile("" : "+v"(lane));
;     const int gidx = lane >> 3; const unsigned coff = (unsigned)(p * 128 + (lane & 7) * 16), toff = (unsigned)(p * (16384 * 128) + (lane & 7) * 16);
; #pragma unroll 1
;     for (int it = 0; it < 8; ++it) {
;         const int t = j * 64 + it * 8 + wave;
;         unsigned E[8];
;         { const LAS v4u* ep = (const LAS v4u*)(EL + (it * 8 + wave) * 128 + 16 * gidx); const v4u e0 = ep[0], e1 = ep[1];
	v_lshl_add_u32 v25, v36, 4, v37
	v_dot8_i32_i4 v34, v154, v194, 0
	v_dot8_i32_i4 v35, v154, v198, 0
	v_dot8_i32_i4 v34, v155, v195, v34
	v_dot8_i32_i4 v35, v155, v199, v35
	v_dot8_i32_i4 v34, v156, v196, v34
	v_dot8_i32_i4 v35, v156, v200, v35
	v_dot8_i32_i4 v34, v157, v197, v34
	v_dot8_i32_i4 v35, v157, v201, v35
	s_nop 2
	s_waitcnt vmcnt(6)
	v_lshl_add_u32 v26, v34, 4, v35
	v_dot8_i32_i4 v36, v158, v194, 0
	v_dot8_i32_i4 v37, v158, v198, 0
	v_dot8_i32_i4 v36, v159, v195, v36
	v_dot8_i32_i4 v37, v159, v199, v37
	v_dot8_i32_i4 v36, v160, v196, v36
	v_dot8_i32_i4 v37, v160, v200, v37
	v_dot8_i32_i4 v36, v161, v197, v36
	v_dot8_i32_i4 v37, v161, v201, v37
	s_nop 2
	s_waitcnt vmcnt(5)
	v_lshl_add_u32 v27, v36, 4, v37
	v_dot8_i32_i4 v34, v162, v194, 0
	v_dot8_i32_i4 v35, v162, v198, 0
	v_dot8_i32_i4 v34, v163, v195, v34
	v_dot8_i32_i4 v35, v163, v199, v35
	v_dot8_i32_i4 v34, v164, v196, v34
	v_dot8_i32_i4 v35, v164, v200, v35
	v_dot8_i32_i4 v34, v165, v197, v34
	v_dot8_i32_i4 v35, v165, v201, v35
	s_nop 2
	s_waitcnt vmcnt(4)
	v_lshl_add_u32 v28, v34, 4, v35
	v_dot8_i32_i4 v36, v166, v194, 0
	v_dot8_i32_i4 v37, v166, v198, 0
	v_dot8_i32_i4 v36, v167, v195, v36
	v_dot8_i32_i4 v37, v167, v199, v37
	v_dot8_i32_i4 v36, v168, v196, v36
	v_dot8_i32_i4 v37, v168, v200, v37
	v_dot8_i32_i4 v36, v169, v197, v36
	v_dot8_i32_i4 v37, v169, v201, v37
	s_nop 2
	s_waitcnt vmcnt(3)
	v_lshl_add_u32 v29, v36, 4, v37
	v_dot8_i32_i4 v34, v170, v194, 0
	v_dot8_i32_i4 v35, v170, v198, 0
	v_dot8_i32_i4 v34, v171, v195, v34
	v_dot8_i32_i4 v35, v171, v199, v35
	v_dot8_i32_i4 v34, v172, v196, v34
	v_dot8_i32_i4 v35, v172, v200, v35
	v_dot8_i32_i4 v34, v173, v197, v34
	v_dot8_i32_i4 v35, v173, v201, v35
	s_nop 2
	s_waitcnt vmcnt(2)
	v_lshl_add_u32 v30, v34, 4, v35
	v_dot8_i32_i4 v36, v174, v194, 0
	v_dot8_i32_i4 v37, v174, v198, 0
	v_dot8_i32_i4 v36, v175, v195, v36
	v_dot8_i32_i4 v37, v175, v199, v37
	v_dot8_i32_i4 v36, v176, v196, v36
	v_dot8_i32_i4 v37, v176, v200, v37
	v_dot8_i32_i4 v36, v177, v197, v36
	v_dot8_i32_i4 v37, v177, v201, v37
	s_nop 2
	s_waitcnt vmcnt(1)
	v_lshl_add_u32 v31, v36, 4, v37
	v_dot8_i32_i4 v34, v178, v194, 0
	v_dot8_i32_i4 v35, v178, v198, 0
	v_dot8_i32_i4 v34, v179, v195, v34
	v_dot8_i32_i4 v35, v179, v199, v35
	v_dot8_i32_i4 v34, v180, v196, v34
	v_dot8_i32_i4 v35, v180, v200, v35
	v_dot8_i32_i4 v34, v181, v197, v34
	v_dot8_i32_i4 v35, v181, v201, v35
	s_nop 2
	s_waitcnt vmcnt(0)
	v_lshl_add_u32 v32, v34, 4, v35
	v_dot8_i32_i4 v36, v182, v194, 0
	v_dot8_i32_i4 v37, v182, v198, 0
	v_dot8_i32_i4 v36, v183, v195, v36
	v_dot8_i32_i4 v37, v183, v199, v37
	v_dot8_i32_i4 v36, v184, v196, v36
	v_dot8_i32_i4 v37, v184, v200, v37
	v_dot8_i32_i4 v36, v185, v197, v36
	v_dot8_i32_i4 v37, v185, v201, v37
	s_nop 2
	s_nop 0
	v_lshl_add_u32 v33, v36, 4, v37
	v_add_u32_dpp v40, v26, v26 row_shr:4 row_mask:0xf bank_mask:0xa
	v_add_u32_dpp v40, v18, v18 row_shl:4 row_mask:0xf bank_mask:0x5
	v_add_u32_dpp v41, v27, v27 row_shr:4 row_mask:0xf bank_mask:0xa
	v_add_u32_dpp v41, v19, v19 row_shl:4 row_mask:0xf bank_mask:0x5
	v_add_u32_dpp v42, v28, v28 row_shr:4 row_mask:0xf bank_mask:0xa
	v_add_u32_dpp v42, v20, v20 row_shl:4 row_mask:0xf bank_mask:0x5
	v_add_u32_dpp v43, v29, v29 row_shr:4 row_mask:0xf bank_mask:0xa
	v_add_u32_dpp v43, v21, v21 row_shl:4 row_mask:0xf bank_mask:0x5
	v_add_u32_dpp v44, v30, v30 row_shr:4 row_mask:0xf bank_mask:0xa
	v_add_u32_dpp v44, v22, v22 row_shl:4 row_mask:0xf bank_mask:0x5
	v_add_u32_dpp v45, v31, v31 row_shr:4 row_mask:0xf bank_mask:0xa
	v_add_u32_dpp v45, v23, v23 row_shl:4 row_mask:0xf bank_mask:0x5
	v_add_u32_dpp v46, v32, v32 row_shr:4 row_mask:0xf bank_mask:0xa
	v_add_u32_dpp v46, v24, v24 row_shl:4 row_mask:0xf bank_mask:0x5
	v_add_u32_dpp v47, v33, v33 row_shr:4 row_mask:0xf bank_mask:0xa
	v_add_u32_dpp v47, v25, v25 row_shl:4 row_mask:0xf bank_mask:0x5
	v_cndmask_b32_e64 v18, v44, v40, s[12:13]
	v_cndmask_b32_e64 v22, v40, v44, s[12:13]
	v_cndmask_b32_e64 v19, v45, v41, s[12:13]
	v_cndmask_b32_e64 v23, v41, v45, s[12:13]
	v_cndmask_b32_e64 v20, v46, v42, s[12:13]
	v_cndmask_b32_e64 v24, v42, v46, s[12:13]
	v_cndmask_b32_e64 v21, v47, v43, s[12:13]
	v_cndmask_b32_e64 v25, v43, v47, s[12:13]
	s_nop 0
	v_add_u32_dpp v26, v18, v22 quad_perm:[2,3,0,1] row_mask:0xf bank_mask:0xf
	v_add_u32_dpp v27, v19, v23 quad_perm:[2,3,0,1] row_mask:0xf bank_mask:0xf
	v_add_u32_dpp v28, v20, v24 quad_perm:[2,3,0,1] row_mask:0xf bank_mask:0xf
	v_add_u32_dpp v29, v21, v25 quad_perm:[2,3,0,1] row_mask:0xf bank_mask:0xf
	v_cndmask_b32_e64 v40, v28, v26, s[14:15]
	v_cndmask_b32_e64 v48, v26, v28, s[14:15]
	v_cndmask_b32_e64 v41, v29, v27, s[14:15]
	v_cndmask_b32_e64 v49, v27, v29, s[14:15]
	s_nop 1
	v_add_u32_dpp v44, v40, v48 quad_perm:[1,0,3,2] row_mask:0xf bank_mask:0xf
	v_add_u32_dpp v45, v41, v49 quad_perm:[1,0,3,2] row_mask:0xf bank_mask:0xf
	s_cmp_eq_u32 s43, 0
	s_cselect_b32 s32, 0, -1
	v_and_b32_e32 v62, s32, v62
	v_and_b32_e32 v63, s32, v63
	v_add_u32_e32 v44, v44, v62
	v_add_u32_e32 v45, v45, v63
	ds_write_b64 v61, v[44:45]
	s_mov_b32 s42, s44
	s_mov_b32 s43, s45
	s_add_i32 s44, s44, 1
	s_and_b32 s44, s44, 7
	s_cmp_eq_u32 s44, 0
	s_cselect_b32 s32, 1, 0
	s_add_i32 s45, s45, s32
	s_and_b32 s45, s45, 3
	s_waitcnt lgkmcnt(0)
; #define LAS __attribute__((address_space(3)))
; __global__ void __launch_bounds__(NTHR, 2) k_main(Args a) {
;     ...
;             for (int it = 0; it < 8; ++it) {
;                 const int tl = it * 8 + wave, t = j * 64 + tl;
;                 const unsigned ew = *(const LAS unsigned*)(EL + tl * 128 + 2 * lane); const int e0 = (int)(ew & 0xffffu), e1 = (int)(ew >> 16);
;                 typedef int i2v __attribute__((ext_vector_type(2))); const i2v si = *(const LAS i2v*)(ACC + tl * 128 + 2 * lane);
;                 typedef float f2v __attribute__((ext_vector_type(2))); const f2v gt = *(const LAS f2v*)(GL + tl * 128 + 2 * lane); const float xs = XS[t];
;                 const int sx = ((const int*)(XS + T))[t];
;                 const float z0 = (float)(2 * si.x + sx) * SU[e0] * xs, z1 = (float)(2 * si.y + sx) * SU[e1] * xs;
.LBB0_674:
	s_nop 0
	s_nop 0
	s_nop 0
	s_nop 0
	s_nop 0
	s_nop 0
	s_nop 0
	s_nop 0
	s_nop 0
	s_nop 0
	s_nop 0
	s_nop 0
	s_ashr_i32 s41, s40, 31
	s_lshl_b64 s[10:11], s[40:41], 2
	s_add_u32 s14, s90, s10
	s_addc_u32 s15, s91, s11
	v_readlane_b32 s42, v235, 36
	v_readlane_b32 s43, v235, 37
	global_load_dword v78, v83, s[38:39] sc1
	v_add_u32_e32 v74, 0x16000, v91
	v_mov_b32_e32 v77, 3
	ds_read_b32 v18, v92
	ds_read_b32 v19, v92 offset:2048
	ds_read_b32 v20, v92 offset:4096
	ds_read_b32 v21, v92 offset:6144
	ds_read_b32 v22, v92 offset:8192
	ds_read_b32 v23, v92 offset:10240
	ds_read_b32 v24, v92 offset:12288
	ds_read_b32 v25, v92 offset:14336
	ds_read_b64 v[26:27], v91
	ds_read_b64 v[42:43], v74
	ds_read_b64 v[28:29], v91 offset:4096
	ds_read_b64 v[44:45], v74 offset:4096
	ds_read_b64 v[30:31], v91 offset:8192
	ds_read_b64 v[46:47], v74 offset:8192
	ds_read_b64 v[32:33], v91 offset:12288
	ds_read_b64 v[48:49], v74 offset:12288
	ds_read_b64 v[34:35], v91 offset:16384
	ds_read_b64 v[50:51], v74 offset:16384
	ds_read_b64 v[36:37], v91 offset:20480
	ds_read_b64 v[52:53], v74 offset:20480
	ds_read_b64 v[38:39], v91 offset:24576
	ds_read_b64 v[54:55], v74 offset:24576
	ds_read_b64 v[40:41], v91 offset:28672
	ds_read_b64 v[56:57], v74 offset:28672
	global_load_dword v58, v109, s[14:15]
	global_load_dword v66, v108, s[14:15]
	global_load_dword v59, v109, s[14:15] offset:32
	global_load_dword v67, v108, s[14:15] offset:32
	global_load_dword v60, v109, s[14:15] offset:64
	global_load_dword v68, v108, s[14:15] offset:64
	global_load_dword v61, v109, s[14:15] offset:96
	global_load_dword v69, v108, s[14:15] offset:96
	global_load_dword v62, v109, s[14:15] offset:128
	global_load_dword v70, v108, s[14:15] offset:128
	global_load_dword v63, v109, s[14:15] offset:160
	global_load_dword v71, v108, s[14:15] offset:160
	global_load_dword v64, v109, s[14:15] offset:192
	global_load_dword v72, v108, s[14:15] offset:192
	global_load_dword v65, v109, s[14:15] offset:224
	global_load_dword v73, v108, s[14:15] offset:224
	s_waitcnt lgkmcnt(0)
	v_lshlrev_b32_sdwa v75, v77, v18 dst_sel:DWORD dst_unused:UNUSED_PAD src0_sel:DWORD src1_sel:WORD_0
	v_lshlrev_b32_sdwa v76, v77, v18 dst_sel:DWORD dst_unused:UNUSED_PAD src0_sel:DWORD src1_sel:WORD_1
	s_nop 1
	global_load_dwordx2 v[122:123], v75, s[42:43]
	global_load_dwordx2 v[138:139], v76, s[42:43]
	v_lshlrev_b32_sdwa v75, v77, v19 dst_sel:DWORD dst_unused:UNUSED_PAD src0_sel:DWORD src1_sel:WORD_0
	v_lshlrev_b32_sdwa v76, v77, v19 dst_sel:DWORD dst_unused:UNUSED_PAD src0_sel:DWORD src1_sel:WORD_1
	s_nop 1
	global_load_dwordx2 v[124:125], v75, s[42:43]
	global_load_dwordx2 v[140:141], v76, s[42:43]
	v_lshlrev_b32_sdwa v75, v77, v20 dst_sel:DWORD dst_unused:UNUSED_PAD src0_sel:DWORD src1_sel:WORD_0
	v_lshlrev_b32_sdwa v76, v77, v20 dst_sel:DWORD dst_unused:UNUSED_PAD src0_sel:DWORD src1_sel:WORD_1
	s_nop 1
	global_load_dwordx2 v[126:127], v75, s[42:43]
	global_load_dwordx2 v[142:143], v76, s[42:43]
	v_lshlrev_b32_sdwa v75, v77, v21 dst_sel:DWORD dst_unused:UNUSED_PAD src0_sel:DWORD src1_sel:WORD_0
	v_lshlrev_b32_sdwa v76, v77, v21 dst_sel:DWORD dst_unused:UNUSED_PAD src0_sel:DWORD src1_sel:WORD_1
	s_nop 1
	global_load_dwordx2 v[128:129], v75, s[42:43]
	global_load_dwordx2 v[144:145], v76, s[42:43]
	v_lshlrev_b32_sdwa v75, v77, v22 dst_sel:DWORD dst_unused:UNUSED_PAD src0_sel:DWORD src1_sel:WORD_0
	v_lshlrev_b32_sdwa v76, v77, v22 dst_sel:DWORD dst_unused:UNUSED_PAD src0_sel:DWORD src1_sel:WORD_1
	s_nop 1
	global_load_dwordx2 v[130:131], v75, s[42:43]
	global_load_dwordx2 v[146:147], v76, s[42:43]
	v_lshlrev_b32_sdwa v75, v77, v23 dst_sel:DWORD dst_unused:UNUSED_PAD src0_sel:DWORD src1_sel:WORD_0
	v_lshlrev_b32_sdwa v76, v77, v23 dst_sel:DWORD dst_unused:UNUSED_PAD src0_sel:DWORD src1_sel:WORD_1
	s_nop 1
	global_load_dwordx2 v[132:133], v75, s[42:43]
	global_load_dwordx2 v[148:149], v76, s[42:43]
	v_lshlrev_b32_sdwa v75, v77, v24 dst_sel:DWORD dst_unused:UNUSED_PAD src0_sel:DWORD src1_sel:WORD_0
	v_lshlrev_b32_sdwa v76, v77, v24 dst_sel:DWORD dst_unused:UNUSED_PAD src0_sel:DWORD src1_sel:WORD_1
	s_nop 1
	global_load_dwordx2 v[134:135], v75, s[42:43]
	global_load_dwordx2 v[150:151], v76, s[42:43]
	v_lshlrev_b32_sdwa v75, v77, v25 dst_sel:DWORD dst_unused:UNUSED_PAD src0_sel:DWORD src1_sel:WORD_0
	v_lshlrev_b32_sdwa v76, v77, v25 dst_sel:DWORD dst_unused:UNUSED_PAD src0_sel:DWORD src1_sel:WORD_1
	s_nop 1
	global_load_dwordx2 v[136:137], v75, s[42:43]
	global_load_dwordx2 v[152:153], v76, s[42:43]
	s_waitcnt vmcnt(14)
; #define LAS __attribute__((address_space(3)))
; __device__ __forceinline__ float gelu_as(float z) {
;     const float ax = fabsf(z) * 0.70710678118654752f, t = __builtin_amdgcn_rcpf(1.f + 0.3275911f * ax);
;     const float poly = t * (0.254829592f + t * (-0.284496736f + t * (1.421413741f + t * (-1.453152027f + t * 1.061405429f))));
;     const float er = 1.f - poly * __expf(-ax * ax);
;     return 0.5f * z * (1.f + copysignf(er, z));
; }
; __global__ void __launch_bounds__(NTHR, 2) k_main(Args a) {
;     ...
;                 const unsigned ew = *(const LAS unsigned*)(EL + tl * 128 + 2 * lane); const int e0 = (int)(ew & 0xffffu), e1 = (int)(ew >> 16);
;                 typedef int i2v __attribute__((ext_vector_type(2))); const i2v si = *(const LAS i2v*)(ACC + tl * 128 + 2 * lane);
;                 typedef float f2v __attribute__((ext_vector_type(2))); const f2v gt = *(const LAS f2v*)(GL + tl * 128 + 2 * lane); const float xs = XS[t];
;                 const int sx = ((const int*)(XS + T))[t];
;                 const float z0 = (float)(2 * si.x + sx) * SU[e0] * xs, z1 = (float)(2 * si.y + sx) * SU[e1] * xs;
;                 const float a0 = gt.x * gelu_as(z0) * SV[e0], a1 = gt.y * gelu_as(z1) * SV[e1];
;                 const float mx = wave_max_dpp(fmaxf(fabsf(a0), fabsf(a1)));
;                 const float sc = mx > 0.f ? mx * (1.f / 119.f) : 1.f, inv = 1.f / sc;
;                 const int q0 = (int)rintf(a0 * inv), q1 = (int)rintf(a1 * inv);
;                 *(LAS unsigned short*)(AL + tl * 128 + 2 * lane) = (unsigned short)((q0 & 255) | ((q1 & 255) << 8));
;                 const int qs = wave_sum_dpp_i(q0 + q1);
;                 if (lane == 0) { ASC[tl] = sc; SAL[tl] = qs; }
	v_lshl_add_u32 v154, v26, 1, v58
	v_lshl_add_u32 v155, v27, 1, v58
	v_cvt_f32_i32_e32 v154, v154
	v_cvt_f32_i32_e32 v155, v155
	v_mul_f32_e32 v154, v122, v154
	v_mul_f32_e32 v155, v138, v155
	v_mul_f32_e32 v154, v66, v154
	v_mul_f32_e32 v155, v66, v155
	v_mul_f32_e64 v156, |v154|, s82
	v_mul_f32_e64 v157, |v155|, s82
	v_fma_f32 v158, v156, s83, 1.0
	v_fma_f32 v159, v157, s83, 1.0
	v_rcp_f32_e32 v158, v158
	v_rcp_f32_e32 v159, v159
	v_mul_f32_e64 v156, v156, -v156
	v_mul_f32_e64 v157, v157, -v157
	v_mul_f32_e32 v156, 0x3fb8aa3b, v156
	v_mul_f32_e32 v157, 0x3fb8aa3b, v157
	v_fmamk_f32 v160, v158, 0x3f87dc22, v110
	v_fmamk_f32 v161, v159, 0x3f87dc22, v110
	v_exp_f32_e32 v156, v156
	v_exp_f32_e32 v157, v157
	v_fmaak_f32 v160, v158, v160, 0x3fb5f0e3
	v_fmaak_f32 v161, v159, v161, 0x3fb5f0e3
	v_fmaak_f32 v160, v158, v160, 0xbe91a98e
	v_fmaak_f32 v161, v159, v161, 0xbe91a98e
	v_fmaak_f32 v160, v158, v160, 0x3e827906
	v_fmaak_f32 v161, v159, v161, 0x3e827906
	v_mul_f32_e32 v158, v158, v160
	v_mul_f32_e32 v159, v159, v161
	v_fma_f32 v156, -v156, v158, 1.0
	v_fma_f32 v157, -v157, v159, 1.0
	v_mul_f32_e32 v162, 0.5, v154
	v_mul_f32_e32 v163, 0.5, v155
	v_bfi_b32 v154, s84, v156, v154
	v_bfi_b32 v155, s84, v157, v155
	v_add_f32_e32 v154, 1.0, v154
	v_add_f32_e32 v155, 1.0, v155
	v_mul_f32_e32 v154, v162, v154
	v_mul_f32_e32 v155, v163, v155
	v_mul_f32_e32 v154, v42, v154
	v_mul_f32_e32 v155, v43, v155
	v_mul_f32_e32 v154, v123, v154
	v_mul_f32_e32 v155, v139, v155
	v_max_f32_e64 v164, |v154|, |v155|
	s_nop 1
	v_max_f32_dpp v164, v164, v164 quad_perm:[1,0,3,2] row_mask:0xf bank_mask:0xf
	s_nop 1
	v_max_f32_dpp v164, v164, v164 quad_perm:[2,3,0,1] row_mask:0xf bank_mask:0xf
	s_nop 1
	v_max_f32_dpp v164, v164, v164 row_half_mirror row_mask:0xf bank_mask:0xf
	s_nop 1
	v_max_f32_dpp v164, v164, v164 row_mirror row_mask:0xf bank_mask:0xf
	s_nop 1
	v_readlane_b32 s46, v164, 32
	v_readlane_b32 s47, v164, 48
	v_readlane_b32 s12, v164, 0
	v_readlane_b32 s13, v164, 16
	s_nop 1
	v_mov_b32_e32 v164, s47
	v_max_f32_e32 v164, s46, v164
	v_mov_b32_e32 v165, s13
	v_max3_f32 v164, s12, v165, v164
	v_mul_f32_e32 v165, 0x3c09ae41, v164
	v_cmp_lt_f32_e32 vcc, 0, v164
	s_nop 1
	v_cndmask_b32_e32 v164, 1.0, v165, vcc
	v_div_scale_f32 v166, s[12:13], v164, v164, 1.0
	v_rcp_f32_e32 v167, v166
	v_div_scale_f32 v168, vcc, 1.0, v164, 1.0
	v_fma_f32 v169, -v166, v167, 1.0
	v_fmac_f32_e32 v167, v169, v167
	v_mul_f32_e32 v169, v168, v167
	v_fma_f32 v170, -v166, v169, v168
	v_fmac_f32_e32 v169, v170, v167
	v_fma_f32 v166, -v166, v169, v168
	v_div_fmas_f32 v166, v166, v167, v169
	v_div_fixup_f32 v166, v166, v164, 1.0
	v_mul_f32_e32 v154, v166, v154
	v_mul_f32_e32 v155, v166, v155
	v_rndne_f32_e32 v154, v154
	v_rndne_f32_e32 v155, v155
	v_cvt_i32_f32_e32 v154, v154
	v_cvt_i32_f32_e32 v155, v155
	v_perm_b32 v167, v155, v154, s85
	v_add_u32_e32 v154, v154, v155
	ds_write_b16 v90, v167
	s_nop 1
	v_add_u32_dpp v154, v154, v154 quad_perm:[1,0,3,2] row_mask:0xf bank_mask:0xf bound_ctrl:1
	s_nop 1
	v_add_u32_dpp v154, v154, v154 quad_perm:[2,3,0,1] row_mask:0xf bank_mask:0xf bound_ctrl:1
	s_nop 1
	v_add_u32_dpp v154, v154, v154 row_half_mirror row_mask:0xf bank_mask:0xf bound_ctrl:1
	s_nop 1
	v_add_u32_dpp v154, v154, v154 row_mirror row_mask:0xf bank_mask:0xf bound_ctrl:1
	s_nop 1
	v_readlane_b32 s46, v154, 0
	v_readlane_b32 s47, v154, 16
	v_readlane_b32 s12, v154, 32
	v_readlane_b32 s13, v154, 48
	s_nop 1
	s_add_i32 s46, s47, s46
	s_add_i32 s46, s46, s12
	s_add_i32 s46, s46, s13
	s_mov_b32 s47, s67
	s_and_saveexec_b64 s[12:13], s[8:9]
	v_mov_b32_e32 v154, s47
	v_mov_b32_e32 v155, s46
	ds_write2st64_b32 v154, v164, v155 offset1:1
	s_or_b64 exec, exec, s[12:13]
	s_waitcnt vmcnt(12)
	v_lshl_add_u32 v154, v28, 1, v59
	v_lshl_add_u32 v155, v29, 1, v59
	v_cvt_f32_i32_e32 v154, v154
	v_cvt_f32_i32_e32 v155, v155
	v_mul_f32_e32 v154, v124, v154
	v_mul_f32_e32 v155, v140, v155
	v_mul_f32_e32 v154, v67, v154
	v_mul_f32_e32 v155, v67, v155
	v_mul_f32_e64 v156, |v154|, s82
	v_mul_f32_e64 v157, |v155|, s82
	v_fma_f32 v158, v156, s83, 1.0
	v_fma_f32 v159, v157, s83, 1.0
	v_rcp_f32_e32 v158, v158
	v_rcp_f32_e32 v159, v159
	v_mul_f32_e64 v156, v156, -v156
	v_mul_f32_e64 v157, v157, -v157
	v_mul_f32_e32 v156, 0x3fb8aa3b, v156
	v_mul_f32_e32 v157, 0x3fb8aa3b, v157
	v_fmamk_f32 v160, v158, 0x3f87dc22, v110
	v_fmamk_f32 v161, v159, 0x3f87dc22, v110
	v_exp_f32_e32 v156, v156
	v_exp_f32_e32 v157, v157
	v_fmaak_f32 v160, v158, v160, 0x3fb5f0e3
	v_fmaak_f32 v161, v159, v161, 0x3fb5f0e3
	v_fmaak_f32 v160, v158, v160, 0xbe91a98e
	v_fmaak_f32 v161, v159, v161, 0xbe91a98e
	v_fmaak_f32 v160, v158, v160, 0x3e827906
	v_fmaak_f32 v161, v159, v161, 0x3e827906
	v_mul_f32_e32 v158, v158, v160
	v_mul_f32_e32 v159, v159, v161
	v_fma_f32 v156, -v156, v158, 1.0
	v_fma_f32 v157, -v157, v159, 1.0
	v_mul_f32_e32 v162, 0.5, v154
	v_mul_f32_e32 v163, 0.5, v155
	v_bfi_b32 v154, s84, v156, v154
	v_bfi_b32 v155, s84, v157, v155
	v_add_f32_e32 v154, 1.0, v154
	v_add_f32_e32 v155, 1.0, v155
	v_mul_f32_e32 v154, v162, v154
	v_mul_f32_e32 v155, v163, v155
	v_mul_f32_e32 v154, v44, v154
	v_mul_f32_e32 v155, v45, v155
	v_mul_f32_e32 v154, v125, v154
	v_mul_f32_e32 v155, v141, v155
	v_max_f32_e64 v164, |v154|, |v155|
	s_nop 1
	v_max_f32_dpp v164, v164, v164 quad_perm:[1,0,3,2] row_mask:0xf bank_mask:0xf
	s_nop 1
	v_max_f32_dpp v164, v164, v164 quad_perm:[2,3,0,1] row_mask:0xf bank_mask:0xf
	s_nop 1
	v_max_f32_dpp v164, v164, v164 row_half_mirror row_mask:0xf bank_mask:0xf
	s_nop 1
	v_max_f32_dpp v164, v164, v164 row_mirror row_mask:0xf bank_mask:0xf
	s_nop 1
	v_readlane_b32 s46, v164, 32
	v_readlane_b32 s47, v164, 48
	v_readlane_b32 s12, v164, 0
; #define LAS __attribute__((address_space(3)))
; #define DPPF_(v, ctrl) __builtin_bit_cast(float, __builtin_amdgcn_update_dpp(0, __builtin_bit_cast(int, v), ctrl, 0xf, 0xf, false))
; __device__ __forceinline__ float wave_max_dpp(float v) {
;     v = fmaxf(v, DPPF_(v, 0xB1)); v = fmaxf(v, DPPF_(v, 0x4E)); v = fmaxf(v, DPPF_(v, 0x141)); v = fmaxf(v, DPPF_(v, 0x140));
;     const int vi = __builtin_bit_cast(int, v);
;     return fmaxf(fmaxf(__builtin_bit_cast(float, __builtin_amdgcn_readlane(vi, 0)), __builtin_bit_cast(float, __builtin_amdgcn_readlane(vi, 16))),
;                  fmaxf(__builtin_bit_cast(float, __builtin_amdgcn_readlane(vi, 32)), __builtin_bit_cast(float, __builtin_amdgcn_readlane(vi, 48))));
; }
; __device__ __forceinline__ int wave_sum_dpp_i(int v) {
;     v += __builtin_amdgcn_update_dpp(0, v, 0xB1, 0xf, 0xf, false); v += __builtin_amdgcn_update_dpp(0, v, 0x4E, 0xf, 0xf, false);
;     v += __builtin_amdgcn_update_dpp(0, v, 0x141, 0xf, 0xf, false); v += __builtin_amdgcn_update_dpp(0, v, 0x140, 0xf, 0xf, false);
;     return __builtin_amdgcn_readlane(v, 0) + __builtin_amdgcn_readlane(v, 16) + __builtin_amdgcn_readlane(v, 32) + __builtin_amdgcn_readlane(v, 48);
; }
; __device__ __forceinline__ float gelu_as(float z) {
;     const float ax = fabsf(z) * 0.70710678118654752f, t = __builtin_amdgcn_rcpf(1.f + 0.3275911f * ax);
;     const float poly = t * (0.254829592f + t * (-0.284496736f + t * (1.421413741f + t * (-1.453152027f + t * 1.061405429f))));
;     const float er = 1.f - poly * __expf(-ax * ax);
;     return 0.5f * z * (1.f + copysignf(er, z));
; }
; __global__ void __launch_bounds__(NTHR, 2) k_main(Args a) {
;     ...
;                 const float z0 = (float)(2 * si.x + sx) * SU[e0] * xs, z1 = (float)(2 * si.y + sx) * SU[e1] * xs;
;                 const float a0 = gt.x * gelu_as(z0) * SV[e0], a1 = gt.y * gelu_as(z1) * SV[e1];
;                 const float mx = wave_max_dpp(fmaxf(fabsf(a0), fabsf(a1)));
;                 const float sc = mx > 0.f ? mx * (1.f / 119.f) : 1.f, inv = 1.f / sc;
;                 const int q0 = (int)rintf(a0 * inv), q1 = (int)rintf(a1 * inv);
;                 *(LAS unsigned short*)(AL + tl * 128 + 2 * lane) = (unsigned short)((q0 & 255) | ((q1 & 255) << 8));
;                 const int qs = wave_sum_dpp_i(q0 + q1);
;                 if (lane == 0) { ASC[tl] = sc; SAL[tl] = qs; }
	v_readlane_b32 s13, v164, 16
	s_nop 1
	v_mov_b32_e32 v164, s47
	v_max_f32_e32 v164, s46, v164
	v_mov_b32_e32 v165, s13
	v_max3_f32 v164, s12, v165, v164
	v_mul_f32_e32 v165, 0x3c09ae41, v164
	v_cmp_lt_f32_e32 vcc, 0, v164
	s_nop 1
	v_cndmask_b32_e32 v164, 1.0, v165, vcc
	v_div_scale_f32 v166, s[12:13], v164, v164, 1.0
	v_rcp_f32_e32 v167, v166
	v_div_scale_f32 v168, vcc, 1.0, v164, 1.0
	v_fma_f32 v169, -v166, v167, 1.0
	v_fmac_f32_e32 v167, v169, v167
	v_mul_f32_e32 v169, v168, v167
	v_fma_f32 v170, -v166, v169, v168
	v_fmac_f32_e32 v169, v170, v167
	v_fma_f32 v166, -v166, v169, v168
	v_div_fmas_f32 v166, v166, v167, v169
	v_div_fixup_f32 v166, v166, v164, 1.0
	v_mul_f32_e32 v154, v166, v154
	v_mul_f32_e32 v155, v166, v155
	v_rndne_f32_e32 v154, v154
	v_rndne_f32_e32 v155, v155
	v_cvt_i32_f32_e32 v154, v154
	v_cvt_i32_f32_e32 v155, v155
	v_perm_b32 v167, v155, v154, s85
	v_add_u32_e32 v154, v154, v155
	ds_write_b16 v90, v167 offset:1024
	s_nop 1
	v_add_u32_dpp v154, v154, v154 quad_perm:[1,0,3,2] row_mask:0xf bank_mask:0xf bound_ctrl:1
	s_nop 1
	v_add_u32_dpp v154, v154, v154 quad_perm:[2,3,0,1] row_mask:0xf bank_mask:0xf bound_ctrl:1
	s_nop 1
	v_add_u32_dpp v154, v154, v154 row_half_mirror row_mask:0xf bank_mask:0xf bound_ctrl:1
	s_nop 1
	v_add_u32_dpp v154, v154, v154 row_mirror row_mask:0xf bank_mask:0xf bound_ctrl:1
	s_nop 1
	v_readlane_b32 s46, v154, 0
	v_readlane_b32 s47, v154, 16
	v_readlane_b32 s12, v154, 32
	v_readlane_b32 s13, v154, 48
	s_nop 1
	s_add_i32 s46, s47, s46
	s_add_i32 s46, s46, s12
	s_add_i32 s46, s46, s13
	s_add_i32 s47, s67, 32
	s_and_saveexec_b64 s[12:13], s[8:9]
	v_mov_b32_e32 v154, s47
	v_mov_b32_e32 v155, s46
	ds_write2st64_b32 v154, v164, v155 offset1:1
	s_or_b64 exec, exec, s[12:13]
	s_waitcnt vmcnt(10)
	v_lshl_add_u32 v154, v30, 1, v60
	v_lshl_add_u32 v155, v31, 1, v60
	v_cvt_f32_i32_e32 v154, v154
	v_cvt_f32_i32_e32 v155, v155
	v_mul_f32_e32 v154, v126, v154
	v_mul_f32_e32 v155, v142, v155
	v_mul_f32_e32 v154, v68, v154
	v_mul_f32_e32 v155, v68, v155
	v_mul_f32_e64 v156, |v154|, s82
	v_mul_f32_e64 v157, |v155|, s82
	v_fma_f32 v158, v156, s83, 1.0
	v_fma_f32 v159, v157, s83, 1.0
	v_rcp_f32_e32 v158, v158
	v_rcp_f32_e32 v159, v159
	v_mul_f32_e64 v156, v156, -v156
	v_mul_f32_e64 v157, v157, -v157
	v_mul_f32_e32 v156, 0x3fb8aa3b, v156
	v_mul_f32_e32 v157, 0x3fb8aa3b, v157
	v_fmamk_f32 v160, v158, 0x3f87dc22, v110
	v_fmamk_f32 v161, v159, 0x3f87dc22, v110
	v_exp_f32_e32 v156, v156
	v_exp_f32_e32 v157, v157
	v_fmaak_f32 v160, v158, v160, 0x3fb5f0e3
	v_fmaak_f32 v161, v159, v161, 0x3fb5f0e3
	v_fmaak_f32 v160, v158, v160, 0xbe91a98e
	v_fmaak_f32 v161, v159, v161, 0xbe91a98e
	v_fmaak_f32 v160, v158, v160, 0x3e827906
	v_fmaak_f32 v161, v159, v161, 0x3e827906
	v_mul_f32_e32 v158, v158, v160
	v_mul_f32_e32 v159, v159, v161
	v_fma_f32 v156, -v156, v158, 1.0
	v_fma_f32 v157, -v157, v159, 1.0
	v_mul_f32_e32 v162, 0.5, v154
	v_mul_f32_e32 v163, 0.5, v155
	v_bfi_b32 v154, s84, v156, v154
	v_bfi_b32 v155, s84, v157, v155
	v_add_f32_e32 v154, 1.0, v154
	v_add_f32_e32 v155, 1.0, v155
	v_mul_f32_e32 v154, v162, v154
	v_mul_f32_e32 v155, v163, v155
	v_mul_f32_e32 v154, v46, v154
	v_mul_f32_e32 v155, v47, v155
	v_mul_f32_e32 v154, v127, v154
	v_mul_f32_e32 v155, v143, v155
	v_max_f32_e64 v164, |v154|, |v155|
	s_nop 1
	v_max_f32_dpp v164, v164, v164 quad_perm:[1,0,3,2] row_mask:0xf bank_mask:0xf
	s_nop 1
	v_max_f32_dpp v164, v164, v164 quad_perm:[2,3,0,1] row_mask:0xf bank_mask:0xf
	s_nop 1
	v_max_f32_dpp v164, v164, v164 row_half_mirror row_mask:0xf bank_mask:0xf
	s_nop 1
	v_max_f32_dpp v164, v164, v164 row_mirror row_mask:0xf bank_mask:0xf
	s_nop 1
	v_readlane_b32 s46, v164, 32
	v_readlane_b32 s47, v164, 48
	v_readlane_b32 s12, v164, 0
	v_readlane_b32 s13, v164, 16
	s_nop 1
	v_mov_b32_e32 v164, s47
	v_max_f32_e32 v164, s46, v164
	v_mov_b32_e32 v165, s13
	v_max3_f32 v164, s12, v165, v164
	v_mul_f32_e32 v165, 0x3c09ae41, v164
	v_cmp_lt_f32_e32 vcc, 0, v164
	s_nop 1
	v_cndmask_b32_e32 v164, 1.0, v165, vcc
	v_div_scale_f32 v166, s[12:13], v164, v164, 1.0
	v_rcp_f32_e32 v167, v166
	v_div_scale_f32 v168, vcc, 1.0, v164, 1.0
	v_fma_f32 v169, -v166, v167, 1.0
	v_fmac_f32_e32 v167, v169, v167
	v_mul_f32_e32 v169, v168, v167
	v_fma_f32 v170, -v166, v169, v168
	v_fmac_f32_e32 v169, v170, v167
	v_fma_f32 v166, -v166, v169, v168
	v_div_fmas_f32 v166, v166, v167, v169
	v_div_fixup_f32 v166, v166, v164, 1.0
	v_mul_f32_e32 v154, v166, v154
	v_mul_f32_e32 v155, v166, v155
	v_rndne_f32_e32 v154, v154
	v_rndne_f32_e32 v155, v155
	v_cvt_i32_f32_e32 v154, v154
	v_cvt_i32_f32_e32 v155, v155
	v_perm_b32 v167, v155, v154, s85
	v_add_u32_e32 v154, v154, v155
	ds_write_b16 v90, v167 offset:2048
	s_nop 1
	v_add_u32_dpp v154, v154, v154 quad_perm:[1,0,3,2] row_mask:0xf bank_mask:0xf bound_ctrl:1
	s_nop 1
	v_add_u32_dpp v154, v154, v154 quad_perm:[2,3,0,1] row_mask:0xf bank_mask:0xf bound_ctrl:1
	s_nop 1
	v_add_u32_dpp v154, v154, v154 row_half_mirror row_mask:0xf bank_mask:0xf bound_ctrl:1
	s_nop 1
	v_add_u32_dpp v154, v154, v154 row_mirror row_mask:0xf bank_mask:0xf bound_ctrl:1
	s_nop 1
	v_readlane_b32 s46, v154, 0
	v_readlane_b32 s47, v154, 16
	v_readlane_b32 s12, v154, 32
	v_readlane_b32 s13, v154, 48
	s_nop 1
	s_add_i32 s46, s47, s46
	s_add_i32 s46, s46, s12
	s_add_i32 s46, s46, s13
	s_add_i32 s47, s67, 64
	s_and_saveexec_b64 s[12:13], s[8:9]
	v_mov_b32_e32 v154, s47
	v_mov_b32_e32 v155, s46
	ds_write2st64_b32 v154, v164, v155 offset1:1
	s_or_b64 exec, exec, s[12:13]
	s_waitcnt vmcnt(8)
; #define LAS __attribute__((address_space(3)))
; __device__ __forceinline__ float gelu_as(float z) {
;     const float ax = fabsf(z) * 0.70710678118654752f, t = __builtin_amdgcn_rcpf(1.f + 0.3275911f * ax);
;     const float poly = t * (0.254829592f + t * (-0.284496736f + t * (1.421413741f + t * (-1.453152027f + t * 1.061405429f))));
;     const float er = 1.f - poly * __expf(-ax * ax);
;     return 0.5f * z * (1.f + copysignf(er, z));
; }
; __global__ void __launch_bounds__(NTHR, 2) k_main(Args a) {
;     ...
;                 const float z0 = (float)(2 * si.x + sx) * SU[e0] * xs, z1 = (float)(2 * si.y + sx) * SU[e1] * xs;
;                 const float a0 = gt.x * gelu_as(z0) * SV[e0], a1 = gt.y * gelu_as(z1) * SV[e1];
;                 const float mx = wave_max_dpp(fmaxf(fabsf(a0), fabsf(a1)));
;                 const float sc = mx > 0.f ? mx * (1.f / 119.f) : 1.f, inv = 1.f / sc;
;                 const int q0 = (int)rintf(a0 * inv), q1 = (int)rintf(a1 * inv);
;                 *(LAS unsigned short*)(AL + tl * 128 + 2 * lane) = (unsigned short)((q0 & 255) | ((q1 & 255) << 8));
;                 const int qs = wave_sum_dpp_i(q0 + q1);
;                 if (lane == 0) { ASC[tl] = sc; SAL[tl] = qs; }
	v_lshl_add_u32 v154, v32, 1, v61
	v_lshl_add_u32 v155, v33, 1, v61
	v_cvt_f32_i32_e32 v154, v154
	v_cvt_f32_i32_e32 v155, v155
	v_mul_f32_e32 v154, v128, v154
	v_mul_f32_e32 v155, v144, v155
	v_mul_f32_e32 v154, v69, v154
	v_mul_f32_e32 v155, v69, v155
	v_mul_f32_e64 v156, |v154|, s82
	v_mul_f32_e64 v157, |v155|, s82
	v_fma_f32 v158, v156, s83, 1.0
	v_fma_f32 v159, v157, s83, 1.0
	v_rcp_f32_e32 v158, v158
	v_rcp_f32_e32 v159, v159
	v_mul_f32_e64 v156, v156, -v156
	v_mul_f32_e64 v157, v157, -v157
	v_mul_f32_e32 v156, 0x3fb8aa3b, v156
	v_mul_f32_e32 v157, 0x3fb8aa3b, v157
	v_fmamk_f32 v160, v158, 0x3f87dc22, v110
	v_fmamk_f32 v161, v159, 0x3f87dc22, v110
	v_exp_f32_e32 v156, v156
	v_exp_f32_e32 v157, v157
	v_fmaak_f32 v160, v158, v160, 0x3fb5f0e3
	v_fmaak_f32 v161, v159, v161, 0x3fb5f0e3
	v_fmaak_f32 v160, v158, v160, 0xbe91a98e
	v_fmaak_f32 v161, v159, v161, 0xbe91a98e
	v_fmaak_f32 v160, v158, v160, 0x3e827906
	v_fmaak_f32 v161, v159, v161, 0x3e827906
	v_mul_f32_e32 v158, v158, v160
	v_mul_f32_e32 v159, v159, v161
	v_fma_f32 v156, -v156, v158, 1.0
	v_fma_f32 v157, -v157, v159, 1.0
	v_mul_f32_e32 v162, 0.5, v154
	v_mul_f32_e32 v163, 0.5, v155
	v_bfi_b32 v154, s84, v156, v154
	v_bfi_b32 v155, s84, v157, v155
	v_add_f32_e32 v154, 1.0, v154
	v_add_f32_e32 v155, 1.0, v155
	v_mul_f32_e32 v154, v162, v154
	v_mul_f32_e32 v155, v163, v155
	v_mul_f32_e32 v154, v48, v154
	v_mul_f32_e32 v155, v49, v155
	v_mul_f32_e32 v154, v129, v154
	v_mul_f32_e32 v155, v145, v155
	v_max_f32_e64 v164, |v154|, |v155|
	s_nop 1
	v_max_f32_dpp v164, v164, v164 quad_perm:[1,0,3,2] row_mask:0xf bank_mask:0xf
	s_nop 1
	v_max_f32_dpp v164, v164, v164 quad_perm:[2,3,0,1] row_mask:0xf bank_mask:0xf
	s_nop 1
	v_max_f32_dpp v164, v164, v164 row_half_mirror row_mask:0xf bank_mask:0xf
	s_nop 1
	v_max_f32_dpp v164, v164, v164 row_mirror row_mask:0xf bank_mask:0xf
	s_nop 1
	v_readlane_b32 s46, v164, 32
	v_readlane_b32 s47, v164, 48
	v_readlane_b32 s12, v164, 0
	v_readlane_b32 s13, v164, 16
	s_nop 1
	v_mov_b32_e32 v164, s47
	v_max_f32_e32 v164, s46, v164
	v_mov_b32_e32 v165, s13
	v_max3_f32 v164, s12, v165, v164
	v_mul_f32_e32 v165, 0x3c09ae41, v164
	v_cmp_lt_f32_e32 vcc, 0, v164
	s_nop 1
	v_cndmask_b32_e32 v164, 1.0, v165, vcc
	v_div_scale_f32 v166, s[12:13], v164, v164, 1.0
	v_rcp_f32_e32 v167, v166
	v_div_scale_f32 v168, vcc, 1.0, v164, 1.0
	v_fma_f32 v169, -v166, v167, 1.0
	v_fmac_f32_e32 v167, v169, v167
	v_mul_f32_e32 v169, v168, v167
	v_fma_f32 v170, -v166, v169, v168
	v_fmac_f32_e32 v169, v170, v167
	v_fma_f32 v166, -v166, v169, v168
	v_div_fmas_f32 v166, v166, v167, v169
	v_div_fixup_f32 v166, v166, v164, 1.0
	v_mul_f32_e32 v154, v166, v154
	v_mul_f32_e32 v155, v166, v155
	v_rndne_f32_e32 v154, v154
	v_rndne_f32_e32 v155, v155
	v_cvt_i32_f32_e32 v154, v154
	v_cvt_i32_f32_e32 v155, v155
	v_perm_b32 v167, v155, v154, s85
	v_add_u32_e32 v154, v154, v155
	ds_write_b16 v90, v167 offset:3072
	s_nop 1
	v_add_u32_dpp v154, v154, v154 quad_perm:[1,0,3,2] row_mask:0xf bank_mask:0xf bound_ctrl:1
	s_nop 1
	v_add_u32_dpp v154, v154, v154 quad_perm:[2,3,0,1] row_mask:0xf bank_mask:0xf bound_ctrl:1
	s_nop 1
	v_add_u32_dpp v154, v154, v154 row_half_mirror row_mask:0xf bank_mask:0xf bound_ctrl:1
	s_nop 1
	v_add_u32_dpp v154, v154, v154 row_mirror row_mask:0xf bank_mask:0xf bound_ctrl:1
	s_nop 1
	v_readlane_b32 s46, v154, 0
	v_readlane_b32 s47, v154, 16
	v_readlane_b32 s12, v154, 32
	v_readlane_b32 s13, v154, 48
	s_nop 1
	s_add_i32 s46, s47, s46
	s_add_i32 s46, s46, s12
	s_add_i32 s46, s46, s13
	s_add_i32 s47, s67, 96
	s_and_saveexec_b64 s[12:13], s[8:9]
	v_mov_b32_e32 v154, s47
	v_mov_b32_e32 v155, s46
	ds_write2st64_b32 v154, v164, v155 offset1:1
	s_or_b64 exec, exec, s[12:13]
	s_waitcnt vmcnt(6)
	v_lshl_add_u32 v154, v34, 1, v62
	v_lshl_add_u32 v155, v35, 1, v62
	v_cvt_f32_i32_e32 v154, v154
	v_cvt_f32_i32_e32 v155, v155
	v_mul_f32_e32 v154, v130, v154
	v_mul_f32_e32 v155, v146, v155
	v_mul_f32_e32 v154, v70, v154
	v_mul_f32_e32 v155, v70, v155
	v_mul_f32_e64 v156, |v154|, s82
	v_mul_f32_e64 v157, |v155|, s82
	v_fma_f32 v158, v156, s83, 1.0
	v_fma_f32 v159, v157, s83, 1.0
	v_rcp_f32_e32 v158, v158
	v_rcp_f32_e32 v159, v159
	v_mul_f32_e64 v156, v156, -v156
	v_mul_f32_e64 v157, v157, -v157
	v_mul_f32_e32 v156, 0x3fb8aa3b, v156
	v_mul_f32_e32 v157, 0x3fb8aa3b, v157
	v_fmamk_f32 v160, v158, 0x3f87dc22, v110
	v_fmamk_f32 v161, v159, 0x3f87dc22, v110
	v_exp_f32_e32 v156, v156
	v_exp_f32_e32 v157, v157
	v_fmaak_f32 v160, v158, v160, 0x3fb5f0e3
	v_fmaak_f32 v161, v159, v161, 0x3fb5f0e3
	v_fmaak_f32 v160, v158, v160, 0xbe91a98e
	v_fmaak_f32 v161, v159, v161, 0xbe91a98e
	v_fmaak_f32 v160, v158, v160, 0x3e827906
	v_fmaak_f32 v161, v159, v161, 0x3e827906
	v_mul_f32_e32 v158, v158, v160
	v_mul_f32_e32 v159, v159, v161
	v_fma_f32 v156, -v156, v158, 1.0
	v_fma_f32 v157, -v157, v159, 1.0
	v_mul_f32_e32 v162, 0.5, v154
	v_mul_f32_e32 v163, 0.5, v155
	v_bfi_b32 v154, s84, v156, v154
	v_bfi_b32 v155, s84, v157, v155
	v_add_f32_e32 v154, 1.0, v154
	v_add_f32_e32 v155, 1.0, v155
	v_mul_f32_e32 v154, v162, v154
	v_mul_f32_e32 v155, v163, v155
	v_mul_f32_e32 v154, v50, v154
	v_mul_f32_e32 v155, v51, v155
	v_mul_f32_e32 v154, v131, v154
	v_mul_f32_e32 v155, v147, v155
	v_max_f32_e64 v164, |v154|, |v155|
	s_nop 1
	v_max_f32_dpp v164, v164, v164 quad_perm:[1,0,3,2] row_mask:0xf bank_mask:0xf
	s_nop 1
	v_max_f32_dpp v164, v164, v164 quad_perm:[2,3,0,1] row_mask:0xf bank_mask:0xf
	s_nop 1
	v_max_f32_dpp v164, v164, v164 row_half_mirror row_mask:0xf bank_mask:0xf
	s_nop 1
	v_max_f32_dpp v164, v164, v164 row_mirror row_mask:0xf bank_mask:0xf
	s_nop 1
	v_readlane_b32 s46, v164, 32
	v_readlane_b32 s47, v164, 48
; #define LAS __attribute__((address_space(3)))
; #define DPPF_(v, ctrl) __builtin_bit_cast(float, __builtin_amdgcn_update_dpp(0, __builtin_bit_cast(int, v), ctrl, 0xf, 0xf, false))
; __device__ __forceinline__ float wave_max_dpp(float v) {
;     v = fmaxf(v, DPPF_(v, 0xB1)); v = fmaxf(v, DPPF_(v, 0x4E)); v = fmaxf(v, DPPF_(v, 0x141)); v = fmaxf(v, DPPF_(v, 0x140));
;     const int vi = __builtin_bit_cast(int, v);
;     return fmaxf(fmaxf(__builtin_bit_cast(float, __builtin_amdgcn_readlane(vi, 0)), __builtin_bit_cast(float, __builtin_amdgcn_readlane(vi, 16))),
;                  fmaxf(__builtin_bit_cast(float, __builtin_amdgcn_readlane(vi, 32)), __builtin_bit_cast(float, __builtin_amdgcn_readlane(vi, 48))));
; }
; __device__ __forceinline__ int wave_sum_dpp_i(int v) {
;     v += __builtin_amdgcn_update_dpp(0, v, 0xB1, 0xf, 0xf, false); v += __builtin_amdgcn_update_dpp(0, v, 0x4E, 0xf, 0xf, false);
;     v += __builtin_amdgcn_update_dpp(0, v, 0x141, 0xf, 0xf, false); v += __builtin_amdgcn_update_dpp(0, v, 0x140, 0xf, 0xf, false);
;     return __builtin_amdgcn_readlane(v, 0) + __builtin_amdgcn_readlane(v, 16) + __builtin_amdgcn_readlane(v, 32) + __builtin_amdgcn_readlane(v, 48);
; }
; __device__ __forceinline__ float gelu_as(float z) {
;     const float ax = fabsf(z) * 0.70710678118654752f, t = __builtin_amdgcn_rcpf(1.f + 0.3275911f * ax);
;     const float poly = t * (0.254829592f + t * (-0.284496736f + t * (1.421413741f + t * (-1.453152027f + t * 1.061405429f))));
;     const float er = 1.f - poly * __expf(-ax * ax);
;     return 0.5f * z * (1.f + copysignf(er, z));
; }
; __global__ void __launch_bounds__(NTHR, 2) k_main(Args a) {
;     ...
;                 const float z0 = (float)(2 * si.x + sx) * SU[e0] * xs, z1 = (float)(2 * si.y + sx) * SU[e1] * xs;
;                 const float a0 = gt.x * gelu_as(z0) * SV[e0], a1 = gt.y * gelu_as(z1) * SV[e1];
;                 const float mx = wave_max_dpp(fmaxf(fabsf(a0), fabsf(a1)));
;                 const float sc = mx > 0.f ? mx * (1.f / 119.f) : 1.f, inv = 1.f / sc;
;                 const int q0 = (int)rintf(a0 * inv), q1 = (int)rintf(a1 * inv);
;                 *(LAS unsigned short*)(AL + tl * 128 + 2 * lane) = (unsigned short)((q0 & 255) | ((q1 & 255) << 8));
;                 const int qs = wave_sum_dpp_i(q0 + q1);
;                 if (lane == 0) { ASC[tl] = sc; SAL[tl] = qs; }
	v_readlane_b32 s12, v164, 0
	v_readlane_b32 s13, v164, 16
	s_nop 1
	v_mov_b32_e32 v164, s47
	v_max_f32_e32 v164, s46, v164
	v_mov_b32_e32 v165, s13
	v_max3_f32 v164, s12, v165, v164
	v_mul_f32_e32 v165, 0x3c09ae41, v164
	v_cmp_lt_f32_e32 vcc, 0, v164
	s_nop 1
	v_cndmask_b32_e32 v164, 1.0, v165, vcc
	v_div_scale_f32 v166, s[12:13], v164, v164, 1.0
	v_rcp_f32_e32 v167, v166
	v_div_scale_f32 v168, vcc, 1.0, v164, 1.0
	v_fma_f32 v169, -v166, v167, 1.0
	v_fmac_f32_e32 v167, v169, v167
	v_mul_f32_e32 v169, v168, v167
	v_fma_f32 v170, -v166, v169, v168
	v_fmac_f32_e32 v169, v170, v167
	v_fma_f32 v166, -v166, v169, v168
	v_div_fmas_f32 v166, v166, v167, v169
	v_div_fixup_f32 v166, v166, v164, 1.0
	v_mul_f32_e32 v154, v166, v154
	v_mul_f32_e32 v155, v166, v155
	v_rndne_f32_e32 v154, v154
	v_rndne_f32_e32 v155, v155
	v_cvt_i32_f32_e32 v154, v154
	v_cvt_i32_f32_e32 v155, v155
	v_perm_b32 v167, v155, v154, s85
	v_add_u32_e32 v154, v154, v155
	ds_write_b16 v90, v167 offset:4096
	s_nop 1
	v_add_u32_dpp v154, v154, v154 quad_perm:[1,0,3,2] row_mask:0xf bank_mask:0xf bound_ctrl:1
	s_nop 1
	v_add_u32_dpp v154, v154, v154 quad_perm:[2,3,0,1] row_mask:0xf bank_mask:0xf bound_ctrl:1
	s_nop 1
	v_add_u32_dpp v154, v154, v154 row_half_mirror row_mask:0xf bank_mask:0xf bound_ctrl:1
	s_nop 1
	v_add_u32_dpp v154, v154, v154 row_mirror row_mask:0xf bank_mask:0xf bound_ctrl:1
	s_nop 1
	v_readlane_b32 s46, v154, 0
	v_readlane_b32 s47, v154, 16
	v_readlane_b32 s12, v154, 32
	v_readlane_b32 s13, v154, 48
	s_nop 1
	s_add_i32 s46, s47, s46
	s_add_i32 s46, s46, s12
	s_add_i32 s46, s46, s13
	s_add_i32 s47, s67, 128
	s_and_saveexec_b64 s[12:13], s[8:9]
	v_mov_b32_e32 v154, s47
	v_mov_b32_e32 v155, s46
	ds_write2st64_b32 v154, v164, v155 offset1:1
	s_or_b64 exec, exec, s[12:13]
	s_waitcnt vmcnt(4)
	v_lshl_add_u32 v154, v36, 1, v63
	v_lshl_add_u32 v155, v37, 1, v63
	v_cvt_f32_i32_e32 v154, v154
	v_cvt_f32_i32_e32 v155, v155
	v_mul_f32_e32 v154, v132, v154
	v_mul_f32_e32 v155, v148, v155
	v_mul_f32_e32 v154, v71, v154
	v_mul_f32_e32 v155, v71, v155
	v_mul_f32_e64 v156, |v154|, s82
	v_mul_f32_e64 v157, |v155|, s82
	v_fma_f32 v158, v156, s83, 1.0
	v_fma_f32 v159, v157, s83, 1.0
	v_rcp_f32_e32 v158, v158
	v_rcp_f32_e32 v159, v159
	v_mul_f32_e64 v156, v156, -v156
	v_mul_f32_e64 v157, v157, -v157
	v_mul_f32_e32 v156, 0x3fb8aa3b, v156
	v_mul_f32_e32 v157, 0x3fb8aa3b, v157
	v_fmamk_f32 v160, v158, 0x3f87dc22, v110
	v_fmamk_f32 v161, v159, 0x3f87dc22, v110
	v_exp_f32_e32 v156, v156
	v_exp_f32_e32 v157, v157
	v_fmaak_f32 v160, v158, v160, 0x3fb5f0e3
	v_fmaak_f32 v161, v159, v161, 0x3fb5f0e3
	v_fmaak_f32 v160, v158, v160, 0xbe91a98e
	v_fmaak_f32 v161, v159, v161, 0xbe91a98e
	v_fmaak_f32 v160, v158, v160, 0x3e827906
	v_fmaak_f32 v161, v159, v161, 0x3e827906
	v_mul_f32_e32 v158, v158, v160
	v_mul_f32_e32 v159, v159, v161
	v_fma_f32 v156, -v156, v158, 1.0
	v_fma_f32 v157, -v157, v159, 1.0
	v_mul_f32_e32 v162, 0.5, v154
	v_mul_f32_e32 v163, 0.5, v155
	v_bfi_b32 v154, s84, v156, v154
	v_bfi_b32 v155, s84, v157, v155
	v_add_f32_e32 v154, 1.0, v154
	v_add_f32_e32 v155, 1.0, v155
	v_mul_f32_e32 v154, v162, v154
	v_mul_f32_e32 v155, v163, v155
	v_mul_f32_e32 v154, v52, v154
	v_mul_f32_e32 v155, v53, v155
	v_mul_f32_e32 v154, v133, v154
	v_mul_f32_e32 v155, v149, v155
	v_max_f32_e64 v164, |v154|, |v155|
	s_nop 1
	v_max_f32_dpp v164, v164, v164 quad_perm:[1,0,3,2] row_mask:0xf bank_mask:0xf
	s_nop 1
	v_max_f32_dpp v164, v164, v164 quad_perm:[2,3,0,1] row_mask:0xf bank_mask:0xf
	s_nop 1
	v_max_f32_dpp v164, v164, v164 row_half_mirror row_mask:0xf bank_mask:0xf
	s_nop 1
	v_max_f32_dpp v164, v164, v164 row_mirror row_mask:0xf bank_mask:0xf
	s_nop 1
	v_readlane_b32 s46, v164, 32
	v_readlane_b32 s47, v164, 48
	v_readlane_b32 s12, v164, 0
	v_readlane_b32 s13, v164, 16
	s_nop 1
	v_mov_b32_e32 v164, s47
	v_max_f32_e32 v164, s46, v164
	v_mov_b32_e32 v165, s13
	v_max3_f32 v164, s12, v165, v164
	v_mul_f32_e32 v165, 0x3c09ae41, v164
	v_cmp_lt_f32_e32 vcc, 0, v164
	s_nop 1
	v_cndmask_b32_e32 v164, 1.0, v165, vcc
	v_div_scale_f32 v166, s[12:13], v164, v164, 1.0
	v_rcp_f32_e32 v167, v166
	v_div_scale_f32 v168, vcc, 1.0, v164, 1.0
	v_fma_f32 v169, -v166, v167, 1.0
	v_fmac_f32_e32 v167, v169, v167
	v_mul_f32_e32 v169, v168, v167
	v_fma_f32 v170, -v166, v169, v168
	v_fmac_f32_e32 v169, v170, v167
	v_fma_f32 v166, -v166, v169, v168
	v_div_fmas_f32 v166, v166, v167, v169
	v_div_fixup_f32 v166, v166, v164, 1.0
	v_mul_f32_e32 v154, v166, v154
	v_mul_f32_e32 v155, v166, v155
	v_rndne_f32_e32 v154, v154
	v_rndne_f32_e32 v155, v155
	v_cvt_i32_f32_e32 v154, v154
	v_cvt_i32_f32_e32 v155, v155
	v_perm_b32 v167, v155, v154, s85
	v_add_u32_e32 v154, v154, v155
	ds_write_b16 v90, v167 offset:5120
	s_nop 1
	v_add_u32_dpp v154, v154, v154 quad_perm:[1,0,3,2] row_mask:0xf bank_mask:0xf bound_ctrl:1
	s_nop 1
	v_add_u32_dpp v154, v154, v154 quad_perm:[2,3,0,1] row_mask:0xf bank_mask:0xf bound_ctrl:1
	s_nop 1
	v_add_u32_dpp v154, v154, v154 row_half_mirror row_mask:0xf bank_mask:0xf bound_ctrl:1
	s_nop 1
	v_add_u32_dpp v154, v154, v154 row_mirror row_mask:0xf bank_mask:0xf bound_ctrl:1
	s_nop 1
	v_readlane_b32 s46, v154, 0
	v_readlane_b32 s47, v154, 16
	v_readlane_b32 s12, v154, 32
	v_readlane_b32 s13, v154, 48
	s_nop 1
	s_add_i32 s46, s47, s46
	s_add_i32 s46, s46, s12
	s_add_i32 s46, s46, s13
	s_add_i32 s47, s67, 160
	s_and_saveexec_b64 s[12:13], s[8:9]
	v_mov_b32_e32 v154, s47
	v_mov_b32_e32 v155, s46
	ds_write2st64_b32 v154, v164, v155 offset1:1
	s_or_b64 exec, exec, s[12:13]
	s_waitcnt vmcnt(2)
; #define LAS __attribute__((address_space(3)))
; __device__ __forceinline__ float gelu_as(float z) {
;     const float ax = fabsf(z) * 0.70710678118654752f, t = __builtin_amdgcn_rcpf(1.f + 0.3275911f * ax);
;     const float poly = t * (0.254829592f + t * (-0.284496736f + t * (1.421413741f + t * (-1.453152027f + t * 1.061405429f))));
;     const float er = 1.f - poly * __expf(-ax * ax);
;     return 0.5f * z * (1.f + copysignf(er, z));
; }
; __global__ void __launch_bounds__(NTHR, 2) k_main(Args a) {
;     ...
;                 const float z0 = (float)(2 * si.x + sx) * SU[e0] * xs, z1 = (float)(2 * si.y + sx) * SU[e1] * xs;
;                 const float a0 = gt.x * gelu_as(z0) * SV[e0], a1 = gt.y * gelu_as(z1) * SV[e1];
;                 const float mx = wave_max_dpp(fmaxf(fabsf(a0), fabsf(a1)));
;                 const float sc = mx > 0.f ? mx * (1.f / 119.f) : 1.f, inv = 1.f / sc;
;                 const int q0 = (int)rintf(a0 * inv), q1 = (int)rintf(a1 * inv);
;                 *(LAS unsigned short*)(AL + tl * 128 + 2 * lane) = (unsigned short)((q0 & 255) | ((q1 & 255) << 8));
;                 const int qs = wave_sum_dpp_i(q0 + q1);
;                 if (lane == 0) { ASC[tl] = sc; SAL[tl] = qs; }
	v_lshl_add_u32 v154, v38, 1, v64
	v_lshl_add_u32 v155, v39, 1, v64
	v_cvt_f32_i32_e32 v154, v154
	v_cvt_f32_i32_e32 v155, v155
	v_mul_f32_e32 v154, v134, v154
	v_mul_f32_e32 v155, v150, v155
	v_mul_f32_e32 v154, v72, v154
	v_mul_f32_e32 v155, v72, v155
	v_mul_f32_e64 v156, |v154|, s82
	v_mul_f32_e64 v157, |v155|, s82
	v_fma_f32 v158, v156, s83, 1.0
	v_fma_f32 v159, v157, s83, 1.0
	v_rcp_f32_e32 v158, v158
	v_rcp_f32_e32 v159, v159
	v_mul_f32_e64 v156, v156, -v156
	v_mul_f32_e64 v157, v157, -v157
	v_mul_f32_e32 v156, 0x3fb8aa3b, v156
	v_mul_f32_e32 v157, 0x3fb8aa3b, v157
	v_fmamk_f32 v160, v158, 0x3f87dc22, v110
	v_fmamk_f32 v161, v159, 0x3f87dc22, v110
	v_exp_f32_e32 v156, v156
	v_exp_f32_e32 v157, v157
	v_fmaak_f32 v160, v158, v160, 0x3fb5f0e3
	v_fmaak_f32 v161, v159, v161, 0x3fb5f0e3
	v_fmaak_f32 v160, v158, v160, 0xbe91a98e
	v_fmaak_f32 v161, v159, v161, 0xbe91a98e
	v_fmaak_f32 v160, v158, v160, 0x3e827906
	v_fmaak_f32 v161, v159, v161, 0x3e827906
	v_mul_f32_e32 v158, v158, v160
	v_mul_f32_e32 v159, v159, v161
	v_fma_f32 v156, -v156, v158, 1.0
	v_fma_f32 v157, -v157, v159, 1.0
	v_mul_f32_e32 v162, 0.5, v154
	v_mul_f32_e32 v163, 0.5, v155
	v_bfi_b32 v154, s84, v156, v154
	v_bfi_b32 v155, s84, v157, v155
	v_add_f32_e32 v154, 1.0, v154
	v_add_f32_e32 v155, 1.0, v155
	v_mul_f32_e32 v154, v162, v154
	v_mul_f32_e32 v155, v163, v155
	v_mul_f32_e32 v154, v54, v154
	v_mul_f32_e32 v155, v55, v155
	v_mul_f32_e32 v154, v135, v154
	v_mul_f32_e32 v155, v151, v155
	v_max_f32_e64 v164, |v154|, |v155|
	s_nop 1
	v_max_f32_dpp v164, v164, v164 quad_perm:[1,0,3,2] row_mask:0xf bank_mask:0xf
	s_nop 1
	v_max_f32_dpp v164, v164, v164 quad_perm:[2,3,0,1] row_mask:0xf bank_mask:0xf
	s_nop 1
	v_max_f32_dpp v164, v164, v164 row_half_mirror row_mask:0xf bank_mask:0xf
	s_nop 1
	v_max_f32_dpp v164, v164, v164 row_mirror row_mask:0xf bank_mask:0xf
	s_nop 1
	v_readlane_b32 s46, v164, 32
	v_readlane_b32 s47, v164, 48
	v_readlane_b32 s12, v164, 0
	v_readlane_b32 s13, v164, 16
	s_nop 1
	v_mov_b32_e32 v164, s47
	v_max_f32_e32 v164, s46, v164
	v_mov_b32_e32 v165, s13
	v_max3_f32 v164, s12, v165, v164
	v_mul_f32_e32 v165, 0x3c09ae41, v164
	v_cmp_lt_f32_e32 vcc, 0, v164
	s_nop 1
	v_cndmask_b32_e32 v164, 1.0, v165, vcc
	v_div_scale_f32 v166, s[12:13], v164, v164, 1.0
	v_rcp_f32_e32 v167, v166
	v_div_scale_f32 v168, vcc, 1.0, v164, 1.0
	v_fma_f32 v169, -v166, v167, 1.0
	v_fmac_f32_e32 v167, v169, v167
	v_mul_f32_e32 v169, v168, v167
	v_fma_f32 v170, -v166, v169, v168
	v_fmac_f32_e32 v169, v170, v167
	v_fma_f32 v166, -v166, v169, v168
	v_div_fmas_f32 v166, v166, v167, v169
	v_div_fixup_f32 v166, v166, v164, 1.0
	v_mul_f32_e32 v154, v166, v154
	v_mul_f32_e32 v155, v166, v155
	v_rndne_f32_e32 v154, v154
	v_rndne_f32_e32 v155, v155
	v_cvt_i32_f32_e32 v154, v154
	v_cvt_i32_f32_e32 v155, v155
	v_perm_b32 v167, v155, v154, s85
	v_add_u32_e32 v154, v154, v155
	ds_write_b16 v90, v167 offset:6144
	s_nop 1
	v_add_u32_dpp v154, v154, v154 quad_perm:[1,0,3,2] row_mask:0xf bank_mask:0xf bound_ctrl:1
	s_nop 1
	v_add_u32_dpp v154, v154, v154 quad_perm:[2,3,0,1] row_mask:0xf bank_mask:0xf bound_ctrl:1
	s_nop 1
	v_add_u32_dpp v154, v154, v154 row_half_mirror row_mask:0xf bank_mask:0xf bound_ctrl:1
	s_nop 1
	v_add_u32_dpp v154, v154, v154 row_mirror row_mask:0xf bank_mask:0xf bound_ctrl:1
	s_nop 1
	v_readlane_b32 s46, v154, 0
	v_readlane_b32 s47, v154, 16
	v_readlane_b32 s12, v154, 32
	v_readlane_b32 s13, v154, 48
	s_nop 1
	s_add_i32 s46, s47, s46
	s_add_i32 s46, s46, s12
	s_add_i32 s46, s46, s13
	s_add_i32 s47, s67, 192
	s_and_saveexec_b64 s[12:13], s[8:9]
	v_mov_b32_e32 v154, s47
	v_mov_b32_e32 v155, s46
	ds_write2st64_b32 v154, v164, v155 offset1:1
	s_or_b64 exec, exec, s[12:13]
	s_waitcnt vmcnt(0)
; #define LAS __attribute__((address_space(3)))
; __device__ __forceinline__ float gelu_as(float z) {
;     const float ax = fabsf(z) * 0.70710678118654752f, t = __builtin_amdgcn_rcpf(1.f + 0.3275911f * ax);
;     const float poly = t * (0.254829592f + t * (-0.284496736f + t * (1.421413741f + t * (-1.453152027f + t * 1.061405429f))));
;     const float er = 1.f - poly * __expf(-ax * ax);
;     return 0.5f * z * (1.f + copysignf(er, z));
; }
; __global__ void __launch_bounds__(NTHR, 2) k_main(Args a) {
;     ...
;                 const float z0 = (float)(2 * si.x + sx) * SU[e0] * xs, z1 = (float)(2 * si.y + sx) * SU[e1] * xs;
;                 const float a0 = gt.x * gelu_as(z0) * SV[e0], a1 = gt.y * gelu_as(z1) * SV[e1];
;                 const float mx = wave_max_dpp(fmaxf(fabsf(a0), fabsf(a1)));
;                 const float sc = mx > 0.f ? mx * (1.f / 119.f) : 1.f, inv = 1.f / sc;
;                 const int q0 = (int)rintf(a0 * inv), q1 = (int)rintf(a1 * inv);
;                 *(LAS unsigned short*)(AL + tl * 128 + 2 * lane) = (unsigned short)((q0 & 255) | ((q1 & 255) << 8));
;                 const int qs = wave_sum_dpp_i(q0 + q1);
;                 if (lane == 0) { ASC[tl] = sc; SAL[tl] = qs; }
	v_lshl_add_u32 v154, v40, 1, v65
	v_lshl_add_u32 v155, v41, 1, v65
	v_cvt_f32_i32_e32 v154, v154
	v_cvt_f32_i32_e32 v155, v155
	v_mul_f32_e32 v154, v136, v154
	v_mul_f32_e32 v155, v152, v155
	v_mul_f32_e32 v154, v73, v154
	v_mul_f32_e32 v155, v73, v155
	v_mul_f32_e64 v156, |v154|, s82
	v_mul_f32_e64 v157, |v155|, s82
	v_fma_f32 v158, v156, s83, 1.0
	v_fma_f32 v159, v157, s83, 1.0
	v_rcp_f32_e32 v158, v158
	v_rcp_f32_e32 v159, v159
	v_mul_f32_e64 v156, v156, -v156
	v_mul_f32_e64 v157, v157, -v157
	v_mul_f32_e32 v156, 0x3fb8aa3b, v156
	v_mul_f32_e32 v157, 0x3fb8aa3b, v157
	v_fmamk_f32 v160, v158, 0x3f87dc22, v110
	v_fmamk_f32 v161, v159, 0x3f87dc22, v110
	v_exp_f32_e32 v156, v156
	v_exp_f32_e32 v157, v157
	v_fmaak_f32 v160, v158, v160, 0x3fb5f0e3
	v_fmaak_f32 v161, v159, v161, 0x3fb5f0e3
	v_fmaak_f32 v160, v158, v160, 0xbe91a98e
	v_fmaak_f32 v161, v159, v161, 0xbe91a98e
	v_fmaak_f32 v160, v158, v160, 0x3e827906
	v_fmaak_f32 v161, v159, v161, 0x3e827906
	v_mul_f32_e32 v158, v158, v160
	v_mul_f32_e32 v159, v159, v161
	v_fma_f32 v156, -v156, v158, 1.0
	v_fma_f32 v157, -v157, v159, 1.0
	v_mul_f32_e32 v162, 0.5, v154
	v_mul_f32_e32 v163, 0.5, v155
	v_bfi_b32 v154, s84, v156, v154
	v_bfi_b32 v155, s84, v157, v155
	v_add_f32_e32 v154, 1.0, v154
	v_add_f32_e32 v155, 1.0, v155
	v_mul_f32_e32 v154, v162, v154
	v_mul_f32_e32 v155, v163, v155
	v_mul_f32_e32 v154, v56, v154
	v_mul_f32_e32 v155, v57, v155
	v_mul_f32_e32 v154, v137, v154
	v_mul_f32_e32 v155, v153, v155
	v_max_f32_e64 v164, |v154|, |v155|
	s_nop 1
	v_max_f32_dpp v164, v164, v164 quad_perm:[1,0,3,2] row_mask:0xf bank_mask:0xf
	s_nop 1
	v_max_f32_dpp v164, v164, v164 quad_perm:[2,3,0,1] row_mask:0xf bank_mask:0xf
	s_nop 1
	v_max_f32_dpp v164, v164, v164 row_half_mirror row_mask:0xf bank_mask:0xf
	s_nop 1
	v_max_f32_dpp v164, v164, v164 row_mirror row_mask:0xf bank_mask:0xf
	s_nop 1
	v_readlane_b32 s46, v164, 32
	v_readlane_b32 s47, v164, 48
	v_readlane_b32 s12, v164, 0
	v_readlane_b32 s13, v164, 16
	s_nop 1
	v_mov_b32_e32 v164, s47
	v_max_f32_e32 v164, s46, v164
	v_mov_b32_e32 v165, s13
	v_max3_f32 v164, s12, v165, v164
	v_mul_f32_e32 v165, 0x3c09ae41, v164
	v_cmp_lt_f32_e32 vcc, 0, v164
	s_nop 1
	v_cndmask_b32_e32 v164, 1.0, v165, vcc
	v_div_scale_f32 v166, s[12:13], v164, v164, 1.0
	v_rcp_f32_e32 v167, v166
	v_div_scale_f32 v168, vcc, 1.0, v164, 1.0
	v_fma_f32 v169, -v166, v167, 1.0
	v_fmac_f32_e32 v167, v169, v167
	v_mul_f32_e32 v169, v168, v167
	v_fma_f32 v170, -v166, v169, v168
	v_fmac_f32_e32 v169, v170, v167
	v_fma_f32 v166, -v166, v169, v168
	v_div_fmas_f32 v166, v166, v167, v169
	v_div_fixup_f32 v166, v166, v164, 1.0
	v_mul_f32_e32 v154, v166, v154
	v_mul_f32_e32 v155, v166, v155
	v_rndne_f32_e32 v154, v154
	v_rndne_f32_e32 v155, v155
	v_cvt_i32_f32_e32 v154, v154
	v_cvt_i32_f32_e32 v155, v155
	v_perm_b32 v167, v155, v154, s85
	v_add_u32_e32 v154, v154, v155
	ds_write_b16 v90, v167 offset:7168
	s_nop 1
	v_add_u32_dpp v154, v154, v154 quad_perm:[1,0,3,2] row_mask:0xf bank_mask:0xf bound_ctrl:1
	s_nop 1
	v_add_u32_dpp v154, v154, v154 quad_perm:[2,3,0,1] row_mask:0xf bank_mask:0xf bound_ctrl:1
	s_nop 1
	v_add_u32_dpp v154, v154, v154 row_half_mirror row_mask:0xf bank_mask:0xf bound_ctrl:1
	s_nop 1
	v_add_u32_dpp v154, v154, v154 row_mirror row_mask:0xf bank_mask:0xf bound_ctrl:1
	s_nop 1
	v_readlane_b32 s46, v154, 0
	v_readlane_b32 s47, v154, 16
	v_readlane_b32 s12, v154, 32
	v_readlane_b32 s13, v154, 48
	s_nop 1
	s_add_i32 s46, s47, s46
	s_add_i32 s46, s46, s12
	s_add_i32 s46, s46, s13
	s_add_i32 s47, s67, 224
	s_and_saveexec_b64 s[12:13], s[8:9]
	v_mov_b32_e32 v154, s47
	v_mov_b32_e32 v155, s46
	ds_write2st64_b32 v154, v164, v155 offset1:1
	s_or_b64 exec, exec, s[12:13]
